# attention selected-branch loop hand-scheduled: K reads batched, counted lgkmcnt, in-place PV accumulate, max3; flat->global
# speedup vs baseline: 1.0022x; 1.0022x over previous
; #define LAS __attribute__((address_space(3)))
; __device__ __forceinline__ unsigned pk2(float lo, float hi) { f32x2_t v = {lo, hi}; bf16x2_t b = __builtin_convertvector(v, bf16x2_t); return __builtin_bit_cast(unsigned, b); }
; __device__ __forceinline__ void transpose_tile(const float* colp  , int ld, int K, bf16_t* dst, int n0, int k0, const float* gk, LAS unsigned char* lds, int tid) {
;     ...
;         const int phys = kq ^ (c4 & 15);
; #pragma unroll
;         for (int e = 0; e < 4; ++e) { u32x2 w; w.x = pk2(r0[e], r1[e]); w.y = pk2(r2[e], r3[e]); *(LAS u32x2*)(lds + (4 * c4 + e) * 512 + phys * 8) = w; }
;     }
;     __syncthreads();
; #pragma unroll
;     for (int it = 0; it < 8; ++it) {
;         const int id = it * 512 + tid, row = id >> 5, q = id & 31, sw = (row >> 2) & 15;
;         u32x4 v = *(const LAS u32x4*)(lds + row * 512 + (q ^ (sw >> 1)) * 16);
;         if (sw & 1) v = (u32x4){v.z, v.w, v.x, v.y};
;         *(u32x4*)(dst + (size_t)(n0 + row) * K + k0 + 8 * q) = v;
;     }
;     __syncthreads();
.LBB0_33:
	v_cvt_pk_bf16_f32 v2, v20, v36
	v_cvt_pk_bf16_f32 v3, v52, v64
	v_cvt_pk_bf16_f32 v4, v21, v37
	v_cvt_pk_bf16_f32 v5, v53, v65
	ds_write2st64_b64 v92, v[2:3], v[4:5] offset1:1
	v_cvt_pk_bf16_f32 v2, v22, v38
	v_cvt_pk_bf16_f32 v3, v54, v66
	v_cvt_pk_bf16_f32 v4, v23, v39
	v_cvt_pk_bf16_f32 v5, v55, v67
	ds_write2st64_b64 v92, v[2:3], v[4:5] offset0:2 offset1:3
	s_waitcnt lgkmcnt(0)
	s_barrier
	ds_read_b128 v[2:5], v93
	s_ashr_i32 s15, s14, 31
	s_lshl_b64 s[8:9], s[14:15], 1
	s_add_u32 s8, s16, s8
	v_add_u32_e32 v1, s4, v69
	s_addc_u32 s9, s17, s9
	v_mov_b32_e32 v71, v0
	s_waitcnt lgkmcnt(0)
	v_cndmask_b32_e64 v6, v2, v4, s[6:7]
	v_cndmask_b32_e64 v4, v4, v2, s[6:7]
	v_ashrrev_i32_e32 v2, 31, v1
	v_lshl_add_u64 v[8:9], s[8:9], 0, v[70:71]
	v_cndmask_b32_e64 v7, v3, v5, s[6:7]
	v_cndmask_b32_e64 v5, v5, v3, s[6:7]
	v_mul_lo_u32 v10, s12, v2
	v_mul_lo_u32 v11, s13, v1
	v_mad_u64_u32 v[2:3], s[8:9], s12, v1, 0
	v_add3_u32 v3, v3, v10, v11
	v_lshl_add_u64 v[2:3], v[2:3], 1, v[8:9]
	global_store_dwordx4 v[2:3], v[4:7], off
	ds_read_b128 v[2:5], v94
	v_add_u32_e32 v1, s4, v82
	v_mul_lo_u32 v11, s13, v1
	s_add_i32 s30, s30, s58
	s_add_i32 s26, s26, s27
	s_waitcnt lgkmcnt(0)
	v_cndmask_b32_e64 v6, v2, v4, s[6:7]
	v_cndmask_b32_e64 v4, v4, v2, s[6:7]
	v_ashrrev_i32_e32 v2, 31, v1
	v_cndmask_b32_e64 v7, v3, v5, s[6:7]
	v_cndmask_b32_e64 v5, v5, v3, s[6:7]
	v_mul_lo_u32 v10, s12, v2
	v_mad_u64_u32 v[2:3], s[8:9], s12, v1, 0
	v_add3_u32 v3, v3, v10, v11
	v_lshl_add_u64 v[2:3], v[2:3], 1, v[8:9]
	global_store_dwordx4 v[2:3], v[4:7], off
	ds_read_b128 v[2:5], v95
	v_add_u32_e32 v1, s4, v83
	v_mul_lo_u32 v11, s13, v1
	s_add_i32 s28, s28, s29
	s_cmpk_gt_i32 s30, 0xa8f
	s_waitcnt lgkmcnt(0)
	v_cndmask_b32_e64 v6, v2, v4, s[6:7]
	v_cndmask_b32_e64 v4, v4, v2, s[6:7]
	v_ashrrev_i32_e32 v2, 31, v1
	v_cndmask_b32_e64 v7, v3, v5, s[6:7]
	v_cndmask_b32_e64 v5, v5, v3, s[6:7]
	v_mul_lo_u32 v10, s12, v2
	v_mad_u64_u32 v[2:3], s[8:9], s12, v1, 0
	v_add3_u32 v3, v3, v10, v11
	v_lshl_add_u64 v[2:3], v[2:3], 1, v[8:9]
	global_store_dwordx4 v[2:3], v[4:7], off
	ds_read_b128 v[2:5], v96
	v_add_u32_e32 v1, s4, v84
	v_mul_lo_u32 v11, s13, v1
	s_waitcnt lgkmcnt(0)
	v_cndmask_b32_e64 v6, v2, v4, s[6:7]
	v_cndmask_b32_e64 v4, v4, v2, s[6:7]
	v_ashrrev_i32_e32 v2, 31, v1
	v_cndmask_b32_e64 v7, v3, v5, s[6:7]
	v_cndmask_b32_e64 v5, v5, v3, s[6:7]
	v_mul_lo_u32 v10, s12, v2
	v_mad_u64_u32 v[2:3], s[8:9], s12, v1, 0
	v_add3_u32 v3, v3, v10, v11
	v_lshl_add_u64 v[2:3], v[2:3], 1, v[8:9]
	global_store_dwordx4 v[2:3], v[4:7], off
	ds_read_b128 v[2:5], v97
	v_add_u32_e32 v1, s4, v85
	v_mul_lo_u32 v11, s13, v1
	s_waitcnt lgkmcnt(0)
	v_cndmask_b32_e64 v6, v2, v4, s[6:7]
	v_cndmask_b32_e64 v4, v4, v2, s[6:7]
	v_ashrrev_i32_e32 v2, 31, v1
	v_cndmask_b32_e64 v7, v3, v5, s[6:7]
	v_cndmask_b32_e64 v5, v5, v3, s[6:7]
	v_mul_lo_u32 v10, s12, v2
	v_mad_u64_u32 v[2:3], s[8:9], s12, v1, 0
	v_add3_u32 v3, v3, v10, v11
	v_lshl_add_u64 v[2:3], v[2:3], 1, v[8:9]
	global_store_dwordx4 v[2:3], v[4:7], off
	ds_read_b128 v[2:5], v98
	v_add_u32_e32 v1, s4, v86
	v_mul_lo_u32 v11, s13, v1
	s_waitcnt lgkmcnt(0)
	v_cndmask_b32_e64 v6, v2, v4, s[6:7]
	v_cndmask_b32_e64 v4, v4, v2, s[6:7]
	v_ashrrev_i32_e32 v2, 31, v1
	v_cndmask_b32_e64 v7, v3, v5, s[6:7]
	v_cndmask_b32_e64 v5, v5, v3, s[6:7]
	v_mul_lo_u32 v10, s12, v2
	v_mad_u64_u32 v[2:3], s[8:9], s12, v1, 0
	v_add3_u32 v3, v3, v10, v11
	v_lshl_add_u64 v[2:3], v[2:3], 1, v[8:9]
	global_store_dwordx4 v[2:3], v[4:7], off
	ds_read_b128 v[2:5], v99
	v_add_u32_e32 v1, s4, v87
	v_mul_lo_u32 v11, s13, v1
	s_waitcnt lgkmcnt(0)
	v_cndmask_b32_e64 v6, v2, v4, s[6:7]
	v_cndmask_b32_e64 v4, v4, v2, s[6:7]
	v_ashrrev_i32_e32 v2, 31, v1
	v_cndmask_b32_e64 v7, v3, v5, s[6:7]
	v_cndmask_b32_e64 v5, v5, v3, s[6:7]
	v_mul_lo_u32 v10, s12, v2
	v_mad_u64_u32 v[2:3], s[8:9], s12, v1, 0
	v_add3_u32 v3, v3, v10, v11
	v_lshl_add_u64 v[2:3], v[2:3], 1, v[8:9]
	global_store_dwordx4 v[2:3], v[4:7], off
	ds_read_b128 v[2:5], v100
	v_add_u32_e32 v1, s4, v88
	v_mul_lo_u32 v11, s13, v1
	s_waitcnt lgkmcnt(0)
	v_cndmask_b32_e64 v6, v2, v4, s[6:7]
	v_cndmask_b32_e64 v4, v4, v2, s[6:7]
	v_ashrrev_i32_e32 v2, 31, v1
	v_cndmask_b32_e64 v7, v3, v5, s[6:7]
	v_cndmask_b32_e64 v5, v5, v3, s[6:7]
	v_mul_lo_u32 v10, s12, v2
	v_mad_u64_u32 v[2:3], s[4:5], s12, v1, 0
	v_add3_u32 v3, v3, v10, v11
	v_lshl_add_u64 v[2:3], v[2:3], 1, v[8:9]
	global_store_dwordx4 v[2:3], v[4:7], off
	s_waitcnt lgkmcnt(0)
	s_barrier
	s_cbranch_scc1 .LBB0_112

; __device__ __forceinline__ unsigned pk2(float lo, float hi) { f32x2_t v = {lo, hi}; bf16x2_t b = __builtin_convertvector(v, bf16x2_t); return __builtin_bit_cast(unsigned, b); }
; __device__ __forceinline__ void p0_phase(const Args& a, unsigned char* ws, LAS unsigned char* lds, const int tid, const int bid) {
;     ...
;         for (int m0 = gw; m0 < T; m0 += 4 * NGW) {
;             f32x4 v[4][4]; float ssum[4] = {0.f, 0.f, 0.f, 0.f};
; #pragma unroll
;             for (int e = 0; e < 4; ++e) { const int mm = (m0 + e * NGW < T) ? m0 + e * NGW : m0; const float* xr = a.in[0] + (size_t)mm * D + 4 * lane;
; #pragma unroll
;                 for (int j = 0; j < 4; ++j) v[e][j] = __builtin_nontemporal_load((const f32x4*)(xr + 256 * j)); }
; #pragma unroll
;             for (int e = 0; e < 4; ++e) { const int mm = (m0 + e * NGW < T) ? m0 + e * NGW : m0; bf16_t* o = XB + (size_t)mm * D + 4 * lane;
; #pragma unroll
;                 for (int j = 0; j < 4; ++j) { u32x2 w; w.x = pk2(v[e][j][0], v[e][j][1]); w.y = pk2(v[e][j][2], v[e][j][3]); *(u32x2*)(o + 256 * j) = w;
;                     const float r0 = bflo(w.x), r1 = bfhi(w.x), r2 = bflo(w.y), r3 = bfhi(w.y);
;                     ssum[e] += (r0 * r0 + r1 * r1) + (r2 * r2 + r3 * r3); } }
.LBB0_115:
	v_ashrrev_i32_e32 v9, 31, v8
	v_lshlrev_b64 v[10:11], 12, v[8:9]
	v_lshl_add_u64 v[10:11], v[6:7], 0, v[10:11]
	v_add_u32_e32 v23, s73, v8
	s_waitcnt lgkmcnt(0)
	global_load_dwordx4 v[24:27], v[10:11], off nt
	global_load_dwordx4 v[28:31], v[10:11], off offset:1024 nt
	global_load_dwordx4 v[32:35], v[10:11], off offset:2048 nt
	global_load_dwordx4 v[36:39], v[10:11], off offset:3072 nt
	v_cmp_gt_i32_e64 s[8:9], s61, v23
	v_lshlrev_b64 v[44:45], 11, v[8:9]
	v_lshl_add_u64 v[88:89], v[2:3], 0, v[44:45]
	v_cndmask_b32_e64 v10, v8, v23, s[8:9]
	v_ashrrev_i32_e32 v11, 31, v10
	v_lshlrev_b64 v[12:13], 12, v[10:11]
	v_lshl_add_u64 v[52:53], v[6:7], 0, v[12:13]
	global_load_dwordx4 v[40:43], v[52:53], off nt
	global_load_dwordx4 v[44:47], v[52:53], off offset:1024 nt
	v_add_u32_e32 v12, s75, v8
	v_add_u32_e32 v13, s50, v8
	v_cmp_gt_i32_e64 s[8:9], s61, v12
	v_lshlrev_b64 v[90:91], 11, v[10:11]
	s_waitcnt vmcnt(0)
	v_cvt_pk_bf16_f32 v24, v24, v25
	v_cndmask_b32_e64 v12, v8, v12, s[8:9]
	v_cmp_gt_i32_e64 s[8:9], s61, v13
	v_cvt_pk_bf16_f32 v25, v26, v27
	v_cvt_pk_bf16_f32 v26, v28, v29
	v_cndmask_b32_e64 v14, v8, v13, s[8:9]
	v_ashrrev_i32_e32 v13, 31, v12
	v_ashrrev_i32_e32 v15, 31, v14
	v_lshlrev_b64 v[48:49], 12, v[12:13]
	v_lshlrev_b64 v[50:51], 12, v[14:15]
	v_lshl_add_u64 v[68:69], v[6:7], 0, v[48:49]
	v_lshl_add_u64 v[84:85], v[6:7], 0, v[50:51]
	global_load_dwordx4 v[48:51], v[52:53], off offset:2048 nt
	s_nop 0
	global_load_dwordx4 v[52:55], v[52:53], off offset:3072 nt
	s_nop 0
	global_load_dwordx4 v[56:59], v[68:69], off nt
	global_load_dwordx4 v[60:63], v[68:69], off offset:1024 nt
	global_load_dwordx4 v[64:67], v[68:69], off offset:2048 nt
	s_nop 0
	global_load_dwordx4 v[68:71], v[68:69], off offset:3072 nt
	s_nop 0
	global_load_dwordx4 v[72:75], v[84:85], off nt
	global_load_dwordx4 v[76:79], v[84:85], off offset:1024 nt
	global_load_dwordx4 v[80:83], v[84:85], off offset:2048 nt
	s_nop 0
	global_load_dwordx4 v[84:87], v[84:85], off offset:3072 nt
	v_cvt_pk_bf16_f32 v27, v30, v31
	v_cvt_pk_bf16_f32 v28, v32, v33
	v_cvt_pk_bf16_f32 v29, v34, v35
	global_store_dwordx2 v[88:89], v[24:25], off
	v_lshlrev_b32_e32 v32, 16, v24
	v_and_b32_e32 v24, 0xffff0000, v24
	v_lshlrev_b32_e32 v33, 16, v25
	v_and_b32_e32 v25, 0xffff0000, v25
	global_store_dwordx2 v[88:89], v[26:27], off offset:512
	v_lshlrev_b32_e32 v34, 16, v26
	v_and_b32_e32 v26, 0xffff0000, v26
	v_lshlrev_b32_e32 v35, 16, v27
	v_and_b32_e32 v27, 0xffff0000, v27
	v_cvt_pk_bf16_f32 v30, v36, v37
	v_cvt_pk_bf16_f32 v31, v38, v39
	global_store_dwordx2 v[88:89], v[28:29], off offset:1024
	v_lshlrev_b32_e32 v36, 16, v28
	v_and_b32_e32 v28, 0xffff0000, v28
	v_lshlrev_b32_e32 v37, 16, v29
	v_and_b32_e32 v29, 0xffff0000, v29
	v_mul_f32_e32 v24, v24, v24
	v_mul_f32_e32 v25, v25, v25
	v_mul_f32_e32 v26, v26, v26
	v_mul_f32_e32 v27, v27, v27
	global_store_dwordx2 v[88:89], v[30:31], off offset:1536
	v_lshlrev_b32_e32 v38, 16, v30
	v_and_b32_e32 v30, 0xffff0000, v30
	v_lshlrev_b32_e32 v39, 16, v31
	v_and_b32_e32 v31, 0xffff0000, v31
	v_mul_f32_e32 v28, v28, v28
	v_mul_f32_e32 v29, v29, v29
	v_fmac_f32_e32 v24, v32, v32
	v_fmac_f32_e32 v25, v33, v33
	v_fmac_f32_e32 v26, v34, v34
	v_fmac_f32_e32 v27, v35, v35
	v_mul_f32_e32 v30, v30, v30
	v_mul_f32_e32 v31, v31, v31
	v_fmac_f32_e32 v28, v36, v36
	v_fmac_f32_e32 v29, v37, v37
	v_add_f32_e32 v24, v24, v25
	v_add_f32_e32 v25, v26, v27
	v_fmac_f32_e32 v30, v38, v38
	v_fmac_f32_e32 v31, v39, v39
	v_add_f32_e32 v26, v28, v29
	v_add_f32_e32 v24, v24, v25
	v_add_f32_e32 v27, v30, v31
	v_add_f32_e32 v24, v24, v26
	v_add_f32_e32 v88, v24, v27
	v_lshl_add_u64 v[24:25], v[2:3], 0, v[90:91]
	v_cvt_pk_bf16_f32 v26, v40, v41
	v_cvt_pk_bf16_f32 v27, v42, v43
	global_store_dwordx2 v[24:25], v[26:27], off
	v_lshlrev_b32_e32 v28, 16, v26
	v_and_b32_e32 v26, 0xffff0000, v26
	v_lshlrev_b32_e32 v29, 16, v27
	v_and_b32_e32 v27, 0xffff0000, v27
	v_mul_f32_e32 v26, v26, v26
	v_mul_f32_e32 v27, v27, v27
	v_fmac_f32_e32 v26, v28, v28
	v_fmac_f32_e32 v27, v29, v29
	v_add_f32_e32 v28, v26, v27
	v_cvt_pk_bf16_f32 v26, v44, v45
	v_cvt_pk_bf16_f32 v27, v46, v47
	global_store_dwordx2 v[24:25], v[26:27], off offset:512
	v_lshlrev_b32_e32 v29, 16, v26
	v_and_b32_e32 v26, 0xffff0000, v26
	v_lshlrev_b32_e32 v30, 16, v27
	v_and_b32_e32 v27, 0xffff0000, v27
	v_mul_f32_e32 v26, v26, v26
	v_mul_f32_e32 v27, v27, v27
	v_fmac_f32_e32 v26, v29, v29
	v_fmac_f32_e32 v27, v30, v30
	v_add_f32_e32 v26, v26, v27
	v_add_f32_e32 v28, v28, v26
	s_waitcnt vmcnt(0)
; __device__ __forceinline__ unsigned pk2(float lo, float hi) { f32x2_t v = {lo, hi}; bf16x2_t b = __builtin_convertvector(v, bf16x2_t); return __builtin_bit_cast(unsigned, b); }
; __device__ __forceinline__ float shflx(float v, int mask, int lane) { return __builtin_bit_cast(float, __builtin_amdgcn_ds_bpermute(((lane ^ mask) & 63) << 2, __builtin_bit_cast(int, v))); }
; __device__ __forceinline__ void p0_phase(const Args& a, unsigned char* ws, LAS unsigned char* lds, const int tid, const int bid) {
;     ...
;             for (int e = 0; e < 4; ++e) { const int mm = (m0 + e * NGW < T) ? m0 + e * NGW : m0; bf16_t* o = XB + (size_t)mm * D + 4 * lane;
; #pragma unroll
;                 for (int j = 0; j < 4; ++j) { u32x2 w; w.x = pk2(v[e][j][0], v[e][j][1]); w.y = pk2(v[e][j][2], v[e][j][3]); *(u32x2*)(o + 256 * j) = w;
;                     const float r0 = bflo(w.x), r1 = bfhi(w.x), r2 = bflo(w.y), r3 = bfhi(w.y);
;                     ssum[e] += (r0 * r0 + r1 * r1) + (r2 * r2 + r3 * r3); } }
; #pragma unroll
;             for (int o_ = 1; o_ < 64; o_ <<= 1) { ssum[0] += shflx(ssum[0], o_, lane); ssum[1] += shflx(ssum[1], o_, lane); ssum[2] += shflx(ssum[2], o_, lane); ssum[3] += shflx(ssum[3], o_, lane); }
; #pragma unroll
;             for (int e = 0; e < 4; ++e) { const int mm = (m0 + e * NGW < T) ? m0 + e * NGW : m0; if (lane < 4) SSP[(size_t)mm * 4 + lane] = lane == 0 ? ssum[e] : 0.f; }
	v_cvt_pk_bf16_f32 v26, v48, v49
	v_cvt_pk_bf16_f32 v27, v50, v51
	global_store_dwordx2 v[24:25], v[26:27], off offset:1024
	v_lshlrev_b32_e32 v29, 16, v26
	v_and_b32_e32 v26, 0xffff0000, v26
	v_lshlrev_b32_e32 v30, 16, v27
	v_and_b32_e32 v27, 0xffff0000, v27
	v_mul_f32_e32 v26, v26, v26
	v_mul_f32_e32 v27, v27, v27
	v_fmac_f32_e32 v26, v29, v29
	v_fmac_f32_e32 v27, v30, v30
	v_add_f32_e32 v26, v26, v27
	v_add_f32_e32 v28, v28, v26
	v_cvt_pk_bf16_f32 v26, v52, v53
	v_cvt_pk_bf16_f32 v27, v54, v55
	global_store_dwordx2 v[24:25], v[26:27], off offset:1536
	v_and_b32_e32 v25, 0xffff0000, v26
	v_lshlrev_b32_e32 v24, 16, v26
	v_lshlrev_b32_e32 v26, 16, v27
	v_and_b32_e32 v27, 0xffff0000, v27
	v_mul_f32_e32 v25, v25, v25
	v_fmac_f32_e32 v25, v24, v24
	v_mul_f32_e32 v24, v27, v27
	v_fmac_f32_e32 v24, v26, v26
	v_add_f32_e32 v24, v25, v24
	v_add_f32_e32 v40, v28, v24
	v_lshlrev_b64 v[24:25], 11, v[12:13]
	v_lshl_add_u64 v[24:25], v[2:3], 0, v[24:25]
	v_cvt_pk_bf16_f32 v26, v56, v57
	v_cvt_pk_bf16_f32 v27, v58, v59
	global_store_dwordx2 v[24:25], v[26:27], off
	v_lshlrev_b32_e32 v28, 16, v26
	v_and_b32_e32 v26, 0xffff0000, v26
	v_lshlrev_b32_e32 v29, 16, v27
	v_and_b32_e32 v27, 0xffff0000, v27
	v_mul_f32_e32 v26, v26, v26
	v_mul_f32_e32 v27, v27, v27
	v_fmac_f32_e32 v26, v28, v28
	v_fmac_f32_e32 v27, v29, v29
	v_add_f32_e32 v28, v26, v27
	v_cvt_pk_bf16_f32 v26, v60, v61
	v_cvt_pk_bf16_f32 v27, v62, v63
	v_and_b32_e32 v30, 0xffff0000, v26
	v_lshlrev_b32_e32 v29, 16, v26
	v_and_b32_e32 v32, 0xffff0000, v27
	v_mul_f32_e32 v30, v30, v30
	v_lshlrev_b32_e32 v31, 16, v27
	v_fmac_f32_e32 v30, v29, v29
	v_mul_f32_e32 v29, v32, v32
	v_fmac_f32_e32 v29, v31, v31
	v_add_f32_e32 v29, v30, v29
	v_add_f32_e32 v30, v28, v29
	v_cvt_pk_bf16_f32 v28, v64, v65
	v_cvt_pk_bf16_f32 v29, v66, v67
	v_and_b32_e32 v32, 0xffff0000, v28
	v_lshlrev_b32_e32 v31, 16, v28
	v_and_b32_e32 v34, 0xffff0000, v29
	v_mul_f32_e32 v32, v32, v32
	v_lshlrev_b32_e32 v33, 16, v29
	v_fmac_f32_e32 v32, v31, v31
	v_mul_f32_e32 v31, v34, v34
	v_fmac_f32_e32 v31, v33, v33
	v_add_f32_e32 v31, v32, v31
	v_add_f32_e32 v32, v30, v31
	v_cvt_pk_bf16_f32 v30, v68, v69
	v_cvt_pk_bf16_f32 v31, v70, v71
	v_and_b32_e32 v34, 0xffff0000, v30
	v_lshlrev_b32_e32 v33, 16, v30
	v_and_b32_e32 v36, 0xffff0000, v31
	v_mul_f32_e32 v34, v34, v34
	v_lshlrev_b32_e32 v35, 16, v31
	v_fmac_f32_e32 v34, v33, v33
	v_mul_f32_e32 v33, v36, v36
	v_fmac_f32_e32 v33, v35, v35
	v_add_f32_e32 v33, v34, v33
	v_add_f32_e32 v41, v32, v33
	v_cvt_pk_bf16_f32 v32, v72, v73
	v_cvt_pk_bf16_f32 v33, v74, v75
	v_and_b32_e32 v35, 0xffff0000, v32
	v_lshlrev_b32_e32 v34, 16, v32
	v_and_b32_e32 v37, 0xffff0000, v33
	v_mul_f32_e32 v35, v35, v35
	v_lshlrev_b32_e32 v36, 16, v33
	v_fmac_f32_e32 v35, v34, v34
	v_mul_f32_e32 v34, v37, v37
	v_fmac_f32_e32 v34, v36, v36
	v_add_f32_e32 v36, v35, v34
	v_cvt_pk_bf16_f32 v34, v76, v77
	v_cvt_pk_bf16_f32 v35, v78, v79
	v_and_b32_e32 v38, 0xffff0000, v34
	v_lshlrev_b32_e32 v37, 16, v34
	v_and_b32_e32 v42, 0xffff0000, v35
	v_mul_f32_e32 v38, v38, v38
	v_lshlrev_b32_e32 v39, 16, v35
	v_fmac_f32_e32 v38, v37, v37
	v_mul_f32_e32 v37, v42, v42
	v_fmac_f32_e32 v37, v39, v39
	v_add_f32_e32 v37, v38, v37
	v_add_f32_e32 v38, v36, v37
	v_cvt_pk_bf16_f32 v36, v80, v81
	v_cvt_pk_bf16_f32 v37, v82, v83
	v_and_b32_e32 v42, 0xffff0000, v36
	v_lshlrev_b32_e32 v39, 16, v36
	v_and_b32_e32 v44, 0xffff0000, v37
	v_mul_f32_e32 v42, v42, v42
	v_lshlrev_b32_e32 v43, 16, v37
	v_fmac_f32_e32 v42, v39, v39
	v_mul_f32_e32 v39, v44, v44
	v_fmac_f32_e32 v39, v43, v43
	v_add_f32_e32 v39, v42, v39
	v_add_f32_e32 v42, v38, v39
	v_cvt_pk_bf16_f32 v38, v84, v85
	v_cvt_pk_bf16_f32 v39, v86, v87
	v_and_b32_e32 v44, 0xffff0000, v38
	v_lshlrev_b32_e32 v43, 16, v38
	v_and_b32_e32 v46, 0xffff0000, v39
	v_mul_f32_e32 v44, v44, v44
	v_lshlrev_b32_e32 v45, 16, v39
	v_fmac_f32_e32 v44, v43, v43
	v_mul_f32_e32 v43, v46, v46
	v_fmac_f32_e32 v43, v45, v45
	v_add_f32_e32 v43, v44, v43
	v_add_f32_e32 v42, v42, v43
	ds_bpermute_b32 v43, v17, v88
	ds_bpermute_b32 v44, v17, v40
	ds_bpermute_b32 v45, v17, v41
	ds_bpermute_b32 v46, v17, v42
	global_store_dwordx2 v[24:25], v[26:27], off offset:512
	s_waitcnt lgkmcnt(0)
	v_add_f32_e32 v26, v88, v43
	v_add_f32_e32 v27, v40, v44
	v_add_f32_e32 v40, v41, v45
	v_add_f32_e32 v41, v42, v46
	ds_bpermute_b32 v42, v18, v26
	ds_bpermute_b32 v43, v18, v27
	ds_bpermute_b32 v44, v18, v40
	ds_bpermute_b32 v45, v18, v41
	global_store_dwordx2 v[24:25], v[28:29], off offset:1024
	s_waitcnt lgkmcnt(0)
	v_add_f32_e32 v26, v26, v42
	v_add_f32_e32 v27, v27, v43
	v_add_f32_e32 v28, v40, v44
	v_add_f32_e32 v29, v41, v45
	ds_bpermute_b32 v40, v19, v26
	ds_bpermute_b32 v41, v19, v27
	ds_bpermute_b32 v42, v19, v28
	ds_bpermute_b32 v43, v19, v29
	global_store_dwordx2 v[24:25], v[30:31], off offset:1536
	s_waitcnt lgkmcnt(0)
	v_add_f32_e32 v26, v26, v40
	v_add_f32_e32 v27, v27, v41
	v_add_f32_e32 v28, v28, v42
	v_add_f32_e32 v29, v29, v43
	ds_bpermute_b32 v30, v20, v26
	ds_bpermute_b32 v31, v20, v27
	ds_bpermute_b32 v40, v20, v28
	ds_bpermute_b32 v41, v20, v29
	v_lshlrev_b64 v[24:25], 11, v[14:15]
	s_waitcnt lgkmcnt(0)
	v_add_f32_e32 v26, v26, v30
	v_add_f32_e32 v27, v27, v31
	v_add_f32_e32 v28, v28, v40
	v_add_f32_e32 v29, v29, v41
	ds_bpermute_b32 v30, v21, v26
	ds_bpermute_b32 v31, v21, v27
	ds_bpermute_b32 v42, v21, v28
	ds_bpermute_b32 v43, v21, v29
	v_lshl_add_u64 v[40:41], v[2:3], 0, v[24:25]
	s_waitcnt lgkmcnt(0)
	v_add_f32_e32 v24, v26, v30
	v_add_f32_e32 v25, v27, v31
	v_add_f32_e32 v26, v28, v42
	v_add_f32_e32 v28, v29, v43
	ds_bpermute_b32 v27, v22, v24
	ds_bpermute_b32 v29, v22, v25
	ds_bpermute_b32 v30, v22, v26
	ds_bpermute_b32 v31, v22, v28
	global_store_dwordx2 v[40:41], v[32:33], off
	global_store_dwordx2 v[40:41], v[34:35], off offset:512
	global_store_dwordx2 v[40:41], v[36:37], off offset:1024
	global_store_dwordx2 v[40:41], v[38:39], off offset:1536
	s_and_saveexec_b64 s[8:9], vcc
	s_cbranch_execz .LBB0_114
	s_waitcnt lgkmcnt(0)
	v_add_f32_e32 v24, v24, v27
	v_add_f32_e32 v25, v25, v29
	v_cndmask_b32_e64 v24, 0, v24, s[6:7]
	v_lshl_add_u64 v[8:9], v[8:9], 4, v[4:5]
	v_add_f32_e32 v26, v26, v30
	global_store_dword v[8:9], v24, off
	v_cndmask_b32_e64 v24, 0, v25, s[6:7]
	v_lshl_add_u64 v[8:9], v[10:11], 4, v[4:5]
	v_add_f32_e32 v28, v28, v31
	global_store_dword v[8:9], v24, off
	v_cndmask_b32_e64 v10, 0, v26, s[6:7]
	v_lshl_add_u64 v[8:9], v[12:13], 4, v[4:5]
	global_store_dword v[8:9], v10, off
	v_cndmask_b32_e64 v10, 0, v28, s[6:7]
	v_lshl_add_u64 v[8:9], v[14:15], 4, v[4:5]
	global_store_dword v[8:9], v10, off
	s_branch .LBB0_114

; __device__ __forceinline__ void p0_phase(const Args& a, unsigned char* ws, LAS unsigned char* lds, const int tid, const int bid) {
;     ...
;         for (int task = gw; task < NL * 2 * 4 * 64; task += NGW) {
;             const int kc = task & 63, cg_ = (task >> 6) & 3, kv = (task >> 8) & 1, l = task >> 9;
;             const int col = cg_ * 64 + lane;
;             const float* pos = a.in[kv ? 10 : 7] + (size_t)l * 2048 + kc * 32;
;             const float* w1 = a.in[kv ? 11 : 8] + (size_t)l * 2048 * 256 + (size_t)kc * 32 * 256 + col;
;             float s0 = 0.f, s1 = 0.f, s2 = 0.f, s3 = 0.f;
; #pragma unroll
;             for (int k = 0; k < 32; k += 4) { s0 += pos[k] * w1[(size_t)k * 256]; s1 += pos[k + 1] * w1[(size_t)(k + 1) * 256]; s2 += pos[k + 2] * w1[(size_t)(k + 2) * 256]; s3 += pos[k + 3] * w1[(size_t)(k + 3) * 256]; }
;             PART[kc * 2048 + (l * 2 + kv) * 256 + col] = (s0 + s1) + (s2 + s3);
;         }
.LBB0_119:
	v_bfe_u32 v17, v16, 8, 1
	v_cmp_eq_u32_e32 vcc, 0, v17
	s_waitcnt lgkmcnt(0)
	v_mov_b32_e32 v3, v0
	v_mov_b32_e32 v5, v0
	v_cndmask_b32_e64 v2, v243, 56, vcc
	v_lshl_add_u64 v[2:3], s[0:1], 0, v[2:3]
	v_cndmask_b32_e64 v4, v244, 64, vcc
	global_load_dwordx2 v[2:3], v[2:3], off
	v_lshl_add_u64 v[4:5], s[0:1], 0, v[4:5]
	global_load_dwordx2 v[4:5], v[4:5], off
	v_ashrrev_i32_e32 v6, 9, v16
	v_ashrrev_i32_e32 v7, 31, v6
	v_and_b32_e32 v70, 63, v16
	v_lshlrev_b64 v[12:13], 13, v[6:7]
	v_mov_b32_e32 v9, v0
	v_lshlrev_b32_e32 v8, 7, v70
	v_lshlrev_b64 v[6:7], 21, v[6:7]
	v_and_or_b32 v71, v16, s70, v1
	v_mov_b32_e32 v11, v0
	v_lshlrev_b32_e32 v10, 15, v70
	v_mov_b32_e32 v15, v0
	v_lshlrev_b32_e32 v14, 2, v71
	v_lshlrev_b32_e32 v17, 8, v17
	s_movk_i32 s10, 0x7ff
	s_waitcnt vmcnt(0)
	v_lshl_add_u64 v[2:3], v[2:3], 0, v[12:13]
	v_lshl_add_u64 v[34:35], v[2:3], 0, v[8:9]
	v_lshl_add_u64 v[2:3], v[4:5], 0, v[6:7]
	v_lshl_add_u64 v[38:39], v[2:3], 0, v[10:11]
	v_lshl_add_u64 v[14:15], v[38:39], 0, v[14:15]
	v_add_co_u32_e32 v38, vcc, s79, v14
	global_load_dwordx4 v[2:5], v[34:35], off offset:48
	global_load_dwordx4 v[6:9], v[34:35], off offset:32
	global_load_dwordx4 v[10:13], v[34:35], off offset:16
	global_load_dwordx4 v[18:21], v[34:35], off
	global_load_dwordx4 v[22:25], v[34:35], off offset:112
	global_load_dwordx4 v[26:29], v[34:35], off offset:96
	global_load_dwordx4 v[30:33], v[34:35], off offset:80
	s_nop 0
	global_load_dwordx4 v[34:37], v[34:35], off offset:64
	v_addc_co_u32_e32 v39, vcc, 0, v15, vcc
	v_add_co_u32_e32 v40, vcc, s80, v14
	s_nop 1
	v_addc_co_u32_e32 v41, vcc, 0, v15, vcc
	v_add_co_u32_e32 v42, vcc, s78, v14
	s_nop 1
	v_addc_co_u32_e32 v43, vcc, 0, v15, vcc
	v_add_co_u32_e32 v44, vcc, s81, v14
	s_nop 1
	v_addc_co_u32_e32 v45, vcc, 0, v15, vcc
	v_add_co_u32_e32 v46, vcc, s74, v14
	s_nop 1
	v_addc_co_u32_e32 v47, vcc, 0, v15, vcc
	v_add_co_u32_e32 v48, vcc, s60, v14
	s_nop 1
	v_addc_co_u32_e32 v49, vcc, 0, v15, vcc
	v_add_co_u32_e32 v50, vcc, s56, v14
	s_nop 1
	v_addc_co_u32_e32 v51, vcc, 0, v15, vcc
	global_load_dword v52, v[14:15], off
	global_load_dword v54, v[14:15], off offset:1024
	global_load_dword v53, v[14:15], off offset:2048
	global_load_dword v55, v[14:15], off offset:3072
	s_nop 0
	global_load_dword v14, v[38:39], off offset:1024
	global_load_dword v57, v[38:39], off offset:2048
	global_load_dword v15, v[38:39], off offset:3072
	s_nop 0
	global_load_dword v38, v[42:43], off offset:1024
	global_load_dword v59, v[42:43], off offset:2048
	global_load_dword v39, v[42:43], off offset:3072
	global_load_dword v56, v[40:41], off offset:-4096
	s_nop 0
	global_load_dword v42, v[40:41], off
	global_load_dword v60, v[40:41], off offset:1024
	global_load_dword v43, v[40:41], off offset:2048
	global_load_dword v61, v[40:41], off offset:3072
	global_load_dword v58, v[44:45], off offset:-4096
	s_nop 0
	global_load_dword v40, v[44:45], off
	global_load_dword v62, v[44:45], off offset:1024
	global_load_dword v41, v[44:45], off offset:2048
	global_load_dword v63, v[44:45], off offset:3072
	s_nop 0
	global_load_dword v44, v[48:49], off offset:-4096
	global_load_dword v64, v[48:49], off
	global_load_dword v66, v[48:49], off offset:1024
	global_load_dword v65, v[48:49], off offset:2048
	global_load_dword v67, v[48:49], off offset:3072
	s_nop 0
	global_load_dword v48, v[46:47], off offset:1024
	global_load_dword v45, v[46:47], off offset:2048
	global_load_dword v49, v[46:47], off offset:3072
	s_nop 0
	global_load_dword v46, v[50:51], off
	global_load_dword v68, v[50:51], off offset:1024
	global_load_dword v47, v[50:51], off offset:2048
	global_load_dword v69, v[50:51], off offset:3072
	v_and_b32_e32 v50, 0xfffffe00, v16
	v_lshl_add_u32 v50, v70, 11, v50
	v_or3_b32 v50, v50, v17, v71
	v_add_u32_e32 v16, s73, v16
	v_cmp_lt_i32_e32 vcc, s10, v16
	v_ashrrev_i32_e32 v51, 31, v50
	s_or_b64 s[8:9], vcc, s[8:9]
	v_lshl_add_u64 v[50:51], v[50:51], 2, s[6:7]
	s_waitcnt vmcnt(36)
	v_mov_b32_e32 v70, v18
	v_mov_b32_e32 v71, v20
	v_mov_b32_e32 v20, v19
	v_mov_b32_e32 v18, v10
	v_mov_b32_e32 v19, v12
	v_mov_b32_e32 v12, v11
	v_mov_b32_e32 v10, v6
	v_mov_b32_e32 v11, v8
	v_mov_b32_e32 v8, v7
	v_mov_b32_e32 v6, v2
	v_mov_b32_e32 v7, v4
	v_mov_b32_e32 v4, v3
	s_waitcnt vmcnt(32)
	v_mov_b32_e32 v2, v34
	v_mov_b32_e32 v3, v36
	v_mov_b32_e32 v36, v35
	v_mov_b32_e32 v34, v30
	v_mov_b32_e32 v35, v32
	v_mov_b32_e32 v32, v31
	v_mov_b32_e32 v30, v26
	v_mov_b32_e32 v31, v28
	v_mov_b32_e32 v28, v27
	v_mov_b32_e32 v26, v22
	v_mov_b32_e32 v27, v24
	v_mov_b32_e32 v24, v23
	s_waitcnt vmcnt(29)
	v_pk_fma_f32 v[22:23], v[70:71], v[52:53], 0 op_sel_hi:[1,1,0]
	s_waitcnt vmcnt(28)
	v_pk_fma_f32 v[20:21], v[20:21], v[54:55], 0 op_sel_hi:[1,1,0]
	s_waitcnt vmcnt(21)
	v_pk_fma_f32 v[18:19], v[18:19], v[56:57], v[22:23]
	v_pk_fma_f32 v[12:13], v[12:13], v[14:15], v[20:21]
	s_waitcnt vmcnt(18)
	v_pk_fma_f32 v[10:11], v[10:11], v[42:43], v[18:19]
	s_waitcnt vmcnt(17)
	v_pk_fma_f32 v[8:9], v[8:9], v[60:61], v[12:13]
	s_waitcnt vmcnt(16)
	v_pk_fma_f32 v[6:7], v[6:7], v[58:59], v[10:11]
	v_pk_fma_f32 v[4:5], v[4:5], v[38:39], v[8:9]
	s_waitcnt vmcnt(13)
	v_pk_fma_f32 v[2:3], v[2:3], v[40:41], v[6:7]
	s_waitcnt vmcnt(12)
	v_pk_fma_f32 v[4:5], v[36:37], v[62:63], v[4:5]
	s_waitcnt vmcnt(5)
	v_pk_fma_f32 v[2:3], v[34:35], v[44:45], v[2:3]
	s_waitcnt vmcnt(4)
	v_pk_fma_f32 v[4:5], v[32:33], v[48:49], v[4:5]
	v_pk_fma_f32 v[2:3], v[30:31], v[64:65], v[2:3]
	v_pk_fma_f32 v[4:5], v[28:29], v[66:67], v[4:5]
	s_waitcnt vmcnt(1)
	v_pk_fma_f32 v[2:3], v[26:27], v[46:47], v[2:3]
	s_waitcnt vmcnt(0)
	v_pk_fma_f32 v[4:5], v[24:25], v[68:69], v[4:5]
	s_nop 0
	v_pk_add_f32 v[2:3], v[2:3], v[4:5]
	s_nop 0
	v_add_f32_e32 v2, v2, v3
	global_store_dword v[50:51], v2, off
	s_andn2_b64 exec, exec, s[8:9]
	s_cbranch_execnz .LBB0_119

; __device__ __forceinline__ unsigned pk2(float lo, float hi) { f32x2_t v = {lo, hi}; bf16x2_t b = __builtin_convertvector(v, bf16x2_t); return __builtin_bit_cast(unsigned, b); }
; __device__ __forceinline__ void attn_unit(unsigned char* ws, LAS unsigned char* lds, int b, int g, int c, const int tid) {
;     ...
;     { const float gate2 = ((const float*)(ws + WS_G))[row * 32 + head * 3 + 2]; const float sc = st.l > 0.f ? gate2 / st.l : 0.f;
; #pragma unroll
;       for (int i = 0; i < 16; ++i) { st.o0[i] = outl[i * 512] + st.o0[i] * sc; st.o1[i] = outl[(16 + i) * 512] + st.o1[i] * sc; } }
;     bf16_t* op = (bf16_t*)(ws + WS_ATT) + row * 1024 + head * 64 + 4 * h;
; #pragma unroll
;     for (int gi = 0; gi < 4; ++gi) {
;         u32x2 w0; w0.x = pk2(st.o0[4 * gi], st.o0[4 * gi + 1]); w0.y = pk2(st.o0[4 * gi + 2], st.o0[4 * gi + 3]); *(u32x2*)(op + 8 * gi) = w0;
;         u32x2 w1; w1.x = pk2(st.o1[4 * gi], st.o1[4 * gi + 1]); w1.y = pk2(st.o1[4 * gi + 2], st.o1[4 * gi + 3]); *(u32x2*)(op + 32 + 8 * gi) = w1;
;     }
; __device__ __forceinline__ void attn_phase(unsigned char* ws, LAS unsigned char* lds, const int tid, const int bid, const int l) {
;     ...
;         __syncthreads();
;         u = slot[0];
.LBB0_131:
	s_or_b64 exec, exec, s[4:5]
	ds_read2st64_b32 v[36:37], v199 offset1:8
	ds_read2st64_b32 v[38:39], v199 offset0:128 offset1:136
	ds_read2st64_b32 v[40:41], v199 offset0:16 offset1:24
	ds_read2st64_b32 v[42:43], v199 offset0:144 offset1:152
	ds_read2st64_b32 v[44:45], v199 offset0:32 offset1:40
	s_waitcnt lgkmcnt(0)
	v_pk_fma_f32 v[18:19], v[18:19], v[34:35], v[36:37] op_sel_hi:[1,0,1]
	v_pk_fma_f32 v[2:3], v[2:3], v[34:35], v[38:39] op_sel_hi:[1,0,1]
	ds_read2st64_b32 v[36:37], v199 offset0:160 offset1:168
	ds_read2st64_b32 v[38:39], v199 offset0:48 offset1:56
	v_pk_fma_f32 v[20:21], v[20:21], v[34:35], v[40:41] op_sel_hi:[1,0,1]
	v_pk_fma_f32 v[4:5], v[4:5], v[34:35], v[42:43] op_sel_hi:[1,0,1]
	v_pk_fma_f32 v[22:23], v[22:23], v[34:35], v[44:45] op_sel_hi:[1,0,1]
	s_waitcnt lgkmcnt(0)
	v_pk_fma_f32 v[6:7], v[6:7], v[34:35], v[36:37] op_sel_hi:[1,0,1]
	ds_read2st64_b32 v[36:37], v199 offset0:176 offset1:184
	ds_read2st64_b32 v[40:41], v199 offset0:64 offset1:72
	ds_read2st64_b32 v[42:43], v199 offset0:192 offset1:200
	v_pk_fma_f32 v[24:25], v[24:25], v[34:35], v[38:39] op_sel_hi:[1,0,1]
	ds_read2st64_b32 v[38:39], v199 offset0:80 offset1:88
	s_waitcnt lgkmcnt(0)
	v_pk_fma_f32 v[8:9], v[8:9], v[34:35], v[36:37] op_sel_hi:[1,0,1]
	v_pk_fma_f32 v[26:27], v[26:27], v[34:35], v[40:41] op_sel_hi:[1,0,1]
	v_pk_fma_f32 v[10:11], v[10:11], v[34:35], v[42:43] op_sel_hi:[1,0,1]
	ds_read2st64_b32 v[36:37], v199 offset0:208 offset1:216
	v_pk_fma_f32 v[28:29], v[28:29], v[34:35], v[38:39] op_sel_hi:[1,0,1]
	ds_read2st64_b32 v[38:39], v199 offset0:96 offset1:104
	ds_read2st64_b32 v[40:41], v199 offset0:224 offset1:232
	ds_read2st64_b32 v[42:43], v199 offset0:112 offset1:120
	ds_read2st64_b32 v[44:45], v199 offset0:240 offset1:248
	v_cvt_pk_bf16_f32 v2, v2, v3
	s_waitcnt lgkmcnt(0)
	v_pk_fma_f32 v[30:31], v[30:31], v[34:35], v[38:39] op_sel_hi:[1,0,1]
	v_pk_fma_f32 v[12:13], v[12:13], v[34:35], v[36:37] op_sel_hi:[1,0,1]
	v_pk_fma_f32 v[14:15], v[14:15], v[34:35], v[40:41] op_sel_hi:[1,0,1]
	v_pk_fma_f32 v[32:33], v[32:33], v[34:35], v[42:43] op_sel_hi:[1,0,1]
	v_pk_fma_f32 v[16:17], v[16:17], v[34:35], v[44:45] op_sel_hi:[1,0,1]
	v_lshlrev_b64 v[34:35], 11, v[184:185]
	v_lshl_add_u64 v[34:35], s[94:95], 0, v[34:35]
	v_lshlrev_b32_e32 v36, 1, v183
	v_mov_b32_e32 v37, v0
	v_lshl_add_u64 v[34:35], v[34:35], 0, v[36:37]
	v_mov_b32_e32 v183, v0
	v_lshl_add_u64 v[34:35], v[34:35], 0, v[182:183]
	v_cvt_pk_bf16_f32 v3, v4, v5
	global_store_dwordx2 v[34:35], v[2:3], off offset:64
	v_cvt_pk_bf16_f32 v2, v22, v23
	v_cvt_pk_bf16_f32 v3, v24, v25
	global_store_dwordx2 v[34:35], v[2:3], off offset:16
	v_cvt_pk_bf16_f32 v2, v6, v7
	v_cvt_pk_bf16_f32 v3, v8, v9
	global_store_dwordx2 v[34:35], v[2:3], off offset:80
	v_cvt_pk_bf16_f32 v2, v26, v27
	v_cvt_pk_bf16_f32 v3, v28, v29
	global_store_dwordx2 v[34:35], v[2:3], off offset:32
	v_cvt_pk_bf16_f32 v2, v10, v11
	v_cvt_pk_bf16_f32 v3, v12, v13
	global_store_dwordx2 v[34:35], v[2:3], off offset:96
	v_cvt_pk_bf16_f32 v2, v30, v31
	v_cvt_pk_bf16_f32 v3, v32, v33
	v_readlane_b32 s4, v255, 8
	v_cvt_pk_bf16_f32 v18, v18, v19
	v_cvt_pk_bf16_f32 v19, v20, v21
	global_store_dwordx2 v[34:35], v[2:3], off offset:48
	v_cvt_pk_bf16_f32 v2, v14, v15
	v_cvt_pk_bf16_f32 v3, v16, v17
	v_mov_b32_e32 v1, s4
	global_store_dwordx2 v[34:35], v[18:19], off
	global_store_dwordx2 v[34:35], v[2:3], off offset:112
	s_waitcnt lgkmcnt(0)
	s_barrier
	ds_read_b32 v1, v1
	s_movk_i32 s4, 0x400
	s_waitcnt lgkmcnt(0)
	v_cmp_gt_i32_e32 vcc, s4, v1
	v_readfirstlane_b32 s14, v1
	s_cbranch_vccz .LBB0_287

; #define LAS __attribute__((address_space(3)))
; __device__ __forceinline__ void attn_unit(unsigned char* ws, LAS unsigned char* lds, int b, int g, int c, const int tid) {
;     const int lane = tid & 63, w = tid >> 6, col = lane & 31, h = lane >> 5, r = col >> 3, qi = col & 7;
;     const int q = 8 * w + qi, t = 64 * c + q, head = g * 4 + r;
;     const size_t row = (size_t)b * SEQ + t;
;     const float slope2 = exp2f(-(float)(head + 1)) * LOG2E;
;     const bf16_t* Qp = (const bf16_t*)(ws + WS_Q) + row * 512 + head * 64 + 8 * h;
;     bf16x8 qf[4];
; #pragma unroll
;     for (int kk = 0; kk < 4; ++kk) qf[kk] = *(const bf16x8*)(Qp + 16 * kk);
;     for (int i = tid; i < 2 * 64 * IMPP; i += 512) ((LAS float*)(lds + A_IMPA))[i] = 0.f;
.LBB0_142:
	s_and_b32 s68, s14, 7
	v_lshl_add_u32 v188, s83, 6, v198
	s_lshl_b32 s62, s68, 12
	v_ashrrev_i32_e32 v189, 31, v188
	v_lshl_add_u64 v[184:185], s[62:63], 0, v[188:189]
	v_lshl_or_b32 v210, s16, 2, v196
	v_lshlrev_b64 v[2:3], 10, v[184:185]
	v_lshl_add_u64 v[2:3], s[38:39], 0, v[2:3]
	v_lshlrev_b32_e32 v4, 7, v210
	v_mov_b32_e32 v5, v0
	v_lshl_add_u64 v[2:3], v[2:3], 0, v[4:5]
	v_lshl_add_u64 v[2:3], v[2:3], 0, v[180:181]
	global_load_dwordx4 v[144:147], v[2:3], off
	global_load_dwordx4 v[148:151], v[2:3], off offset:32
	global_load_dwordx4 v[152:155], v[2:3], off offset:64
	global_load_dwordx4 v[156:159], v[2:3], off offset:96
	s_and_saveexec_b64 s[4:5], s[8:9]
	s_cbranch_execz .LBB0_145
	s_mov_b64 s[14:15], 0
	v_mov_b32_e32 v1, v207
	v_mov_b32_e32 v2, v206

; #define LAS __attribute__((address_space(3)))
; template <int MODE  > ...
;     ...
;     unsigned long long rem = blockmask;
;     if (!rem) return;
;     int j = 63 - __builtin_clzll(rem); rem &= ~(1ull << j);
;     u32x4 kreg, vreg;
;     kreg = *(const u32x4*)(Kg + (size_t)(64 * j + skey) * 128 + schunk * 8);
;     if (NEEDV) vreg = *(const u32x4*)(Vg + (size_t)(64 * j + skey) * 128 + schunk * 8);
;     int cur = 0;
;     {
;         LAS bf16_t* kb = (LAS bf16_t*)(lds + A_KBUF) + cur * 64 * KPITCH;
;         *(LAS u32x4*)(kb + skey * KPITCH + schunk * 8) = kreg;
;         if (NEEDV) { LAS bf16_t* vb = (LAS bf16_t*)(lds + A_VBUF) + cur * 64 * VPITCH;
;             *(LAS u32x4*)(vb + skey * VPITCH + schunk * 8) = vreg; }
;     }
;     __syncthreads();
;     for (;;) {
;         const bool has_next = rem != 0ull; int jn = 0;
;         if (has_next) { jn = 63 - __builtin_clzll(rem); rem &= ~(1ull << jn);
;             kreg = *(const u32x4*)(Kg + (size_t)(64 * jn + skey) * 128 + schunk * 8);
;             if (NEEDV) vreg = *(const u32x4*)(Vg + (size_t)(64 * jn + skey) * 128 + schunk * 8); }
; __device__ __forceinline__ void attn_unit(unsigned char* ws, LAS unsigned char* lds, int b, int g, int c, const int tid) {
;     ...
;     const size_t boff = (size_t)b * SEQ * 128 + g * 64;
;     const int nvalid = 4 * c + 3 > 255 ? 255 : 4 * c + 3;
;     const int nkb = (nvalid + 63) >> 6;
;     const unsigned long long cmpmask = (nkb >= 64) ? ~0ull : ((1ull << nkb) - 1ull);
;     const bf16_t* KCp = (const bf16_t*)(ws + WS_KC) + (size_t)b * 256 * 128 + g * 64;
;     const bf16_t* VCp = (const bf16_t*)(ws + WS_VC) + (size_t)b * 256 * 128 + g * 64;
;     AttnState st; st.m = -1e29f; st.l = 0.f; st.o0 = (f32x16){}; st.o1 = (f32x16){};
;     attn_pass<0>(lds, KCp, VCp, cmpmask, qf, st, t, slope2, 0ull, w, lane, tid, c);
.LBB0_145:
	s_or_b64 exec, exec, s[4:5]
	s_lshl_b32 s69, s83, 2
	s_add_i32 s4, s69, 0x42
	s_lshl_b32 s62, s16, 6
	s_lshr_b32 s4, s4, 6
	s_cmp_lt_u32 s83, 64
	s_cselect_b32 s4, s4, 4
	s_lshl_b64 s[4:5], -1, s4
	s_not_b64 s[20:21], s[4:5]
	s_lshl_b32 s14, s68, 16
	s_add_u32 s15, s37, s14
	s_addc_u32 s17, s40, 0
	s_lshl_b32 s16, s16, 7
	s_add_u32 s18, s15, s16
	s_addc_u32 s19, s17, 0
	s_add_u32 s14, s41, s14
	s_addc_u32 s15, s42, 0
	s_add_u32 s14, s14, s16
	s_flbit_i32_b64 s16, s[20:21]
	s_addc_u32 s15, s15, 0
	v_mov_b32_e32 v1, v178
	v_mov_b32_e32 v18, v179
	s_xor_b32 s84, s16, 63
	s_lshl_b32 s85, s84, 6
	v_ashrrev_i32_e32 v211, 3, v1
	v_add_u32_e32 v2, s85, v211
	v_ashrrev_i32_e32 v3, 31, v2
	v_lshlrev_b64 v[2:3], 8, v[2:3]
	v_lshlrev_b32_e32 v1, 4, v1
	v_lshl_add_u64 v[4:5], s[18:19], 0, v[2:3]
	v_and_b32_e32 v16, 0x70, v1
	v_mov_b32_e32 v17, v0
	v_lshl_add_u64 v[4:5], v[4:5], 0, v[16:17]
	v_lshl_add_u64 v[2:3], s[14:15], 0, v[2:3]
	v_lshl_add_u64 v[2:3], v[2:3], 0, v[16:17]
	global_load_dwordx4 v[160:163], v[4:5], off
	global_load_dwordx4 v[164:167], v[2:3], off
	v_add_u32_e32 v19, 1, v210
	v_cvt_f32_u32_e32 v19, v19
	v_and_b32_e32 v20, 31, v18
	v_ashrrev_i32_e32 v21, 5, v18
	v_lshlrev_b32_e32 v22, 2, v18
	v_bfe_u32 v23, v18, 2, 2
	s_movk_i32 s16, 0x90
	v_mul_lo_u32 v25, v211, s16
	v_lshlrev_b32_e32 v27, 6, v21
	v_mul_u32_u24_e32 v20, 0x90, v20
	v_bitop3_b32 v212, v22, s66, v240 bitop3:0x6c
	v_lshl_or_b32 v22, v21, 2, v23
	v_lshlrev_b32_e32 v21, 4, v21
	s_mov_b32 s16, 0x42fc0000
	v_add3_u32 v216, 0, v20, v21
	v_cmp_lt_f32_e32 vcc, s16, v19
	v_mov_b32_e32 v20, 0x42800000
	v_and_b32_e32 v24, 16, v18
	v_cndmask_b32_e32 v20, 0, v20, vcc
	v_sub_f32_e32 v19, v20, v19
	v_exp_f32_e32 v19, v19
	v_lshlrev_b32_e32 v18, 3, v18
	v_mul_lo_u32 v22, v22, s70
	v_not_b32_e32 v20, 63
	v_lshlrev_b32_e32 v23, 1, v24
	v_and_b32_e32 v18, 24, v18
	v_add_u32_e32 v21, 0, v22
	v_cndmask_b32_e32 v20, 0, v20, vcc
	v_add3_u32 v218, v21, v23, v18
	v_ldexp_f32 v18, v19, v20
	v_mul_f32_e32 v186, 0x3fb8aa3b, v18
	s_lshl_b64 s[16:17], 1, s84
	v_mov_b32_e32 v14, v0
	v_mov_b32_e32 v15, v0
	v_mul_lo_u32 v26, v211, s70
	v_sub_u32_e32 v24, v27, v188
	v_mul_f32_e32 v190, 0x41800000, v186
	v_lshl_add_u64 v[194:195], s[14:15], 0, v[16:17]
	s_not_b64 s[14:15], s[16:17]
	v_mov_b32_e32 v1, v0
	v_mov_b32_e32 v2, v0
	v_mov_b32_e32 v3, v0
	v_mov_b32_e32 v4, v0
	v_mov_b32_e32 v5, v0
	v_mov_b32_e32 v6, v0
	v_mov_b32_e32 v7, v0
	v_mov_b32_e32 v8, v0
	v_mov_b32_e32 v9, v0
	v_mov_b32_e32 v10, v0
	v_mov_b32_e32 v11, v0
	v_mov_b32_e32 v12, v0
	v_mov_b32_e32 v13, v0
	v_add3_u32 v214, 0, v25, v16
	v_add3_u32 v215, 0, v26, v16
	v_add_u32_e32 v217, 31, v24
	v_lshl_add_u64 v[192:193], s[18:19], 0, v[16:17]
	v_add_f32_e32 v191, v190, v190
	s_andn2_b64 s[4:5], s[14:15], s[4:5]
	v_mov_b64_e32 v[30:31], v[14:15]
	v_mov_b64_e32 v[46:47], v[14:15]
	v_lshlrev_b32_e32 v183, 6, v210
	s_mov_b32 s88, 0
	v_mov_b32_e32 v219, 0xefa18f08
	v_mov_b32_e32 v213, 0
	v_mul_f32_e32 v189, 0.5, v186
	s_add_i32 s69, s69, -2
	v_fmamk_f32 v187, v186, 0x41800000, v191
	v_mov_b64_e32 v[28:29], v[12:13]
	v_mov_b64_e32 v[26:27], v[10:11]
	v_mov_b64_e32 v[24:25], v[8:9]
	v_mov_b64_e32 v[22:23], v[6:7]
	v_mov_b64_e32 v[20:21], v[4:5]
	v_mov_b64_e32 v[18:19], v[2:3]
	v_mov_b64_e32 v[16:17], v[0:1]
	v_mov_b64_e32 v[44:45], v[12:13]
	v_mov_b64_e32 v[42:43], v[10:11]
	v_mov_b64_e32 v[40:41], v[8:9]
	v_mov_b64_e32 v[38:39], v[6:7]
	v_mov_b64_e32 v[36:37], v[4:5]
	v_mov_b64_e32 v[34:35], v[2:3]
	v_mov_b64_e32 v[32:33], v[0:1]
	s_mov_b32 s90, s84
	s_mov_b64 s[14:15], s[4:5]
	s_waitcnt vmcnt(0) lgkmcnt(0)
	ds_write_b128 v214, v[160:163]
	ds_write_b128 v215, v[164:167] offset:18432
	s_waitcnt lgkmcnt(0)
	s_barrier
.LBB0_146:
	s_cmp_eq_u64 s[14:15], 0
	s_cselect_b64 s[16:17], -1, 0
	s_cmp_lg_u64 s[14:15], 0
	s_mov_b64 s[20:21], 0
	s_cselect_b64 s[22:23], -1, 0
	s_and_b64 vcc, exec, s[16:17]
	s_mov_b32 s89, 0
	s_cbranch_vccnz .LBB0_148
	s_flbit_i32_b64 s20, s[14:15]
	s_xor_b32 s89, s20, 63
	v_lshl_add_u32 v2, s89, 6, v211
	v_ashrrev_i32_e32 v3, 31, v2
	v_lshlrev_b64 v[2:3], 8, v[2:3]
	v_lshl_add_u64 v[4:5], v[192:193], 0, v[2:3]
	v_lshl_add_u64 v[2:3], v[194:195], 0, v[2:3]
	s_waitcnt vmcnt(0)
	global_load_dwordx4 v[160:163], v[4:5], off
	global_load_dwordx4 v[164:167], v[2:3], off
	s_lshl_b64 s[20:21], 1, s89
	s_andn2_b64 s[20:21], s[14:15], s[20:21]

; __device__ __forceinline__ void attn_unit(unsigned char* ws, LAS unsigned char* lds, int b, int g, int c, const int tid) {
;     ...
;     { const float gate0 = ((const float*)(ws + WS_G))[row * 32 + head * 3 + 0]; const float sc = st.l > 0.f ? gate0 / st.l : 0.f;
.LBB0_159:
	v_lshlrev_b64 v[4:5], 5, v[184:185]
	v_mul_u32_u24_e32 v2, 3, v210
	v_or_b32_e32 v4, v4, v2
	v_mov_b32_e32 v2, 0
	v_cmp_lt_f32_e64 s[16:17], 0, v3
	v_lshl_add_u64 v[138:139], v[4:5], 2, s[92:93]
	s_and_saveexec_b64 s[14:15], s[16:17]
	s_cbranch_execz .LBB0_161
	global_load_dword v2, v[138:139], off
	s_waitcnt vmcnt(0) lgkmcnt(0)
	v_div_scale_f32 v4, s[20:21], v3, v3, v2
	v_rcp_f32_e32 v5, v4
	v_div_scale_f32 v6, vcc, v2, v3, v2
	v_fma_f32 v7, -v4, v5, 1.0
	v_fmac_f32_e32 v5, v7, v5
	v_mul_f32_e32 v7, v6, v5
	v_fma_f32 v8, -v4, v7, v6
	v_fmac_f32_e32 v7, v8, v5
	v_fma_f32 v4, -v4, v7, v6
	v_div_fmas_f32 v4, v4, v5, v7
	v_div_fixup_f32 v2, v4, v3, v2

; #define LAS __attribute__((address_space(3)))
; template <int MODE  > ...
;     ...
;     unsigned long long rem = blockmask;
;     if (!rem) return;
;     int j = 63 - __builtin_clzll(rem); rem &= ~(1ull << j);
;     u32x4 kreg, vreg;
;     kreg = *(const u32x4*)(Kg + (size_t)(64 * j + skey) * 128 + schunk * 8);
;     if (NEEDV) vreg = *(const u32x4*)(Vg + (size_t)(64 * j + skey) * 128 + schunk * 8);
;     int cur = 0;
;     {
;         LAS bf16_t* kb = (LAS bf16_t*)(lds + A_KBUF) + cur * 64 * KPITCH;
;         *(LAS u32x4*)(kb + skey * KPITCH + schunk * 8) = kreg;
;         if (NEEDV) { LAS bf16_t* vb = (LAS bf16_t*)(lds + A_VBUF) + cur * 64 * VPITCH;
;             *(LAS u32x4*)(vb + skey * VPITCH + schunk * 8) = vreg; }
;     }
;     __syncthreads();
;     ...
;                 const float inv = st.l > 0.f ? 1.f / st.l : 0.f;
;                 LAS float* impA = (LAS float*)(lds + A_IMPA); LAS float* impB = (LAS float*)(lds + A_IMPB);
;                 const int q = 8 * w + (col & 7);
; __device__ __forceinline__ void attn_unit(unsigned char* ws, LAS unsigned char* lds, int b, int g, int c, const int tid) {
;     ...
;         attn_pass<3>(lds, KCp, VCp, cmpmask, qf, st, t, slope2, 0ull, w, lane, tid, c);
.LBB0_163:
	s_andn2_b64 vcc, exec, s[20:21]
	v_mov_b64_e32 v[140:141], s[14:15]
	s_cbranch_vccnz .LBB0_246
	v_mov_b32_e32 v2, v178
	v_mov_b32_e32 v8, v179
	v_mov_b32_e32 v7, v0
	v_ashrrev_i32_e32 v58, 3, v2
	v_add_u32_e32 v4, s85, v58
	v_ashrrev_i32_e32 v5, 31, v4
	v_lshlrev_b64 v[4:5], 8, v[4:5]
	v_lshlrev_b32_e32 v2, 4, v2
	v_lshl_add_u64 v[4:5], s[18:19], 0, v[4:5]
	v_and_b32_e32 v6, 0x70, v2
	v_lshl_add_u64 v[4:5], v[4:5], 0, v[6:7]
	global_load_dwordx4 v[34:37], v[4:5], off
	v_cmp_lt_f32_e32 vcc, s71, v1
	v_lshl_add_u64 v[38:39], s[18:19], 0, v[6:7]
	v_and_or_b32 v5, v8, 7, v197
	v_cndmask_b32_e32 v63, 0, v1, vcc
	v_div_scale_f32 v1, s[18:19], v3, v3, 1.0
	v_lshl_add_u32 v62, v5, 6, v5
	v_rcp_f32_e32 v5, v1
	s_movk_i32 s14, 0x90
	v_mul_lo_u32 v2, v58, s14
	v_add3_u32 v59, 0, v2, v6
	v_lshlrev_b32_e32 v6, 2, v8
	v_bitop3_b32 v60, v6, 32, v240 bitop3:0x6c
	v_bitop3_b32 v61, v6, 64, v240 bitop3:0x6c
	v_fma_f32 v6, -v1, v5, 1.0
	v_fmac_f32_e32 v5, v6, v5
	v_div_scale_f32 v6, vcc, 1.0, v3, 1.0
	v_mul_f32_e32 v7, v6, v5
	v_and_b32_e32 v9, 31, v8
	v_ashrrev_i32_e32 v41, 5, v8
	v_fma_f32 v8, -v1, v7, v6
	v_fmac_f32_e32 v7, v8, v5
	v_fma_f32 v1, -v1, v7, v6
	v_div_fmas_f32 v1, v1, v5, v7
	v_lshlrev_b32_e32 v2, 6, v41
	v_div_fixup_f32 v1, v1, v3, 1.0
	v_mul_u32_u24_e32 v4, 0x90, v9
	v_cndmask_b32_e64 v64, 0, v1, s[16:17]
	v_sub_f32_e32 v40, v189, v63
	v_sub_u32_e32 v1, v2, v188
	v_lshlrev_b32_e32 v2, 4, v41
	v_cmp_gt_u32_e64 s[14:15], 8, v9
	v_add_u32_e32 v65, 31, v1
	v_mov_b32_e32 v1, v40
	v_add3_u32 v66, 0, v4, v2
	s_mov_b32 s22, 0
	s_waitcnt vmcnt(0) lgkmcnt(0)
	ds_write_b128 v59, v[34:37]
	s_waitcnt lgkmcnt(0)
	s_barrier
	s_branch .LBB0_166

; template <int MODE  > ...
;     ...
;         const bool has_next = rem != 0ull; int jn = 0;
;         if (has_next) { jn = 63 - __builtin_clzll(rem); rem &= ~(1ull << jn);
;             kreg = *(const u32x4*)(Kg + (size_t)(64 * jn + skey) * 128 + schunk * 8);
;             if (NEEDV) vreg = *(const u32x4*)(Vg + (size_t)(64 * jn + skey) * 128 + schunk * 8); }
.LBB0_166:
	s_cmp_eq_u64 s[4:5], 0
	s_cselect_b64 s[16:17], -1, 0
	s_cmp_lg_u64 s[4:5], 0
	s_mov_b64 s[18:19], 0
	s_cselect_b64 s[20:21], -1, 0
	s_and_b64 vcc, exec, s[16:17]
	s_mov_b32 s23, 0
	s_cbranch_vccnz .LBB0_168
	s_flbit_i32_b64 s18, s[4:5]
	s_xor_b32 s23, s18, 63
	v_lshl_add_u32 v2, s23, 6, v58
	v_ashrrev_i32_e32 v3, 31, v2
	v_lshlrev_b64 v[2:3], 8, v[2:3]
	v_lshl_add_u64 v[2:3], v[38:39], 0, v[2:3]
	s_waitcnt vmcnt(0)
	global_load_dwordx4 v[34:37], v[2:3], off
	s_lshl_b64 s[18:19], 1, s23
	s_andn2_b64 s[18:19], s[4:5], s[18:19]

; #define LAS __attribute__((address_space(3)))
; template <int MODE  > ...
;     ...
;         const bool has_next = rem != 0ull; int jn = 0;
;         if (has_next) { jn = 63 - __builtin_clzll(rem); rem &= ~(1ull << jn);
;             kreg = *(const u32x4*)(Kg + (size_t)(64 * jn + skey) * 128 + schunk * 8);
;             if (NEEDV) vreg = *(const u32x4*)(Vg + (size_t)(64 * jn + skey) * 128 + schunk * 8); }
;         const bool selbit = (MODE == 1) ? (((selmask >> j) & 1ull) != 0ull) : true;
;         bool active = true;
;         if (MODE == 1) active = __builtin_amdgcn_ballot_w64(selbit) != 0ull;
;         if (active) {
;             const LAS bf16_t* kb = (const LAS bf16_t*)(lds + A_KBUF) + cur * 64 * KPITCH;
;             constexpr int STEP = CMPM ? 16 : 1;
;             const int Bint = CMPM ? (1024 * j + 31 - t + 64 * h) : (64 * j - t + 4 * h);
;             const float sl = slope2 * (float)STEP;
;             const float mref = st.m; const bool fresh = !(mref > -1e28f);
;             const float mest = fresh ? 0.f : mref;
;             const float basef = selbit ? (slope2 * (float)Bint - mest) : -1e30f;
;             int ptype;
;             if (MODE == 1) ptype = (j == cblk) ? 1 : 0;
;             else if (MODE == 2) ptype = (j == cblk) ? 1 : ((j == cblk - 8) ? 2 : 0);
;             else ptype = (64 * j + 63 <= 4 * cblk - 2) ? 0 : 1;
;             f32x16 s0, s1;
;             { const float sl2 = sl + sl, sl3 = sl2 + sl;
; #pragma unroll
;               for (int g8 = 0; g8 < 4; ++g8) {
;                   const float b0 = __builtin_fmaf(sl, (float)(8 * g8), basef), b1 = __builtin_fmaf(sl, (float)(8 * g8 + 32), basef);
;                   s0[4 * g8] = b0; s0[4 * g8 + 1] = b0 + sl; s0[4 * g8 + 2] = b0 + sl2; s0[4 * g8 + 3] = b0 + sl3;
;                   s1[4 * g8] = b1; s1[4 * g8 + 1] = b1 + sl; s1[4 * g8 + 2] = b1 + sl2; s1[4 * g8 + 3] = b1 + sl3;
;               } }
.LBB0_246:
	s_lshl_b32 s4, s68, 19
	s_or_b32 s22, s62, s4
	v_mov_b32_e32 v1, v179
	v_mov_b32_e32 v2, v178
	s_cmp_eq_u64 s[14:15], 0
	v_add_f32_e32 v187, v186, v186
	s_waitcnt vmcnt(0)
	v_fma_f32 v163, 2.0, v186, v186
	s_cbranch_scc1 .LBB0_263
	s_lshl_b32 s16, s22, 1
	s_add_u32 s4, s43, s16
	s_addc_u32 s5, s44, 0
	s_add_u32 s16, s45, s16
	s_flbit_i32_b64 s18, s[14:15]
	v_ashrrev_i32_e32 v164, 3, v2
	s_addc_u32 s17, s46, 0
	s_xor_b32 s68, s18, 63
	v_lshl_add_u32 v4, s68, 6, v164
	v_ashrrev_i32_e32 v5, 31, v4
	v_lshlrev_b64 v[4:5], 8, v[4:5]
	v_lshlrev_b32_e32 v2, 4, v2
	v_lshl_add_u64 v[6:7], s[16:17], 0, v[4:5]
	v_and_b32_e32 v16, 0x70, v2
	v_mov_b32_e32 v17, v0
	v_lshl_add_u64 v[2:3], v[6:7], 0, v[16:17]
	v_lshl_add_u64 v[4:5], s[4:5], 0, v[4:5]
	v_lshl_add_u64 v[4:5], v[4:5], 0, v[16:17]
	global_load_dwordx4 v[130:133], v[2:3], off
	global_load_dwordx4 v[134:137], v[4:5], off
	v_ashrrev_i32_e32 v18, 5, v1
	v_lshrrev_b32_e32 v34, 2, v1
	v_lshlrev_b32_e32 v37, 2, v18
	v_and_or_b32 v34, v34, 3, v37
	v_and_b32_e32 v19, 31, v1
	v_and_b32_e32 v21, 16, v1
	v_lshlrev_b32_e32 v22, 3, v1
	s_movk_i32 s18, 0x90
	v_mul_lo_u32 v34, v34, s70
	v_lshlrev_b32_e32 v20, 2, v1
	v_mov_b32_e32 v14, v0
	v_mov_b32_e32 v15, v0
	v_mul_lo_u32 v35, v164, s18
	v_mul_lo_u32 v36, v164, s70
	v_mul_u32_u24_e32 v38, 0x90, v19
	v_lshlrev_b32_e32 v39, 1, v21
	v_and_b32_e32 v40, 24, v22
	v_lshlrev_b32_e32 v41, 4, v18
	v_add_u32_e32 v34, 0, v34
	v_mov_b32_e32 v1, v0
	v_mov_b32_e32 v2, v0
	v_mov_b32_e32 v3, v0
	v_mov_b32_e32 v4, v0
	v_mov_b32_e32 v5, v0
	v_mov_b32_e32 v6, v0
	v_mov_b32_e32 v7, v0
	v_mov_b32_e32 v8, v0
	v_mov_b32_e32 v9, v0
	v_mov_b32_e32 v10, v0
	v_mov_b32_e32 v11, v0
	v_mov_b32_e32 v12, v0
	v_mov_b32_e32 v13, v0
	v_bitop3_b32 v165, v20, s66, v240 bitop3:0x6c
	v_mov_b64_e32 v[32:33], v[14:15]
	v_add3_u32 v166, 0, v35, v16
	v_add3_u32 v167, 0, v36, v16
	v_sub_u32_e32 v190, v37, v188
	v_add3_u32 v191, 0, v38, v41
	v_lshl_add_u64 v[142:143], s[4:5], 0, v[16:17]
	s_lshl_b64 s[4:5], 1, s68
	v_add3_u32 v192, v34, v39, v40
	v_mov_b64_e32 v[48:49], v[14:15]
	s_mov_b32 s23, 0
	v_mov_b32_e32 v194, 0xefa18f08
	v_mov_b32_e32 v193, 0
	v_mov_b64_e32 v[30:31], v[12:13]
	v_mov_b64_e32 v[28:29], v[10:11]
	v_mov_b64_e32 v[26:27], v[8:9]
	v_mov_b64_e32 v[24:25], v[6:7]
	v_mov_b64_e32 v[22:23], v[4:5]
	v_mov_b64_e32 v[20:21], v[2:3]
	v_mov_b64_e32 v[18:19], v[0:1]
	v_lshl_add_u64 v[160:161], s[16:17], 0, v[16:17]
	s_andn2_b64 s[14:15], s[14:15], s[4:5]
	v_mov_b64_e32 v[46:47], v[12:13]
	v_mov_b64_e32 v[44:45], v[10:11]
	v_mov_b64_e32 v[42:43], v[8:9]
	v_mov_b64_e32 v[40:41], v[6:7]
	v_mov_b64_e32 v[38:39], v[4:5]
	v_mov_b64_e32 v[36:37], v[2:3]
	v_mov_b64_e32 v[34:35], v[0:1]
	s_waitcnt vmcnt(0) lgkmcnt(0)
	ds_write_b128 v166, v[130:133]
	ds_write_b128 v167, v[134:137] offset:18432
	s_waitcnt lgkmcnt(0)
	s_barrier
.LBB0_248:
	s_cmp_eq_u64 s[14:15], 0
	s_cselect_b64 s[4:5], -1, 0
	s_cmp_lg_u64 s[14:15], 0
	s_mov_b64 s[18:19], 0
	s_cselect_b64 s[20:21], -1, 0
	s_and_b64 vcc, exec, s[4:5]
	s_mov_b32 s62, 0
	s_cbranch_vccnz .LBB0_250
	s_flbit_i32_b64 s16, s[14:15]
	s_xor_b32 s62, s16, 63
	v_lshl_add_u32 v2, s62, 6, v164
	v_ashrrev_i32_e32 v3, 31, v2
	v_lshlrev_b64 v[2:3], 8, v[2:3]
	v_lshl_add_u64 v[4:5], v[160:161], 0, v[2:3]
	v_lshl_add_u64 v[2:3], v[142:143], 0, v[2:3]
	s_waitcnt vmcnt(0)
	global_load_dwordx4 v[130:133], v[4:5], off
	global_load_dwordx4 v[134:137], v[2:3], off
	s_lshl_b64 s[16:17], 1, s62
	s_andn2_b64 s[18:19], s[14:15], s[16:17]
.LBB0_250:
	v_lshrrev_b64 v[2:3], s68, v[140:141]
	v_and_b32_e32 v1, 1, v2
	v_cmp_eq_u32_e64 s[16:17], 1, v1
	v_cmp_ne_u32_e32 vcc, 0, v1
	s_cbranch_vccz .LBB0_258
	s_mul_i32 vcc_lo, s23, 0x2400
	s_mul_i32 vcc_hi, s23, 0x3000
	v_add_u32_e32 v223, vcc_lo, v191
	v_add_u32_e32 v222, vcc_hi, v192
	ds_read_b128 v[66:69], v223
	ds_read_b128 v[70:73], v223 offset:4608
	ds_read_b128 v[74:77], v223 offset:32
	ds_read_b128 v[78:81], v223 offset:4640
	ds_read_b128 v[82:85], v223 offset:64
	ds_read_b128 v[86:89], v223 offset:4672
	ds_read_b128 v[90:93], v223 offset:96
	ds_read_b128 v[94:97], v223 offset:4704
	v_lshl_add_u32 v1, s68, 6, v190
	v_cvt_f32_i32_e32 v2, v1
	v_cmp_nlt_f32_e64 s[14:15], s71, v194
	s_cmp_lg_u32 s68, s83
	s_nop 0
	v_cndmask_b32_e64 v1, v194, 0, s[14:15]
	v_fma_f32 v2, v186, v2, -v1
	v_cndmask_b32_e64 v14, v241, v2, s[16:17]
	v_fma_f32 v50, 0, v186, v14
	v_fmamk_f32 v54, v186, 0x41000000, v14
	v_fmamk_f32 v58, v186, 0x41800000, v14
	v_fmamk_f32 v62, v186, 0x41c00000, v14
	v_fmamk_f32 v2, v186, 0x42000000, v14
	v_fmamk_f32 v6, v186, 0x42200000, v14
	v_fmamk_f32 v10, v186, 0x42400000, v14
	v_fmac_f32_e32 v14, 0x42600000, v186
	v_add_f32_e32 v51, v186, v50
	v_add_f32_e32 v52, v187, v50
	v_add_f32_e32 v53, v163, v50
	v_add_f32_e32 v55, v186, v54
	v_add_f32_e32 v56, v187, v54
	v_add_f32_e32 v57, v163, v54
	v_add_f32_e32 v59, v186, v58
	v_add_f32_e32 v60, v187, v58
	v_add_f32_e32 v61, v163, v58
	v_add_f32_e32 v63, v186, v62
	v_add_f32_e32 v64, v187, v62
	v_add_f32_e32 v65, v163, v62
	v_add_f32_e32 v3, v186, v2
	v_add_f32_e32 v4, v187, v2
	v_add_f32_e32 v5, v163, v2
	v_add_f32_e32 v7, v186, v6
	v_add_f32_e32 v8, v187, v6
	v_add_f32_e32 v9, v163, v6
	v_add_f32_e32 v11, v186, v10
	v_add_f32_e32 v12, v187, v10
	v_add_f32_e32 v13, v163, v10
	v_add_f32_e32 v15, v186, v14
	v_add_f32_e32 v16, v187, v14
	v_add_f32_e32 v17, v163, v14
	s_cbranch_scc1 .Lm1_qk
; #define LAS __attribute__((address_space(3)))
; __device__ __forceinline__ float shflx(float v, int mask, int lane) { return __builtin_bit_cast(float, __builtin_amdgcn_ds_bpermute(((lane ^ mask) & 63) << 2, __builtin_bit_cast(int, v))); }
; template <int MODE  > ...
;     ...
;             if (ptype == 1) {
;                 const float thr = 0.5f * slope2 - mest;
; #pragma unroll
;                 for (int i = 0; i < 16; ++i) { s0[i] = (s0[i] < thr) ? s0[i] : -1e30f; s1[i] = (s1[i] < thr) ? s1[i] : -1e30f; }
;             } else if (ptype == 2) {
;                 const float thr = -511.5f * slope2 - mest;
; #pragma unroll
;                 for (int i = 0; i < 16; ++i) { s0[i] = (s0[i] > thr) ? s0[i] : -1e30f; s1[i] = (s1[i] > thr) ? s1[i] : -1e30f; }
;             }
; #pragma unroll
;             for (int kk = 0; kk < 4; ++kk) {
;                 const bf16x8 k0 = *(const LAS bf16x8*)(kb + col * KPITCH + kk * 16 + h * 8);
;                 const bf16x8 k1 = *(const LAS bf16x8*)(kb + (32 + col) * KPITCH + kk * 16 + h * 8);
;                 s0 = __builtin_amdgcn_mfma_f32_32x32x16_bf16(k0, qf[kk], s0, 0, 0, 0);
;                 s1 = __builtin_amdgcn_mfma_f32_32x32x16_bf16(k1, qf[kk], s1, 0, 0, 0);
;             }
;             if (MODE != 3) {
;                 float mx = fmaxf(s0[0], s1[0]);
; #pragma unroll
;                 for (int i = 1; i < 16; ++i) mx = fmaxf(mx, fmaxf(s0[i], s1[i]));
;                 mx = fmaxf(mx, shflx(mx, 32, lane));
;                 float alpha = 1.f;
;                 if (__builtin_amdgcn_ballot_w64(fresh || mx > 0.f) != 0ull) {
	v_sub_f32_e32 v224, v189, v1
	v_cmp_lt_f32_e32 vcc, v50, v224
	s_nop 1
	v_cndmask_b32_e32 v50, v241, v50, vcc
	v_cmp_lt_f32_e32 vcc, v51, v224
	s_nop 1
	v_cndmask_b32_e32 v51, v241, v51, vcc
	v_cmp_lt_f32_e32 vcc, v52, v224
	s_nop 1
	v_cndmask_b32_e32 v52, v241, v52, vcc
	v_cmp_lt_f32_e32 vcc, v53, v224
	s_nop 1
	v_cndmask_b32_e32 v53, v241, v53, vcc
	v_cmp_lt_f32_e32 vcc, v54, v224
	s_nop 1
	v_cndmask_b32_e32 v54, v241, v54, vcc
	v_cmp_lt_f32_e32 vcc, v55, v224
	s_nop 1
	v_cndmask_b32_e32 v55, v241, v55, vcc
	v_cmp_lt_f32_e32 vcc, v56, v224
	s_nop 1
	v_cndmask_b32_e32 v56, v241, v56, vcc
	v_cmp_lt_f32_e32 vcc, v57, v224
	s_nop 1
	v_cndmask_b32_e32 v57, v241, v57, vcc
	v_cmp_lt_f32_e32 vcc, v58, v224
	s_nop 1
	v_cndmask_b32_e32 v58, v241, v58, vcc
	v_cmp_lt_f32_e32 vcc, v59, v224
	s_nop 1
	v_cndmask_b32_e32 v59, v241, v59, vcc
	v_cmp_lt_f32_e32 vcc, v60, v224
	s_nop 1
	v_cndmask_b32_e32 v60, v241, v60, vcc
	v_cmp_lt_f32_e32 vcc, v61, v224
	s_nop 1
	v_cndmask_b32_e32 v61, v241, v61, vcc
	v_cmp_lt_f32_e32 vcc, v62, v224
	s_nop 1
	v_cndmask_b32_e32 v62, v241, v62, vcc
	v_cmp_lt_f32_e32 vcc, v63, v224
	s_nop 1
	v_cndmask_b32_e32 v63, v241, v63, vcc
	v_cmp_lt_f32_e32 vcc, v64, v224
	s_nop 1
	v_cndmask_b32_e32 v64, v241, v64, vcc
	v_cmp_lt_f32_e32 vcc, v65, v224
	s_nop 1
	v_cndmask_b32_e32 v65, v241, v65, vcc
	v_cmp_lt_f32_e32 vcc, v2, v224
	s_nop 1
	v_cndmask_b32_e32 v2, v241, v2, vcc
	v_cmp_lt_f32_e32 vcc, v3, v224
	s_nop 1
	v_cndmask_b32_e32 v3, v241, v3, vcc
	v_cmp_lt_f32_e32 vcc, v4, v224
	s_nop 1
	v_cndmask_b32_e32 v4, v241, v4, vcc
	v_cmp_lt_f32_e32 vcc, v5, v224
	s_nop 1
	v_cndmask_b32_e32 v5, v241, v5, vcc
	v_cmp_lt_f32_e32 vcc, v6, v224
	s_nop 1
	v_cndmask_b32_e32 v6, v241, v6, vcc
	v_cmp_lt_f32_e32 vcc, v7, v224
	s_nop 1
	v_cndmask_b32_e32 v7, v241, v7, vcc
	v_cmp_lt_f32_e32 vcc, v8, v224
	s_nop 1
	v_cndmask_b32_e32 v8, v241, v8, vcc
	v_cmp_lt_f32_e32 vcc, v9, v224
	s_nop 1
	v_cndmask_b32_e32 v9, v241, v9, vcc
	v_cmp_lt_f32_e32 vcc, v10, v224
	s_nop 1
	v_cndmask_b32_e32 v10, v241, v10, vcc
	v_cmp_lt_f32_e32 vcc, v11, v224
	s_nop 1
	v_cndmask_b32_e32 v11, v241, v11, vcc
	v_cmp_lt_f32_e32 vcc, v12, v224
	s_nop 1
	v_cndmask_b32_e32 v12, v241, v12, vcc
	v_cmp_lt_f32_e32 vcc, v13, v224
	s_nop 1
	v_cndmask_b32_e32 v13, v241, v13, vcc
	v_cmp_lt_f32_e32 vcc, v14, v224
	s_nop 1
	v_cndmask_b32_e32 v14, v241, v14, vcc
	v_cmp_lt_f32_e32 vcc, v15, v224
	s_nop 1
	v_cndmask_b32_e32 v15, v241, v15, vcc
	v_cmp_lt_f32_e32 vcc, v16, v224
	s_nop 1
	v_cndmask_b32_e32 v16, v241, v16, vcc
	v_cmp_lt_f32_e32 vcc, v17, v224
	s_nop 1
	v_cndmask_b32_e32 v17, v241, v17, vcc
.Lm1_qk:
	s_waitcnt lgkmcnt(7)
	v_mfma_f32_32x32x16_bf16 v[50:65], v[66:69], v[144:147], v[50:65]
	s_waitcnt lgkmcnt(6)
	v_mfma_f32_32x32x16_bf16 v[2:17], v[70:73], v[144:147], v[2:17]
	s_waitcnt lgkmcnt(5)
	v_mfma_f32_32x32x16_bf16 v[50:65], v[74:77], v[148:151], v[50:65]
	s_waitcnt lgkmcnt(4)
	v_mfma_f32_32x32x16_bf16 v[2:17], v[78:81], v[148:151], v[2:17]
	s_waitcnt lgkmcnt(3)
	v_mfma_f32_32x32x16_bf16 v[50:65], v[82:85], v[152:155], v[50:65]
	s_waitcnt lgkmcnt(2)
	v_mfma_f32_32x32x16_bf16 v[2:17], v[86:89], v[152:155], v[2:17]
	s_waitcnt lgkmcnt(1)
	v_mfma_f32_32x32x16_bf16 v[50:65], v[90:93], v[156:159], v[50:65]
	s_waitcnt lgkmcnt(0)
	v_mfma_f32_32x32x16_bf16 v[2:17], v[94:97], v[156:159], v[2:17]
	ds_read_b64_tr_b16 v[66:67], v222 offset:18432
	ds_read_b64_tr_b16 v[68:69], v222 offset:19968
	ds_read_b64_tr_b16 v[70:71], v222 offset:18496
	ds_read_b64_tr_b16 v[72:73], v222 offset:20032
	ds_read_b64_tr_b16 v[74:75], v222 offset:21504
	ds_read_b64_tr_b16 v[76:77], v222 offset:23040
	ds_read_b64_tr_b16 v[78:79], v222 offset:21568
	ds_read_b64_tr_b16 v[80:81], v222 offset:23104
	s_nop 3
	v_max3_f32 v220, v50, v51, v52
	v_max3_f32 v220, v220, v53, v54
	v_max3_f32 v220, v220, v55, v56
	v_max3_f32 v220, v220, v57, v58
	v_max3_f32 v220, v220, v59, v60
	v_max3_f32 v220, v220, v61, v62
	v_max3_f32 v220, v220, v63, v64
	v_max3_f32 v221, v2, v3, v4
	v_max3_f32 v221, v221, v5, v6
	v_max3_f32 v221, v221, v7, v8
	v_max3_f32 v221, v221, v9, v10
	v_max3_f32 v221, v221, v11, v12
	v_max3_f32 v221, v221, v13, v14
	v_max3_f32 v221, v221, v15, v16
	v_max3_f32 v220, v220, v65, v17
	v_max_f32_e32 v220, v220, v221
	ds_bpermute_b32 v221, v165, v220
	ds_read_b64_tr_b16 v[82:83], v222 offset:24576
	ds_read_b64_tr_b16 v[84:85], v222 offset:26112
	ds_read_b64_tr_b16 v[86:87], v222 offset:24640
	ds_read_b64_tr_b16 v[88:89], v222 offset:26176
	ds_read_b64_tr_b16 v[90:91], v222 offset:27648
	ds_read_b64_tr_b16 v[92:93], v222 offset:29184
	ds_read_b64_tr_b16 v[94:95], v222 offset:27712
	ds_read_b64_tr_b16 v[96:97], v222 offset:29248
	s_waitcnt lgkmcnt(8)
	v_max_f32_e32 v220, v220, v221
	v_cmp_lt_f32_e32 vcc, 0, v220
	s_or_b64 vcc, s[14:15], vcc
	s_cbranch_vccz .Lm1_norescale
; #define LAS __attribute__((address_space(3)))
; template <int MODE  > ...
;     ...
;                     const float moldr = fresh ? -1e29f : 0.f, mnewr = fmaxf(moldr, mx);
;                     alpha = __builtin_amdgcn_exp2f(moldr - mnewr);
;                     st.m = mest + mnewr;
; #pragma unroll
;                     for (int i = 0; i < 16; ++i) { s0[i] = __builtin_amdgcn_exp2f(s0[i] - mnewr); s1[i] = __builtin_amdgcn_exp2f(s1[i] - mnewr); }
;                     st.o0 *= alpha; st.o1 *= alpha;
;                 } else {
; #pragma unroll
;                     for (int i = 0; i < 16; ++i) { s0[i] = __builtin_amdgcn_exp2f(s0[i]); s1[i] = __builtin_amdgcn_exp2f(s1[i]); }
;                 }
;                 { typedef float f32x8 __attribute__((ext_vector_type(8)));
;                   const f32x16 t16 = s0 + s1;
;                   const f32x8 t8 = __builtin_shufflevector(t16, t16, 0, 1, 2, 3, 4, 5, 6, 7) + __builtin_shufflevector(t16, t16, 8, 9, 10, 11, 12, 13, 14, 15);
;                   const f32x4 t4 = __builtin_shufflevector(t8, t8, 0, 1, 2, 3) + __builtin_shufflevector(t8, t8, 4, 5, 6, 7);
;                   float ps = (t4[0] + t4[1]) + (t4[2] + t4[3]);
;                   ps += shflx(ps, 32, lane);
;                   st.l = st.l * alpha + ps; }
;                 bf16x8 pf[4];
; #pragma unroll
;                 for (int kk = 0; kk < 4; ++kk) {
;                     u32x4 pw;
;                     if (kk < 2) { pw.x = pk2(s0[8 * kk], s0[8 * kk + 1]); pw.y = pk2(s0[8 * kk + 2], s0[8 * kk + 3]); pw.z = pk2(s0[8 * kk + 4], s0[8 * kk + 5]); pw.w = pk2(s0[8 * kk + 6], s0[8 * kk + 7]); }
;                     else { const int k2 = kk - 2; pw.x = pk2(s1[8 * k2], s1[8 * k2 + 1]); pw.y = pk2(s1[8 * k2 + 2], s1[8 * k2 + 3]); pw.z = pk2(s1[8 * k2 + 4], s1[8 * k2 + 5]); pw.w = pk2(s1[8 * k2 + 6], s1[8 * k2 + 7]); }
;                     pf[kk] = __builtin_bit_cast(bf16x8, pw);
;                 }
;                 const LAS bf16_t* vb = (const LAS bf16_t*)(lds + A_VBUF) + cur * 64 * VPITCH + (4 * h + ((lane & 15) >> 2)) * VPITCH + ((lane >> 4) & 1) * 16 + 4 * (lane & 3);
; #pragma unroll
;                 for (int kk = 0; kk < 4; ++kk) {
;                     typedef short v4i16_t __attribute__((ext_vector_type(4)));
;                     const v4i16_t a0 = __builtin_amdgcn_ds_read_tr16_b64_v4i16((LAS v4i16_t*)(vb + (16 * kk) * VPITCH));
	v_cndmask_b32_e64 v221, 0, v242, s[14:15]
	v_max_f32_e32 v220, v221, v220
	v_sub_f32_e32 v221, v221, v220
	v_exp_f32_e32 v162, v221
	v_add_f32_e32 v194, v1, v220
	v_sub_f32_e32 v114, v50, v220
	v_exp_f32_e32 v114, v114
	v_sub_f32_e32 v98, v2, v220
	v_exp_f32_e32 v98, v98
	v_sub_f32_e32 v115, v51, v220
	v_exp_f32_e32 v115, v115
	v_sub_f32_e32 v99, v3, v220
	v_exp_f32_e32 v99, v99
	v_sub_f32_e32 v116, v52, v220
	v_exp_f32_e32 v116, v116
	v_sub_f32_e32 v100, v4, v220
	v_exp_f32_e32 v100, v100
	v_sub_f32_e32 v117, v53, v220
	v_exp_f32_e32 v117, v117
	v_sub_f32_e32 v101, v5, v220
	v_exp_f32_e32 v101, v101
	v_sub_f32_e32 v118, v54, v220
	v_exp_f32_e32 v118, v118
	v_sub_f32_e32 v102, v6, v220
	v_exp_f32_e32 v102, v102
	v_sub_f32_e32 v119, v55, v220
	v_exp_f32_e32 v119, v119
	v_sub_f32_e32 v103, v7, v220
	v_exp_f32_e32 v103, v103
	v_sub_f32_e32 v120, v56, v220
	v_exp_f32_e32 v120, v120
	v_sub_f32_e32 v104, v8, v220
	v_exp_f32_e32 v104, v104
	v_sub_f32_e32 v121, v57, v220
	v_exp_f32_e32 v121, v121
	v_sub_f32_e32 v105, v9, v220
	v_exp_f32_e32 v105, v105
	v_sub_f32_e32 v122, v58, v220
	v_exp_f32_e32 v122, v122
	v_sub_f32_e32 v106, v10, v220
	v_exp_f32_e32 v106, v106
	v_sub_f32_e32 v123, v59, v220
	v_exp_f32_e32 v123, v123
	v_sub_f32_e32 v107, v11, v220
	v_exp_f32_e32 v107, v107
	v_sub_f32_e32 v124, v60, v220
	v_exp_f32_e32 v124, v124
	v_sub_f32_e32 v108, v12, v220
	v_exp_f32_e32 v108, v108
	v_sub_f32_e32 v125, v61, v220
	v_exp_f32_e32 v125, v125
	v_sub_f32_e32 v109, v13, v220
	v_exp_f32_e32 v109, v109
	v_sub_f32_e32 v126, v62, v220
	v_exp_f32_e32 v126, v126
	v_sub_f32_e32 v110, v14, v220
	v_exp_f32_e32 v110, v110
	v_sub_f32_e32 v127, v63, v220
	v_exp_f32_e32 v127, v127
	v_sub_f32_e32 v111, v15, v220
	v_exp_f32_e32 v111, v111
	v_sub_f32_e32 v128, v64, v220
	v_exp_f32_e32 v128, v128
	v_sub_f32_e32 v112, v16, v220
	v_exp_f32_e32 v112, v112
	v_sub_f32_e32 v129, v65, v220
	v_exp_f32_e32 v129, v129
	v_sub_f32_e32 v113, v17, v220
	v_exp_f32_e32 v113, v113
	v_pk_mul_f32 v[18:19], v[18:19], v[162:163] op_sel_hi:[1,0]
	v_pk_mul_f32 v[20:21], v[20:21], v[162:163] op_sel_hi:[1,0]
	v_pk_mul_f32 v[22:23], v[22:23], v[162:163] op_sel_hi:[1,0]
	v_pk_mul_f32 v[24:25], v[24:25], v[162:163] op_sel_hi:[1,0]
	v_pk_mul_f32 v[26:27], v[26:27], v[162:163] op_sel_hi:[1,0]
	v_pk_mul_f32 v[28:29], v[28:29], v[162:163] op_sel_hi:[1,0]
	v_pk_mul_f32 v[30:31], v[30:31], v[162:163] op_sel_hi:[1,0]
	v_pk_mul_f32 v[32:33], v[32:33], v[162:163] op_sel_hi:[1,0]
	v_pk_mul_f32 v[34:35], v[34:35], v[162:163] op_sel_hi:[1,0]
	v_pk_mul_f32 v[36:37], v[36:37], v[162:163] op_sel_hi:[1,0]
	v_pk_mul_f32 v[38:39], v[38:39], v[162:163] op_sel_hi:[1,0]
	v_pk_mul_f32 v[40:41], v[40:41], v[162:163] op_sel_hi:[1,0]
	v_pk_mul_f32 v[42:43], v[42:43], v[162:163] op_sel_hi:[1,0]
	v_pk_mul_f32 v[44:45], v[44:45], v[162:163] op_sel_hi:[1,0]
	v_pk_mul_f32 v[46:47], v[46:47], v[162:163] op_sel_hi:[1,0]
	v_pk_mul_f32 v[48:49], v[48:49], v[162:163] op_sel_hi:[1,0]
	s_branch .Lm1_pv
.Lm1_norescale:
	v_exp_f32_e32 v114, v50
	v_exp_f32_e32 v98, v2
	v_exp_f32_e32 v115, v51
	v_exp_f32_e32 v99, v3
	v_exp_f32_e32 v116, v52
	v_exp_f32_e32 v100, v4
	v_exp_f32_e32 v117, v53
	v_exp_f32_e32 v101, v5
	v_exp_f32_e32 v118, v54
	v_exp_f32_e32 v102, v6
	v_exp_f32_e32 v119, v55
	v_exp_f32_e32 v103, v7
	v_exp_f32_e32 v120, v56
	v_exp_f32_e32 v104, v8
	v_exp_f32_e32 v121, v57
	v_exp_f32_e32 v105, v9
	v_exp_f32_e32 v122, v58
	v_exp_f32_e32 v106, v10
	v_exp_f32_e32 v123, v59
	v_exp_f32_e32 v107, v11
	v_exp_f32_e32 v124, v60
	v_exp_f32_e32 v108, v12
	v_exp_f32_e32 v125, v61
	v_exp_f32_e32 v109, v13
	v_exp_f32_e32 v126, v62
	v_exp_f32_e32 v110, v14
	v_exp_f32_e32 v127, v63
	v_exp_f32_e32 v111, v15
	v_exp_f32_e32 v128, v64
	v_exp_f32_e32 v112, v16
	v_exp_f32_e32 v129, v65
	v_exp_f32_e32 v113, v17
	v_mov_b32_e32 v162, 1.0
.Lm1_pv:
	v_cvt_pk_bf16_f32 v50, v114, v115
	v_cvt_pk_bf16_f32 v51, v116, v117
	v_cvt_pk_bf16_f32 v52, v118, v119
	v_cvt_pk_bf16_f32 v53, v120, v121
	s_waitcnt lgkmcnt(0)
	s_nop 0
	v_mfma_f32_32x32x16_bf16 v[18:33], v[66:69], v[50:53], v[18:33]
	v_mfma_f32_32x32x16_bf16 v[34:49], v[70:73], v[50:53], v[34:49]
	v_cvt_pk_bf16_f32 v54, v122, v123
	v_cvt_pk_bf16_f32 v55, v124, v125
	v_cvt_pk_bf16_f32 v56, v126, v127
	v_cvt_pk_bf16_f32 v57, v128, v129
	v_pk_add_f32 v[16:17], v[98:99], v[114:115]
	v_pk_add_f32 v[14:15], v[102:103], v[118:119]
	v_pk_add_f32 v[2:3], v[106:107], v[122:123]
	v_pk_add_f32 v[12:13], v[110:111], v[126:127]
	v_pk_add_f32 v[10:11], v[104:105], v[120:121]
	v_mfma_f32_32x32x16_bf16 v[18:33], v[74:77], v[54:57], v[18:33]
	v_mfma_f32_32x32x16_bf16 v[34:49], v[78:81], v[54:57], v[34:49]
	v_cvt_pk_bf16_f32 v58, v98, v99
	v_cvt_pk_bf16_f32 v59, v100, v101
	v_cvt_pk_bf16_f32 v60, v102, v103
	v_cvt_pk_bf16_f32 v61, v104, v105
	v_pk_add_f32 v[8:9], v[112:113], v[128:129]
	v_pk_add_f32 v[4:5], v[108:109], v[124:125]
	v_pk_add_f32 v[6:7], v[100:101], v[116:117]
	v_pk_add_f32 v[12:13], v[14:15], v[12:13]
	v_pk_add_f32 v[2:3], v[16:17], v[2:3]
	v_mfma_f32_32x32x16_bf16 v[18:33], v[82:85], v[58:61], v[18:33]
	v_mfma_f32_32x32x16_bf16 v[34:49], v[86:89], v[58:61], v[34:49]
	v_cvt_pk_bf16_f32 v62, v106, v107
	v_cvt_pk_bf16_f32 v63, v108, v109
	v_cvt_pk_bf16_f32 v64, v110, v111
	v_cvt_pk_bf16_f32 v65, v112, v113
	v_pk_add_f32 v[8:9], v[10:11], v[8:9]
	v_pk_add_f32 v[4:5], v[6:7], v[4:5]
	v_pk_add_f32 v[2:3], v[2:3], v[12:13]
	v_pk_add_f32 v[4:5], v[4:5], v[8:9]
	v_mfma_f32_32x32x16_bf16 v[18:33], v[90:93], v[62:65], v[18:33]
	v_mfma_f32_32x32x16_bf16 v[34:49], v[94:97], v[62:65], v[34:49]
	v_add_f32_e32 v2, v2, v3
	v_add_f32_e32 v3, v4, v5
	v_add_f32_e32 v2, v2, v3
	ds_bpermute_b32 v3, v165, v2
	s_waitcnt lgkmcnt(0)
	v_add_f32_e32 v2, v2, v3
	v_fmac_f32_e32 v2, v193, v162
	v_mov_b32_e32 v193, v2

; template <int MODE  > ...
;     ...
;         __syncthreads();
;         if (!has_next) break;
;         j = jn; cur ^= 1;
; __device__ __forceinline__ void attn_unit(unsigned char* ws, LAS unsigned char* lds, int b, int g, int c, const int tid) {
;     ...
;     { const float gate1 = ((const float*)(ws + WS_G))[row * 32 + head * 3 + 1]; const float sc = st.l > 0.f ? gate1 / st.l : 0.f;
; #pragma unroll
;       for (int i = 0; i < 16; ++i) { outl[i * 512] += st.o0[i] * sc; outl[(16 + i) * 512] += st.o1[i] * sc; } }
;     st.m = -1e29f; st.l = 0.f; st.o0 = (f32x16){}; st.o1 = (f32x16){};
;     { const int jlo = c >= 8 ? c - 8 : 0; const unsigned long long upto = (c >= 63) ? ~0ull : ((1ull << (c + 1)) - 1ull);
;       const unsigned long long winmask = upto & ~((1ull << jlo) - 1ull);
;       attn_pass<2>(lds, (const bf16_t*)(ws + WS_KW) + boff, (const bf16_t*)(ws + WS_VW) + boff, winmask, qf, st, t, slope2, 0ull, w, lane, tid, c); }
.LBB0_260:
	s_andn2_b64 vcc, exec, s[4:5]
	s_xor_b32 s23, s23, 1
	s_waitcnt lgkmcnt(0)
	s_barrier
	s_cbranch_vccz .Lm1_exit
	s_mov_b32 s68, s62
	s_mov_b64 s[14:15], s[18:19]
	s_branch .LBB0_248
.LBB0_263:
	v_mov_b32_e32 v14, v0
	v_mov_b32_e32 v15, v0
	v_mov_b32_e32 v1, v0
	v_mov_b32_e32 v2, v0
	v_mov_b32_e32 v3, v0
	v_mov_b32_e32 v4, v0
	v_mov_b32_e32 v5, v0
	v_mov_b32_e32 v6, v0
	v_mov_b32_e32 v7, v0
	v_mov_b32_e32 v8, v0
	v_mov_b32_e32 v9, v0
	v_mov_b32_e32 v10, v0
	v_mov_b32_e32 v11, v0
	v_mov_b32_e32 v12, v0
	v_mov_b32_e32 v13, v0
	v_mov_b64_e32 v[48:49], v[14:15]
	v_mov_b64_e32 v[32:33], v[14:15]
	v_mov_b32_e32 v193, 0
	v_mov_b64_e32 v[46:47], v[12:13]
	v_mov_b64_e32 v[44:45], v[10:11]
	v_mov_b64_e32 v[42:43], v[8:9]
	v_mov_b64_e32 v[40:41], v[6:7]
	v_mov_b64_e32 v[38:39], v[4:5]
	v_mov_b64_e32 v[36:37], v[2:3]
	v_mov_b64_e32 v[34:35], v[0:1]
	v_mov_b64_e32 v[30:31], v[12:13]
	v_mov_b64_e32 v[28:29], v[10:11]
	v_mov_b64_e32 v[26:27], v[8:9]
	v_mov_b64_e32 v[24:25], v[6:7]
	v_mov_b64_e32 v[22:23], v[4:5]
	v_mov_b64_e32 v[20:21], v[2:3]
	v_mov_b64_e32 v[18:19], v[0:1]
.Lm1_exit:
	s_nop 11
.LBB0_264:
	v_mov_b32_e32 v17, 0
	v_cmp_lt_f32_e32 vcc, 0, v193
	v_mov_b32_e32 v1, 0
	s_and_saveexec_b64 s[4:5], vcc
	s_cbranch_execz .LBB0_266
	global_load_dword v1, v[138:139], off offset:4
	s_waitcnt vmcnt(0) lgkmcnt(0)
	v_div_scale_f32 v2, s[14:15], v193, v193, v1
	v_rcp_f32_e32 v3, v2
	v_div_scale_f32 v4, vcc, v1, v193, v1
	v_fma_f32 v5, -v2, v3, 1.0
	v_fmac_f32_e32 v3, v5, v3
	v_mul_f32_e32 v5, v4, v3
	v_fma_f32 v6, -v2, v5, v4
	v_fmac_f32_e32 v5, v6, v3
	v_fma_f32 v2, -v2, v5, v4
	v_div_fmas_f32 v2, v2, v3, v5
	v_div_fixup_f32 v1, v2, v193, v1
.LBB0_266:
	s_or_b64 exec, exec, s[4:5]
	ds_read2st64_b32 v[2:3], v199 offset1:8
	ds_read2st64_b32 v[4:5], v199 offset0:128 offset1:136
	s_add_i32 s4, s83, 1
	s_lshl_b64 s[4:5], -1, s4
	s_not_b64 s[4:5], s[4:5]
	s_waitcnt lgkmcnt(0)
	v_fma_f32 v2, v18, v1, v2
	v_fma_f32 v4, v34, v1, v4
	v_fmac_f32_e32 v3, v19, v1
	v_fmac_f32_e32 v5, v35, v1
	ds_write2st64_b32 v199, v2, v3 offset1:8
	ds_write2st64_b32 v199, v4, v5 offset0:128 offset1:136
	ds_read2st64_b32 v[2:3], v199 offset0:16 offset1:24
	ds_read2st64_b32 v[4:5], v199 offset0:144 offset1:152
	s_cmp_lt_u32 s83, 63
	s_cselect_b32 s5, s5, -1
	s_cselect_b32 s4, s4, -1
	s_waitcnt lgkmcnt(0)
	v_fma_f32 v2, v20, v1, v2
	v_fma_f32 v4, v36, v1, v4
	v_fmac_f32_e32 v3, v21, v1
	v_fmac_f32_e32 v5, v37, v1
	ds_write2st64_b32 v199, v2, v3 offset0:16 offset1:24
	ds_write2st64_b32 v199, v4, v5 offset0:144 offset1:152
	ds_read2st64_b32 v[2:3], v199 offset0:32 offset1:40
	ds_read2st64_b32 v[4:5], v199 offset0:160 offset1:168
	v_mov_b32_e32 v34, v178
	v_mov_b32_e32 v16, 0
	v_mov_b32_e32 v15, 0
	s_waitcnt lgkmcnt(0)
	v_fma_f32 v2, v22, v1, v2
	v_fma_f32 v4, v38, v1, v4
	v_fmac_f32_e32 v3, v23, v1
	v_fmac_f32_e32 v5, v39, v1
	ds_write2st64_b32 v199, v2, v3 offset0:32 offset1:40
	ds_write2st64_b32 v199, v4, v5 offset0:160 offset1:168
	ds_read2st64_b32 v[2:3], v199 offset0:48 offset1:56
	ds_read2st64_b32 v[4:5], v199 offset0:176 offset1:184
	v_mov_b32_e32 v14, 0
	v_mov_b32_e32 v13, 0
	v_mov_b32_e32 v12, 0
	s_waitcnt lgkmcnt(0)
	v_fma_f32 v2, v24, v1, v2
	v_fma_f32 v4, v40, v1, v4
	v_fmac_f32_e32 v3, v25, v1
	v_fmac_f32_e32 v5, v41, v1
	ds_write2st64_b32 v199, v2, v3 offset0:48 offset1:56
	ds_write2st64_b32 v199, v4, v5 offset0:176 offset1:184
	ds_read2st64_b32 v[2:3], v199 offset0:64 offset1:72
	ds_read2st64_b32 v[4:5], v199 offset0:192 offset1:200
	v_mov_b32_e32 v11, 0
	v_mov_b32_e32 v10, 0
	v_mov_b32_e32 v9, 0
	s_waitcnt lgkmcnt(0)
	v_fma_f32 v2, v26, v1, v2
	v_fma_f32 v4, v42, v1, v4
	v_fmac_f32_e32 v3, v27, v1
	v_fmac_f32_e32 v5, v43, v1
	ds_write2st64_b32 v199, v2, v3 offset0:64 offset1:72
	ds_write2st64_b32 v199, v4, v5 offset0:192 offset1:200
	ds_read2st64_b32 v[2:3], v199 offset0:80 offset1:88
	ds_read2st64_b32 v[4:5], v199 offset0:208 offset1:216
	v_mov_b32_e32 v8, 0
	v_mov_b32_e32 v7, 0
	v_mov_b32_e32 v6, 0
	s_waitcnt lgkmcnt(0)
	v_fma_f32 v2, v28, v1, v2
	v_fma_f32 v4, v44, v1, v4
	v_fmac_f32_e32 v3, v29, v1
	v_fmac_f32_e32 v5, v45, v1
	ds_write2st64_b32 v199, v2, v3 offset0:80 offset1:88
	ds_write2st64_b32 v199, v4, v5 offset0:208 offset1:216
	ds_read2st64_b32 v[2:3], v199 offset0:96 offset1:104
	ds_read2st64_b32 v[4:5], v199 offset0:224 offset1:232
	v_mov_b32_e32 v29, 0
	v_mov_b32_e32 v28, 0
	v_mov_b32_e32 v27, 0
	s_waitcnt lgkmcnt(0)
	v_fma_f32 v2, v30, v1, v2
	v_fma_f32 v4, v46, v1, v4
	v_fmac_f32_e32 v3, v31, v1
	v_fmac_f32_e32 v5, v47, v1
	ds_write2st64_b32 v199, v2, v3 offset0:96 offset1:104
	ds_write2st64_b32 v199, v4, v5 offset0:224 offset1:232
	ds_read2st64_b32 v[2:3], v199 offset0:112 offset1:120
	ds_read2st64_b32 v[4:5], v199 offset0:240 offset1:248
	v_mov_b32_e32 v31, 0
	v_mov_b32_e32 v30, 0
	v_mov_b32_e32 v26, 0
	s_waitcnt lgkmcnt(0)
	v_fma_f32 v2, v32, v1, v2
	v_fma_f32 v4, v48, v1, v4
	v_fmac_f32_e32 v3, v33, v1
	v_fmac_f32_e32 v5, v49, v1
	v_sub_u32_e64 v1, s83, 8 clamp
	ds_write2st64_b32 v199, v2, v3 offset0:112 offset1:120
	v_readfirstlane_b32 s14, v1
	s_lshl_b64 s[14:15], -1, s14
	s_and_b64 s[4:5], s[4:5], s[14:15]
	ds_write2st64_b32 v199, v4, v5 offset0:240 offset1:248
	v_mov_b32_e32 v1, v179
	s_cmp_eq_u64 s[4:5], 0
	v_mov_b32_e32 v5, 0
	v_mov_b32_e32 v4, 0
	v_mov_b32_e32 v3, 0
	v_mov_b32_e32 v2, 0
	v_mov_b32_e32 v33, 0
	v_mov_b32_e32 v32, 0
	v_mov_b32_e32 v25, 0
	v_mov_b32_e32 v24, 0
	v_mov_b32_e32 v23, 0
	v_mov_b32_e32 v22, 0
	v_mov_b32_e32 v21, 0
	v_mov_b32_e32 v20, 0
	v_mov_b32_e32 v19, 0
	v_mov_b32_e32 v18, 0
	v_mov_b32_e32 v35, 0
	s_cbranch_scc1 .LBB0_285
; #define LAS __attribute__((address_space(3)))
; template <int MODE  > ...
;     ...
;     unsigned long long rem = blockmask;
;     if (!rem) return;
;     int j = 63 - __builtin_clzll(rem); rem &= ~(1ull << j);
;     u32x4 kreg, vreg;
;     kreg = *(const u32x4*)(Kg + (size_t)(64 * j + skey) * 128 + schunk * 8);
;     if (NEEDV) vreg = *(const u32x4*)(Vg + (size_t)(64 * j + skey) * 128 + schunk * 8);
;     int cur = 0;
;     {
;         LAS bf16_t* kb = (LAS bf16_t*)(lds + A_KBUF) + cur * 64 * KPITCH;
;         *(LAS u32x4*)(kb + skey * KPITCH + schunk * 8) = kreg;
;         if (NEEDV) { LAS bf16_t* vb = (LAS bf16_t*)(lds + A_VBUF) + cur * 64 * VPITCH;
;             *(LAS u32x4*)(vb + skey * VPITCH + schunk * 8) = vreg; }
;     }
;     __syncthreads();
;     for (;;) {
;         const bool has_next = rem != 0ull; int jn = 0;
;         if (has_next) { jn = 63 - __builtin_clzll(rem); rem &= ~(1ull << jn);
;             kreg = *(const u32x4*)(Kg + (size_t)(64 * jn + skey) * 128 + schunk * 8);
;             if (NEEDV) vreg = *(const u32x4*)(Vg + (size_t)(64 * jn + skey) * 128 + schunk * 8); }
;     ...
;             } else if (ptype == 2) {
;                 const float thr = -511.5f * slope2 - mest;
; __device__ __forceinline__ void attn_unit(unsigned char* ws, LAS unsigned char* lds, int b, int g, int c, const int tid) {
;     ...
;     st.m = -1e29f; st.l = 0.f; st.o0 = (f32x16){}; st.o1 = (f32x16){};
;     { const int jlo = c >= 8 ? c - 8 : 0; const unsigned long long upto = (c >= 63) ? ~0ull : ((1ull << (c + 1)) - 1ull);
;       const unsigned long long winmask = upto & ~((1ull << jlo) - 1ull);
;       attn_pass<2>(lds, (const bf16_t*)(ws + WS_KW) + boff, (const bf16_t*)(ws + WS_VW) + boff, winmask, qf, st, t, slope2, 0ull, w, lane, tid, c); }
	s_lshl_b32 s16, s22, 1
	s_add_u32 s14, s47, s16
	s_addc_u32 s15, s48, 0
	s_add_u32 s16, s49, s16
	s_flbit_i32_b64 s18, s[4:5]
	v_ashrrev_i32_e32 v161, 3, v34
	s_addc_u32 s17, s82, 0
	s_xor_b32 s20, s18, 63
	v_lshl_add_u32 v2, s20, 6, v161
	v_ashrrev_i32_e32 v3, 31, v2
	v_lshlrev_b64 v[2:3], 8, v[2:3]
	v_lshlrev_b32_e32 v6, 4, v34
	v_lshl_add_u64 v[4:5], s[16:17], 0, v[2:3]
	v_and_b32_e32 v16, 0x70, v6
	v_mov_b32_e32 v17, v0
	v_lshl_add_u64 v[4:5], v[4:5], 0, v[16:17]
	v_lshl_add_u64 v[2:3], s[14:15], 0, v[2:3]
	v_lshl_add_u64 v[2:3], v[2:3], 0, v[16:17]
	s_waitcnt vmcnt(0)
	global_load_dwordx4 v[130:133], v[4:5], off
	global_load_dwordx4 v[134:137], v[2:3], off
	v_ashrrev_i32_e32 v18, 5, v1
	v_lshrrev_b32_e32 v34, 2, v1
	v_lshlrev_b32_e32 v37, 2, v18
	v_and_b32_e32 v19, 31, v1
	v_lshlrev_b32_e32 v20, 2, v1
	v_and_b32_e32 v21, 16, v1
	v_lshlrev_b32_e32 v22, 3, v1
	v_mov_b32_e32 v14, v0
	v_mov_b32_e32 v15, v0
	s_movk_i32 s18, 0x90
	v_and_or_b32 v34, v34, 3, v37
	v_mov_b32_e32 v1, v0
	v_mov_b32_e32 v2, v0
	v_mov_b32_e32 v3, v0
	v_mov_b32_e32 v4, v0
	v_mov_b32_e32 v5, v0
	v_mov_b32_e32 v6, v0
	v_mov_b32_e32 v7, v0
	v_mov_b32_e32 v8, v0
	v_mov_b32_e32 v9, v0
	v_mov_b32_e32 v10, v0
	v_mov_b32_e32 v11, v0
	v_mov_b32_e32 v12, v0
	v_mov_b32_e32 v13, v0
	v_mul_lo_u32 v35, v161, s18
	v_mul_lo_u32 v36, v161, s70
	v_mul_u32_u24_e32 v38, 0x90, v19
	v_bitop3_b32 v164, v20, s66, v240 bitop3:0x6c
	v_lshlrev_b32_e32 v39, 1, v21
	v_and_b32_e32 v40, 24, v22
	v_lshlrev_b32_e32 v41, 4, v18
	v_mov_b64_e32 v[32:33], v[14:15]
	v_mul_lo_u32 v34, v34, s70
	v_mov_b64_e32 v[30:31], v[12:13]
	v_mov_b64_e32 v[28:29], v[10:11]
	v_mov_b64_e32 v[26:27], v[8:9]
	v_mov_b64_e32 v[24:25], v[6:7]
	v_mov_b64_e32 v[22:23], v[4:5]
	v_mov_b64_e32 v[20:21], v[2:3]
	v_mov_b64_e32 v[18:19], v[0:1]
	v_add3_u32 v165, 0, v35, v16
	v_add3_u32 v166, 0, v36, v16
	v_lshl_add_u64 v[140:141], s[14:15], 0, v[16:17]
	v_add_u32_e32 v34, 0, v34
	s_lshl_b64 s[14:15], 1, s20
	v_lshl_add_u64 v[142:143], s[16:17], 0, v[16:17]
	v_mov_b64_e32 v[16:17], v[14:15]
	v_mul_f32_e32 v162, 0xc3ffc000, v186
	s_mov_b32 s22, 0
	v_mov_b32_e32 v192, 0xefa18f08
	v_mov_b32_e32 v190, 0
	v_sub_u32_e32 v167, v37, v188
	v_add3_u32 v188, 0, v38, v41
	s_add_i32 s23, s83, -8
	v_add3_u32 v191, v34, v39, v40
	s_andn2_b64 s[14:15], s[4:5], s[14:15]
	v_mov_b64_e32 v[14:15], v[12:13]
	v_mov_b64_e32 v[12:13], v[10:11]
	v_mov_b64_e32 v[10:11], v[8:9]
	v_mov_b64_e32 v[8:9], v[6:7]
	v_mov_b64_e32 v[6:7], v[4:5]
	v_mov_b64_e32 v[4:5], v[2:3]
	v_mov_b64_e32 v[2:3], v[0:1]
	s_waitcnt vmcnt(0) lgkmcnt(0)
	ds_write_b128 v165, v[130:133]
	ds_write_b128 v166, v[134:137] offset:18432
	s_waitcnt lgkmcnt(0)
	s_barrier
.LBB0_268:
	s_cmp_eq_u64 s[14:15], 0
	s_cselect_b64 s[4:5], -1, 0
	s_cmp_lg_u64 s[14:15], 0
	s_mov_b64 s[16:17], 0
	s_cselect_b64 s[18:19], -1, 0
	s_and_b64 vcc, exec, s[4:5]
	s_mov_b32 s62, 0
	s_cbranch_vccnz .LBB0_270
	s_flbit_i32_b64 s16, s[14:15]
	s_xor_b32 s62, s16, 63
	v_lshl_add_u32 v34, s62, 6, v161
	v_ashrrev_i32_e32 v35, 31, v34
	v_lshlrev_b64 v[34:35], 8, v[34:35]
	v_lshl_add_u64 v[36:37], v[142:143], 0, v[34:35]
	v_lshl_add_u64 v[34:35], v[140:141], 0, v[34:35]
	s_waitcnt vmcnt(0)
	global_load_dwordx4 v[130:133], v[36:37], off
	global_load_dwordx4 v[134:137], v[34:35], off
	s_lshl_b64 s[16:17], 1, s62
	s_andn2_b64 s[16:17], s[14:15], s[16:17]

; __device__ __forceinline__ void attn_unit(unsigned char* ws, LAS unsigned char* lds, int b, int g, int c, const int tid) {
;     ...
;     { const float gate2 = ((const float*)(ws + WS_G))[row * 32 + head * 3 + 2]; const float sc = st.l > 0.f ? gate2 / st.l : 0.f;
.LBB0_285:
	v_mov_b32_e32 v34, 0
	v_cmp_lt_f32_e32 vcc, 0, v35
	s_and_saveexec_b64 s[4:5], vcc
	s_cbranch_execz .LBB0_131
	global_load_dword v1, v[138:139], off offset:8
	s_waitcnt vmcnt(0) lgkmcnt(0)
	v_div_scale_f32 v34, s[14:15], v35, v35, v1
	v_rcp_f32_e32 v36, v34
	v_div_scale_f32 v37, vcc, v1, v35, v1
	v_fma_f32 v38, -v34, v36, 1.0
	v_fmac_f32_e32 v36, v38, v36
	v_mul_f32_e32 v38, v37, v36
	v_fma_f32 v39, -v34, v38, v37
	v_fmac_f32_e32 v38, v39, v36
	v_fma_f32 v34, -v34, v38, v37
	v_div_fmas_f32 v34, v34, v36, v38
	v_div_fixup_f32 v34, v34, v35, v1
	s_branch .LBB0_131

; __device__ __forceinline__ unsigned pk2(float lo, float hi) { f32x2_t v = {lo, hi}; bf16x2_t b = __builtin_convertvector(v, bf16x2_t); return __builtin_bit_cast(unsigned, b); }
; __device__ __forceinline__ float fsilu(float x) { return x * fsigmoid(x); }
;     __device__ __forceinline__ void operator()(const f32x4 (&acc)[2][2][4][2], const Unit& u, int wr, int wc, int fr, int fq) const {
;         const int row0 = u.pm * BM + wr * 64 + fr, cl = wc * 32 + 8 * fq;
;         const float* bb = bias1 + u.pn * 256;
; #pragma unroll
;         for (int bj = 0; bj < 2; ++bj) {
;             const f32x4 c0 = *(const f32x4*)(bb + bj * 128 + cl), c1 = *(const f32x4*)(bb + bj * 128 + cl + 4);
; #pragma unroll
;             for (int ai = 0; ai < 2; ++ai)
; #pragma unroll
;                 for (int m = 0; m < 4; ++m) {
;                     const f32x4 v0 = acc[ai][bj][m][0] + c0, v1 = acc[ai][bj][m][1] + c1;
;                     u32x4 w; w.x = pk2(fsilu(v0[0]), fsilu(v0[1])); w.y = pk2(fsilu(v0[2]), fsilu(v0[3])); w.z = pk2(fsilu(v1[0]), fsilu(v1[1])); w.w = pk2(fsilu(v1[2]), fsilu(v1[3]));
;                     *(u32x4*)(HID + (size_t)(row0 + ai * HALF + m * 16) * 256 + bj * 128 + cl) = w;
;                 }
;         }
;     }
.LBB0_302:
	s_lshl_b32 s10, s91, 8
	v_mov_b32_e32 v98, v1
	v_mov_b32_e32 v99, v156
	s_lshl_b32 s6, s92, 8
	s_ashr_i32 s11, s10, 31
	s_add_i32 s6, s6, s82
	s_lshl_b64 s[10:11], s[10:11], 2
	v_add_u32_e32 v152, s6, v98
	v_lshl_add_u32 v98, v99, 3, s83
	s_add_u32 s10, s68, s10
	s_addc_u32 s11, s69, s11
	v_ashrrev_i32_e32 v99, 31, v98
	v_lshl_add_u64 v[150:151], v[98:99], 2, s[10:11]
	v_lshl_add_u64 v[154:155], v[98:99], 1, s[8:9]
	global_load_dwordx4 v[102:105], v[150:151], off
	global_load_dwordx4 v[98:101], v[150:151], off offset:16
	v_ashrrev_i32_e32 v153, 31, v152
	s_mov_b64 s[6:7], 0x10000
	s_mov_b64 s[10:11], 0x2000
	s_mov_b64 s[22:23], -1
	s_waitcnt vmcnt(0) lgkmcnt(0)
	v_pk_add_f32 v[134:135], v[134:135], v[102:103]
	v_pk_add_f32 v[180:181], v[132:133], v[100:101]
	v_mul_f32_e32 v132, 0xbfb8aa3b, v134
	v_mul_f32_e32 v133, 0xbfb8aa3b, v135
	v_exp_f32_e32 v132, v132
	v_exp_f32_e32 v133, v133
	v_pk_add_f32 v[136:137], v[136:137], v[104:105]
	v_pk_add_f32 v[130:131], v[130:131], v[98:99]
	v_add_f32_e32 v132, 1.0, v132
	v_add_f32_e32 v133, 1.0, v133
	v_rcp_f32_e32 v132, v132
	v_rcp_f32_e32 v133, v133
	v_pk_add_f32 v[128:129], v[128:129], v[104:105]
	v_pk_add_f32 v[118:119], v[118:119], v[102:103]
	v_pk_add_f32 v[120:121], v[120:121], v[104:105]
	v_pk_mul_f32 v[132:133], v[134:135], v[132:133]
	v_pk_add_f32 v[114:115], v[114:115], v[98:99]
	v_cvt_pk_bf16_f32 v132, v132, v133
	v_mul_f32_e32 v133, 0xbfb8aa3b, v136
	v_exp_f32_e32 v133, v133
	v_pk_add_f32 v[110:111], v[110:111], v[102:103]
	v_pk_add_f32 v[112:113], v[112:113], v[104:105]
	v_pk_add_f32 v[106:107], v[106:107], v[98:99]
	v_add_f32_e32 v133, 1.0, v133
	v_rcp_f32_e32 v134, v133
	v_mul_f32_e32 v133, 0xbfb8aa3b, v137
	v_exp_f32_e32 v133, v133
	v_pk_add_f32 v[94:95], v[94:95], v[102:103]
	v_pk_add_f32 v[96:97], v[96:97], v[104:105]
	v_pk_add_f32 v[90:91], v[90:91], v[98:99]
	v_add_f32_e32 v133, 1.0, v133
	v_rcp_f32_e32 v135, v133
	v_pk_add_f32 v[86:87], v[86:87], v[102:103]
	v_pk_add_f32 v[88:89], v[88:89], v[104:105]
	v_pk_add_f32 v[82:83], v[82:83], v[98:99]
	v_pk_mul_f32 v[134:135], v[136:137], v[134:135]
	v_pk_add_f32 v[78:79], v[78:79], v[102:103]
	v_cvt_pk_bf16_f32 v133, v134, v135
	v_mul_f32_e32 v134, 0xbfb8aa3b, v130
	v_mul_f32_e32 v135, 0xbfb8aa3b, v131
	v_exp_f32_e32 v134, v134
	v_exp_f32_e32 v135, v135
	v_pk_add_f32 v[80:81], v[80:81], v[104:105]
	v_pk_add_f32 v[74:75], v[74:75], v[98:99]
	v_add_f32_e32 v134, 1.0, v134
	v_add_f32_e32 v135, 1.0, v135
	v_rcp_f32_e32 v134, v134
	v_rcp_f32_e32 v135, v135
	v_pk_add_f32 v[70:71], v[70:71], v[102:103]
	v_pk_add_f32 v[72:73], v[72:73], v[104:105]
	v_pk_mul_f32 v[130:131], v[130:131], v[134:135]
	s_nop 0
	v_cvt_pk_bf16_f32 v134, v130, v131
	v_mul_f32_e32 v130, 0xbfb8aa3b, v180
	v_mul_f32_e32 v131, 0xbfb8aa3b, v181
	v_exp_f32_e32 v130, v130
	v_exp_f32_e32 v131, v131
	v_add_f32_e32 v130, 1.0, v130
	v_add_f32_e32 v131, 1.0, v131
	v_rcp_f32_e32 v130, v130
	v_rcp_f32_e32 v131, v131
	s_nop 0
	v_pk_mul_f32 v[130:131], v[180:181], v[130:131]
	s_nop 0
	v_cvt_pk_bf16_f32 v135, v130, v131
	v_lshlrev_b64 v[130:131], 9, v[152:153]
	v_lshl_add_u64 v[130:131], v[154:155], 0, v[130:131]
	global_store_dwordx4 v[130:131], v[132:135], off
	s_nop 1
	v_pk_add_f32 v[132:133], v[126:127], v[102:103]
	v_pk_add_f32 v[126:127], v[124:125], v[100:101]
	v_pk_add_f32 v[124:125], v[122:123], v[98:99]
	v_mul_f32_e32 v122, 0xbfb8aa3b, v132
	v_mul_f32_e32 v123, 0xbfb8aa3b, v133
	v_exp_f32_e32 v122, v122
	v_exp_f32_e32 v123, v123
	v_add_f32_e32 v122, 1.0, v122
	v_add_f32_e32 v123, 1.0, v123
	v_rcp_f32_e32 v122, v122
	v_rcp_f32_e32 v123, v123
	s_nop 0
	v_pk_mul_f32 v[122:123], v[132:133], v[122:123]
	s_nop 0
	v_cvt_pk_bf16_f32 v122, v122, v123
	v_mul_f32_e32 v123, 0xbfb8aa3b, v128
	v_exp_f32_e32 v123, v123
	s_nop 0
	v_add_f32_e32 v123, 1.0, v123
	v_rcp_f32_e32 v132, v123
	v_mul_f32_e32 v123, 0xbfb8aa3b, v129
	v_exp_f32_e32 v123, v123
	s_nop 0
	v_add_f32_e32 v123, 1.0, v123
	v_rcp_f32_e32 v133, v123
	s_nop 0
	v_pk_mul_f32 v[128:129], v[128:129], v[132:133]
	s_nop 0
	v_cvt_pk_bf16_f32 v123, v128, v129
	v_mul_f32_e32 v128, 0xbfb8aa3b, v124
	v_mul_f32_e32 v129, 0xbfb8aa3b, v125
	v_exp_f32_e32 v128, v128
	v_exp_f32_e32 v129, v129
	v_add_f32_e32 v128, 1.0, v128
	v_add_f32_e32 v129, 1.0, v129
	v_rcp_f32_e32 v128, v128
	v_rcp_f32_e32 v129, v129
	s_nop 0
	v_pk_mul_f32 v[124:125], v[124:125], v[128:129]
	s_nop 0
	v_cvt_pk_bf16_f32 v124, v124, v125
	v_mul_f32_e32 v125, 0xbfb8aa3b, v126
	v_exp_f32_e32 v125, v125
	s_nop 0
	v_add_f32_e32 v125, 1.0, v125
	v_rcp_f32_e32 v128, v125
	v_mul_f32_e32 v125, 0xbfb8aa3b, v127
	v_exp_f32_e32 v125, v125
	s_nop 0
	v_add_f32_e32 v125, 1.0, v125
	v_rcp_f32_e32 v129, v125
	s_nop 0
	v_pk_mul_f32 v[126:127], v[126:127], v[128:129]
	v_add_co_u32_e32 v128, vcc, s80, v130
	v_cvt_pk_bf16_f32 v125, v126, v127
	s_nop 0
	v_addc_co_u32_e32 v129, vcc, 0, v131, vcc
	global_store_dwordx4 v[128:129], v[122:125], off
	v_lshl_add_u64 v[126:127], v[130:131], 0, s[10:11]
	s_mov_b64 s[10:11], 0x4000
	v_pk_add_f32 v[122:123], v[116:117], v[100:101]
	v_mul_f32_e32 v116, 0xbfb8aa3b, v118
	v_mul_f32_e32 v117, 0xbfb8aa3b, v119
	v_exp_f32_e32 v116, v116
	v_exp_f32_e32 v117, v117
	v_add_f32_e32 v116, 1.0, v116
	v_add_f32_e32 v117, 1.0, v117
	v_rcp_f32_e32 v116, v116
	v_rcp_f32_e32 v117, v117
	s_nop 0
	v_pk_mul_f32 v[116:117], v[118:119], v[116:117]
	s_nop 0
	v_cvt_pk_bf16_f32 v116, v116, v117
	v_mul_f32_e32 v117, 0xbfb8aa3b, v120
	v_exp_f32_e32 v117, v117
	s_nop 0
	v_add_f32_e32 v117, 1.0, v117
	v_rcp_f32_e32 v118, v117
	v_mul_f32_e32 v117, 0xbfb8aa3b, v121
	v_exp_f32_e32 v117, v117
	s_nop 0
	v_add_f32_e32 v117, 1.0, v117
	v_rcp_f32_e32 v119, v117
	s_nop 0
; __device__ __forceinline__ unsigned pk2(float lo, float hi) { f32x2_t v = {lo, hi}; bf16x2_t b = __builtin_convertvector(v, bf16x2_t); return __builtin_bit_cast(unsigned, b); }
; __device__ __forceinline__ float fsilu(float x) { return x * fsigmoid(x); }
;     __device__ __forceinline__ void operator()(const f32x4 (&acc)[2][2][4][2], const Unit& u, int wr, int wc, int fr, int fq) const {
;     ...
;         for (int bj = 0; bj < 2; ++bj) {
;             const f32x4 c0 = *(const f32x4*)(bb + bj * 128 + cl), c1 = *(const f32x4*)(bb + bj * 128 + cl + 4);
; #pragma unroll
;             for (int ai = 0; ai < 2; ++ai)
; #pragma unroll
;                 for (int m = 0; m < 4; ++m) {
;                     const f32x4 v0 = acc[ai][bj][m][0] + c0, v1 = acc[ai][bj][m][1] + c1;
;                     u32x4 w; w.x = pk2(fsilu(v0[0]), fsilu(v0[1])); w.y = pk2(fsilu(v0[2]), fsilu(v0[3])); w.z = pk2(fsilu(v1[0]), fsilu(v1[1])); w.w = pk2(fsilu(v1[2]), fsilu(v1[3]));
;                     *(u32x4*)(HID + (size_t)(row0 + ai * HALF + m * 16) * 256 + bj * 128 + cl) = w;
;                 }
	v_pk_mul_f32 v[118:119], v[120:121], v[118:119]
	s_nop 0
	v_cvt_pk_bf16_f32 v117, v118, v119
	v_mul_f32_e32 v118, 0xbfb8aa3b, v114
	v_mul_f32_e32 v119, 0xbfb8aa3b, v115
	v_exp_f32_e32 v118, v118
	v_exp_f32_e32 v119, v119
	v_add_co_u32_e32 v120, vcc, s81, v130
	v_add_f32_e32 v118, 1.0, v118
	v_add_f32_e32 v119, 1.0, v119
	v_rcp_f32_e32 v118, v118
	v_rcp_f32_e32 v119, v119
	v_addc_co_u32_e32 v121, vcc, 0, v131, vcc
	v_pk_mul_f32 v[114:115], v[114:115], v[118:119]
	s_nop 0
	v_cvt_pk_bf16_f32 v118, v114, v115
	v_mul_f32_e32 v114, 0xbfb8aa3b, v122
	v_mul_f32_e32 v115, 0xbfb8aa3b, v123
	v_exp_f32_e32 v114, v114
	v_exp_f32_e32 v115, v115
	v_add_f32_e32 v114, 1.0, v114
	v_add_f32_e32 v115, 1.0, v115
	v_rcp_f32_e32 v114, v114
	v_rcp_f32_e32 v115, v115
	s_nop 0
	v_pk_mul_f32 v[114:115], v[122:123], v[114:115]
	s_nop 0
	v_cvt_pk_bf16_f32 v119, v114, v115
	global_store_dwordx4 v[120:121], v[116:119], off
	v_lshl_add_u64 v[114:115], v[130:131], 0, s[10:11]
	s_mov_b64 s[10:11], 0x6000
	v_pk_add_f32 v[116:117], v[108:109], v[100:101]
	v_mul_f32_e32 v108, 0xbfb8aa3b, v110
	v_mul_f32_e32 v109, 0xbfb8aa3b, v111
	v_exp_f32_e32 v108, v108
	v_exp_f32_e32 v109, v109
	v_add_f32_e32 v108, 1.0, v108
	v_add_f32_e32 v109, 1.0, v109
	v_rcp_f32_e32 v108, v108
	v_rcp_f32_e32 v109, v109
	s_nop 0
	v_pk_mul_f32 v[108:109], v[110:111], v[108:109]
	s_nop 0
	v_cvt_pk_bf16_f32 v108, v108, v109
	v_mul_f32_e32 v109, 0xbfb8aa3b, v112
	v_exp_f32_e32 v109, v109
	s_nop 0
	v_add_f32_e32 v109, 1.0, v109
	v_rcp_f32_e32 v110, v109
	v_mul_f32_e32 v109, 0xbfb8aa3b, v113
	v_exp_f32_e32 v109, v109
	s_nop 0
	v_add_f32_e32 v109, 1.0, v109
	v_rcp_f32_e32 v111, v109
	s_nop 0
	v_pk_mul_f32 v[110:111], v[112:113], v[110:111]
	s_nop 0
	v_cvt_pk_bf16_f32 v109, v110, v111
	v_mul_f32_e32 v110, 0xbfb8aa3b, v106
	v_mul_f32_e32 v111, 0xbfb8aa3b, v107
	v_exp_f32_e32 v110, v110
	v_exp_f32_e32 v111, v111
	v_add_co_u32_e32 v112, vcc, s60, v130
	v_add_f32_e32 v110, 1.0, v110
	v_add_f32_e32 v111, 1.0, v111
	v_rcp_f32_e32 v110, v110
	v_rcp_f32_e32 v111, v111
	v_addc_co_u32_e32 v113, vcc, 0, v131, vcc
	v_pk_mul_f32 v[106:107], v[106:107], v[110:111]
	s_nop 0
	v_cvt_pk_bf16_f32 v110, v106, v107
	v_mul_f32_e32 v106, 0xbfb8aa3b, v116
	v_mul_f32_e32 v107, 0xbfb8aa3b, v117
	v_exp_f32_e32 v106, v106
	v_exp_f32_e32 v107, v107
	v_add_f32_e32 v106, 1.0, v106
	v_add_f32_e32 v107, 1.0, v107
	v_rcp_f32_e32 v106, v106
	v_rcp_f32_e32 v107, v107
	s_nop 0
	v_pk_mul_f32 v[106:107], v[116:117], v[106:107]
	s_nop 0
	v_cvt_pk_bf16_f32 v111, v106, v107
	global_store_dwordx4 v[112:113], v[108:111], off
	v_lshl_add_u64 v[106:107], v[130:131], 0, s[10:11]
	s_mov_b64 s[10:11], 0x12000
	v_pk_add_f32 v[108:109], v[92:93], v[100:101]
	v_mul_f32_e32 v92, 0xbfb8aa3b, v94
	v_mul_f32_e32 v93, 0xbfb8aa3b, v95
	v_exp_f32_e32 v92, v92
	v_exp_f32_e32 v93, v93
	v_add_f32_e32 v92, 1.0, v92
	v_add_f32_e32 v93, 1.0, v93
	v_rcp_f32_e32 v92, v92
	v_rcp_f32_e32 v93, v93
	s_nop 0
	v_pk_mul_f32 v[92:93], v[94:95], v[92:93]
	s_nop 0
	v_cvt_pk_bf16_f32 v92, v92, v93
	v_mul_f32_e32 v93, 0xbfb8aa3b, v96
	v_exp_f32_e32 v93, v93
	s_nop 0
	v_add_f32_e32 v93, 1.0, v93
	v_rcp_f32_e32 v94, v93
	v_mul_f32_e32 v93, 0xbfb8aa3b, v97
	v_exp_f32_e32 v93, v93
	s_nop 0
	v_add_f32_e32 v93, 1.0, v93
	v_rcp_f32_e32 v95, v93
	s_nop 0
	v_pk_mul_f32 v[94:95], v[96:97], v[94:95]
	s_nop 0
	v_cvt_pk_bf16_f32 v93, v94, v95
	v_mul_f32_e32 v94, 0xbfb8aa3b, v90
	v_mul_f32_e32 v95, 0xbfb8aa3b, v91
	v_exp_f32_e32 v94, v94
	v_exp_f32_e32 v95, v95
	v_add_f32_e32 v94, 1.0, v94
	v_add_f32_e32 v95, 1.0, v95
	v_rcp_f32_e32 v94, v94
	v_rcp_f32_e32 v95, v95
	s_nop 0
	v_pk_mul_f32 v[90:91], v[90:91], v[94:95]
	s_nop 0
	v_cvt_pk_bf16_f32 v94, v90, v91
	v_mul_f32_e32 v90, 0xbfb8aa3b, v108
	v_mul_f32_e32 v91, 0xbfb8aa3b, v109
	v_exp_f32_e32 v90, v90
	v_exp_f32_e32 v91, v91
	v_add_f32_e32 v90, 1.0, v90
	v_add_f32_e32 v91, 1.0, v91
	v_rcp_f32_e32 v90, v90
	v_rcp_f32_e32 v91, v91
	s_nop 0
	v_pk_mul_f32 v[90:91], v[108:109], v[90:91]
	s_nop 0
	v_cvt_pk_bf16_f32 v95, v90, v91
	v_lshl_add_u64 v[90:91], v[130:131], 0, s[6:7]
	s_mov_b32 s6, 0x10000
	v_add_co_u32_e32 v96, vcc, s6, v130
	s_mov_b32 s6, 0x12000
	s_nop 0
	v_addc_co_u32_e32 v97, vcc, 0, v131, vcc
	global_store_dwordx4 v[96:97], v[92:95], off
	s_nop 1
	v_pk_add_f32 v[92:93], v[84:85], v[100:101]
	v_mul_f32_e32 v84, 0xbfb8aa3b, v86
	v_mul_f32_e32 v85, 0xbfb8aa3b, v87
	v_exp_f32_e32 v84, v84
	v_exp_f32_e32 v85, v85
	v_add_f32_e32 v84, 1.0, v84
	v_add_f32_e32 v85, 1.0, v85
	v_rcp_f32_e32 v84, v84
	v_rcp_f32_e32 v85, v85
	s_nop 0
	v_pk_mul_f32 v[84:85], v[86:87], v[84:85]
	s_nop 0
	v_cvt_pk_bf16_f32 v84, v84, v85
	v_mul_f32_e32 v85, 0xbfb8aa3b, v88
	v_exp_f32_e32 v85, v85
	s_nop 0
	v_add_f32_e32 v85, 1.0, v85
	v_rcp_f32_e32 v86, v85
	v_mul_f32_e32 v85, 0xbfb8aa3b, v89
	v_exp_f32_e32 v85, v85
	s_nop 0
	v_add_f32_e32 v85, 1.0, v85
	v_rcp_f32_e32 v87, v85
	s_nop 0
	v_pk_mul_f32 v[86:87], v[88:89], v[86:87]
	s_nop 0
	v_cvt_pk_bf16_f32 v85, v86, v87
	v_mul_f32_e32 v86, 0xbfb8aa3b, v82
	v_mul_f32_e32 v87, 0xbfb8aa3b, v83
	v_exp_f32_e32 v86, v86
	v_exp_f32_e32 v87, v87
	v_add_co_u32_e32 v88, vcc, s6, v130
	v_add_f32_e32 v86, 1.0, v86
	v_add_f32_e32 v87, 1.0, v87
	v_rcp_f32_e32 v86, v86
	v_rcp_f32_e32 v87, v87
	v_addc_co_u32_e32 v89, vcc, 0, v131, vcc
	s_mov_b32 s6, 0x14000
	v_pk_mul_f32 v[82:83], v[82:83], v[86:87]
	s_nop 0
	v_cvt_pk_bf16_f32 v86, v82, v83
	v_mul_f32_e32 v82, 0xbfb8aa3b, v92
	v_mul_f32_e32 v83, 0xbfb8aa3b, v93
	v_exp_f32_e32 v82, v82
	v_exp_f32_e32 v83, v83
	v_add_f32_e32 v82, 1.0, v82
	v_add_f32_e32 v83, 1.0, v83
	v_rcp_f32_e32 v82, v82
	v_rcp_f32_e32 v83, v83
	s_nop 0
	v_pk_mul_f32 v[82:83], v[92:93], v[82:83]
	s_nop 0
; __device__ __forceinline__ unsigned pk2(float lo, float hi) { f32x2_t v = {lo, hi}; bf16x2_t b = __builtin_convertvector(v, bf16x2_t); return __builtin_bit_cast(unsigned, b); }
; __device__ __forceinline__ float fsilu(float x) { return x * fsigmoid(x); }
;     __device__ __forceinline__ void operator()(const f32x4 (&acc)[2][2][4][2], const Unit& u, int wr, int wc, int fr, int fq) const {
;     ...
;         for (int bj = 0; bj < 2; ++bj) {
;             const f32x4 c0 = *(const f32x4*)(bb + bj * 128 + cl), c1 = *(const f32x4*)(bb + bj * 128 + cl + 4);
; #pragma unroll
;             for (int ai = 0; ai < 2; ++ai)
; #pragma unroll
;                 for (int m = 0; m < 4; ++m) {
;                     const f32x4 v0 = acc[ai][bj][m][0] + c0, v1 = acc[ai][bj][m][1] + c1;
;                     u32x4 w; w.x = pk2(fsilu(v0[0]), fsilu(v0[1])); w.y = pk2(fsilu(v0[2]), fsilu(v0[3])); w.z = pk2(fsilu(v1[0]), fsilu(v1[1])); w.w = pk2(fsilu(v1[2]), fsilu(v1[3]));
;                     *(u32x4*)(HID + (size_t)(row0 + ai * HALF + m * 16) * 256 + bj * 128 + cl) = w;
;                 }
	v_cvt_pk_bf16_f32 v87, v82, v83
	global_store_dwordx4 v[88:89], v[84:87], off
	v_lshl_add_u64 v[82:83], v[130:131], 0, s[10:11]
	s_mov_b64 s[10:11], 0x14000
	v_pk_add_f32 v[84:85], v[76:77], v[100:101]
	v_mul_f32_e32 v76, 0xbfb8aa3b, v78
	v_mul_f32_e32 v77, 0xbfb8aa3b, v79
	v_exp_f32_e32 v76, v76
	v_exp_f32_e32 v77, v77
	v_add_f32_e32 v76, 1.0, v76
	v_add_f32_e32 v77, 1.0, v77
	v_rcp_f32_e32 v76, v76
	v_rcp_f32_e32 v77, v77
	s_nop 0
	v_pk_mul_f32 v[76:77], v[78:79], v[76:77]
	s_nop 0
	v_cvt_pk_bf16_f32 v76, v76, v77
	v_mul_f32_e32 v77, 0xbfb8aa3b, v80
	v_exp_f32_e32 v77, v77
	s_nop 0
	v_add_f32_e32 v77, 1.0, v77
	v_rcp_f32_e32 v78, v77
	v_mul_f32_e32 v77, 0xbfb8aa3b, v81
	v_exp_f32_e32 v77, v77
	s_nop 0
	v_add_f32_e32 v77, 1.0, v77
	v_rcp_f32_e32 v79, v77
	s_nop 0
	v_pk_mul_f32 v[78:79], v[80:81], v[78:79]
	s_nop 0
	v_cvt_pk_bf16_f32 v77, v78, v79
	v_mul_f32_e32 v78, 0xbfb8aa3b, v74
	v_mul_f32_e32 v79, 0xbfb8aa3b, v75
	v_exp_f32_e32 v78, v78
	v_exp_f32_e32 v79, v79
	v_add_co_u32_e32 v80, vcc, s6, v130
	v_add_f32_e32 v78, 1.0, v78
	v_add_f32_e32 v79, 1.0, v79
	v_rcp_f32_e32 v78, v78
	v_rcp_f32_e32 v79, v79
	v_addc_co_u32_e32 v81, vcc, 0, v131, vcc
	s_mov_b32 s6, 0x16000
	v_pk_mul_f32 v[74:75], v[74:75], v[78:79]
	s_nop 0
	v_cvt_pk_bf16_f32 v78, v74, v75
	v_mul_f32_e32 v74, 0xbfb8aa3b, v84
	v_mul_f32_e32 v75, 0xbfb8aa3b, v85
	v_exp_f32_e32 v74, v74
	v_exp_f32_e32 v75, v75
	v_add_f32_e32 v74, 1.0, v74
	v_add_f32_e32 v75, 1.0, v75
	v_rcp_f32_e32 v74, v74
	v_rcp_f32_e32 v75, v75
	s_nop 0
	v_pk_mul_f32 v[74:75], v[84:85], v[74:75]
	s_nop 0
	v_cvt_pk_bf16_f32 v79, v74, v75
	global_store_dwordx4 v[80:81], v[76:79], off
	v_lshl_add_u64 v[74:75], v[130:131], 0, s[10:11]
	s_mov_b64 s[10:11], 0x16000
	v_pk_add_f32 v[76:77], v[68:69], v[100:101]
	v_pk_add_f32 v[68:69], v[66:67], v[98:99]
	v_mul_f32_e32 v66, 0xbfb8aa3b, v70
	v_mul_f32_e32 v67, 0xbfb8aa3b, v71
	v_exp_f32_e32 v66, v66
	v_exp_f32_e32 v67, v67
	v_add_f32_e32 v66, 1.0, v66
	v_add_f32_e32 v67, 1.0, v67
	v_rcp_f32_e32 v66, v66
	v_rcp_f32_e32 v67, v67
	s_nop 0
	v_pk_mul_f32 v[66:67], v[70:71], v[66:67]
	s_nop 0
	v_cvt_pk_bf16_f32 v66, v66, v67
	v_mul_f32_e32 v67, 0xbfb8aa3b, v72
	v_exp_f32_e32 v67, v67
	s_nop 0
	v_add_f32_e32 v67, 1.0, v67
	v_rcp_f32_e32 v70, v67
	v_mul_f32_e32 v67, 0xbfb8aa3b, v73
	v_exp_f32_e32 v67, v67
	s_nop 0
	v_add_f32_e32 v67, 1.0, v67
	v_rcp_f32_e32 v71, v67
	s_nop 0
	v_pk_mul_f32 v[70:71], v[72:73], v[70:71]
	s_nop 0
	v_cvt_pk_bf16_f32 v67, v70, v71
	v_mul_f32_e32 v70, 0xbfb8aa3b, v68
	v_mul_f32_e32 v71, 0xbfb8aa3b, v69
	v_exp_f32_e32 v70, v70
	v_exp_f32_e32 v71, v71
	v_add_f32_e32 v70, 1.0, v70
	v_add_f32_e32 v71, 1.0, v71
	v_rcp_f32_e32 v70, v70
	v_rcp_f32_e32 v71, v71
	s_nop 0
	v_pk_mul_f32 v[68:69], v[68:69], v[70:71]
	s_nop 0
	v_cvt_pk_bf16_f32 v68, v68, v69
	v_mul_f32_e32 v69, 0xbfb8aa3b, v76
	v_exp_f32_e32 v69, v69
	s_nop 0
	v_add_f32_e32 v69, 1.0, v69
	v_rcp_f32_e32 v70, v69
	v_mul_f32_e32 v69, 0xbfb8aa3b, v77
	v_exp_f32_e32 v69, v69
	s_nop 0
	v_add_f32_e32 v69, 1.0, v69
	v_rcp_f32_e32 v71, v69
	s_nop 0
	v_pk_mul_f32 v[70:71], v[76:77], v[70:71]
	s_nop 0
	v_cvt_pk_bf16_f32 v69, v70, v71
	v_add_co_u32_e32 v70, vcc, s6, v130
	v_lshl_add_u64 v[76:77], v[130:131], 0, s[10:11]
	s_nop 0
	v_addc_co_u32_e32 v71, vcc, 0, v131, vcc
	global_store_dwordx4 v[70:71], v[66:69], off
	global_load_dwordx4 v[70:73], v[150:151], off offset:512
	s_nop 0
	global_load_dwordx4 v[66:69], v[150:151], off offset:528
	s_andn2_b64 vcc, exec, s[20:21]
	s_waitcnt vmcnt(0) lgkmcnt(0)
	v_pk_add_f32 v[62:63], v[62:63], v[70:71]
	v_pk_add_f32 v[78:79], v[60:61], v[68:69]
	v_pk_add_f32 v[60:61], v[58:59], v[66:67]
	v_mul_f32_e32 v58, 0xbfb8aa3b, v62
	v_mul_f32_e32 v59, 0xbfb8aa3b, v63
	v_exp_f32_e32 v58, v58
	v_exp_f32_e32 v59, v59
	v_pk_add_f32 v[64:65], v[64:65], v[72:73]
	v_pk_add_f32 v[54:55], v[54:55], v[70:71]
	v_add_f32_e32 v58, 1.0, v58
	v_add_f32_e32 v59, 1.0, v59
	v_rcp_f32_e32 v58, v58
	v_rcp_f32_e32 v59, v59
	v_pk_add_f32 v[56:57], v[56:57], v[72:73]
	v_pk_add_f32 v[46:47], v[46:47], v[70:71]
	v_pk_add_f32 v[48:49], v[48:49], v[72:73]
	v_pk_mul_f32 v[58:59], v[62:63], v[58:59]
	v_pk_add_f32 v[38:39], v[38:39], v[70:71]
	v_cvt_pk_bf16_f32 v58, v58, v59
	v_mul_f32_e32 v59, 0xbfb8aa3b, v64
	v_exp_f32_e32 v59, v59
	v_pk_add_f32 v[40:41], v[40:41], v[72:73]
	v_pk_add_f32 v[30:31], v[30:31], v[70:71]
	v_pk_add_f32 v[32:33], v[32:33], v[72:73]
	v_add_f32_e32 v59, 1.0, v59
	v_rcp_f32_e32 v62, v59
	v_mul_f32_e32 v59, 0xbfb8aa3b, v65
	v_exp_f32_e32 v59, v59
	v_pk_add_f32 v[22:23], v[22:23], v[70:71]
	v_pk_add_f32 v[24:25], v[24:25], v[72:73]
	v_pk_add_f32 v[14:15], v[14:15], v[70:71]
	v_add_f32_e32 v59, 1.0, v59
	v_rcp_f32_e32 v63, v59
	v_pk_add_f32 v[16:17], v[16:17], v[72:73]
	v_pk_add_f32 v[6:7], v[6:7], v[70:71]
	v_pk_add_f32 v[8:9], v[8:9], v[72:73]
	v_pk_mul_f32 v[62:63], v[64:65], v[62:63]
	s_nop 0
	v_cvt_pk_bf16_f32 v59, v62, v63
	v_mul_f32_e32 v62, 0xbfb8aa3b, v60
	v_mul_f32_e32 v63, 0xbfb8aa3b, v61
	v_exp_f32_e32 v62, v62
	v_exp_f32_e32 v63, v63
	v_add_f32_e32 v62, 1.0, v62
	v_add_f32_e32 v63, 1.0, v63
	v_rcp_f32_e32 v62, v62
	v_rcp_f32_e32 v63, v63
	s_nop 0
	v_pk_mul_f32 v[60:61], v[60:61], v[62:63]
	s_nop 0
	v_cvt_pk_bf16_f32 v60, v60, v61
	v_mul_f32_e32 v61, 0xbfb8aa3b, v78
	v_exp_f32_e32 v61, v61
	s_nop 0
	v_add_f32_e32 v61, 1.0, v61
	v_rcp_f32_e32 v62, v61
	v_mul_f32_e32 v61, 0xbfb8aa3b, v79
	v_exp_f32_e32 v61, v61
	s_nop 0
	v_add_f32_e32 v61, 1.0, v61
	v_rcp_f32_e32 v63, v61
	s_nop 0
	v_pk_mul_f32 v[62:63], v[78:79], v[62:63]
	s_nop 0
	v_cvt_pk_bf16_f32 v61, v62, v63
	global_store_dwordx4 v[130:131], v[58:61], off offset:256
	s_nop 1
	v_pk_add_f32 v[58:59], v[52:53], v[68:69]
; __device__ __forceinline__ unsigned pk2(float lo, float hi) { f32x2_t v = {lo, hi}; bf16x2_t b = __builtin_convertvector(v, bf16x2_t); return __builtin_bit_cast(unsigned, b); }
; __device__ __forceinline__ float fsilu(float x) { return x * fsigmoid(x); }
;     __device__ __forceinline__ void operator()(const f32x4 (&acc)[2][2][4][2], const Unit& u, int wr, int wc, int fr, int fq) const {
;     ...
;         for (int bj = 0; bj < 2; ++bj) {
;             const f32x4 c0 = *(const f32x4*)(bb + bj * 128 + cl), c1 = *(const f32x4*)(bb + bj * 128 + cl + 4);
; #pragma unroll
;             for (int ai = 0; ai < 2; ++ai)
; #pragma unroll
;                 for (int m = 0; m < 4; ++m) {
;                     const f32x4 v0 = acc[ai][bj][m][0] + c0, v1 = acc[ai][bj][m][1] + c1;
;                     u32x4 w; w.x = pk2(fsilu(v0[0]), fsilu(v0[1])); w.y = pk2(fsilu(v0[2]), fsilu(v0[3])); w.z = pk2(fsilu(v1[0]), fsilu(v1[1])); w.w = pk2(fsilu(v1[2]), fsilu(v1[3]));
;                     *(u32x4*)(HID + (size_t)(row0 + ai * HALF + m * 16) * 256 + bj * 128 + cl) = w;
;                 }
	v_pk_add_f32 v[52:53], v[50:51], v[66:67]
	v_mul_f32_e32 v50, 0xbfb8aa3b, v54
	v_mul_f32_e32 v51, 0xbfb8aa3b, v55
	v_exp_f32_e32 v50, v50
	v_exp_f32_e32 v51, v51
	v_add_f32_e32 v50, 1.0, v50
	v_add_f32_e32 v51, 1.0, v51
	v_rcp_f32_e32 v50, v50
	v_rcp_f32_e32 v51, v51
	s_nop 0
	v_pk_mul_f32 v[50:51], v[54:55], v[50:51]
	s_nop 0
	v_cvt_pk_bf16_f32 v50, v50, v51
	v_mul_f32_e32 v51, 0xbfb8aa3b, v56
	v_exp_f32_e32 v51, v51
	s_nop 0
	v_add_f32_e32 v51, 1.0, v51
	v_rcp_f32_e32 v54, v51
	v_mul_f32_e32 v51, 0xbfb8aa3b, v57
	v_exp_f32_e32 v51, v51
	s_nop 0
	v_add_f32_e32 v51, 1.0, v51
	v_rcp_f32_e32 v55, v51
	s_nop 0
	v_pk_mul_f32 v[54:55], v[56:57], v[54:55]
	s_nop 0
	v_cvt_pk_bf16_f32 v51, v54, v55
	v_mul_f32_e32 v54, 0xbfb8aa3b, v52
	v_mul_f32_e32 v55, 0xbfb8aa3b, v53
	v_exp_f32_e32 v54, v54
	v_exp_f32_e32 v55, v55
	v_add_f32_e32 v54, 1.0, v54
	v_add_f32_e32 v55, 1.0, v55
	v_rcp_f32_e32 v54, v54
	v_rcp_f32_e32 v55, v55
	s_nop 0
	v_pk_mul_f32 v[52:53], v[52:53], v[54:55]
	s_nop 0
	v_cvt_pk_bf16_f32 v52, v52, v53
	v_mul_f32_e32 v53, 0xbfb8aa3b, v58
	v_exp_f32_e32 v53, v53
	s_nop 0
	v_add_f32_e32 v53, 1.0, v53
	v_rcp_f32_e32 v54, v53
	v_mul_f32_e32 v53, 0xbfb8aa3b, v59
	v_exp_f32_e32 v53, v53
	s_nop 0
	v_add_f32_e32 v53, 1.0, v53
	v_rcp_f32_e32 v55, v53
	s_nop 0
	v_pk_mul_f32 v[54:55], v[58:59], v[54:55]
	s_nop 0
	v_cvt_pk_bf16_f32 v53, v54, v55
	global_store_dwordx4 v[126:127], v[50:53], off offset:256
	s_nop 1
	v_pk_add_f32 v[50:51], v[44:45], v[68:69]
	v_pk_add_f32 v[44:45], v[42:43], v[66:67]
	v_mul_f32_e32 v42, 0xbfb8aa3b, v46
	v_mul_f32_e32 v43, 0xbfb8aa3b, v47
	v_exp_f32_e32 v42, v42
	v_exp_f32_e32 v43, v43
	v_add_f32_e32 v42, 1.0, v42
	v_add_f32_e32 v43, 1.0, v43
	v_rcp_f32_e32 v42, v42
	v_rcp_f32_e32 v43, v43
	s_nop 0
	v_pk_mul_f32 v[42:43], v[46:47], v[42:43]
	s_nop 0
	v_cvt_pk_bf16_f32 v42, v42, v43
	v_mul_f32_e32 v43, 0xbfb8aa3b, v48
	v_exp_f32_e32 v43, v43
	s_nop 0
	v_add_f32_e32 v43, 1.0, v43
	v_rcp_f32_e32 v46, v43
	v_mul_f32_e32 v43, 0xbfb8aa3b, v49
	v_exp_f32_e32 v43, v43
	s_nop 0
	v_add_f32_e32 v43, 1.0, v43
	v_rcp_f32_e32 v47, v43
	s_nop 0
	v_pk_mul_f32 v[46:47], v[48:49], v[46:47]
	s_nop 0
	v_cvt_pk_bf16_f32 v43, v46, v47
	v_mul_f32_e32 v46, 0xbfb8aa3b, v44
	v_mul_f32_e32 v47, 0xbfb8aa3b, v45
	v_exp_f32_e32 v46, v46
	v_exp_f32_e32 v47, v47
	v_add_f32_e32 v46, 1.0, v46
	v_add_f32_e32 v47, 1.0, v47
	v_rcp_f32_e32 v46, v46
	v_rcp_f32_e32 v47, v47
	s_nop 0
	v_pk_mul_f32 v[44:45], v[44:45], v[46:47]
	s_nop 0
	v_cvt_pk_bf16_f32 v44, v44, v45
	v_mul_f32_e32 v45, 0xbfb8aa3b, v50
	v_exp_f32_e32 v45, v45
	s_nop 0
	v_add_f32_e32 v45, 1.0, v45
	v_rcp_f32_e32 v46, v45
	v_mul_f32_e32 v45, 0xbfb8aa3b, v51
	v_exp_f32_e32 v45, v45
	s_nop 0
	v_add_f32_e32 v45, 1.0, v45
	v_rcp_f32_e32 v47, v45
	s_nop 0
	v_pk_mul_f32 v[46:47], v[50:51], v[46:47]
	s_nop 0
	v_cvt_pk_bf16_f32 v45, v46, v47
	global_store_dwordx4 v[114:115], v[42:45], off offset:256
	s_nop 1
	v_pk_add_f32 v[42:43], v[36:37], v[68:69]
	v_pk_add_f32 v[36:37], v[34:35], v[66:67]
	v_mul_f32_e32 v34, 0xbfb8aa3b, v38
	v_mul_f32_e32 v35, 0xbfb8aa3b, v39
	v_exp_f32_e32 v34, v34
	v_exp_f32_e32 v35, v35
	v_add_f32_e32 v34, 1.0, v34
	v_add_f32_e32 v35, 1.0, v35
	v_rcp_f32_e32 v34, v34
	v_rcp_f32_e32 v35, v35
	s_nop 0
	v_pk_mul_f32 v[34:35], v[38:39], v[34:35]
	s_nop 0
	v_cvt_pk_bf16_f32 v34, v34, v35
	v_mul_f32_e32 v35, 0xbfb8aa3b, v40
	v_exp_f32_e32 v35, v35
	s_nop 0
	v_add_f32_e32 v35, 1.0, v35
	v_rcp_f32_e32 v38, v35
	v_mul_f32_e32 v35, 0xbfb8aa3b, v41
	v_exp_f32_e32 v35, v35
	s_nop 0
	v_add_f32_e32 v35, 1.0, v35
	v_rcp_f32_e32 v39, v35
	s_nop 0
	v_pk_mul_f32 v[38:39], v[40:41], v[38:39]
	s_nop 0
	v_cvt_pk_bf16_f32 v35, v38, v39
	v_mul_f32_e32 v38, 0xbfb8aa3b, v36
	v_mul_f32_e32 v39, 0xbfb8aa3b, v37
	v_exp_f32_e32 v38, v38
	v_exp_f32_e32 v39, v39
	v_add_f32_e32 v38, 1.0, v38
	v_add_f32_e32 v39, 1.0, v39
	v_rcp_f32_e32 v38, v38
	v_rcp_f32_e32 v39, v39
	s_nop 0
	v_pk_mul_f32 v[36:37], v[36:37], v[38:39]
	s_nop 0
	v_cvt_pk_bf16_f32 v36, v36, v37
	v_mul_f32_e32 v37, 0xbfb8aa3b, v42
	v_exp_f32_e32 v37, v37
	s_nop 0
	v_add_f32_e32 v37, 1.0, v37
	v_rcp_f32_e32 v38, v37
	v_mul_f32_e32 v37, 0xbfb8aa3b, v43
	v_exp_f32_e32 v37, v37
	s_nop 0
	v_add_f32_e32 v37, 1.0, v37
	v_rcp_f32_e32 v39, v37
	s_nop 0
	v_pk_mul_f32 v[38:39], v[42:43], v[38:39]
	s_nop 0
	v_cvt_pk_bf16_f32 v37, v38, v39
	global_store_dwordx4 v[106:107], v[34:37], off offset:256
	s_nop 1
	v_pk_add_f32 v[34:35], v[28:29], v[68:69]
	v_pk_add_f32 v[28:29], v[26:27], v[66:67]
	v_mul_f32_e32 v26, 0xbfb8aa3b, v30
	v_mul_f32_e32 v27, 0xbfb8aa3b, v31
	v_exp_f32_e32 v26, v26
	v_exp_f32_e32 v27, v27
	v_add_f32_e32 v26, 1.0, v26
	v_add_f32_e32 v27, 1.0, v27
	v_rcp_f32_e32 v26, v26
	v_rcp_f32_e32 v27, v27
	s_nop 0
	v_pk_mul_f32 v[26:27], v[30:31], v[26:27]
	s_nop 0
	v_cvt_pk_bf16_f32 v26, v26, v27
	v_mul_f32_e32 v27, 0xbfb8aa3b, v32
	v_exp_f32_e32 v27, v27
	s_nop 0
	v_add_f32_e32 v27, 1.0, v27
	v_rcp_f32_e32 v30, v27
	v_mul_f32_e32 v27, 0xbfb8aa3b, v33
	v_exp_f32_e32 v27, v27
	s_nop 0
	v_add_f32_e32 v27, 1.0, v27
	v_rcp_f32_e32 v31, v27
	s_nop 0
	v_pk_mul_f32 v[30:31], v[32:33], v[30:31]
	s_nop 0
	v_cvt_pk_bf16_f32 v27, v30, v31
; __device__ __forceinline__ unsigned pk2(float lo, float hi) { f32x2_t v = {lo, hi}; bf16x2_t b = __builtin_convertvector(v, bf16x2_t); return __builtin_bit_cast(unsigned, b); }
; __device__ __forceinline__ float fsilu(float x) { return x * fsigmoid(x); }
;     __device__ __forceinline__ void operator()(const f32x4 (&acc)[2][2][4][2], const Unit& u, int wr, int wc, int fr, int fq) const {
;     ...
;         for (int bj = 0; bj < 2; ++bj) {
;             const f32x4 c0 = *(const f32x4*)(bb + bj * 128 + cl), c1 = *(const f32x4*)(bb + bj * 128 + cl + 4);
; #pragma unroll
;             for (int ai = 0; ai < 2; ++ai)
; #pragma unroll
;                 for (int m = 0; m < 4; ++m) {
;                     const f32x4 v0 = acc[ai][bj][m][0] + c0, v1 = acc[ai][bj][m][1] + c1;
;                     u32x4 w; w.x = pk2(fsilu(v0[0]), fsilu(v0[1])); w.y = pk2(fsilu(v0[2]), fsilu(v0[3])); w.z = pk2(fsilu(v1[0]), fsilu(v1[1])); w.w = pk2(fsilu(v1[2]), fsilu(v1[3]));
;                     *(u32x4*)(HID + (size_t)(row0 + ai * HALF + m * 16) * 256 + bj * 128 + cl) = w;
;                 }
;         }
;     }
	v_mul_f32_e32 v30, 0xbfb8aa3b, v28
	v_mul_f32_e32 v31, 0xbfb8aa3b, v29
	v_exp_f32_e32 v30, v30
	v_exp_f32_e32 v31, v31
	v_add_f32_e32 v30, 1.0, v30
	v_add_f32_e32 v31, 1.0, v31
	v_rcp_f32_e32 v30, v30
	v_rcp_f32_e32 v31, v31
	s_nop 0
	v_pk_mul_f32 v[28:29], v[28:29], v[30:31]
	s_nop 0
	v_cvt_pk_bf16_f32 v28, v28, v29
	v_mul_f32_e32 v29, 0xbfb8aa3b, v34
	v_exp_f32_e32 v29, v29
	s_nop 0
	v_add_f32_e32 v29, 1.0, v29
	v_rcp_f32_e32 v30, v29
	v_mul_f32_e32 v29, 0xbfb8aa3b, v35
	v_exp_f32_e32 v29, v29
	s_nop 0
	v_add_f32_e32 v29, 1.0, v29
	v_rcp_f32_e32 v31, v29
	s_nop 0
	v_pk_mul_f32 v[30:31], v[34:35], v[30:31]
	s_nop 0
	v_cvt_pk_bf16_f32 v29, v30, v31
	global_store_dwordx4 v[90:91], v[26:29], off offset:256
	s_nop 1
	v_pk_add_f32 v[26:27], v[20:21], v[68:69]
	v_pk_add_f32 v[20:21], v[18:19], v[66:67]
	v_mul_f32_e32 v18, 0xbfb8aa3b, v22
	v_mul_f32_e32 v19, 0xbfb8aa3b, v23
	v_exp_f32_e32 v18, v18
	v_exp_f32_e32 v19, v19
	v_add_f32_e32 v18, 1.0, v18
	v_add_f32_e32 v19, 1.0, v19
	v_rcp_f32_e32 v18, v18
	v_rcp_f32_e32 v19, v19
	s_nop 0
	v_pk_mul_f32 v[18:19], v[22:23], v[18:19]
	s_nop 0
	v_cvt_pk_bf16_f32 v18, v18, v19
	v_mul_f32_e32 v19, 0xbfb8aa3b, v24
	v_exp_f32_e32 v19, v19
	s_nop 0
	v_add_f32_e32 v19, 1.0, v19
	v_rcp_f32_e32 v22, v19
	v_mul_f32_e32 v19, 0xbfb8aa3b, v25
	v_exp_f32_e32 v19, v19
	s_nop 0
	v_add_f32_e32 v19, 1.0, v19
	v_rcp_f32_e32 v23, v19
	s_nop 0
	v_pk_mul_f32 v[22:23], v[24:25], v[22:23]
	s_nop 0
	v_cvt_pk_bf16_f32 v19, v22, v23
	v_mul_f32_e32 v22, 0xbfb8aa3b, v20
	v_mul_f32_e32 v23, 0xbfb8aa3b, v21
	v_exp_f32_e32 v22, v22
	v_exp_f32_e32 v23, v23
	v_add_f32_e32 v22, 1.0, v22
	v_add_f32_e32 v23, 1.0, v23
	v_rcp_f32_e32 v22, v22
	v_rcp_f32_e32 v23, v23
	s_nop 0
	v_pk_mul_f32 v[20:21], v[20:21], v[22:23]
	s_nop 0
	v_cvt_pk_bf16_f32 v20, v20, v21
	v_mul_f32_e32 v21, 0xbfb8aa3b, v26
	v_exp_f32_e32 v21, v21
	s_nop 0
	v_add_f32_e32 v21, 1.0, v21
	v_rcp_f32_e32 v22, v21
	v_mul_f32_e32 v21, 0xbfb8aa3b, v27
	v_exp_f32_e32 v21, v21
	s_nop 0
	v_add_f32_e32 v21, 1.0, v21
	v_rcp_f32_e32 v23, v21
	s_nop 0
	v_pk_mul_f32 v[22:23], v[26:27], v[22:23]
	s_nop 0
	v_cvt_pk_bf16_f32 v21, v22, v23
	global_store_dwordx4 v[82:83], v[18:21], off offset:256
	s_nop 1
	v_pk_add_f32 v[18:19], v[12:13], v[68:69]
	v_pk_add_f32 v[12:13], v[10:11], v[66:67]
	v_mul_f32_e32 v10, 0xbfb8aa3b, v14
	v_mul_f32_e32 v11, 0xbfb8aa3b, v15
	v_exp_f32_e32 v10, v10
	v_exp_f32_e32 v11, v11
	v_add_f32_e32 v10, 1.0, v10
	v_add_f32_e32 v11, 1.0, v11
	v_rcp_f32_e32 v10, v10
	v_rcp_f32_e32 v11, v11
	s_nop 0
	v_pk_mul_f32 v[10:11], v[14:15], v[10:11]
	s_nop 0
	v_cvt_pk_bf16_f32 v10, v10, v11
	v_mul_f32_e32 v11, 0xbfb8aa3b, v16
	v_exp_f32_e32 v11, v11
	s_nop 0
	v_add_f32_e32 v11, 1.0, v11
	v_rcp_f32_e32 v14, v11
	v_mul_f32_e32 v11, 0xbfb8aa3b, v17
	v_exp_f32_e32 v11, v11
	s_nop 0
	v_add_f32_e32 v11, 1.0, v11
	v_rcp_f32_e32 v15, v11
	s_nop 0
	v_pk_mul_f32 v[14:15], v[16:17], v[14:15]
	s_nop 0
	v_cvt_pk_bf16_f32 v11, v14, v15
	v_mul_f32_e32 v14, 0xbfb8aa3b, v12
	v_mul_f32_e32 v15, 0xbfb8aa3b, v13
	v_exp_f32_e32 v14, v14
	v_exp_f32_e32 v15, v15
	v_add_f32_e32 v14, 1.0, v14
	v_add_f32_e32 v15, 1.0, v15
	v_rcp_f32_e32 v14, v14
	v_rcp_f32_e32 v15, v15
	s_nop 0
	v_pk_mul_f32 v[12:13], v[12:13], v[14:15]
	s_nop 0
	v_cvt_pk_bf16_f32 v12, v12, v13
	v_mul_f32_e32 v13, 0xbfb8aa3b, v18
	v_exp_f32_e32 v13, v13
	s_nop 0
	v_add_f32_e32 v13, 1.0, v13
	v_rcp_f32_e32 v14, v13
	v_mul_f32_e32 v13, 0xbfb8aa3b, v19
	v_exp_f32_e32 v13, v13
	s_nop 0
	v_add_f32_e32 v13, 1.0, v13
	v_rcp_f32_e32 v15, v13
	s_nop 0
	v_pk_mul_f32 v[14:15], v[18:19], v[14:15]
	s_nop 0
	v_cvt_pk_bf16_f32 v13, v14, v15
	global_store_dwordx4 v[74:75], v[10:13], off offset:256
	s_nop 1
	v_pk_add_f32 v[10:11], v[4:5], v[68:69]
	v_pk_add_f32 v[4:5], v[2:3], v[66:67]
	v_mul_f32_e32 v2, 0xbfb8aa3b, v6
	v_mul_f32_e32 v3, 0xbfb8aa3b, v7
	v_exp_f32_e32 v2, v2
	v_exp_f32_e32 v3, v3
	v_add_f32_e32 v2, 1.0, v2
	v_add_f32_e32 v3, 1.0, v3
	v_rcp_f32_e32 v2, v2
	v_rcp_f32_e32 v3, v3
	s_nop 0
	v_pk_mul_f32 v[2:3], v[6:7], v[2:3]
	s_nop 0
	v_cvt_pk_bf16_f32 v2, v2, v3
	v_mul_f32_e32 v3, 0xbfb8aa3b, v8
	v_exp_f32_e32 v3, v3
	s_nop 0
	v_add_f32_e32 v3, 1.0, v3
	v_rcp_f32_e32 v6, v3
	v_mul_f32_e32 v3, 0xbfb8aa3b, v9
	v_exp_f32_e32 v3, v3
	s_nop 0
	v_add_f32_e32 v3, 1.0, v3
	v_rcp_f32_e32 v7, v3
	s_nop 0
	v_pk_mul_f32 v[6:7], v[8:9], v[6:7]
	s_nop 0
	v_cvt_pk_bf16_f32 v3, v6, v7
	v_mul_f32_e32 v6, 0xbfb8aa3b, v4
	v_mul_f32_e32 v7, 0xbfb8aa3b, v5
	v_exp_f32_e32 v6, v6
	v_exp_f32_e32 v7, v7
	v_add_f32_e32 v6, 1.0, v6
	v_add_f32_e32 v7, 1.0, v7
	v_rcp_f32_e32 v6, v6
	v_rcp_f32_e32 v7, v7
	s_nop 0
	v_pk_mul_f32 v[4:5], v[4:5], v[6:7]
	s_nop 0
	v_cvt_pk_bf16_f32 v4, v4, v5
	v_mul_f32_e32 v5, 0xbfb8aa3b, v10
	v_exp_f32_e32 v5, v5
	s_nop 0
	v_add_f32_e32 v5, 1.0, v5
	v_rcp_f32_e32 v6, v5
	v_mul_f32_e32 v5, 0xbfb8aa3b, v11
	v_exp_f32_e32 v5, v5
	s_nop 0
	v_add_f32_e32 v5, 1.0, v5
	v_rcp_f32_e32 v7, v5
	s_nop 0
	v_pk_mul_f32 v[6:7], v[10:11], v[6:7]
	s_nop 0
	v_cvt_pk_bf16_f32 v5, v6, v7
	global_store_dwordx4 v[76:77], v[2:5], off offset:256
	s_cbranch_vccnz .LBB0_297
	s_andn2_b64 vcc, exec, s[16:17]
	s_cbranch_vccnz .LBB0_296
	s_barrier
	s_branch .LBB0_296

; __device__ __forceinline__ unsigned pk2(float lo, float hi) { f32x2_t v = {lo, hi}; bf16x2_t b = __builtin_convertvector(v, bf16x2_t); return __builtin_bit_cast(unsigned, b); }
;     __device__ __forceinline__ void operator()(const f32x4 (&acc)[2][2][4][2], const Unit& u, int wr, int wc, int fr, int fq) const {
;         if (wc >= 2) return;
;         bf16_t* dst = u.pn ? VC : KC;
;         const int slab = u.pm & 15, b = slab >> 1, gg = slab & 1;
; #pragma unroll
;         for (int ai = 0; ai < 2; ++ai)
; #pragma unroll
;             for (int m = 0; m < 4; ++m) {
;                 const int nrow = ai * HALF + wr * 64 + m * 16 + fr;
; #pragma unroll
;                 for (int n = 0; n < 2; ++n) {
;                     f32x4 v = acc[ai][0][m][n]; if (nrow == 255) v = (f32x4){0.f, 0.f, 0.f, 0.f};
;                     u32x2 w; w.x = pk2(v[0], v[1]); w.y = pk2(v[2], v[3]);
;                     *(u32x2*)(dst + (size_t)(b * 256 + nrow) * 128 + gg * 64 + wc * 32 + 16 * n + 4 * fq) = w;
;                 }
;             }
;     }
.LBB0_312:
	v_mov_b32_e32 v73, v1
	v_mov_b32_e32 v72, v156
	s_andn2_b64 vcc, exec, s[20:21]
	s_cbranch_vccnz .LBB0_314
	s_cmp_eq_u32 s12, 0
	s_mov_b32 s6, 0x1a200000
	s_cselect_b32 s6, s6, 0x1a280000
	s_add_u32 s6, s86, s6
	s_addc_u32 s7, s87, 0
	s_lshl_b32 s10, s93, 7
	s_and_b32 s12, s10, 0x700
	s_and_b32 s10, s10, 0x80
	s_add_u32 s6, s6, s10
	v_add_u32_e32 v76, s82, v73
	s_addc_u32 s7, s7, 0
	s_add_u32 s10, s6, s91
	v_lshlrev_b32_e32 v72, 2, v72
	v_add_u32_e32 v74, s12, v76
	s_movk_i32 s6, 0xff
	s_addc_u32 s11, s7, 0
	v_ashrrev_i32_e32 v73, 31, v72
	v_ashrrev_i32_e32 v75, 31, v74
	v_cmp_eq_u32_e32 vcc, s6, v76
	v_lshl_add_u64 v[72:73], v[72:73], 1, s[10:11]
	v_lshlrev_b64 v[74:75], 8, v[74:75]
	v_cndmask_b32_e64 v61, v61, 0, vcc
	v_cndmask_b32_e64 v60, v60, 0, vcc
	v_cndmask_b32_e64 v59, v59, 0, vcc
	v_cndmask_b32_e64 v58, v58, 0, vcc
	v_lshl_add_u64 v[74:75], v[72:73], 0, v[74:75]
	v_cvt_pk_bf16_f32 v58, v58, v59
	v_cvt_pk_bf16_f32 v59, v60, v61
	v_add_u32_e32 v60, 16, v76
	global_store_dwordx2 v[74:75], v[58:59], off offset:32
	v_add_u32_e32 v58, s12, v60
	v_cndmask_b32_e64 v65, v65, 0, vcc
	v_cndmask_b32_e64 v64, v64, 0, vcc
	v_cndmask_b32_e64 v63, v63, 0, vcc
	v_cndmask_b32_e64 v62, v62, 0, vcc
	v_ashrrev_i32_e32 v59, 31, v58
	v_cmp_eq_u32_e32 vcc, s6, v60
	v_lshlrev_b64 v[58:59], 8, v[58:59]
	v_lshl_add_u64 v[58:59], v[72:73], 0, v[58:59]
	v_cndmask_b32_e64 v53, v53, 0, vcc
	v_cndmask_b32_e64 v52, v52, 0, vcc
	v_cndmask_b32_e64 v51, v51, 0, vcc
	v_cndmask_b32_e64 v50, v50, 0, vcc
	v_cvt_pk_bf16_f32 v50, v50, v51
	v_cvt_pk_bf16_f32 v51, v52, v53
	v_add_u32_e32 v52, 32, v76
	global_store_dwordx2 v[58:59], v[50:51], off offset:32
	v_add_u32_e32 v50, s12, v52
	v_cndmask_b32_e64 v57, v57, 0, vcc
	v_cndmask_b32_e64 v56, v56, 0, vcc
	v_cndmask_b32_e64 v55, v55, 0, vcc
	v_cndmask_b32_e64 v54, v54, 0, vcc
	v_ashrrev_i32_e32 v51, 31, v50
	v_cmp_eq_u32_e32 vcc, s6, v52
	v_lshlrev_b64 v[50:51], 8, v[50:51]
	v_lshl_add_u64 v[50:51], v[72:73], 0, v[50:51]
	v_cndmask_b32_e64 v41, v41, 0, vcc
	v_cndmask_b32_e64 v40, v40, 0, vcc
	v_cndmask_b32_e64 v39, v39, 0, vcc
	v_cndmask_b32_e64 v38, v38, 0, vcc
	v_cvt_pk_bf16_f32 v38, v38, v39
	v_cvt_pk_bf16_f32 v39, v40, v41
	v_add_u32_e32 v40, 48, v76
	global_store_dwordx2 v[50:51], v[38:39], off offset:32
	v_add_u32_e32 v38, s12, v40
	v_cndmask_b32_e64 v49, v49, 0, vcc
	v_cndmask_b32_e64 v48, v48, 0, vcc
	v_cndmask_b32_e64 v47, v47, 0, vcc
	v_cndmask_b32_e64 v46, v46, 0, vcc
	v_ashrrev_i32_e32 v39, 31, v38
	v_cmp_eq_u32_e32 vcc, s6, v40
	v_lshlrev_b64 v[38:39], 8, v[38:39]
	v_lshl_add_u64 v[38:39], v[72:73], 0, v[38:39]
	v_cndmask_b32_e64 v25, v25, 0, vcc
	v_cndmask_b32_e64 v24, v24, 0, vcc
	v_cndmask_b32_e64 v23, v23, 0, vcc
	v_cndmask_b32_e64 v22, v22, 0, vcc
	v_cvt_pk_bf16_f32 v22, v22, v23
	v_cvt_pk_bf16_f32 v23, v24, v25
	v_add_u32_e32 v24, 0x80, v76
	v_cndmask_b32_e64 v33, v33, 0, vcc
	v_cndmask_b32_e64 v32, v32, 0, vcc
	v_cndmask_b32_e64 v31, v31, 0, vcc
	v_cndmask_b32_e64 v30, v30, 0, vcc
	global_store_dwordx2 v[38:39], v[22:23], off offset:32
	v_add_u32_e32 v22, s12, v24
	v_cvt_pk_bf16_f32 v30, v30, v31
	v_cvt_pk_bf16_f32 v31, v32, v33
	v_ashrrev_i32_e32 v23, 31, v22
	v_cmp_eq_u32_e32 vcc, s6, v24
	global_store_dwordx2 v[38:39], v[30:31], off
	v_lshlrev_b64 v[22:23], 8, v[22:23]
	v_cndmask_b32_e64 v25, v45, 0, vcc
	v_cndmask_b32_e64 v30, v44, 0, vcc
	v_cndmask_b32_e64 v24, v43, 0, vcc
	v_cndmask_b32_e64 v31, v42, 0, vcc
	v_lshl_add_u64 v[22:23], v[72:73], 0, v[22:23]
	v_cvt_pk_bf16_f32 v24, v31, v24
	v_cvt_pk_bf16_f32 v25, v30, v25
	global_store_dwordx2 v[22:23], v[24:25], off
	v_cndmask_b32_e64 v25, v37, 0, vcc
	v_cndmask_b32_e64 v30, v36, 0, vcc
	v_cndmask_b32_e64 v24, v35, 0, vcc
	v_cndmask_b32_e64 v31, v34, 0, vcc
	v_cvt_pk_bf16_f32 v24, v31, v24
	v_cvt_pk_bf16_f32 v25, v30, v25
	global_store_dwordx2 v[22:23], v[24:25], off offset:32
	v_add_u32_e32 v24, 0x90, v76
	v_add_u32_e32 v22, s12, v24
	v_ashrrev_i32_e32 v23, 31, v22
	v_cmp_eq_u32_e32 vcc, s6, v24
	v_lshlrev_b64 v[22:23], 8, v[22:23]
	v_lshl_add_u64 v[22:23], v[72:73], 0, v[22:23]
	v_cndmask_b32_e64 v21, v21, 0, vcc
	v_cndmask_b32_e64 v20, v20, 0, vcc
	v_cndmask_b32_e64 v19, v19, 0, vcc
	v_cndmask_b32_e64 v18, v18, 0, vcc
	v_cvt_pk_bf16_f32 v18, v18, v19
	v_cvt_pk_bf16_f32 v19, v20, v21
	v_add_u32_e32 v20, 0xa0, v76
	global_store_dwordx2 v[22:23], v[18:19], off offset:32
	v_add_u32_e32 v18, s12, v20
	v_cndmask_b32_e64 v25, v29, 0, vcc
	v_cndmask_b32_e64 v28, v28, 0, vcc
	v_cndmask_b32_e64 v24, v27, 0, vcc
	v_cndmask_b32_e64 v26, v26, 0, vcc
	v_ashrrev_i32_e32 v19, 31, v18
	v_cmp_eq_u32_e32 vcc, s6, v20
	v_lshlrev_b64 v[18:19], 8, v[18:19]
	v_lshl_add_u64 v[18:19], v[72:73], 0, v[18:19]
	v_cndmask_b32_e64 v13, v13, 0, vcc
	v_cndmask_b32_e64 v12, v12, 0, vcc
	v_cndmask_b32_e64 v11, v11, 0, vcc
	v_cndmask_b32_e64 v10, v10, 0, vcc
	v_cvt_pk_bf16_f32 v10, v10, v11
	v_cvt_pk_bf16_f32 v11, v12, v13
	v_add_u32_e32 v12, 0xb0, v76
	global_store_dwordx2 v[18:19], v[10:11], off offset:32
	v_add_u32_e32 v10, s12, v12
	v_cndmask_b32_e64 v17, v17, 0, vcc
	v_cndmask_b32_e64 v16, v16, 0, vcc
	v_cndmask_b32_e64 v15, v15, 0, vcc
	v_cndmask_b32_e64 v14, v14, 0, vcc
	v_ashrrev_i32_e32 v11, 31, v10
	v_cmp_eq_u32_e32 vcc, s6, v12
	v_lshlrev_b64 v[10:11], 8, v[10:11]
	v_cvt_pk_bf16_f32 v62, v62, v63
	v_cndmask_b32_e64 v9, v9, 0, vcc
	v_cndmask_b32_e64 v8, v8, 0, vcc
	v_cndmask_b32_e64 v7, v7, 0, vcc
	v_cndmask_b32_e64 v6, v6, 0, vcc
	v_cndmask_b32_e64 v5, v5, 0, vcc
	v_cndmask_b32_e64 v4, v4, 0, vcc
	v_cndmask_b32_e64 v3, v3, 0, vcc
	v_cndmask_b32_e64 v2, v2, 0, vcc
	v_cvt_pk_bf16_f32 v63, v64, v65
	v_cvt_pk_bf16_f32 v54, v54, v55
	v_cvt_pk_bf16_f32 v55, v56, v57
	v_cvt_pk_bf16_f32 v46, v46, v47
	v_cvt_pk_bf16_f32 v47, v48, v49
	v_cvt_pk_bf16_f32 v24, v26, v24
	v_cvt_pk_bf16_f32 v25, v28, v25
	v_cvt_pk_bf16_f32 v14, v14, v15
	v_cvt_pk_bf16_f32 v15, v16, v17
	v_lshl_add_u64 v[10:11], v[72:73], 0, v[10:11]
	v_cvt_pk_bf16_f32 v6, v6, v7
	v_cvt_pk_bf16_f32 v7, v8, v9
	v_cvt_pk_bf16_f32 v2, v2, v3
	v_cvt_pk_bf16_f32 v3, v4, v5
	global_store_dwordx2 v[74:75], v[62:63], off
	global_store_dwordx2 v[58:59], v[54:55], off
	global_store_dwordx2 v[50:51], v[46:47], off
	global_store_dwordx2 v[22:23], v[24:25], off
	global_store_dwordx2 v[18:19], v[14:15], off
	global_store_dwordx2 v[10:11], v[6:7], off
	global_store_dwordx2 v[10:11], v[2:3], off offset:32
	s_andn2_b64 vcc, exec, s[22:23]
	s_mov_b64 s[12:13], -1
	s_cbranch_vccnz .LBB0_309
	s_branch .LBB0_315

; #define LAS __attribute__((address_space(3)))
; __device__ __forceinline__ float row_rscale(const float* SSP, int row) {
;     const f32x4 p = *(const f32x4*)(SSP + (size_t)row * 4);
;     return rsqrtf(((p[0] + p[1]) + (p[2] + p[3])) * (1.f / 1024.f) + 1e-6f);
; }
; __device__ __forceinline__ void row_scales8(const float* SSP, int row0, int key, LAS float* rsc  , LAS int* rtag  , int wv, int fr, int fq, float (&rsv)[2][4]) {
;     const int tag = __builtin_amdgcn_readfirstlane(rtag[wv]);
;     LAS float* tab = rsc + (wv * 16 + fr) * 8;
;     if (tag == key) {
;         const f32x4 a = *(const LAS f32x4*)tab, b = *(const LAS f32x4*)(tab + 4);
; #pragma unroll
;         for (int m = 0; m < 4; ++m) { rsv[0][m] = a[m]; rsv[1][m] = b[m]; }
;     } else {
; #pragma unroll
;         for (int ai = 0; ai < 2; ++ai)
; #pragma unroll
;             for (int m = 0; m < 4; ++m) rsv[ai][m] = row_rscale(SSP, row0 + ai * HALF + m * 16);
;         if (fq == 0) { *(LAS f32x4*)tab = (f32x4){rsv[0][0], rsv[0][1], rsv[0][2], rsv[0][3]}; *(LAS f32x4*)(tab + 4) = (f32x4){rsv[1][0], rsv[1][1], rsv[1][2], rsv[1][3]}; if (fr == 0) rtag[wv] = key; }
;     }
.LBB0_335:
	v_mov_b32_e32 v159, v1
	v_mov_b32_e32 v154, v156
	v_mov_b32_e32 v130, s90
	ds_read_b32 v130, v130
	s_lshl_b32 s7, s6, 8
	s_add_i32 s7, s7, s84
	s_add_i32 s44, s69, s6
	v_add_u32_e32 v150, s7, v159
	s_waitcnt lgkmcnt(0)
	v_readfirstlane_b32 s6, v130
	v_lshlrev_b32_e32 v155, 5, v159
	s_cmp_eq_u32 s6, s44
	s_mov_b64 s[6:7], -1
	s_cbranch_scc1 .LBB0_340
	v_ashrrev_i32_e32 v151, 31, v150
	v_lshl_add_u64 v[152:153], v[150:151], 4, s[16:17]
	global_load_dwordx4 v[130:133], v[152:153], off
	global_load_dwordx4 v[134:137], v[152:153], off offset:256
	s_mov_b32 s6, 0x358637bd
	s_waitcnt vmcnt(0) lgkmcnt(0)
	v_mov_b32_e32 v160, v130
	v_mov_b32_e32 v161, v134
	v_mov_b32_e32 v134, v131
	v_pk_add_f32 v[130:131], v[160:161], v[134:135]
	global_load_dwordx4 v[160:163], v[152:153], off offset:512
	v_mov_b32_e32 v134, v132
	v_mov_b32_e32 v135, v136
	v_mov_b32_e32 v136, v133
	v_pk_add_f32 v[132:133], v[134:135], v[136:137]
	s_waitcnt vmcnt(0) lgkmcnt(0)
	v_add_f32_e32 v136, v162, v163
	v_pk_add_f32 v[130:131], v[130:131], v[132:133]
	v_mov_b64_e32 v[132:133], s[6:7]
	v_pk_fma_f32 v[130:131], v[130:131], s[72:73], v[132:133] op_sel_hi:[1,0,0]
	s_nop 0
	v_mul_f32_e32 v134, 0x4b800000, v130
	v_cmp_gt_f32_e64 s[6:7], s67, v130
	v_cmp_gt_f32_e32 vcc, s67, v131
	s_nop 0
	v_cndmask_b32_e64 v130, v130, v134, s[6:7]
	v_mul_f32_e32 v134, 0x4b800000, v131
	v_cndmask_b32_e32 v131, v131, v134, vcc
	v_rsq_f32_e32 v130, v130
	v_rsq_f32_e32 v131, v131
	s_nop 0
	v_pk_mul_f32 v[134:135], v[130:131], s[76:77] op_sel_hi:[1,0]
	s_nop 0
	v_cndmask_b32_e64 v134, v130, v134, s[6:7]
	v_add_f32_e32 v130, v160, v161
	global_load_dwordx4 v[160:163], v[152:153], off offset:768
	v_cndmask_b32_e32 v135, v131, v135, vcc
	s_waitcnt vmcnt(0) lgkmcnt(0)
	v_mov_b32_e32 v164, v161
	v_mov_b32_e32 v165, v162
	v_mov_b32_e32 v161, v163
	v_pk_add_f32 v[160:161], v[164:165], v[160:161]
	s_nop 0
	v_mov_b32_e32 v131, v160
	v_mov_b32_e32 v137, v161
	global_load_dwordx4 v[160:163], v[152:153], off offset:2048
	global_load_dwordx4 v[164:167], v[152:153], off offset:2304
	v_pk_add_f32 v[130:131], v[130:131], v[136:137]
	s_nop 0
	v_pk_fma_f32 v[130:131], v[130:131], s[72:73], v[132:133] op_sel_hi:[1,0,0]
	s_nop 0
	v_mul_f32_e32 v136, 0x4b800000, v130
	v_cmp_gt_f32_e64 s[6:7], s67, v130
	v_cmp_gt_f32_e32 vcc, s67, v131
	s_nop 0
	v_cndmask_b32_e64 v130, v130, v136, s[6:7]
	v_mul_f32_e32 v136, 0x4b800000, v131
	v_cndmask_b32_e32 v131, v131, v136, vcc
	v_rsq_f32_e32 v130, v130
	v_rsq_f32_e32 v131, v131
	s_nop 0
	v_pk_mul_f32 v[136:137], v[130:131], s[76:77] op_sel_hi:[1,0]
	s_nop 0
	v_cndmask_b32_e32 v137, v131, v137, vcc
	v_cndmask_b32_e64 v136, v130, v136, s[6:7]
	s_waitcnt vmcnt(0) lgkmcnt(0)
	v_mov_b32_e32 v130, v160
	v_mov_b32_e32 v131, v164
	v_mov_b32_e32 v164, v161
	v_mov_b32_e32 v160, v162
	v_mov_b32_e32 v161, v166
	v_mov_b32_e32 v166, v163
	v_pk_add_f32 v[130:131], v[130:131], v[164:165]
	v_pk_add_f32 v[160:161], v[160:161], v[166:167]
	s_nop 0
	v_pk_add_f32 v[130:131], v[130:131], v[160:161]
	s_nop 0
	v_pk_fma_f32 v[130:131], v[130:131], s[72:73], v[132:133] op_sel_hi:[1,0,0]
	s_nop 0
	v_mul_f32_e32 v151, 0x4b800000, v130
	v_cmp_gt_f32_e64 s[6:7], s67, v130
	v_cmp_gt_f32_e32 vcc, s67, v131
	s_nop 0
	v_cndmask_b32_e64 v130, v130, v151, s[6:7]
	v_mul_f32_e32 v151, 0x4b800000, v131
	v_cndmask_b32_e32 v131, v131, v151, vcc
	v_rsq_f32_e32 v130, v130
	v_rsq_f32_e32 v131, v131
	s_nop 0
	v_pk_mul_f32 v[160:161], v[130:131], s[76:77] op_sel_hi:[1,0]
	s_nop 0
	v_cndmask_b32_e32 v131, v131, v161, vcc
	v_cndmask_b32_e64 v130, v130, v160, s[6:7]
	global_load_dwordx4 v[160:163], v[152:153], off offset:2560
	s_waitcnt vmcnt(0) lgkmcnt(0)
	v_add_f32_e32 v164, v160, v161
	v_add_f32_e32 v166, v162, v163
	global_load_dwordx4 v[160:163], v[152:153], off offset:2816
	s_waitcnt vmcnt(0) lgkmcnt(0)
	v_mov_b32_e32 v152, v161
	v_mov_b32_e32 v153, v162
	v_mov_b32_e32 v161, v163
	v_pk_add_f32 v[152:153], v[152:153], v[160:161]
	s_nop 0
	v_mov_b32_e32 v165, v152
	v_mov_b32_e32 v167, v153
	v_pk_add_f32 v[152:153], v[164:165], v[166:167]
	s_nop 0
	v_pk_fma_f32 v[132:133], v[152:153], s[72:73], v[132:133] op_sel_hi:[1,0,0]
	s_nop 0
	v_mul_f32_e32 v151, 0x4b800000, v132
	v_cmp_gt_f32_e64 s[6:7], s67, v132
	v_cmp_gt_f32_e32 vcc, s67, v133
	s_nop 0
	v_cndmask_b32_e64 v132, v132, v151, s[6:7]
	v_mul_f32_e32 v151, 0x4b800000, v133
	v_cndmask_b32_e32 v133, v133, v151, vcc
	v_rsq_f32_e32 v132, v132
	v_rsq_f32_e32 v133, v133
	s_nop 0
	v_pk_mul_f32 v[152:153], v[132:133], s[76:77] op_sel_hi:[1,0]
	s_nop 0
	v_cndmask_b32_e32 v133, v133, v153, vcc
	v_cndmask_b32_e64 v132, v132, v152, s[6:7]
	v_cmp_eq_u32_e32 vcc, 0, v154
	s_and_saveexec_b64 s[6:7], vcc
	s_cbranch_execz .LBB0_339
	v_add_u32_e32 v151, s91, v155
	v_cmp_eq_u32_e32 vcc, 0, v159
	ds_write_b128 v151, v[134:137]
	ds_write_b128 v151, v[130:133] offset:16
	s_and_b64 exec, exec, vcc
	v_mov_b32_e32 v151, s90
	v_mov_b32_e32 v152, s44
	ds_write_b32 v151, v152

; __device__ __forceinline__ unsigned pk2(float lo, float hi) { f32x2_t v = {lo, hi}; bf16x2_t b = __builtin_convertvector(v, bf16x2_t); return __builtin_bit_cast(unsigned, b); }
;     __device__ __forceinline__ void operator()(const f32x4 (&acc)[2][2][4][2], const Unit& u, int wr, int wc, int fr, int fq) const {
;     ...
;                 } else {
; #pragma unroll
;                     for (int bj = 0; bj < 2; ++bj) {
;                         const float rq = (pn < 2) ? rs * (0.125f * LOG2E) : rs;
;                         const f32x4 v0 = acc[ai][bj][m][0] * rq, v1 = acc[ai][bj][m][1] * rq;
;                         u32x4 w; w.x = pk2(v0[0], v0[1]); w.y = pk2(v0[2], v0[3]); w.z = pk2(v1[0], v1[1]); w.w = pk2(v1[2], v1[3]);
;                         bf16_t* dst;
;                         if (pn < 2) dst = (bf16_t*)(ws + WS_Q) + (size_t)row * 512 + pn * 256 + bj * 128 + cl;
;                         else if (pn == 2) { const int b = row >> 12, tok = row & 4095, gg = cl >> 6, d0 = cl & 63;
;                             dst = (bf16_t*)(ws + WS_KCMP) + ((size_t)((bj * 16 + b * 2 + gg) * 4096 + tok)) * 64 + d0; }
;                         else if (pn == 3) dst = (bf16_t*)(ws + (bj ? WS_VS : WS_KS)) + (size_t)row * 128 + cl;
;                         else dst = (bf16_t*)(ws + (bj ? WS_VW : WS_KW)) + (size_t)row * 128 + cl;
;                         *(u32x4*)dst = w;
;                     }
.LBB0_342:
	v_lshlrev_b32_e32 v152, 3, v154
	v_add_u32_e32 v154, s85, v152
	v_ashrrev_i32_e32 v155, 31, v154
	v_cndmask_b32_e64 v151, 0, 1, s[8:9]
	s_mov_b64 s[44:45], -1
	v_cmp_ne_u32_e64 s[6:7], 1, v151
	s_andn2_b64 vcc, exec, s[8:9]
	v_lshlrev_b64 v[154:155], 1, v[154:155]
	s_cbranch_vccnz .LBB0_344
	v_ashrrev_i32_e32 v151, 31, v150
	v_lshlrev_b64 v[164:165], 8, v[150:151]
	s_waitcnt lgkmcnt(0)
	v_pk_mul_f32 v[162:163], v[124:125], v[134:135] op_sel_hi:[1,0]
	v_pk_mul_f32 v[160:161], v[122:123], v[134:135] op_sel_hi:[1,0]
	v_pk_mul_f32 v[166:167], v[116:117], v[134:135] op_sel_hi:[1,0]
	v_pk_mul_f32 v[180:181], v[114:115], v[134:135] op_sel_hi:[1,0]
	v_cvt_pk_bf16_f32 v160, v160, v161
	v_cvt_pk_bf16_f32 v161, v162, v163
	v_cvt_pk_bf16_f32 v163, v166, v167
	v_lshl_add_u64 v[166:167], s[20:21], 0, v[164:165]
	v_cvt_pk_bf16_f32 v162, v180, v181
	v_lshl_add_u64 v[166:167], v[166:167], 0, v[154:155]
	v_pk_mul_f32 v[126:127], v[126:127], v[134:135] op_sel_hi:[1,0]
	global_store_dwordx4 v[166:167], v[160:163], off
	v_pk_mul_f32 v[128:129], v[128:129], v[134:135] op_sel_hi:[1,0]
	s_mov_b64 s[44:45], 0
	v_pk_mul_f32 v[160:161], v[120:121], v[134:135] op_sel_hi:[1,0]
	v_pk_mul_f32 v[120:121], v[118:119], v[134:135] op_sel_hi:[1,0]
	v_cvt_pk_bf16_f32 v118, v126, v127
	v_lshl_add_u64 v[126:127], s[22:23], 0, v[164:165]
	v_cvt_pk_bf16_f32 v119, v128, v129
	v_cvt_pk_bf16_f32 v120, v120, v121
	v_cvt_pk_bf16_f32 v121, v160, v161
	v_lshl_add_u64 v[126:127], v[126:127], 0, v[154:155]
	global_store_dwordx4 v[126:127], v[118:121], off

; __device__ __forceinline__ unsigned pk2(float lo, float hi) { f32x2_t v = {lo, hi}; bf16x2_t b = __builtin_convertvector(v, bf16x2_t); return __builtin_bit_cast(unsigned, b); }
;     __device__ __forceinline__ void operator()(const f32x4 (&acc)[2][2][4][2], const Unit& u, int wr, int wc, int fr, int fq) const {
;     ...
;                 } else {
; #pragma unroll
;                     for (int bj = 0; bj < 2; ++bj) {
;                         const float rq = (pn < 2) ? rs * (0.125f * LOG2E) : rs;
;                         const f32x4 v0 = acc[ai][bj][m][0] * rq, v1 = acc[ai][bj][m][1] * rq;
;                         u32x4 w; w.x = pk2(v0[0], v0[1]); w.y = pk2(v0[2], v0[3]); w.z = pk2(v1[0], v1[1]); w.w = pk2(v1[2], v1[3]);
;                         bf16_t* dst;
;                         if (pn < 2) dst = (bf16_t*)(ws + WS_Q) + (size_t)row * 512 + pn * 256 + bj * 128 + cl;
;                         else if (pn == 2) { const int b = row >> 12, tok = row & 4095, gg = cl >> 6, d0 = cl & 63;
;                             dst = (bf16_t*)(ws + WS_KCMP) + ((size_t)((bj * 16 + b * 2 + gg) * 4096 + tok)) * 64 + d0; }
;                         else if (pn == 3) dst = (bf16_t*)(ws + (bj ? WS_VS : WS_KS)) + (size_t)row * 128 + cl;
;                         else dst = (bf16_t*)(ws + (bj ? WS_VW : WS_KW)) + (size_t)row * 128 + cl;
;                         *(u32x4*)dst = w;
;                     }
.LBB0_347:
	v_ashrrev_i32_e32 v115, 31, v114
	v_lshlrev_b64 v[120:121], 8, v[114:115]
	s_waitcnt lgkmcnt(0)
	v_pk_mul_f32 v[118:119], v[108:109], v[134:135] op_sel:[0,1]
	v_pk_mul_f32 v[116:117], v[106:107], v[134:135] op_sel:[0,1]
	v_pk_mul_f32 v[122:123], v[100:101], v[134:135] op_sel:[0,1]
	v_pk_mul_f32 v[124:125], v[98:99], v[134:135] op_sel:[0,1]
	v_cvt_pk_bf16_f32 v116, v116, v117
	v_cvt_pk_bf16_f32 v117, v118, v119
	v_cvt_pk_bf16_f32 v119, v122, v123
	v_lshl_add_u64 v[122:123], s[20:21], 0, v[120:121]
	v_cvt_pk_bf16_f32 v118, v124, v125
	v_lshl_add_u64 v[122:123], v[122:123], 0, v[154:155]
	v_pk_mul_f32 v[110:111], v[110:111], v[134:135] op_sel:[0,1]
	global_store_dwordx4 v[122:123], v[116:119], off
	v_pk_mul_f32 v[112:113], v[112:113], v[134:135] op_sel:[0,1]
	s_mov_b64 s[44:45], 0
	v_pk_mul_f32 v[116:117], v[104:105], v[134:135] op_sel:[0,1]
	v_pk_mul_f32 v[104:105], v[102:103], v[134:135] op_sel:[0,1]
	v_cvt_pk_bf16_f32 v102, v110, v111
	v_lshl_add_u64 v[110:111], s[22:23], 0, v[120:121]
	v_cvt_pk_bf16_f32 v103, v112, v113
	v_cvt_pk_bf16_f32 v104, v104, v105
	v_cvt_pk_bf16_f32 v105, v116, v117
	v_lshl_add_u64 v[110:111], v[110:111], 0, v[154:155]
	global_store_dwordx4 v[110:111], v[102:105], off

; __device__ __forceinline__ unsigned pk2(float lo, float hi) { f32x2_t v = {lo, hi}; bf16x2_t b = __builtin_convertvector(v, bf16x2_t); return __builtin_bit_cast(unsigned, b); }
;     __device__ __forceinline__ void operator()(const f32x4 (&acc)[2][2][4][2], const Unit& u, int wr, int wc, int fr, int fq) const {
;     ...
;                 } else {
; #pragma unroll
;                     for (int bj = 0; bj < 2; ++bj) {
;                         const float rq = (pn < 2) ? rs * (0.125f * LOG2E) : rs;
;                         const f32x4 v0 = acc[ai][bj][m][0] * rq, v1 = acc[ai][bj][m][1] * rq;
;                         u32x4 w; w.x = pk2(v0[0], v0[1]); w.y = pk2(v0[2], v0[3]); w.z = pk2(v1[0], v1[1]); w.w = pk2(v1[2], v1[3]);
;                         bf16_t* dst;
;                         if (pn < 2) dst = (bf16_t*)(ws + WS_Q) + (size_t)row * 512 + pn * 256 + bj * 128 + cl;
;                         else if (pn == 2) { const int b = row >> 12, tok = row & 4095, gg = cl >> 6, d0 = cl & 63;
;                             dst = (bf16_t*)(ws + WS_KCMP) + ((size_t)((bj * 16 + b * 2 + gg) * 4096 + tok)) * 64 + d0; }
;                         else if (pn == 3) dst = (bf16_t*)(ws + (bj ? WS_VS : WS_KS)) + (size_t)row * 128 + cl;
;                         else dst = (bf16_t*)(ws + (bj ? WS_VW : WS_KW)) + (size_t)row * 128 + cl;
;                         *(u32x4*)dst = w;
;                     }
.LBB0_351:
	v_ashrrev_i32_e32 v99, 31, v98
	v_lshlrev_b64 v[104:105], 8, v[98:99]
	s_waitcnt lgkmcnt(0)
	v_pk_mul_f32 v[102:103], v[92:93], v[136:137] op_sel_hi:[1,0]
	v_pk_mul_f32 v[100:101], v[90:91], v[136:137] op_sel_hi:[1,0]
	v_pk_mul_f32 v[106:107], v[84:85], v[136:137] op_sel_hi:[1,0]
	v_pk_mul_f32 v[108:109], v[82:83], v[136:137] op_sel_hi:[1,0]
	v_cvt_pk_bf16_f32 v100, v100, v101
	v_cvt_pk_bf16_f32 v101, v102, v103
	v_cvt_pk_bf16_f32 v103, v106, v107
	v_lshl_add_u64 v[106:107], s[20:21], 0, v[104:105]
	v_cvt_pk_bf16_f32 v102, v108, v109
	v_lshl_add_u64 v[106:107], v[106:107], 0, v[154:155]
	v_pk_mul_f32 v[94:95], v[94:95], v[136:137] op_sel_hi:[1,0]
	global_store_dwordx4 v[106:107], v[100:103], off
	v_pk_mul_f32 v[96:97], v[96:97], v[136:137] op_sel_hi:[1,0]
	s_mov_b64 s[44:45], 0
	v_pk_mul_f32 v[100:101], v[88:89], v[136:137] op_sel_hi:[1,0]
	v_pk_mul_f32 v[88:89], v[86:87], v[136:137] op_sel_hi:[1,0]
	v_cvt_pk_bf16_f32 v86, v94, v95
	v_lshl_add_u64 v[94:95], s[22:23], 0, v[104:105]
	v_cvt_pk_bf16_f32 v87, v96, v97
	v_cvt_pk_bf16_f32 v88, v88, v89
	v_cvt_pk_bf16_f32 v89, v100, v101
	v_lshl_add_u64 v[94:95], v[94:95], 0, v[154:155]
	global_store_dwordx4 v[94:95], v[86:89], off

; __device__ __forceinline__ unsigned pk2(float lo, float hi) { f32x2_t v = {lo, hi}; bf16x2_t b = __builtin_convertvector(v, bf16x2_t); return __builtin_bit_cast(unsigned, b); }
;     __device__ __forceinline__ void operator()(const f32x4 (&acc)[2][2][4][2], const Unit& u, int wr, int wc, int fr, int fq) const {
;     ...
;                 } else {
; #pragma unroll
;                     for (int bj = 0; bj < 2; ++bj) {
;                         const float rq = (pn < 2) ? rs * (0.125f * LOG2E) : rs;
;                         const f32x4 v0 = acc[ai][bj][m][0] * rq, v1 = acc[ai][bj][m][1] * rq;
;                         u32x4 w; w.x = pk2(v0[0], v0[1]); w.y = pk2(v0[2], v0[3]); w.z = pk2(v1[0], v1[1]); w.w = pk2(v1[2], v1[3]);
;                         bf16_t* dst;
;                         if (pn < 2) dst = (bf16_t*)(ws + WS_Q) + (size_t)row * 512 + pn * 256 + bj * 128 + cl;
;                         else if (pn == 2) { const int b = row >> 12, tok = row & 4095, gg = cl >> 6, d0 = cl & 63;
;                             dst = (bf16_t*)(ws + WS_KCMP) + ((size_t)((bj * 16 + b * 2 + gg) * 4096 + tok)) * 64 + d0; }
;                         else if (pn == 3) dst = (bf16_t*)(ws + (bj ? WS_VS : WS_KS)) + (size_t)row * 128 + cl;
;                         else dst = (bf16_t*)(ws + (bj ? WS_VW : WS_KW)) + (size_t)row * 128 + cl;
;                         *(u32x4*)dst = w;
;                     }
.LBB0_355:
	v_ashrrev_i32_e32 v83, 31, v82
	s_waitcnt lgkmcnt(0)
	v_mov_b32_e32 v90, v137
	v_lshlrev_b64 v[88:89], 8, v[82:83]
	v_pk_mul_f32 v[86:87], v[76:77], v[90:91] op_sel_hi:[1,0]
	v_pk_mul_f32 v[84:85], v[74:75], v[90:91] op_sel_hi:[1,0]
	v_pk_mul_f32 v[92:93], v[68:69], v[90:91] op_sel_hi:[1,0]
	v_pk_mul_f32 v[94:95], v[66:67], v[90:91] op_sel_hi:[1,0]
	v_cvt_pk_bf16_f32 v84, v84, v85
	v_cvt_pk_bf16_f32 v85, v86, v87
	v_cvt_pk_bf16_f32 v87, v92, v93
	v_lshl_add_u64 v[92:93], s[20:21], 0, v[88:89]
	v_cvt_pk_bf16_f32 v86, v94, v95
	v_lshl_add_u64 v[92:93], v[92:93], 0, v[154:155]
	v_pk_mul_f32 v[78:79], v[78:79], v[90:91] op_sel_hi:[1,0]
	global_store_dwordx4 v[92:93], v[84:87], off
	v_pk_mul_f32 v[80:81], v[80:81], v[90:91] op_sel_hi:[1,0]
	s_mov_b64 s[44:45], 0
	v_pk_mul_f32 v[84:85], v[72:73], v[90:91] op_sel_hi:[1,0]
	v_pk_mul_f32 v[72:73], v[70:71], v[90:91] op_sel_hi:[1,0]
	v_cvt_pk_bf16_f32 v70, v78, v79
	v_lshl_add_u64 v[78:79], s[22:23], 0, v[88:89]
	v_cvt_pk_bf16_f32 v71, v80, v81
	v_cvt_pk_bf16_f32 v72, v72, v73
	v_cvt_pk_bf16_f32 v73, v84, v85
	v_lshl_add_u64 v[78:79], v[78:79], 0, v[154:155]
	global_store_dwordx4 v[78:79], v[70:73], off

; __device__ __forceinline__ unsigned pk2(float lo, float hi) { f32x2_t v = {lo, hi}; bf16x2_t b = __builtin_convertvector(v, bf16x2_t); return __builtin_bit_cast(unsigned, b); }
;     __device__ __forceinline__ void operator()(const f32x4 (&acc)[2][2][4][2], const Unit& u, int wr, int wc, int fr, int fq) const {
;     ...
;                 } else {
; #pragma unroll
;                     for (int bj = 0; bj < 2; ++bj) {
;                         const float rq = (pn < 2) ? rs * (0.125f * LOG2E) : rs;
;                         const f32x4 v0 = acc[ai][bj][m][0] * rq, v1 = acc[ai][bj][m][1] * rq;
;                         u32x4 w; w.x = pk2(v0[0], v0[1]); w.y = pk2(v0[2], v0[3]); w.z = pk2(v1[0], v1[1]); w.w = pk2(v1[2], v1[3]);
;                         bf16_t* dst;
;                         if (pn < 2) dst = (bf16_t*)(ws + WS_Q) + (size_t)row * 512 + pn * 256 + bj * 128 + cl;
;                         else if (pn == 2) { const int b = row >> 12, tok = row & 4095, gg = cl >> 6, d0 = cl & 63;
;                             dst = (bf16_t*)(ws + WS_KCMP) + ((size_t)((bj * 16 + b * 2 + gg) * 4096 + tok)) * 64 + d0; }
;                         else if (pn == 3) dst = (bf16_t*)(ws + (bj ? WS_VS : WS_KS)) + (size_t)row * 128 + cl;
;                         else dst = (bf16_t*)(ws + (bj ? WS_VW : WS_KW)) + (size_t)row * 128 + cl;
;                         *(u32x4*)dst = w;
;                     }
.LBB0_359:
	v_ashrrev_i32_e32 v67, 31, v66
	v_lshlrev_b64 v[72:73], 8, v[66:67]
	s_waitcnt lgkmcnt(0)
	v_pk_mul_f32 v[70:71], v[60:61], v[130:131] op_sel_hi:[1,0]
	v_pk_mul_f32 v[68:69], v[58:59], v[130:131] op_sel_hi:[1,0]
	v_pk_mul_f32 v[74:75], v[52:53], v[130:131] op_sel_hi:[1,0]
	v_pk_mul_f32 v[76:77], v[50:51], v[130:131] op_sel_hi:[1,0]
	v_cvt_pk_bf16_f32 v68, v68, v69
	v_cvt_pk_bf16_f32 v69, v70, v71
	v_cvt_pk_bf16_f32 v71, v74, v75
	v_lshl_add_u64 v[74:75], s[20:21], 0, v[72:73]
	v_cvt_pk_bf16_f32 v70, v76, v77
	v_lshl_add_u64 v[74:75], v[74:75], 0, v[154:155]
	v_pk_mul_f32 v[62:63], v[62:63], v[130:131] op_sel_hi:[1,0]
	global_store_dwordx4 v[74:75], v[68:71], off
	v_pk_mul_f32 v[64:65], v[64:65], v[130:131] op_sel_hi:[1,0]
	s_mov_b64 s[44:45], 0
	v_pk_mul_f32 v[68:69], v[56:57], v[130:131] op_sel_hi:[1,0]
	v_pk_mul_f32 v[56:57], v[54:55], v[130:131] op_sel_hi:[1,0]
	v_cvt_pk_bf16_f32 v54, v62, v63
	v_lshl_add_u64 v[62:63], s[22:23], 0, v[72:73]
	v_cvt_pk_bf16_f32 v55, v64, v65
	v_cvt_pk_bf16_f32 v56, v56, v57
	v_cvt_pk_bf16_f32 v57, v68, v69
	v_lshl_add_u64 v[62:63], v[62:63], 0, v[154:155]
	global_store_dwordx4 v[62:63], v[54:57], off

; __device__ __forceinline__ unsigned pk2(float lo, float hi) { f32x2_t v = {lo, hi}; bf16x2_t b = __builtin_convertvector(v, bf16x2_t); return __builtin_bit_cast(unsigned, b); }
;     __device__ __forceinline__ void operator()(const f32x4 (&acc)[2][2][4][2], const Unit& u, int wr, int wc, int fr, int fq) const {
;     ...
;                 } else {
; #pragma unroll
;                     for (int bj = 0; bj < 2; ++bj) {
;                         const float rq = (pn < 2) ? rs * (0.125f * LOG2E) : rs;
;                         const f32x4 v0 = acc[ai][bj][m][0] * rq, v1 = acc[ai][bj][m][1] * rq;
;                         u32x4 w; w.x = pk2(v0[0], v0[1]); w.y = pk2(v0[2], v0[3]); w.z = pk2(v1[0], v1[1]); w.w = pk2(v1[2], v1[3]);
;                         bf16_t* dst;
;                         if (pn < 2) dst = (bf16_t*)(ws + WS_Q) + (size_t)row * 512 + pn * 256 + bj * 128 + cl;
;                         else if (pn == 2) { const int b = row >> 12, tok = row & 4095, gg = cl >> 6, d0 = cl & 63;
;                             dst = (bf16_t*)(ws + WS_KCMP) + ((size_t)((bj * 16 + b * 2 + gg) * 4096 + tok)) * 64 + d0; }
;                         else if (pn == 3) dst = (bf16_t*)(ws + (bj ? WS_VS : WS_KS)) + (size_t)row * 128 + cl;
;                         else dst = (bf16_t*)(ws + (bj ? WS_VW : WS_KW)) + (size_t)row * 128 + cl;
;                         *(u32x4*)dst = w;
;                     }
.LBB0_363:
	v_ashrrev_i32_e32 v51, 31, v50
	v_lshlrev_b64 v[56:57], 8, v[50:51]
	s_waitcnt lgkmcnt(0)
	v_pk_mul_f32 v[54:55], v[44:45], v[130:131] op_sel:[0,1]
	v_pk_mul_f32 v[52:53], v[42:43], v[130:131] op_sel:[0,1]
	v_pk_mul_f32 v[58:59], v[36:37], v[130:131] op_sel:[0,1]
	v_pk_mul_f32 v[60:61], v[34:35], v[130:131] op_sel:[0,1]
	v_cvt_pk_bf16_f32 v52, v52, v53
	v_cvt_pk_bf16_f32 v53, v54, v55
	v_cvt_pk_bf16_f32 v55, v58, v59
	v_lshl_add_u64 v[58:59], s[20:21], 0, v[56:57]
	v_cvt_pk_bf16_f32 v54, v60, v61
	v_lshl_add_u64 v[58:59], v[58:59], 0, v[154:155]
	v_pk_mul_f32 v[46:47], v[46:47], v[130:131] op_sel:[0,1]
	global_store_dwordx4 v[58:59], v[52:55], off
	v_pk_mul_f32 v[48:49], v[48:49], v[130:131] op_sel:[0,1]
	s_mov_b64 s[44:45], 0
	v_pk_mul_f32 v[52:53], v[40:41], v[130:131] op_sel:[0,1]
	v_pk_mul_f32 v[40:41], v[38:39], v[130:131] op_sel:[0,1]
	v_cvt_pk_bf16_f32 v38, v46, v47
	v_lshl_add_u64 v[46:47], s[22:23], 0, v[56:57]
	v_cvt_pk_bf16_f32 v39, v48, v49
	v_cvt_pk_bf16_f32 v40, v40, v41
	v_cvt_pk_bf16_f32 v41, v52, v53
	v_lshl_add_u64 v[46:47], v[46:47], 0, v[154:155]
	global_store_dwordx4 v[46:47], v[38:41], off

; __device__ __forceinline__ unsigned pk2(float lo, float hi) { f32x2_t v = {lo, hi}; bf16x2_t b = __builtin_convertvector(v, bf16x2_t); return __builtin_bit_cast(unsigned, b); }
;     __device__ __forceinline__ void operator()(const f32x4 (&acc)[2][2][4][2], const Unit& u, int wr, int wc, int fr, int fq) const {
;     ...
;                 } else {
; #pragma unroll
;                     for (int bj = 0; bj < 2; ++bj) {
;                         const float rq = (pn < 2) ? rs * (0.125f * LOG2E) : rs;
;                         const f32x4 v0 = acc[ai][bj][m][0] * rq, v1 = acc[ai][bj][m][1] * rq;
;                         u32x4 w; w.x = pk2(v0[0], v0[1]); w.y = pk2(v0[2], v0[3]); w.z = pk2(v1[0], v1[1]); w.w = pk2(v1[2], v1[3]);
;                         bf16_t* dst;
;                         if (pn < 2) dst = (bf16_t*)(ws + WS_Q) + (size_t)row * 512 + pn * 256 + bj * 128 + cl;
;                         else if (pn == 2) { const int b = row >> 12, tok = row & 4095, gg = cl >> 6, d0 = cl & 63;
;                             dst = (bf16_t*)(ws + WS_KCMP) + ((size_t)((bj * 16 + b * 2 + gg) * 4096 + tok)) * 64 + d0; }
;                         else if (pn == 3) dst = (bf16_t*)(ws + (bj ? WS_VS : WS_KS)) + (size_t)row * 128 + cl;
;                         else dst = (bf16_t*)(ws + (bj ? WS_VW : WS_KW)) + (size_t)row * 128 + cl;
;                         *(u32x4*)dst = w;
;                     }
.LBB0_367:
	v_ashrrev_i32_e32 v35, 31, v34
	v_lshlrev_b64 v[40:41], 8, v[34:35]
	s_waitcnt lgkmcnt(0)
	v_pk_mul_f32 v[38:39], v[28:29], v[132:133] op_sel_hi:[1,0]
	v_pk_mul_f32 v[36:37], v[26:27], v[132:133] op_sel_hi:[1,0]
	v_pk_mul_f32 v[42:43], v[20:21], v[132:133] op_sel_hi:[1,0]
	v_pk_mul_f32 v[44:45], v[18:19], v[132:133] op_sel_hi:[1,0]
	v_cvt_pk_bf16_f32 v36, v36, v37
	v_cvt_pk_bf16_f32 v37, v38, v39
	v_cvt_pk_bf16_f32 v39, v42, v43
	v_lshl_add_u64 v[42:43], s[20:21], 0, v[40:41]
	v_cvt_pk_bf16_f32 v38, v44, v45
	v_lshl_add_u64 v[42:43], v[42:43], 0, v[154:155]
	v_pk_mul_f32 v[30:31], v[30:31], v[132:133] op_sel_hi:[1,0]
	global_store_dwordx4 v[42:43], v[36:39], off
	v_pk_mul_f32 v[32:33], v[32:33], v[132:133] op_sel_hi:[1,0]
	s_mov_b64 s[44:45], 0
	v_pk_mul_f32 v[36:37], v[24:25], v[132:133] op_sel_hi:[1,0]
	v_pk_mul_f32 v[24:25], v[22:23], v[132:133] op_sel_hi:[1,0]
	v_cvt_pk_bf16_f32 v22, v30, v31
	v_lshl_add_u64 v[30:31], s[22:23], 0, v[40:41]
	v_cvt_pk_bf16_f32 v23, v32, v33
	v_cvt_pk_bf16_f32 v24, v24, v25
	v_cvt_pk_bf16_f32 v25, v36, v37
	v_lshl_add_u64 v[30:31], v[30:31], 0, v[154:155]
	global_store_dwordx4 v[30:31], v[22:25], off

; __device__ __forceinline__ unsigned pk2(float lo, float hi) { f32x2_t v = {lo, hi}; bf16x2_t b = __builtin_convertvector(v, bf16x2_t); return __builtin_bit_cast(unsigned, b); }
;     __device__ __forceinline__ void operator()(const f32x4 (&acc)[2][2][4][2], const Unit& u, int wr, int wc, int fr, int fq) const {
;     ...
;                 } else {
; #pragma unroll
;                     for (int bj = 0; bj < 2; ++bj) {
;                         const float rq = (pn < 2) ? rs * (0.125f * LOG2E) : rs;
;                         const f32x4 v0 = acc[ai][bj][m][0] * rq, v1 = acc[ai][bj][m][1] * rq;
;                         u32x4 w; w.x = pk2(v0[0], v0[1]); w.y = pk2(v0[2], v0[3]); w.z = pk2(v1[0], v1[1]); w.w = pk2(v1[2], v1[3]);
;                         bf16_t* dst;
;                         if (pn < 2) dst = (bf16_t*)(ws + WS_Q) + (size_t)row * 512 + pn * 256 + bj * 128 + cl;
;                         else if (pn == 2) { const int b = row >> 12, tok = row & 4095, gg = cl >> 6, d0 = cl & 63;
;                             dst = (bf16_t*)(ws + WS_KCMP) + ((size_t)((bj * 16 + b * 2 + gg) * 4096 + tok)) * 64 + d0; }
;                         else if (pn == 3) dst = (bf16_t*)(ws + (bj ? WS_VS : WS_KS)) + (size_t)row * 128 + cl;
;                         else dst = (bf16_t*)(ws + (bj ? WS_VW : WS_KW)) + (size_t)row * 128 + cl;
;                         *(u32x4*)dst = w;
;                     }
.LBB0_371:
	v_ashrrev_i32_e32 v19, 31, v18
	s_waitcnt lgkmcnt(0)
	v_mov_b32_e32 v26, v133
	v_lshlrev_b64 v[24:25], 8, v[18:19]
	v_pk_mul_f32 v[22:23], v[12:13], v[26:27] op_sel_hi:[1,0]
	v_pk_mul_f32 v[20:21], v[10:11], v[26:27] op_sel_hi:[1,0]
	v_pk_mul_f32 v[28:29], v[8:9], v[26:27] op_sel_hi:[1,0]
	v_pk_mul_f32 v[30:31], v[6:7], v[26:27] op_sel_hi:[1,0]
	v_cvt_pk_bf16_f32 v20, v20, v21
	v_cvt_pk_bf16_f32 v21, v22, v23
	v_cvt_pk_bf16_f32 v23, v28, v29
	v_lshl_add_u64 v[28:29], s[20:21], 0, v[24:25]
	v_cvt_pk_bf16_f32 v22, v30, v31
	v_lshl_add_u64 v[28:29], v[28:29], 0, v[154:155]
	v_pk_mul_f32 v[14:15], v[14:15], v[26:27] op_sel_hi:[1,0]
	global_store_dwordx4 v[28:29], v[20:23], off
	v_pk_mul_f32 v[16:17], v[16:17], v[26:27] op_sel_hi:[1,0]
	s_mov_b64 s[6:7], 0
	v_pk_mul_f32 v[20:21], v[4:5], v[26:27] op_sel_hi:[1,0]
	v_pk_mul_f32 v[4:5], v[2:3], v[26:27] op_sel_hi:[1,0]
	v_cvt_pk_bf16_f32 v2, v14, v15
	v_lshl_add_u64 v[14:15], s[22:23], 0, v[24:25]
	v_cvt_pk_bf16_f32 v3, v16, v17
	v_cvt_pk_bf16_f32 v4, v4, v5
	v_cvt_pk_bf16_f32 v5, v20, v21
	v_lshl_add_u64 v[14:15], v[14:15], 0, v[154:155]
	global_store_dwordx4 v[14:15], v[2:5], off

; __device__ __forceinline__ float fsigmoid(float x) { return __builtin_amdgcn_rcpf(1.0f + __expf(-x)); }
;     __device__ __forceinline__ void operator()(const f32x4 (&acc)[2][2][4][2], const Unit& u, int wr, int wc, int fr, int fq) const {
;     ...
;                     if (wc == 0) {
;                         const f32x4 a0 = acc[ai][0][m][0] * rs, a1 = acc[ai][0][m][1] * rs;
;                         float* gp = (float*)(ws + WS_G) + (size_t)row * 32 + 8 * fq;
;                         *(f32x4*)gp = (f32x4){fsigmoid(a0[0]), fsigmoid(a0[1]), fsigmoid(a0[2]), fsigmoid(a0[3])};
;                         *(f32x4*)(gp + 4) = (f32x4){fsigmoid(a1[0]), fsigmoid(a1[1]), fsigmoid(a1[2]), fsigmoid(a1[3])};
;                     }
.LBB0_377:
	s_waitcnt lgkmcnt(0)
	v_pk_mul_f32 v[118:119], v[124:125], v[134:135] op_sel_hi:[1,0]
	v_pk_mul_f32 v[120:121], v[122:123], v[134:135] op_sel_hi:[1,0]
	v_pk_mul_f32 v[122:123], v[116:117], v[134:135] op_sel_hi:[1,0]
	v_pk_mul_f32 v[124:125], v[114:115], v[134:135] op_sel_hi:[1,0]
	v_mul_f32_e32 v114, 0xbfb8aa3b, v120
	v_mul_f32_e32 v115, 0xbfb8aa3b, v121
	v_mul_f32_e32 v116, 0xbfb8aa3b, v118
	v_mul_f32_e32 v117, 0xbfb8aa3b, v119
	v_exp_f32_e32 v114, v114
	v_exp_f32_e32 v115, v115
	v_exp_f32_e32 v116, v116
	v_exp_f32_e32 v117, v117
	v_mul_f32_e32 v118, 0xbfb8aa3b, v124
	v_mul_f32_e32 v119, 0xbfb8aa3b, v125
	v_mul_f32_e32 v120, 0xbfb8aa3b, v122
	v_mul_f32_e32 v121, 0xbfb8aa3b, v123
	v_exp_f32_e32 v118, v118
	v_exp_f32_e32 v119, v119
	v_exp_f32_e32 v120, v120
	v_exp_f32_e32 v121, v121
	v_add_f32_e32 v114, 1.0, v114
	v_add_f32_e32 v115, 1.0, v115
	v_add_f32_e32 v116, 1.0, v116
	v_add_f32_e32 v117, 1.0, v117
	v_ashrrev_i32_e32 v151, 31, v150
	v_rcp_f32_e32 v114, v114
	v_rcp_f32_e32 v115, v115
	v_rcp_f32_e32 v116, v116
	v_rcp_f32_e32 v117, v117
	v_add_f32_e32 v118, 1.0, v118
	v_add_f32_e32 v119, 1.0, v119
	v_add_f32_e32 v120, 1.0, v120
	v_add_f32_e32 v121, 1.0, v121
	v_lshlrev_b64 v[126:127], 7, v[150:151]
	v_rcp_f32_e32 v118, v118
	v_rcp_f32_e32 v119, v119
	v_rcp_f32_e32 v120, v120
	v_rcp_f32_e32 v121, v121
	v_lshl_add_u64 v[122:123], s[26:27], 0, v[126:127]
	v_lshl_add_u64 v[122:123], v[152:153], 2, v[122:123]
	global_store_dwordx4 v[122:123], v[114:117], off
	global_store_dwordx4 v[122:123], v[118:121], off offset:16
	s_nop 0
	v_add_u32_e32 v114, 16, v150
	s_and_b64 vcc, exec, s[6:7]
	s_mov_b64 s[44:45], -1
	s_cbranch_vccz .LBB0_347
	s_branch .LBB0_348
.LBB0_378:
	s_waitcnt lgkmcnt(0)
	v_pk_mul_f32 v[102:103], v[108:109], v[134:135] op_sel:[0,1]
	v_pk_mul_f32 v[104:105], v[106:107], v[134:135] op_sel:[0,1]
	v_pk_mul_f32 v[106:107], v[100:101], v[134:135] op_sel:[0,1]
	v_pk_mul_f32 v[108:109], v[98:99], v[134:135] op_sel:[0,1]
	v_mul_f32_e32 v98, 0xbfb8aa3b, v104
	v_mul_f32_e32 v99, 0xbfb8aa3b, v105
	v_mul_f32_e32 v100, 0xbfb8aa3b, v102
	v_mul_f32_e32 v101, 0xbfb8aa3b, v103
	v_exp_f32_e32 v98, v98
	v_exp_f32_e32 v99, v99
	v_exp_f32_e32 v100, v100
	v_exp_f32_e32 v101, v101
	v_mul_f32_e32 v102, 0xbfb8aa3b, v108
	v_mul_f32_e32 v103, 0xbfb8aa3b, v109
	v_mul_f32_e32 v104, 0xbfb8aa3b, v106
	v_mul_f32_e32 v105, 0xbfb8aa3b, v107
	v_exp_f32_e32 v102, v102
	v_exp_f32_e32 v103, v103
	v_exp_f32_e32 v104, v104
	v_exp_f32_e32 v105, v105
	v_add_f32_e32 v98, 1.0, v98
	v_add_f32_e32 v99, 1.0, v99
	v_add_f32_e32 v100, 1.0, v100
	v_add_f32_e32 v101, 1.0, v101
	v_ashrrev_i32_e32 v115, 31, v114
	v_rcp_f32_e32 v98, v98
	v_rcp_f32_e32 v99, v99
	v_rcp_f32_e32 v100, v100
	v_rcp_f32_e32 v101, v101
	v_add_f32_e32 v102, 1.0, v102
	v_add_f32_e32 v103, 1.0, v103
	v_add_f32_e32 v104, 1.0, v104
	v_add_f32_e32 v105, 1.0, v105
	v_lshlrev_b64 v[110:111], 7, v[114:115]
	v_rcp_f32_e32 v102, v102
	v_rcp_f32_e32 v103, v103
	v_rcp_f32_e32 v104, v104
	v_rcp_f32_e32 v105, v105
	v_lshl_add_u64 v[106:107], s[26:27], 0, v[110:111]
	v_lshl_add_u64 v[106:107], v[152:153], 2, v[106:107]
	global_store_dwordx4 v[106:107], v[98:101], off
	global_store_dwordx4 v[106:107], v[102:105], off offset:16
	s_nop 0
	v_add_u32_e32 v98, 32, v150
	s_and_b64 vcc, exec, s[6:7]
	s_mov_b64 s[44:45], -1
	s_cbranch_vccz .LBB0_351
	s_branch .LBB0_352
.LBB0_379:
	s_waitcnt lgkmcnt(0)
	v_pk_mul_f32 v[86:87], v[92:93], v[136:137] op_sel_hi:[1,0]
	v_pk_mul_f32 v[88:89], v[90:91], v[136:137] op_sel_hi:[1,0]
	v_pk_mul_f32 v[90:91], v[84:85], v[136:137] op_sel_hi:[1,0]
	v_pk_mul_f32 v[92:93], v[82:83], v[136:137] op_sel_hi:[1,0]
	v_mul_f32_e32 v82, 0xbfb8aa3b, v88
	v_mul_f32_e32 v83, 0xbfb8aa3b, v89
	v_mul_f32_e32 v84, 0xbfb8aa3b, v86
	v_mul_f32_e32 v85, 0xbfb8aa3b, v87
	v_exp_f32_e32 v82, v82
	v_exp_f32_e32 v83, v83
	v_exp_f32_e32 v84, v84
	v_exp_f32_e32 v85, v85
	v_mul_f32_e32 v86, 0xbfb8aa3b, v92
	v_mul_f32_e32 v87, 0xbfb8aa3b, v93
	v_mul_f32_e32 v88, 0xbfb8aa3b, v90
	v_mul_f32_e32 v89, 0xbfb8aa3b, v91
	v_exp_f32_e32 v86, v86
	v_exp_f32_e32 v87, v87
	v_exp_f32_e32 v88, v88
	v_exp_f32_e32 v89, v89
	v_add_f32_e32 v82, 1.0, v82
	v_add_f32_e32 v83, 1.0, v83
	v_add_f32_e32 v84, 1.0, v84
	v_add_f32_e32 v85, 1.0, v85
	v_ashrrev_i32_e32 v99, 31, v98
	v_rcp_f32_e32 v82, v82
	v_rcp_f32_e32 v83, v83
	v_rcp_f32_e32 v84, v84
	v_rcp_f32_e32 v85, v85
	v_add_f32_e32 v86, 1.0, v86
	v_add_f32_e32 v87, 1.0, v87
	v_add_f32_e32 v88, 1.0, v88
	v_add_f32_e32 v89, 1.0, v89
	v_lshlrev_b64 v[94:95], 7, v[98:99]
	v_rcp_f32_e32 v86, v86
	v_rcp_f32_e32 v87, v87
	v_rcp_f32_e32 v88, v88
	v_rcp_f32_e32 v89, v89
	v_lshl_add_u64 v[90:91], s[26:27], 0, v[94:95]
	v_lshl_add_u64 v[90:91], v[152:153], 2, v[90:91]
	global_store_dwordx4 v[90:91], v[82:85], off
	global_store_dwordx4 v[90:91], v[86:89], off offset:16
	s_nop 0
	v_add_u32_e32 v82, 48, v150
	s_and_b64 vcc, exec, s[6:7]
	s_mov_b64 s[44:45], -1
	s_cbranch_vccz .LBB0_355
	s_branch .LBB0_356
; __device__ __forceinline__ float fsigmoid(float x) { return __builtin_amdgcn_rcpf(1.0f + __expf(-x)); }
;     __device__ __forceinline__ void operator()(const f32x4 (&acc)[2][2][4][2], const Unit& u, int wr, int wc, int fr, int fq) const {
;     ...
;                     if (wc == 0) {
;                         const f32x4 a0 = acc[ai][0][m][0] * rs, a1 = acc[ai][0][m][1] * rs;
;                         float* gp = (float*)(ws + WS_G) + (size_t)row * 32 + 8 * fq;
;                         *(f32x4*)gp = (f32x4){fsigmoid(a0[0]), fsigmoid(a0[1]), fsigmoid(a0[2]), fsigmoid(a0[3])};
;                         *(f32x4*)(gp + 4) = (f32x4){fsigmoid(a1[0]), fsigmoid(a1[1]), fsigmoid(a1[2]), fsigmoid(a1[3])};
;                     }
.LBB0_380:
	s_waitcnt lgkmcnt(0)
	v_mov_b32_e32 v70, v137
	v_pk_mul_f32 v[72:73], v[76:77], v[70:71] op_sel_hi:[1,0]
	v_pk_mul_f32 v[74:75], v[74:75], v[70:71] op_sel_hi:[1,0]
	v_pk_mul_f32 v[76:77], v[68:69], v[70:71] op_sel_hi:[1,0]
	v_pk_mul_f32 v[70:71], v[66:67], v[70:71] op_sel_hi:[1,0]
	v_mul_f32_e32 v66, 0xbfb8aa3b, v74
	v_mul_f32_e32 v67, 0xbfb8aa3b, v75
	v_mul_f32_e32 v68, 0xbfb8aa3b, v72
	v_mul_f32_e32 v69, 0xbfb8aa3b, v73
	v_exp_f32_e32 v66, v66
	v_exp_f32_e32 v67, v67
	v_exp_f32_e32 v68, v68
	v_exp_f32_e32 v69, v69
	v_mul_f32_e32 v70, 0xbfb8aa3b, v70
	v_mul_f32_e32 v71, 0xbfb8aa3b, v71
	v_mul_f32_e32 v72, 0xbfb8aa3b, v76
	v_mul_f32_e32 v73, 0xbfb8aa3b, v77
	v_exp_f32_e32 v70, v70
	v_exp_f32_e32 v71, v71
	v_exp_f32_e32 v72, v72
	v_exp_f32_e32 v73, v73
	v_add_f32_e32 v66, 1.0, v66
	v_add_f32_e32 v67, 1.0, v67
	v_add_f32_e32 v68, 1.0, v68
	v_add_f32_e32 v69, 1.0, v69
	v_ashrrev_i32_e32 v83, 31, v82
	v_rcp_f32_e32 v66, v66
	v_rcp_f32_e32 v67, v67
	v_rcp_f32_e32 v68, v68
	v_rcp_f32_e32 v69, v69
	v_add_f32_e32 v70, 1.0, v70
	v_add_f32_e32 v71, 1.0, v71
	v_add_f32_e32 v72, 1.0, v72
	v_add_f32_e32 v73, 1.0, v73
	v_lshlrev_b64 v[74:75], 7, v[82:83]
	v_rcp_f32_e32 v70, v70
	v_rcp_f32_e32 v71, v71
	v_rcp_f32_e32 v72, v72
	v_rcp_f32_e32 v73, v73
	v_lshl_add_u64 v[74:75], s[26:27], 0, v[74:75]
	v_lshl_add_u64 v[74:75], v[152:153], 2, v[74:75]
	global_store_dwordx4 v[74:75], v[66:69], off
	global_store_dwordx4 v[74:75], v[70:73], off offset:16
	s_nop 0
	v_add_u32_e32 v66, 0x80, v150
	s_and_b64 vcc, exec, s[6:7]
	s_mov_b64 s[44:45], -1
	s_cbranch_vccz .LBB0_359
	s_branch .LBB0_360
.LBB0_381:
	s_waitcnt lgkmcnt(0)
	v_pk_mul_f32 v[54:55], v[60:61], v[130:131] op_sel_hi:[1,0]
	v_pk_mul_f32 v[56:57], v[58:59], v[130:131] op_sel_hi:[1,0]
	v_pk_mul_f32 v[58:59], v[52:53], v[130:131] op_sel_hi:[1,0]
	v_pk_mul_f32 v[60:61], v[50:51], v[130:131] op_sel_hi:[1,0]
	v_mul_f32_e32 v50, 0xbfb8aa3b, v56
	v_mul_f32_e32 v51, 0xbfb8aa3b, v57
	v_mul_f32_e32 v52, 0xbfb8aa3b, v54
	v_mul_f32_e32 v53, 0xbfb8aa3b, v55
	v_exp_f32_e32 v50, v50
	v_exp_f32_e32 v51, v51
	v_exp_f32_e32 v52, v52
	v_exp_f32_e32 v53, v53
	v_mul_f32_e32 v54, 0xbfb8aa3b, v60
	v_mul_f32_e32 v55, 0xbfb8aa3b, v61
	v_mul_f32_e32 v56, 0xbfb8aa3b, v58
	v_mul_f32_e32 v57, 0xbfb8aa3b, v59
	v_exp_f32_e32 v54, v54
	v_exp_f32_e32 v55, v55
	v_exp_f32_e32 v56, v56
	v_exp_f32_e32 v57, v57
	v_add_f32_e32 v50, 1.0, v50
	v_add_f32_e32 v51, 1.0, v51
	v_add_f32_e32 v52, 1.0, v52
	v_add_f32_e32 v53, 1.0, v53
	v_ashrrev_i32_e32 v67, 31, v66
	v_rcp_f32_e32 v50, v50
	v_rcp_f32_e32 v51, v51
	v_rcp_f32_e32 v52, v52
	v_rcp_f32_e32 v53, v53
	v_add_f32_e32 v54, 1.0, v54
	v_add_f32_e32 v55, 1.0, v55
	v_add_f32_e32 v56, 1.0, v56
	v_add_f32_e32 v57, 1.0, v57
	v_lshlrev_b64 v[62:63], 7, v[66:67]
	v_rcp_f32_e32 v54, v54
	v_rcp_f32_e32 v55, v55
	v_rcp_f32_e32 v56, v56
	v_rcp_f32_e32 v57, v57
	v_lshl_add_u64 v[58:59], s[26:27], 0, v[62:63]
	v_lshl_add_u64 v[58:59], v[152:153], 2, v[58:59]
	global_store_dwordx4 v[58:59], v[50:53], off
	global_store_dwordx4 v[58:59], v[54:57], off offset:16
	s_nop 0
	v_add_u32_e32 v50, 0x90, v150
	s_and_b64 vcc, exec, s[6:7]
	s_mov_b64 s[44:45], -1
	s_cbranch_vccz .LBB0_363
	s_branch .LBB0_364
; __device__ __forceinline__ float fsigmoid(float x) { return __builtin_amdgcn_rcpf(1.0f + __expf(-x)); }
;     __device__ __forceinline__ void operator()(const f32x4 (&acc)[2][2][4][2], const Unit& u, int wr, int wc, int fr, int fq) const {
;     ...
;                     if (wc == 0) {
;                         const f32x4 a0 = acc[ai][0][m][0] * rs, a1 = acc[ai][0][m][1] * rs;
;                         float* gp = (float*)(ws + WS_G) + (size_t)row * 32 + 8 * fq;
;                         *(f32x4*)gp = (f32x4){fsigmoid(a0[0]), fsigmoid(a0[1]), fsigmoid(a0[2]), fsigmoid(a0[3])};
;                         *(f32x4*)(gp + 4) = (f32x4){fsigmoid(a1[0]), fsigmoid(a1[1]), fsigmoid(a1[2]), fsigmoid(a1[3])};
;                     }
.LBB0_382:
	s_waitcnt lgkmcnt(0)
	v_pk_mul_f32 v[38:39], v[44:45], v[130:131] op_sel:[0,1]
	v_pk_mul_f32 v[40:41], v[42:43], v[130:131] op_sel:[0,1]
	v_pk_mul_f32 v[42:43], v[36:37], v[130:131] op_sel:[0,1]
	v_pk_mul_f32 v[44:45], v[34:35], v[130:131] op_sel:[0,1]
	v_mul_f32_e32 v34, 0xbfb8aa3b, v40
	v_mul_f32_e32 v35, 0xbfb8aa3b, v41
	v_mul_f32_e32 v36, 0xbfb8aa3b, v38
	v_mul_f32_e32 v37, 0xbfb8aa3b, v39
	v_exp_f32_e32 v34, v34
	v_exp_f32_e32 v35, v35
	v_exp_f32_e32 v36, v36
	v_exp_f32_e32 v37, v37
	v_mul_f32_e32 v38, 0xbfb8aa3b, v44
	v_mul_f32_e32 v39, 0xbfb8aa3b, v45
	v_mul_f32_e32 v40, 0xbfb8aa3b, v42
	v_mul_f32_e32 v41, 0xbfb8aa3b, v43
	v_exp_f32_e32 v38, v38
	v_exp_f32_e32 v39, v39
	v_exp_f32_e32 v40, v40
	v_exp_f32_e32 v41, v41
	v_add_f32_e32 v34, 1.0, v34
	v_add_f32_e32 v35, 1.0, v35
	v_add_f32_e32 v36, 1.0, v36
	v_add_f32_e32 v37, 1.0, v37
	v_ashrrev_i32_e32 v51, 31, v50
	v_rcp_f32_e32 v34, v34
	v_rcp_f32_e32 v35, v35
	v_rcp_f32_e32 v36, v36
	v_rcp_f32_e32 v37, v37
	v_add_f32_e32 v38, 1.0, v38
	v_add_f32_e32 v39, 1.0, v39
	v_add_f32_e32 v40, 1.0, v40
	v_add_f32_e32 v41, 1.0, v41
	v_lshlrev_b64 v[46:47], 7, v[50:51]
	v_rcp_f32_e32 v38, v38
	v_rcp_f32_e32 v39, v39
	v_rcp_f32_e32 v40, v40
	v_rcp_f32_e32 v41, v41
	v_lshl_add_u64 v[42:43], s[26:27], 0, v[46:47]
	v_lshl_add_u64 v[42:43], v[152:153], 2, v[42:43]
	global_store_dwordx4 v[42:43], v[34:37], off
	global_store_dwordx4 v[42:43], v[38:41], off offset:16
	s_nop 0
	v_add_u32_e32 v34, 0xa0, v150
	s_and_b64 vcc, exec, s[6:7]
	s_mov_b64 s[44:45], -1
	s_cbranch_vccz .LBB0_367
	s_branch .LBB0_368
.LBB0_383:
	s_waitcnt lgkmcnt(0)
	v_pk_mul_f32 v[22:23], v[28:29], v[132:133] op_sel_hi:[1,0]
	v_pk_mul_f32 v[24:25], v[26:27], v[132:133] op_sel_hi:[1,0]
	v_pk_mul_f32 v[26:27], v[20:21], v[132:133] op_sel_hi:[1,0]
	v_pk_mul_f32 v[28:29], v[18:19], v[132:133] op_sel_hi:[1,0]
	v_mul_f32_e32 v18, 0xbfb8aa3b, v24
	v_mul_f32_e32 v19, 0xbfb8aa3b, v25
	v_mul_f32_e32 v20, 0xbfb8aa3b, v22
	v_mul_f32_e32 v21, 0xbfb8aa3b, v23
	v_exp_f32_e32 v18, v18
	v_exp_f32_e32 v19, v19
	v_exp_f32_e32 v20, v20
	v_exp_f32_e32 v21, v21
	v_mul_f32_e32 v22, 0xbfb8aa3b, v28
	v_mul_f32_e32 v23, 0xbfb8aa3b, v29
	v_mul_f32_e32 v24, 0xbfb8aa3b, v26
	v_mul_f32_e32 v25, 0xbfb8aa3b, v27
	v_exp_f32_e32 v22, v22
	v_exp_f32_e32 v23, v23
	v_exp_f32_e32 v24, v24
	v_exp_f32_e32 v25, v25
	v_add_f32_e32 v18, 1.0, v18
	v_add_f32_e32 v19, 1.0, v19
	v_add_f32_e32 v20, 1.0, v20
	v_add_f32_e32 v21, 1.0, v21
	v_ashrrev_i32_e32 v35, 31, v34
	v_rcp_f32_e32 v18, v18
	v_rcp_f32_e32 v19, v19
	v_rcp_f32_e32 v20, v20
	v_rcp_f32_e32 v21, v21
	v_add_f32_e32 v22, 1.0, v22
	v_add_f32_e32 v23, 1.0, v23
	v_add_f32_e32 v24, 1.0, v24
	v_add_f32_e32 v25, 1.0, v25
	v_lshlrev_b64 v[30:31], 7, v[34:35]
	v_rcp_f32_e32 v22, v22
	v_rcp_f32_e32 v23, v23
	v_rcp_f32_e32 v24, v24
	v_rcp_f32_e32 v25, v25
	v_lshl_add_u64 v[26:27], s[26:27], 0, v[30:31]
	v_lshl_add_u64 v[26:27], v[152:153], 2, v[26:27]
	global_store_dwordx4 v[26:27], v[18:21], off
	global_store_dwordx4 v[26:27], v[22:25], off offset:16
	s_nop 0
	v_add_u32_e32 v18, 0xb0, v150
	s_and_b64 vcc, exec, s[6:7]
	s_mov_b64 s[6:7], -1
	s_cbranch_vccz .LBB0_371
	s_branch .LBB0_372
.LBB0_384:
	s_waitcnt lgkmcnt(0)
	v_mov_b32_e32 v2, v133
	v_pk_mul_f32 v[4:5], v[12:13], v[2:3] op_sel_hi:[1,0]
	v_pk_mul_f32 v[10:11], v[10:11], v[2:3] op_sel_hi:[1,0]
	v_pk_mul_f32 v[8:9], v[8:9], v[2:3] op_sel_hi:[1,0]
	v_pk_mul_f32 v[6:7], v[6:7], v[2:3] op_sel_hi:[1,0]
	v_mul_f32_e32 v2, 0xbfb8aa3b, v10
	v_mul_f32_e32 v3, 0xbfb8aa3b, v11
	v_mul_f32_e32 v4, 0xbfb8aa3b, v4
	v_mul_f32_e32 v5, 0xbfb8aa3b, v5
	v_exp_f32_e32 v2, v2
	v_exp_f32_e32 v3, v3
	v_exp_f32_e32 v4, v4
	v_exp_f32_e32 v5, v5
	v_mul_f32_e32 v6, 0xbfb8aa3b, v6
	v_mul_f32_e32 v7, 0xbfb8aa3b, v7
	v_mul_f32_e32 v8, 0xbfb8aa3b, v8
	v_mul_f32_e32 v9, 0xbfb8aa3b, v9
	v_exp_f32_e32 v6, v6
	v_exp_f32_e32 v7, v7
	v_exp_f32_e32 v8, v8
	v_exp_f32_e32 v9, v9
	v_add_f32_e32 v2, 1.0, v2
	v_add_f32_e32 v3, 1.0, v3
	v_add_f32_e32 v4, 1.0, v4
	v_add_f32_e32 v5, 1.0, v5
	v_ashrrev_i32_e32 v19, 31, v18
	v_rcp_f32_e32 v2, v2
	v_rcp_f32_e32 v3, v3
	v_rcp_f32_e32 v4, v4
	v_rcp_f32_e32 v5, v5
	v_add_f32_e32 v6, 1.0, v6
	v_add_f32_e32 v7, 1.0, v7
	v_add_f32_e32 v8, 1.0, v8
	v_add_f32_e32 v9, 1.0, v9
	v_lshlrev_b64 v[10:11], 7, v[18:19]
	v_rcp_f32_e32 v6, v6
	v_rcp_f32_e32 v7, v7
	v_rcp_f32_e32 v8, v8
	v_rcp_f32_e32 v9, v9
	v_lshl_add_u64 v[10:11], s[26:27], 0, v[10:11]
	v_lshl_add_u64 v[10:11], v[152:153], 2, v[10:11]
	global_store_dwordx4 v[10:11], v[2:5], off
	global_store_dwordx4 v[10:11], v[6:9], off offset:16
	s_mov_b64 s[8:9], -1
	s_andn2_b64 vcc, exec, s[42:43]
	s_mov_b64 s[6:7], -1
	s_cbranch_vccnz .LBB0_330
	s_branch .LBB0_375

; __device__ __forceinline__ void conv_phase(const Args& a, unsigned char* ws, int l, LAS unsigned char* lds, const int tid, const int bid) {
;     ...
;         const f32x4 biasA = *(const f32x4*)(a.in[14] + l * 512 + cA), biasB = *(const f32x4*)(a.in[14] + l * 512 + cB);
;         const f32x4 lgA = *(const f32x4*)(a.in[15] + l * 512 + cA), lgB = *(const f32x4*)(a.in[15] + l * 512 + cB);
;         const f32x4 lbA = *(const f32x4*)(a.in[16] + l * 512 + cA), lbB = *(const f32x4*)(a.in[16] + l * 512 + cB);
; #pragma unroll
;         for (int tt = 0; tt < 8; ++tt) {
;             const f32x4 ya = accA[tt] + biasA, yb = accB[tt] + biasB;
;             const float mu = wave_sum((ya[0] + ya[1]) + (ya[2] + ya[3]) + (yb[0] + yb[1]) + (yb[2] + yb[3]), lane) * (1.f / 512);
;             const f32x4 da = ya - mu, db = yb - mu;
;             const float var = wave_sum((da[0] * da[0] + da[1] * da[1]) + (da[2] * da[2] + da[3] * da[3]) + (db[0] * db[0] + db[1] * db[1]) + (db[2] * db[2] + db[3] * db[3]), lane) * (1.f / 512);
;             const float rs = rsqrtf(var + EPS);
.LBB0_389:
	v_ashrrev_i32_e32 v123, 31, v122
	v_lshlrev_b64 v[28:29], 2, v[122:123]
	v_lshl_add_u64 v[30:31], s[40:41], 0, v[28:29]
	global_load_dwordx4 v[44:47], v[30:31], off
	global_load_dwordx4 v[40:43], v[30:31], off offset:1024
	v_bitop3_b32 v1, v122, 4, v240 bitop3:0x6c
	v_bitop3_b32 v80, v122, 8, v240 bitop3:0x6c
	v_bitop3_b32 v79, v122, 16, v240 bitop3:0x6c
	v_bitop3_b32 v78, v122, 32, v240 bitop3:0x6c
	v_bitop3_b32 v76, v122, 64, v240 bitop3:0x6c
	v_bitop3_b32 v77, v122, s66, v240 bitop3:0x6c
	s_mov_b32 s6, 0x358637bd
	s_mov_b32 s10, 0x3b000000
	s_mov_b64 s[8:9], 0x15a00400
	s_waitcnt vmcnt(1)
	v_pk_add_f32 v[68:69], v[204:205], v[44:45]
	v_pk_add_f32 v[70:71], v[206:207], v[46:47]
	s_waitcnt vmcnt(0)
	v_pk_add_f32 v[72:73], v[26:27], v[42:43]
	v_pk_add_f32 v[74:75], v[24:25], v[40:41]
	v_pk_add_f32 v[60:61], v[200:201], v[44:45]
	v_pk_add_f32 v[64:65], v[202:203], v[46:47]
	v_pk_add_f32 v[62:63], v[22:23], v[42:43]
	v_pk_add_f32 v[66:67], v[20:21], v[40:41]
	v_pk_mov_b32 v[20:21], v[68:69], v[70:71] op_sel:[1,0]
	v_mov_b32_e32 v22, v68
	v_mov_b32_e32 v23, v71
	v_mov_b32_e32 v24, v72
	v_mov_b32_e32 v25, v74
	v_mov_b32_e32 v26, v73
	v_mov_b32_e32 v27, v75
	v_pk_mov_b32 v[30:31], v[60:61], v[64:65] op_sel:[1,0]
	v_mov_b32_e32 v36, v60
	v_mov_b32_e32 v37, v65
	v_mov_b32_e32 v38, v62
	v_mov_b32_e32 v39, v66
	v_mov_b32_e32 v52, v63
	v_mov_b32_e32 v53, v67
	v_pk_add_f32 v[20:21], v[20:21], v[22:23]
	v_pk_add_f32 v[22:23], v[24:25], v[26:27]
	v_pk_add_f32 v[24:25], v[30:31], v[36:37]
	v_pk_add_f32 v[26:27], v[38:39], v[52:53]
	v_add_f32_e32 v20, v20, v21
	v_add_f32_e32 v21, v24, v25
	v_add_f32_e32 v20, v20, v23
	v_add_f32_e32 v21, v21, v27
	v_add_f32_e32 v20, v22, v20
	v_add_f32_e32 v21, v26, v21
	ds_bpermute_b32 v22, v1, v20
	ds_bpermute_b32 v23, v1, v21
	v_lshl_add_u64 v[24:25], s[42:43], 0, v[28:29]
	v_lshl_add_u64 v[28:29], s[44:45], 0, v[28:29]
	v_pk_add_f32 v[50:51], v[50:51], v[42:43]
	s_waitcnt lgkmcnt(1)
	v_add_f32_e32 v20, v20, v22
	s_waitcnt lgkmcnt(0)
	v_add_f32_e32 v21, v21, v23
	ds_bpermute_b32 v22, v80, v20
	ds_bpermute_b32 v23, v80, v21
	v_pk_add_f32 v[48:49], v[48:49], v[40:41]
	v_pk_add_f32 v[34:35], v[34:35], v[42:43]
	v_pk_add_f32 v[32:33], v[32:33], v[40:41]
	s_waitcnt lgkmcnt(1)
	v_add_f32_e32 v20, v20, v22
	s_waitcnt lgkmcnt(0)
	v_add_f32_e32 v21, v21, v23
	ds_bpermute_b32 v22, v79, v20
	ds_bpermute_b32 v23, v79, v21
	v_pk_add_f32 v[18:19], v[18:19], v[42:43]
	v_pk_add_f32 v[16:17], v[16:17], v[40:41]
	v_pk_add_f32 v[14:15], v[14:15], v[42:43]
	s_waitcnt lgkmcnt(1)
	v_add_f32_e32 v20, v20, v22
	s_waitcnt lgkmcnt(0)
	v_add_f32_e32 v21, v21, v23
	ds_bpermute_b32 v22, v78, v20
	ds_bpermute_b32 v23, v78, v21
	v_pk_add_f32 v[12:13], v[12:13], v[40:41]
	v_pk_add_f32 v[10:11], v[10:11], v[42:43]
	v_pk_add_f32 v[8:9], v[8:9], v[40:41]
	s_waitcnt lgkmcnt(1)
	v_add_f32_e32 v20, v20, v22
	s_waitcnt lgkmcnt(0)
	v_add_f32_e32 v21, v21, v23
	ds_bpermute_b32 v22, v76, v20
	ds_bpermute_b32 v23, v76, v21
	v_pk_add_f32 v[2:3], v[2:3], v[44:45]
	v_pk_add_f32 v[6:7], v[6:7], v[42:43]
	v_pk_add_f32 v[4:5], v[4:5], v[40:41]
	s_waitcnt lgkmcnt(1)
	v_add_f32_e32 v52, v20, v22
	s_waitcnt lgkmcnt(0)
	v_add_f32_e32 v53, v21, v23
	global_load_dwordx4 v[20:23], v[24:25], off
	s_nop 0
	global_load_dwordx4 v[24:27], v[24:25], off offset:1024
	s_nop 0
	global_load_dwordx4 v[36:39], v[28:29], off
	s_nop 0
	global_load_dwordx4 v[28:31], v[28:29], off offset:1024
	ds_bpermute_b32 v54, v77, v52
	ds_bpermute_b32 v55, v77, v53
	v_mov_b32_e32 v42, v2
	s_waitcnt lgkmcnt(1)
	v_add_f32_e32 v52, v52, v54
	s_waitcnt lgkmcnt(0)
	v_add_f32_e32 v53, v53, v55
	v_fmamk_f32 v69, v52, 0xbb000000, v69
	v_fmac_f32_e32 v68, 0xbb000000, v52
	v_fmamk_f32 v71, v52, 0xbb000000, v71
	v_fmac_f32_e32 v70, 0xbb000000, v52
	v_fmamk_f32 v75, v52, 0xbb000000, v75
	v_fmac_f32_e32 v74, 0xbb000000, v52
	v_fmamk_f32 v73, v52, 0xbb000000, v73
	v_fmac_f32_e32 v72, 0xbb000000, v52
	v_fmamk_f32 v61, v53, 0xbb000000, v61
	v_fmac_f32_e32 v60, 0xbb000000, v53
	v_fmamk_f32 v65, v53, 0xbb000000, v65
	v_fmac_f32_e32 v64, 0xbb000000, v53
	v_fmamk_f32 v67, v53, 0xbb000000, v67
	v_fmac_f32_e32 v66, 0xbb000000, v53
	v_fmamk_f32 v63, v53, 0xbb000000, v63
	v_fmac_f32_e32 v62, 0xbb000000, v53
	v_pk_mul_f32 v[52:53], v[70:71], v[70:71]
	v_pk_mul_f32 v[54:55], v[68:69], v[68:69]
	v_pk_mul_f32 v[56:57], v[72:73], v[72:73]
	v_pk_mul_f32 v[58:59], v[74:75], v[74:75]
	v_pk_mul_f32 v[82:83], v[64:65], v[64:65]
	v_pk_mul_f32 v[84:85], v[60:61], v[60:61]
	v_pk_mul_f32 v[86:87], v[62:63], v[62:63]
	v_pk_mul_f32 v[88:89], v[66:67], v[66:67]
	v_pk_mov_b32 v[90:91], v[54:55], v[52:53] op_sel:[1,0]
	v_mov_b32_e32 v55, v53
	v_mov_b32_e32 v52, v56
	v_mov_b32_e32 v53, v58
	v_mov_b32_e32 v58, v57
	v_pk_mov_b32 v[56:57], v[84:85], v[82:83] op_sel:[1,0]
	v_mov_b32_e32 v85, v83
	v_mov_b32_e32 v82, v86
	v_mov_b32_e32 v83, v88
	v_mov_b32_e32 v88, v87
	v_pk_add_f32 v[54:55], v[90:91], v[54:55]
	v_pk_add_f32 v[56:57], v[56:57], v[84:85]
	v_pk_add_f32 v[52:53], v[52:53], v[58:59]
	v_pk_add_f32 v[58:59], v[82:83], v[88:89]
	v_mov_b32_e32 v82, v56
	v_mov_b32_e32 v83, v54
	v_mov_b32_e32 v54, v57
	v_mov_b32_e32 v56, v59
	v_mov_b32_e32 v57, v53
	v_mov_b32_e32 v59, v52
	v_pk_add_f32 v[52:53], v[82:83], v[54:55]
	s_nop 0
	v_pk_add_f32 v[52:53], v[56:57], v[52:53]
	v_mov_b64_e32 v[56:57], s[6:7]
	v_pk_add_f32 v[52:53], v[58:59], v[52:53]
	ds_bpermute_b32 v55, v1, v53
	ds_bpermute_b32 v54, v1, v52
	s_mov_b64 s[6:7], 0x200
	s_waitcnt lgkmcnt(0)
	v_pk_add_f32 v[52:53], v[52:53], v[54:55]
	ds_bpermute_b32 v55, v80, v53
	ds_bpermute_b32 v54, v80, v52
	s_waitcnt lgkmcnt(0)
; __device__ __forceinline__ unsigned pk2(float lo, float hi) { f32x2_t v = {lo, hi}; bf16x2_t b = __builtin_convertvector(v, bf16x2_t); return __builtin_bit_cast(unsigned, b); }
; __device__ __forceinline__ float fsilu(float x) { return x * fsigmoid(x); }
; __device__ __forceinline__ void conv_phase(const Args& a, unsigned char* ws, int l, LAS unsigned char* lds, const int tid, const int bid) {
;     ...
; #pragma unroll
;         for (int tt = 0; tt < 8; ++tt) {
;             const f32x4 ya = accA[tt] + biasA, yb = accB[tt] + biasB;
;             const float mu = wave_sum((ya[0] + ya[1]) + (ya[2] + ya[3]) + (yb[0] + yb[1]) + (yb[2] + yb[3]), lane) * (1.f / 512);
;             const f32x4 da = ya - mu, db = yb - mu;
;             const float var = wave_sum((da[0] * da[0] + da[1] * da[1]) + (da[2] * da[2] + da[3] * da[3]) + (db[0] * db[0] + db[1] * db[1]) + (db[2] * db[2] + db[3] * db[3]), lane) * (1.f / 512);
;             const float rs = rsqrtf(var + EPS);
;             const f32x4 za = da * rs * lgA + lbA, zb = db * rs * lgB + lbB;
;             bf16_t* op = ATT + (size_t)(row0 + tt) * 1024 + 512;
;             u32x2 w; w.x = pk2(fsilu(za[0]), fsilu(za[1])); w.y = pk2(fsilu(za[2]), fsilu(za[3])); *(u32x2*)(op + cA) = w;
;             w.x = pk2(fsilu(zb[0]), fsilu(zb[1])); w.y = pk2(fsilu(zb[2]), fsilu(zb[3])); *(u32x2*)(op + cB) = w;
	v_pk_add_f32 v[52:53], v[52:53], v[54:55]
	ds_bpermute_b32 v55, v79, v53
	ds_bpermute_b32 v54, v79, v52
	s_waitcnt lgkmcnt(0)
	v_pk_add_f32 v[52:53], v[52:53], v[54:55]
	ds_bpermute_b32 v55, v78, v53
	ds_bpermute_b32 v54, v78, v52
	s_waitcnt lgkmcnt(0)
	v_pk_add_f32 v[52:53], v[52:53], v[54:55]
	ds_bpermute_b32 v59, v76, v53
	ds_bpermute_b32 v58, v76, v52
	v_add_u32_e32 v54, s48, v179
	v_ashrrev_i32_e32 v55, 31, v54
	v_lshlrev_b64 v[86:87], 11, v[54:55]
	s_waitcnt lgkmcnt(0)
	v_pk_add_f32 v[82:83], v[52:53], v[58:59]
	ds_bpermute_b32 v85, v77, v83
	ds_bpermute_b32 v84, v77, v82
	v_lshlrev_b64 v[52:53], 1, v[122:123]
	v_lshl_add_u64 v[58:59], v[52:53], 0, s[6:7]
	s_mov_b32 s6, 0x15a00000
	s_waitcnt lgkmcnt(0)
	v_pk_add_f32 v[82:83], v[82:83], v[84:85]
	s_nop 0
	v_pk_fma_f32 v[82:83], v[82:83], s[10:11], v[56:57] op_sel_hi:[1,0,0]
	v_lshl_add_u64 v[84:85], s[86:87], 0, v[86:87]
	v_mul_f32_e32 v55, 0x4b800000, v83
	v_cmp_gt_f32_e32 vcc, s67, v83
	v_lshl_add_u64 v[84:85], v[84:85], 0, v[52:53]
	v_lshl_add_u64 v[86:87], v[84:85], 0, s[8:9]
	v_cndmask_b32_e32 v55, v83, v55, vcc
	v_rsq_f32_e32 v55, v55
	s_nop 0
	v_mul_f32_e32 v81, 0x45800000, v55
	v_cndmask_b32_e32 v88, v55, v81, vcc
	v_pk_mul_f32 v[68:69], v[68:69], v[88:89] op_sel_hi:[1,0]
	v_pk_mul_f32 v[70:71], v[70:71], v[88:89] op_sel_hi:[1,0]
	v_pk_mul_f32 v[74:75], v[74:75], v[88:89] op_sel_hi:[1,0]
	s_waitcnt vmcnt(1)
	v_pk_fma_f32 v[70:71], v[22:23], v[70:71], v[38:39]
	v_pk_fma_f32 v[68:69], v[20:21], v[68:69], v[36:37]
	v_pk_mul_f32 v[72:73], v[72:73], v[88:89] op_sel_hi:[1,0]
	s_waitcnt vmcnt(0)
	v_pk_fma_f32 v[74:75], v[24:25], v[74:75], v[28:29]
	v_mul_f32_e32 v55, 0xbfb8aa3b, v68
	v_mul_f32_e32 v81, 0xbfb8aa3b, v69
	v_mul_f32_e32 v83, 0xbfb8aa3b, v70
	v_mul_f32_e32 v88, 0xbfb8aa3b, v71
	v_mul_f32_e32 v89, 0xbfb8aa3b, v74
	v_mul_f32_e32 v90, 0xbfb8aa3b, v75
	v_exp_f32_e32 v55, v55
	v_exp_f32_e32 v81, v81
	v_exp_f32_e32 v83, v83
	v_exp_f32_e32 v88, v88
	v_exp_f32_e32 v89, v89
	v_exp_f32_e32 v90, v90
	v_add_f32_e32 v55, 1.0, v55
	v_add_f32_e32 v81, 1.0, v81
	v_add_f32_e32 v83, 1.0, v83
	v_add_f32_e32 v91, 1.0, v88
	v_add_f32_e32 v92, 1.0, v89
	v_add_f32_e32 v93, 1.0, v90
	v_rcp_f32_e32 v88, v55
	v_rcp_f32_e32 v89, v81
	v_rcp_f32_e32 v90, v83
	v_rcp_f32_e32 v91, v91
	v_pk_fma_f32 v[72:73], v[26:27], v[72:73], v[30:31]
	v_pk_mul_f32 v[68:69], v[68:69], v[88:89]
	v_mul_f32_e32 v55, 0xbfb8aa3b, v72
	v_pk_mul_f32 v[70:71], v[70:71], v[90:91]
	v_cvt_pk_bf16_f32 v68, v68, v69
	v_cvt_pk_bf16_f32 v69, v70, v71
	v_add_co_u32_e32 v70, vcc, s6, v84
	v_exp_f32_e32 v55, v55
	s_nop 0
	v_addc_co_u32_e32 v71, vcc, 0, v85, vcc
	global_store_dwordx2 v[70:71], v[68:69], off offset:1024
	v_mul_f32_e32 v70, 0xbfb8aa3b, v73
	v_exp_f32_e32 v71, v70
	v_add_f32_e32 v55, 1.0, v55
	v_rcp_f32_e32 v70, v55
	v_rcp_f32_e32 v92, v92
	v_add_f32_e32 v55, 1.0, v71
	v_rcp_f32_e32 v93, v93
	v_rcp_f32_e32 v71, v55
	v_mul_f32_e32 v55, 0x4b800000, v82
	v_cmp_gt_f32_e32 vcc, s67, v82
	v_pk_mul_f32 v[68:69], v[74:75], v[92:93]
	v_pk_mul_f32 v[70:71], v[72:73], v[70:71]
	v_cndmask_b32_e32 v55, v82, v55, vcc
	v_rsq_f32_e32 v55, v55
	v_cvt_pk_bf16_f32 v68, v68, v69
	v_cvt_pk_bf16_f32 v69, v70, v71
	global_store_dwordx2 v[86:87], v[68:69], off offset:512
	v_mul_f32_e32 v68, 0x45800000, v55
	v_cndmask_b32_e32 v68, v55, v68, vcc
	v_pk_mul_f32 v[60:61], v[60:61], v[68:69] op_sel_hi:[1,0]
	v_pk_mul_f32 v[64:65], v[64:65], v[68:69] op_sel_hi:[1,0]
	v_pk_fma_f32 v[72:73], v[20:21], v[60:61], v[36:37]
	v_pk_fma_f32 v[70:71], v[22:23], v[64:65], v[38:39]
	v_mul_f32_e32 v55, 0xbfb8aa3b, v72
	v_pk_mul_f32 v[64:65], v[66:67], v[68:69] op_sel_hi:[1,0]
	v_exp_f32_e32 v55, v55
	v_mul_f32_e32 v66, 0xbfb8aa3b, v73
	v_exp_f32_e32 v66, v66
	v_pk_mul_f32 v[60:61], v[62:63], v[68:69] op_sel_hi:[1,0]
	v_pk_fma_f32 v[62:63], v[24:25], v[64:65], v[28:29]
	v_or_b32_e32 v64, 1, v54
	v_ashrrev_i32_e32 v65, 31, v64
	v_lshlrev_b64 v[64:65], 11, v[64:65]
	v_add_f32_e32 v55, 1.0, v55
	v_lshl_add_u64 v[68:69], s[86:87], 0, v[64:65]
	v_rcp_f32_e32 v74, v55
	v_add_f32_e32 v55, 1.0, v66
	v_pk_add_f32 v[64:65], v[128:129], v[44:45]
	v_pk_add_f32 v[66:67], v[130:131], v[46:47]
	v_mov_b32_e32 v84, v64
	v_pk_mov_b32 v[82:83], v[64:65], v[66:67] op_sel:[1,0]
	v_mov_b32_e32 v85, v67
	v_pk_add_f32 v[82:83], v[82:83], v[84:85]
	v_mov_b32_e32 v84, v50
	v_mov_b32_e32 v85, v48
	v_mov_b32_e32 v86, v51
	v_mov_b32_e32 v87, v49
	v_rcp_f32_e32 v75, v55
	v_pk_add_f32 v[84:85], v[84:85], v[86:87]
	v_add_f32_e32 v55, v82, v83
	v_add_f32_e32 v55, v55, v85
	v_add_f32_e32 v55, v84, v55
	ds_bpermute_b32 v81, v1, v55
	v_mul_f32_e32 v82, 0xbfb8aa3b, v70
	v_mul_f32_e32 v83, 0xbfb8aa3b, v71
	v_exp_f32_e32 v82, v82
	v_exp_f32_e32 v83, v83
	s_waitcnt lgkmcnt(0)
	v_add_f32_e32 v55, v55, v81
	ds_bpermute_b32 v81, v80, v55
	v_add_f32_e32 v82, 1.0, v82
	v_add_f32_e32 v83, 1.0, v83
	v_rcp_f32_e32 v82, v82
	v_rcp_f32_e32 v83, v83
	s_waitcnt lgkmcnt(0)
	v_add_f32_e32 v55, v55, v81
	ds_bpermute_b32 v81, v79, v55
	v_pk_mul_f32 v[72:73], v[72:73], v[74:75]
	v_pk_mul_f32 v[70:71], v[70:71], v[82:83]
	v_cvt_pk_bf16_f32 v72, v72, v73
	v_cvt_pk_bf16_f32 v73, v70, v71
	s_waitcnt lgkmcnt(0)
	v_add_f32_e32 v55, v55, v81
	ds_bpermute_b32 v70, v78, v55
	v_lshl_add_u64 v[74:75], v[68:69], 0, v[52:53]
	v_mul_f32_e32 v68, 0xbfb8aa3b, v62
	v_exp_f32_e32 v81, v68
	v_pk_add_f32 v[68:69], v[124:125], v[44:45]
	s_waitcnt lgkmcnt(0)
; __device__ __forceinline__ unsigned pk2(float lo, float hi) { f32x2_t v = {lo, hi}; bf16x2_t b = __builtin_convertvector(v, bf16x2_t); return __builtin_bit_cast(unsigned, b); }
; __device__ __forceinline__ float fsilu(float x) { return x * fsigmoid(x); }
; __device__ __forceinline__ void conv_phase(const Args& a, unsigned char* ws, int l, LAS unsigned char* lds, const int tid, const int bid) {
;     ...
; #pragma unroll
;         for (int tt = 0; tt < 8; ++tt) {
;             const f32x4 ya = accA[tt] + biasA, yb = accB[tt] + biasB;
;             const float mu = wave_sum((ya[0] + ya[1]) + (ya[2] + ya[3]) + (yb[0] + yb[1]) + (yb[2] + yb[3]), lane) * (1.f / 512);
;             const f32x4 da = ya - mu, db = yb - mu;
;             const float var = wave_sum((da[0] * da[0] + da[1] * da[1]) + (da[2] * da[2] + da[3] * da[3]) + (db[0] * db[0] + db[1] * db[1]) + (db[2] * db[2] + db[3] * db[3]), lane) * (1.f / 512);
;             const float rs = rsqrtf(var + EPS);
;             const f32x4 za = da * rs * lgA + lbA, zb = db * rs * lgB + lbB;
;             bf16_t* op = ATT + (size_t)(row0 + tt) * 1024 + 512;
;             u32x2 w; w.x = pk2(fsilu(za[0]), fsilu(za[1])); w.y = pk2(fsilu(za[2]), fsilu(za[3])); *(u32x2*)(op + cA) = w;
;             w.x = pk2(fsilu(zb[0]), fsilu(zb[1])); w.y = pk2(fsilu(zb[2]), fsilu(zb[3])); *(u32x2*)(op + cB) = w;
	v_add_f32_e32 v55, v55, v70
	v_pk_add_f32 v[70:71], v[126:127], v[46:47]
	v_mov_b32_e32 v86, v68
	v_pk_mov_b32 v[84:85], v[68:69], v[70:71] op_sel:[1,0]
	v_mov_b32_e32 v87, v71
	v_pk_add_f32 v[84:85], v[84:85], v[86:87]
	v_mov_b32_e32 v86, v34
	v_mov_b32_e32 v87, v32
	v_mov_b32_e32 v88, v35
	v_mov_b32_e32 v89, v33
	v_pk_add_f32 v[86:87], v[86:87], v[88:89]
	v_add_f32_e32 v84, v84, v85
	v_add_f32_e32 v84, v84, v87
	v_add_f32_e32 v84, v86, v84
	ds_bpermute_b32 v85, v1, v84
	ds_bpermute_b32 v90, v76, v55
	v_mul_f32_e32 v87, 0xbfb8aa3b, v63
	v_exp_f32_e32 v96, v87
	v_lshl_add_u64 v[82:83], v[74:75], 0, s[8:9]
	s_waitcnt lgkmcnt(0)
	v_add_f32_e32 v84, v84, v85
	ds_bpermute_b32 v85, v80, v84
	v_add_f32_e32 v55, v55, v90
	ds_bpermute_b32 v86, v77, v55
	v_add_co_u32_e32 v74, vcc, s6, v74
	s_waitcnt lgkmcnt(0)
	v_add_f32_e32 v84, v84, v85
	ds_bpermute_b32 v85, v79, v84
	v_add_f32_e32 v55, v55, v86
	v_fmamk_f32 v65, v55, 0xbb000000, v65
	v_fmac_f32_e32 v64, 0xbb000000, v55
	v_fmamk_f32 v67, v55, 0xbb000000, v67
	s_waitcnt lgkmcnt(0)
	v_add_f32_e32 v90, v84, v85
	ds_bpermute_b32 v91, v78, v90
	v_fmac_f32_e32 v66, 0xbb000000, v55
	v_fmamk_f32 v49, v55, 0xbb000000, v49
	v_fmac_f32_e32 v48, 0xbb000000, v55
	v_fmamk_f32 v51, v55, 0xbb000000, v51
	v_fmac_f32_e32 v50, 0xbb000000, v55
	s_waitcnt lgkmcnt(0)
	v_add_f32_e32 v55, v90, v91
	ds_bpermute_b32 v90, v76, v55
	v_pk_mul_f32 v[84:85], v[66:67], v[66:67]
	v_pk_mul_f32 v[86:87], v[64:65], v[64:65]
	v_addc_co_u32_e32 v75, vcc, 0, v75, vcc
	s_waitcnt lgkmcnt(0)
	v_add_f32_e32 v55, v55, v90
	ds_bpermute_b32 v92, v77, v55
	v_pk_mov_b32 v[88:89], v[86:87], v[84:85] op_sel:[1,0]
	v_mov_b32_e32 v87, v85
	v_pk_add_f32 v[84:85], v[88:89], v[86:87]
	v_pk_mul_f32 v[86:87], v[50:51], v[50:51]
	v_pk_mul_f32 v[88:89], v[48:49], v[48:49]
	s_waitcnt lgkmcnt(0)
	v_add_f32_e32 v55, v55, v92
	v_mov_b32_e32 v90, v86
	v_mov_b32_e32 v91, v88
	v_mov_b32_e32 v88, v87
	v_fmamk_f32 v69, v55, 0xbb000000, v69
	v_fmac_f32_e32 v68, 0xbb000000, v55
	v_fmamk_f32 v71, v55, 0xbb000000, v71
	v_fmac_f32_e32 v70, 0xbb000000, v55
	v_pk_add_f32 v[86:87], v[90:91], v[88:89]
	v_pk_mul_f32 v[88:89], v[70:71], v[70:71]
	v_pk_mul_f32 v[90:91], v[68:69], v[68:69]
	v_fmamk_f32 v33, v55, 0xbb000000, v33
	v_fmac_f32_e32 v32, 0xbb000000, v55
	v_fmamk_f32 v35, v55, 0xbb000000, v35
	v_fmac_f32_e32 v34, 0xbb000000, v55
	v_pk_mov_b32 v[92:93], v[90:91], v[88:89] op_sel:[1,0]
	v_mov_b32_e32 v91, v89
	v_pk_add_f32 v[88:89], v[92:93], v[90:91]
	v_pk_mul_f32 v[90:91], v[34:35], v[34:35]
	v_pk_mul_f32 v[92:93], v[32:33], v[32:33]
	v_mov_b32_e32 v94, v90
	v_mov_b32_e32 v95, v92
	v_mov_b32_e32 v92, v91
	v_pk_add_f32 v[90:91], v[94:95], v[92:93]
	v_mov_b32_e32 v92, v88
	v_mov_b32_e32 v93, v84
	v_mov_b32_e32 v84, v89
	v_pk_add_f32 v[84:85], v[92:93], v[84:85]
	v_mov_b32_e32 v88, v91
	v_mov_b32_e32 v89, v87
	v_pk_add_f32 v[84:85], v[88:89], v[84:85]
	v_mov_b32_e32 v91, v86
	v_pk_add_f32 v[84:85], v[90:91], v[84:85]
	ds_bpermute_b32 v87, v1, v85
	ds_bpermute_b32 v86, v1, v84
	global_store_dwordx2 v[74:75], v[72:73], off offset:1024
	v_add_f32_e32 v55, 1.0, v81
	v_pk_fma_f32 v[60:61], v[26:27], v[60:61], v[30:31]
	v_rcp_f32_e32 v88, v55
	s_waitcnt lgkmcnt(0)
	v_pk_add_f32 v[84:85], v[84:85], v[86:87]
	ds_bpermute_b32 v87, v80, v85
	ds_bpermute_b32 v86, v80, v84
	v_add_f32_e32 v55, 1.0, v96
	v_rcp_f32_e32 v89, v55
	v_mul_f32_e32 v55, 0xbfb8aa3b, v60
	v_exp_f32_e32 v55, v55
	s_waitcnt lgkmcnt(0)
	v_pk_add_f32 v[72:73], v[84:85], v[86:87]
	ds_bpermute_b32 v75, v79, v73
	ds_bpermute_b32 v74, v79, v72
	v_mul_f32_e32 v81, 0xbfb8aa3b, v61
	v_exp_f32_e32 v81, v81
	v_add_f32_e32 v55, 1.0, v55
	v_rcp_f32_e32 v84, v55
	s_waitcnt lgkmcnt(0)
	v_pk_add_f32 v[72:73], v[72:73], v[74:75]
	ds_bpermute_b32 v75, v78, v73
	ds_bpermute_b32 v74, v78, v72
	v_add_f32_e32 v55, 1.0, v81
	v_rcp_f32_e32 v85, v55
	v_pk_mul_f32 v[62:63], v[62:63], v[88:89]
	s_waitcnt lgkmcnt(0)
	v_pk_add_f32 v[72:73], v[72:73], v[74:75]
	ds_bpermute_b32 v75, v76, v73
	ds_bpermute_b32 v74, v76, v72
	v_pk_mul_f32 v[60:61], v[60:61], v[84:85]
	v_cvt_pk_bf16_f32 v62, v62, v63
	v_cvt_pk_bf16_f32 v63, v60, v61
	global_store_dwordx2 v[82:83], v[62:63], off offset:512
	s_waitcnt lgkmcnt(0)
	v_pk_add_f32 v[60:61], v[72:73], v[74:75]
	ds_bpermute_b32 v63, v77, v61
	ds_bpermute_b32 v62, v77, v60
	v_or_b32_e32 v72, 2, v54
	v_ashrrev_i32_e32 v73, 31, v72
	v_lshlrev_b64 v[72:73], 11, v[72:73]
	v_lshl_add_u64 v[72:73], s[86:87], 0, v[72:73]
	s_waitcnt lgkmcnt(0)
; __device__ __forceinline__ unsigned pk2(float lo, float hi) { f32x2_t v = {lo, hi}; bf16x2_t b = __builtin_convertvector(v, bf16x2_t); return __builtin_bit_cast(unsigned, b); }
; __device__ __forceinline__ float fsilu(float x) { return x * fsigmoid(x); }
; __device__ __forceinline__ void conv_phase(const Args& a, unsigned char* ws, int l, LAS unsigned char* lds, const int tid, const int bid) {
;     ...
; #pragma unroll
;         for (int tt = 0; tt < 8; ++tt) {
;             const f32x4 ya = accA[tt] + biasA, yb = accB[tt] + biasB;
;             const float mu = wave_sum((ya[0] + ya[1]) + (ya[2] + ya[3]) + (yb[0] + yb[1]) + (yb[2] + yb[3]), lane) * (1.f / 512);
;             const f32x4 da = ya - mu, db = yb - mu;
;             const float var = wave_sum((da[0] * da[0] + da[1] * da[1]) + (da[2] * da[2] + da[3] * da[3]) + (db[0] * db[0] + db[1] * db[1]) + (db[2] * db[2] + db[3] * db[3]), lane) * (1.f / 512);
;             const float rs = rsqrtf(var + EPS);
;             const f32x4 za = da * rs * lgA + lbA, zb = db * rs * lgB + lbB;
;             bf16_t* op = ATT + (size_t)(row0 + tt) * 1024 + 512;
;             u32x2 w; w.x = pk2(fsilu(za[0]), fsilu(za[1])); w.y = pk2(fsilu(za[2]), fsilu(za[3])); *(u32x2*)(op + cA) = w;
;             w.x = pk2(fsilu(zb[0]), fsilu(zb[1])); w.y = pk2(fsilu(zb[2]), fsilu(zb[3])); *(u32x2*)(op + cB) = w;
;         }
	v_pk_add_f32 v[60:61], v[60:61], v[62:63]
	v_lshl_add_u64 v[62:63], v[72:73], 0, s[8:9]
	v_pk_fma_f32 v[60:61], v[60:61], s[10:11], v[56:57] op_sel_hi:[1,0,0]
	v_lshl_add_u64 v[72:73], v[62:63], 0, v[52:53]
	v_mul_f32_e32 v55, 0x4b800000, v61
	v_cmp_gt_f32_e32 vcc, s67, v61
	v_lshl_add_u64 v[62:63], v[62:63], 0, v[58:59]
	s_nop 0
	v_cndmask_b32_e32 v55, v61, v55, vcc
	v_rsq_f32_e32 v55, v55
	s_nop 0
	v_mul_f32_e32 v61, 0x45800000, v55
	v_cndmask_b32_e32 v74, v55, v61, vcc
	v_pk_mul_f32 v[64:65], v[64:65], v[74:75] op_sel_hi:[1,0]
	v_pk_mul_f32 v[66:67], v[66:67], v[74:75] op_sel_hi:[1,0]
	v_pk_fma_f32 v[64:65], v[20:21], v[64:65], v[36:37]
	v_pk_fma_f32 v[66:67], v[22:23], v[66:67], v[38:39]
	v_mul_f32_e32 v55, 0xbfb8aa3b, v64
	v_exp_f32_e32 v55, v55
	v_mul_f32_e32 v61, 0xbfb8aa3b, v65
	v_exp_f32_e32 v61, v61
	v_pk_mul_f32 v[48:49], v[48:49], v[74:75] op_sel_hi:[1,0]
	v_add_f32_e32 v55, 1.0, v55
	v_rcp_f32_e32 v82, v55
	v_add_f32_e32 v55, 1.0, v61
	v_rcp_f32_e32 v83, v55
	v_mul_f32_e32 v55, 0xbfb8aa3b, v66
	v_exp_f32_e32 v55, v55
	v_mul_f32_e32 v61, 0xbfb8aa3b, v67
	v_exp_f32_e32 v61, v61
	v_pk_fma_f32 v[48:49], v[24:25], v[48:49], v[28:29]
	v_add_f32_e32 v55, 1.0, v55
	v_pk_mul_f32 v[50:51], v[50:51], v[74:75] op_sel_hi:[1,0]
	v_pk_mul_f32 v[64:65], v[64:65], v[82:83]
	v_rcp_f32_e32 v74, v55
	v_add_f32_e32 v55, 1.0, v61
	v_mul_f32_e32 v61, 0xbfb8aa3b, v48
	v_cvt_pk_bf16_f32 v64, v64, v65
	v_exp_f32_e32 v61, v61
	v_mul_f32_e32 v65, 0xbfb8aa3b, v49
	v_exp_f32_e32 v65, v65
	v_rcp_f32_e32 v75, v55
	v_add_f32_e32 v55, 1.0, v61
	v_pk_fma_f32 v[50:51], v[26:27], v[50:51], v[30:31]
	v_rcp_f32_e32 v82, v55
	v_add_f32_e32 v55, 1.0, v65
	v_rcp_f32_e32 v83, v55
	v_mul_f32_e32 v55, 0xbfb8aa3b, v50
	v_exp_f32_e32 v55, v55
	v_mul_f32_e32 v61, 0xbfb8aa3b, v51
	v_exp_f32_e32 v61, v61
	v_pk_mul_f32 v[66:67], v[66:67], v[74:75]
	v_pk_mul_f32 v[48:49], v[48:49], v[82:83]
	v_cvt_pk_bf16_f32 v65, v66, v67
	v_cvt_pk_bf16_f32 v48, v48, v49
	v_add_f32_e32 v49, 1.0, v55
	global_store_dwordx2 v[72:73], v[64:65], off
	v_rcp_f32_e32 v64, v49
	v_add_f32_e32 v49, 1.0, v61
	v_rcp_f32_e32 v65, v49
	v_mul_f32_e32 v49, 0x4b800000, v60
	v_cmp_gt_f32_e32 vcc, s67, v60
	v_mov_b32_e32 v72, v19
	v_pk_mul_f32 v[50:51], v[50:51], v[64:65]
	v_cndmask_b32_e32 v49, v60, v49, vcc
	v_rsq_f32_e32 v55, v49
	v_cvt_pk_bf16_f32 v49, v50, v51
	global_store_dwordx2 v[62:63], v[48:49], off
	v_mov_b32_e32 v73, v17
	v_mul_f32_e32 v48, 0x45800000, v55
	v_cndmask_b32_e32 v48, v55, v48, vcc
	v_pk_mul_f32 v[50:51], v[68:69], v[48:49] op_sel_hi:[1,0]
	v_pk_mul_f32 v[60:61], v[70:71], v[48:49] op_sel_hi:[1,0]
	v_pk_fma_f32 v[62:63], v[20:21], v[50:51], v[36:37]
	v_pk_mul_f32 v[50:51], v[32:33], v[48:49] op_sel_hi:[1,0]
	v_pk_mul_f32 v[32:33], v[34:35], v[48:49] op_sel_hi:[1,0]
	v_pk_fma_f32 v[34:35], v[24:25], v[50:51], v[28:29]
	v_mul_f32_e32 v50, 0xbfb8aa3b, v62
	v_exp_f32_e32 v50, v50
	v_mul_f32_e32 v51, 0xbfb8aa3b, v63
	v_or_b32_e32 v48, 3, v54
	v_exp_f32_e32 v51, v51
	v_ashrrev_i32_e32 v49, 31, v48
	v_lshlrev_b64 v[48:49], 11, v[48:49]
	v_lshl_add_u64 v[64:65], s[86:87], 0, v[48:49]
	v_add_f32_e32 v48, 1.0, v50
	v_rcp_f32_e32 v66, v48
	v_add_f32_e32 v48, 1.0, v51
	v_rcp_f32_e32 v67, v48
	v_pk_add_f32 v[48:49], v[118:119], v[44:45]
	v_pk_add_f32 v[50:51], v[120:121], v[46:47]
	v_mov_b32_e32 v70, v48
	v_pk_mov_b32 v[68:69], v[48:49], v[50:51] op_sel:[1,0]
	v_mov_b32_e32 v71, v51
	v_pk_add_f32 v[68:69], v[68:69], v[70:71]
	v_mov_b32_e32 v70, v18
	v_mov_b32_e32 v71, v16
	v_pk_add_f32 v[70:71], v[70:71], v[72:73]
	v_add_f32_e32 v55, v68, v69
	v_add_f32_e32 v55, v55, v71
	v_add_f32_e32 v55, v70, v55
	ds_bpermute_b32 v68, v1, v55
	v_pk_fma_f32 v[60:61], v[22:23], v[60:61], v[38:39]
	v_pk_mul_f32 v[62:63], v[62:63], v[66:67]
	v_mul_f32_e32 v69, 0xbfb8aa3b, v60
	v_mul_f32_e32 v70, 0xbfb8aa3b, v61
	s_waitcnt lgkmcnt(0)
	v_add_f32_e32 v55, v55, v68
	ds_bpermute_b32 v71, v80, v55
	v_exp_f32_e32 v69, v69
	v_exp_f32_e32 v70, v70
	v_cvt_pk_bf16_f32 v66, v62, v63
	v_pk_add_f32 v[62:63], v[116:117], v[46:47]
	s_waitcnt lgkmcnt(0)
	v_add_f32_e32 v55, v55, v71
	v_add_f32_e32 v68, 1.0, v69
	v_add_f32_e32 v69, 1.0, v70
	ds_bpermute_b32 v70, v79, v55
	v_rcp_f32_e32 v68, v68
	v_rcp_f32_e32 v69, v69
	v_mov_b32_e32 v73, v63
	v_mov_b32_e32 v74, v15
	s_waitcnt lgkmcnt(0)
	v_add_f32_e32 v55, v55, v70
	v_pk_mul_f32 v[60:61], v[60:61], v[68:69]
	v_mov_b32_e32 v75, v13
	v_cvt_pk_bf16_f32 v67, v60, v61
	ds_bpermute_b32 v60, v78, v55
	v_mul_f32_e32 v61, 0xbfb8aa3b, v34
	v_exp_f32_e32 v81, v61
	v_lshl_add_u64 v[64:65], v[64:65], 0, v[52:53]
	v_lshl_add_u64 v[68:69], v[64:65], 0, s[8:9]
	s_waitcnt lgkmcnt(0)
	v_add_f32_e32 v55, v55, v60
	v_pk_add_f32 v[60:61], v[114:115], v[44:45]
	ds_bpermute_b32 v82, v76, v55
	v_pk_mov_b32 v[70:71], v[60:61], v[62:63] op_sel:[1,0]
	v_mov_b32_e32 v72, v60
	v_pk_add_f32 v[70:71], v[70:71], v[72:73]
	v_mov_b32_e32 v72, v14
	v_mov_b32_e32 v73, v12
	v_pk_add_f32 v[72:73], v[72:73], v[74:75]
	v_add_f32_e32 v70, v70, v71
	v_add_f32_e32 v70, v70, v73
	v_add_f32_e32 v70, v72, v70
	ds_bpermute_b32 v71, v1, v70
	s_waitcnt lgkmcnt(0)
	v_add_f32_e32 v55, v55, v82
	ds_bpermute_b32 v72, v77, v55
	v_mul_f32_e32 v73, 0xbfb8aa3b, v35
	v_exp_f32_e32 v88, v73
	v_add_f32_e32 v70, v70, v71
	ds_bpermute_b32 v71, v80, v70
	s_waitcnt lgkmcnt(0)
	v_add_f32_e32 v55, v55, v72
	v_fmamk_f32 v49, v55, 0xbb000000, v49
	v_fmac_f32_e32 v48, 0xbb000000, v55
	v_fmamk_f32 v51, v55, 0xbb000000, v51
	v_add_f32_e32 v70, v70, v71
	ds_bpermute_b32 v71, v79, v70
	v_fmac_f32_e32 v50, 0xbb000000, v55
	v_fmamk_f32 v17, v55, 0xbb000000, v17
	v_fmac_f32_e32 v16, 0xbb000000, v55
	v_fmamk_f32 v19, v55, 0xbb000000, v19
	s_waitcnt lgkmcnt(0)
; __device__ __forceinline__ unsigned pk2(float lo, float hi) { f32x2_t v = {lo, hi}; bf16x2_t b = __builtin_convertvector(v, bf16x2_t); return __builtin_bit_cast(unsigned, b); }
; __device__ __forceinline__ float fsilu(float x) { return x * fsigmoid(x); }
; __device__ __forceinline__ void conv_phase(const Args& a, unsigned char* ws, int l, LAS unsigned char* lds, const int tid, const int bid) {
;     ...
; #pragma unroll
;         for (int tt = 0; tt < 8; ++tt) {
;             const f32x4 ya = accA[tt] + biasA, yb = accB[tt] + biasB;
;             const float mu = wave_sum((ya[0] + ya[1]) + (ya[2] + ya[3]) + (yb[0] + yb[1]) + (yb[2] + yb[3]), lane) * (1.f / 512);
;             const f32x4 da = ya - mu, db = yb - mu;
;             const float var = wave_sum((da[0] * da[0] + da[1] * da[1]) + (da[2] * da[2] + da[3] * da[3]) + (db[0] * db[0] + db[1] * db[1]) + (db[2] * db[2] + db[3] * db[3]), lane) * (1.f / 512);
;             const float rs = rsqrtf(var + EPS);
;             const f32x4 za = da * rs * lgA + lbA, zb = db * rs * lgB + lbB;
;             bf16_t* op = ATT + (size_t)(row0 + tt) * 1024 + 512;
;             u32x2 w; w.x = pk2(fsilu(za[0]), fsilu(za[1])); w.y = pk2(fsilu(za[2]), fsilu(za[3])); *(u32x2*)(op + cA) = w;
;             w.x = pk2(fsilu(zb[0]), fsilu(zb[1])); w.y = pk2(fsilu(zb[2]), fsilu(zb[3])); *(u32x2*)(op + cB) = w;
;         }
	v_add_f32_e32 v82, v70, v71
	ds_bpermute_b32 v83, v78, v82
	v_fmac_f32_e32 v18, 0xbb000000, v55
	v_pk_mul_f32 v[70:71], v[50:51], v[50:51]
	v_pk_mul_f32 v[72:73], v[48:49], v[48:49]
	v_add_co_u32_e32 v64, vcc, s6, v64
	s_waitcnt lgkmcnt(0)
	v_add_f32_e32 v55, v82, v83
	ds_bpermute_b32 v82, v76, v55
	v_pk_mov_b32 v[74:75], v[72:73], v[70:71] op_sel:[1,0]
	v_mov_b32_e32 v73, v71
	v_pk_add_f32 v[70:71], v[74:75], v[72:73]
	v_pk_mul_f32 v[72:73], v[18:19], v[18:19]
	s_waitcnt lgkmcnt(0)
	v_add_f32_e32 v55, v55, v82
	ds_bpermute_b32 v84, v77, v55
	v_pk_mul_f32 v[74:75], v[16:17], v[16:17]
	v_mov_b32_e32 v82, v72
	v_mov_b32_e32 v83, v74
	v_mov_b32_e32 v74, v73
	s_waitcnt lgkmcnt(0)
	v_add_f32_e32 v55, v55, v84
	v_fmamk_f32 v61, v55, 0xbb000000, v61
	v_fmac_f32_e32 v60, 0xbb000000, v55
	v_fmamk_f32 v63, v55, 0xbb000000, v63
	v_fmac_f32_e32 v62, 0xbb000000, v55
	v_pk_add_f32 v[72:73], v[82:83], v[74:75]
	v_pk_mul_f32 v[74:75], v[62:63], v[62:63]
	v_pk_mul_f32 v[82:83], v[60:61], v[60:61]
	v_fmamk_f32 v13, v55, 0xbb000000, v13
	v_fmac_f32_e32 v12, 0xbb000000, v55
	v_fmamk_f32 v15, v55, 0xbb000000, v15
	v_fmac_f32_e32 v14, 0xbb000000, v55
	v_pk_mov_b32 v[84:85], v[82:83], v[74:75] op_sel:[1,0]
	v_mov_b32_e32 v83, v75
	v_pk_add_f32 v[74:75], v[84:85], v[82:83]
	v_pk_mul_f32 v[82:83], v[14:15], v[14:15]
	v_pk_mul_f32 v[84:85], v[12:13], v[12:13]
	v_mov_b32_e32 v86, v82
	v_mov_b32_e32 v87, v84
	v_mov_b32_e32 v84, v83
	v_pk_add_f32 v[82:83], v[86:87], v[84:85]
	v_mov_b32_e32 v84, v74
	v_mov_b32_e32 v85, v70
	v_mov_b32_e32 v70, v75
	v_pk_add_f32 v[70:71], v[84:85], v[70:71]
	v_mov_b32_e32 v74, v83
	v_mov_b32_e32 v75, v73
	v_pk_add_f32 v[70:71], v[74:75], v[70:71]
	v_mov_b32_e32 v83, v72
	v_pk_add_f32 v[70:71], v[82:83], v[70:71]
	ds_bpermute_b32 v73, v1, v71
	ds_bpermute_b32 v72, v1, v70
	v_addc_co_u32_e32 v65, vcc, 0, v65, vcc
	global_store_dwordx2 v[64:65], v[66:67], off offset:1024
	v_add_f32_e32 v55, 1.0, v81
	s_waitcnt lgkmcnt(0)
	v_pk_add_f32 v[70:71], v[70:71], v[72:73]
	ds_bpermute_b32 v73, v80, v71
	ds_bpermute_b32 v72, v80, v70
	v_pk_fma_f32 v[32:33], v[26:27], v[32:33], v[30:31]
	v_rcp_f32_e32 v74, v55
	v_add_f32_e32 v55, 1.0, v88
	v_rcp_f32_e32 v75, v55
	s_waitcnt lgkmcnt(0)
	v_pk_add_f32 v[64:65], v[70:71], v[72:73]
	ds_bpermute_b32 v67, v79, v65
	ds_bpermute_b32 v66, v79, v64
	v_mul_f32_e32 v55, 0xbfb8aa3b, v32
	v_exp_f32_e32 v55, v55
	v_mul_f32_e32 v70, 0xbfb8aa3b, v33
	v_exp_f32_e32 v71, v70
	s_waitcnt lgkmcnt(0)
	v_pk_add_f32 v[64:65], v[64:65], v[66:67]
	ds_bpermute_b32 v67, v78, v65
	ds_bpermute_b32 v66, v78, v64
	v_add_f32_e32 v55, 1.0, v55
	v_rcp_f32_e32 v70, v55
	v_add_f32_e32 v55, 1.0, v71
	v_rcp_f32_e32 v71, v55
	s_waitcnt lgkmcnt(0)
	v_pk_add_f32 v[64:65], v[64:65], v[66:67]
	ds_bpermute_b32 v67, v76, v65
	ds_bpermute_b32 v66, v76, v64
	v_pk_mul_f32 v[34:35], v[34:35], v[74:75]
	v_pk_mul_f32 v[32:33], v[32:33], v[70:71]
	v_cvt_pk_bf16_f32 v34, v34, v35
	v_cvt_pk_bf16_f32 v35, v32, v33
	s_waitcnt lgkmcnt(0)
	v_pk_add_f32 v[32:33], v[64:65], v[66:67]
	global_store_dwordx2 v[68:69], v[34:35], off offset:512
	ds_bpermute_b32 v35, v77, v33
	ds_bpermute_b32 v34, v77, v32
	v_or_b32_e32 v64, 4, v54
	v_ashrrev_i32_e32 v65, 31, v64
	v_lshlrev_b64 v[64:65], 11, v[64:65]
	v_lshl_add_u64 v[64:65], s[86:87], 0, v[64:65]
	s_waitcnt lgkmcnt(0)
	v_pk_add_f32 v[32:33], v[32:33], v[34:35]
	s_nop 0
	v_pk_fma_f32 v[32:33], v[32:33], s[10:11], v[56:57] op_sel_hi:[1,0,0]
	s_nop 0
	v_mul_f32_e32 v34, 0x4b800000, v33
	v_cmp_gt_f32_e32 vcc, s67, v33
	s_nop 1
	v_cndmask_b32_e32 v33, v33, v34, vcc
	v_rsq_f32_e32 v33, v33
	v_lshl_add_u64 v[34:35], v[64:65], 0, s[8:9]
	v_lshl_add_u64 v[64:65], v[34:35], 0, v[52:53]
	v_lshl_add_u64 v[34:35], v[34:35], 0, v[58:59]
	v_mul_f32_e32 v55, 0x45800000, v33
	v_cndmask_b32_e32 v66, v33, v55, vcc
	v_pk_mul_f32 v[48:49], v[48:49], v[66:67] op_sel_hi:[1,0]
	v_pk_mul_f32 v[50:51], v[50:51], v[66:67] op_sel_hi:[1,0]
	v_pk_fma_f32 v[48:49], v[20:21], v[48:49], v[36:37]
	v_pk_fma_f32 v[50:51], v[22:23], v[50:51], v[38:39]
	v_mul_f32_e32 v33, 0xbfb8aa3b, v48
	v_exp_f32_e32 v33, v33
	v_mul_f32_e32 v55, 0xbfb8aa3b, v49
	v_exp_f32_e32 v55, v55
	v_pk_mul_f32 v[16:17], v[16:17], v[66:67] op_sel_hi:[1,0]
	v_add_f32_e32 v33, 1.0, v33
	v_rcp_f32_e32 v68, v33
	v_add_f32_e32 v33, 1.0, v55
	v_rcp_f32_e32 v69, v33
	v_mul_f32_e32 v33, 0xbfb8aa3b, v50
	v_exp_f32_e32 v33, v33
	v_mul_f32_e32 v55, 0xbfb8aa3b, v51
	v_exp_f32_e32 v55, v55
	v_pk_fma_f32 v[16:17], v[24:25], v[16:17], v[28:29]
	v_pk_mul_f32 v[48:49], v[48:49], v[68:69]
	v_add_f32_e32 v33, 1.0, v33
	v_cvt_pk_bf16_f32 v48, v48, v49
	v_mul_f32_e32 v49, 0xbfb8aa3b, v16
	v_pk_mul_f32 v[18:19], v[18:19], v[66:67] op_sel_hi:[1,0]
	v_rcp_f32_e32 v66, v33
	v_add_f32_e32 v33, 1.0, v55
	v_exp_f32_e32 v49, v49
	v_mul_f32_e32 v55, 0xbfb8aa3b, v17
	v_exp_f32_e32 v55, v55
	v_rcp_f32_e32 v67, v33
	v_add_f32_e32 v33, 1.0, v49
	v_pk_fma_f32 v[18:19], v[26:27], v[18:19], v[30:31]
	v_rcp_f32_e32 v68, v33
	v_add_f32_e32 v33, 1.0, v55
	v_pk_mul_f32 v[50:51], v[50:51], v[66:67]
	v_rcp_f32_e32 v69, v33
	v_cvt_pk_bf16_f32 v49, v50, v51
	v_mul_f32_e32 v33, 0xbfb8aa3b, v18
	global_store_dwordx2 v[64:65], v[48:49], off
	v_exp_f32_e32 v33, v33
	v_mul_f32_e32 v48, 0xbfb8aa3b, v19
	v_exp_f32_e32 v49, v48
	v_pk_mul_f32 v[16:17], v[16:17], v[68:69]
	v_cmp_gt_f32_e32 vcc, s67, v32
	v_cvt_pk_bf16_f32 v16, v16, v17
	v_add_f32_e32 v17, 1.0, v33
	v_rcp_f32_e32 v48, v17
	v_add_f32_e32 v17, 1.0, v49
	v_rcp_f32_e32 v49, v17
	v_mul_f32_e32 v17, 0x4b800000, v32
	v_cndmask_b32_e32 v17, v32, v17, vcc
	v_rsq_f32_e32 v32, v17
	v_pk_mul_f32 v[18:19], v[18:19], v[48:49]
	v_mov_b32_e32 v64, v11
	v_cvt_pk_bf16_f32 v17, v18, v19
; __device__ __forceinline__ unsigned pk2(float lo, float hi) { f32x2_t v = {lo, hi}; bf16x2_t b = __builtin_convertvector(v, bf16x2_t); return __builtin_bit_cast(unsigned, b); }
; __device__ __forceinline__ float fsilu(float x) { return x * fsigmoid(x); }
; __device__ __forceinline__ void conv_phase(const Args& a, unsigned char* ws, int l, LAS unsigned char* lds, const int tid, const int bid) {
;     ...
; #pragma unroll
;         for (int tt = 0; tt < 8; ++tt) {
;             const f32x4 ya = accA[tt] + biasA, yb = accB[tt] + biasB;
;             const float mu = wave_sum((ya[0] + ya[1]) + (ya[2] + ya[3]) + (yb[0] + yb[1]) + (yb[2] + yb[3]), lane) * (1.f / 512);
;             const f32x4 da = ya - mu, db = yb - mu;
;             const float var = wave_sum((da[0] * da[0] + da[1] * da[1]) + (da[2] * da[2] + da[3] * da[3]) + (db[0] * db[0] + db[1] * db[1]) + (db[2] * db[2] + db[3] * db[3]), lane) * (1.f / 512);
;             const float rs = rsqrtf(var + EPS);
;             const f32x4 za = da * rs * lgA + lbA, zb = db * rs * lgB + lbB;
;             bf16_t* op = ATT + (size_t)(row0 + tt) * 1024 + 512;
;             u32x2 w; w.x = pk2(fsilu(za[0]), fsilu(za[1])); w.y = pk2(fsilu(za[2]), fsilu(za[3])); *(u32x2*)(op + cA) = w;
;             w.x = pk2(fsilu(zb[0]), fsilu(zb[1])); w.y = pk2(fsilu(zb[2]), fsilu(zb[3])); *(u32x2*)(op + cB) = w;
;         }
	global_store_dwordx2 v[34:35], v[16:17], off
	v_mul_f32_e32 v16, 0x45800000, v32
	v_cndmask_b32_e32 v16, v32, v16, vcc
	v_pk_mul_f32 v[18:19], v[60:61], v[16:17] op_sel_hi:[1,0]
	v_pk_mul_f32 v[32:33], v[62:63], v[16:17] op_sel_hi:[1,0]
	v_pk_fma_f32 v[34:35], v[20:21], v[18:19], v[36:37]
	v_pk_mul_f32 v[18:19], v[12:13], v[16:17] op_sel_hi:[1,0]
	v_pk_mul_f32 v[12:13], v[14:15], v[16:17] op_sel_hi:[1,0]
	v_pk_fma_f32 v[14:15], v[24:25], v[18:19], v[28:29]
	v_mul_f32_e32 v18, 0xbfb8aa3b, v34
	v_exp_f32_e32 v18, v18
	v_mul_f32_e32 v19, 0xbfb8aa3b, v35
	v_or_b32_e32 v16, 5, v54
	v_exp_f32_e32 v19, v19
	v_ashrrev_i32_e32 v17, 31, v16
	v_lshlrev_b64 v[16:17], 11, v[16:17]
	v_lshl_add_u64 v[48:49], s[86:87], 0, v[16:17]
	v_add_f32_e32 v16, 1.0, v18
	v_rcp_f32_e32 v50, v16
	v_add_f32_e32 v16, 1.0, v19
	v_rcp_f32_e32 v51, v16
	v_pk_add_f32 v[16:17], v[110:111], v[44:45]
	v_pk_add_f32 v[18:19], v[112:113], v[46:47]
	v_mov_b32_e32 v62, v16
	v_pk_mov_b32 v[60:61], v[16:17], v[18:19] op_sel:[1,0]
	v_mov_b32_e32 v63, v19
	v_pk_add_f32 v[60:61], v[60:61], v[62:63]
	v_mov_b32_e32 v62, v10
	v_mov_b32_e32 v63, v8
	v_mov_b32_e32 v65, v9
	v_pk_add_f32 v[62:63], v[62:63], v[64:65]
	v_add_f32_e32 v55, v60, v61
	v_add_f32_e32 v55, v55, v63
	v_add_f32_e32 v55, v62, v55
	ds_bpermute_b32 v60, v1, v55
	v_pk_fma_f32 v[32:33], v[22:23], v[32:33], v[38:39]
	v_pk_mul_f32 v[34:35], v[34:35], v[50:51]
	v_mul_f32_e32 v61, 0xbfb8aa3b, v32
	v_mul_f32_e32 v62, 0xbfb8aa3b, v33
	s_waitcnt lgkmcnt(0)
	v_add_f32_e32 v55, v55, v60
	ds_bpermute_b32 v63, v80, v55
	v_exp_f32_e32 v61, v61
	v_exp_f32_e32 v62, v62
	v_cvt_pk_bf16_f32 v34, v34, v35
	v_mov_b32_e32 v44, v7
	v_add_f32_e32 v60, 1.0, v61
	v_add_f32_e32 v61, 1.0, v62
	s_waitcnt lgkmcnt(0)
	v_add_f32_e32 v55, v55, v63
	v_rcp_f32_e32 v60, v60
	v_rcp_f32_e32 v61, v61
	ds_bpermute_b32 v62, v79, v55
	v_mov_b32_e32 v45, v5
	v_lshl_add_u64 v[48:49], v[48:49], 0, v[52:53]
	v_pk_mul_f32 v[32:33], v[32:33], v[60:61]
	v_pk_fma_f32 v[12:13], v[26:27], v[12:13], v[30:31]
	v_cvt_pk_bf16_f32 v35, v32, v33
	s_waitcnt lgkmcnt(0)
	v_add_f32_e32 v32, v55, v62
	ds_bpermute_b32 v33, v78, v32
	v_mul_f32_e32 v55, 0xbfb8aa3b, v14
	v_exp_f32_e32 v55, v55
	v_lshl_add_u64 v[50:51], v[48:49], 0, s[8:9]
	s_waitcnt lgkmcnt(0)
	v_add_f32_e32 v60, v32, v33
	v_pk_add_f32 v[32:33], v[108:109], v[46:47]
	ds_bpermute_b32 v61, v76, v60
	v_pk_mov_b32 v[40:41], v[2:3], v[32:33] op_sel:[1,0]
	v_mov_b32_e32 v43, v33
	v_pk_add_f32 v[40:41], v[40:41], v[42:43]
	v_mov_b32_e32 v42, v6
	v_mov_b32_e32 v43, v4
	v_pk_add_f32 v[42:43], v[42:43], v[44:45]
	v_add_f32_e32 v40, v40, v41
	v_add_f32_e32 v40, v40, v43
	v_add_f32_e32 v40, v42, v40
	ds_bpermute_b32 v41, v1, v40
	s_waitcnt lgkmcnt(0)
	v_add_f32_e32 v42, v60, v61
	ds_bpermute_b32 v43, v77, v42
	v_mul_f32_e32 v44, 0xbfb8aa3b, v15
	v_exp_f32_e32 v64, v44
	v_add_f32_e32 v40, v40, v41
	ds_bpermute_b32 v41, v80, v40
	s_waitcnt lgkmcnt(0)
	v_add_f32_e32 v42, v42, v43
	v_fmamk_f32 v17, v42, 0xbb000000, v17
	v_fmac_f32_e32 v16, 0xbb000000, v42
	v_fmamk_f32 v19, v42, 0xbb000000, v19
	v_add_f32_e32 v40, v40, v41
	ds_bpermute_b32 v41, v79, v40
	v_fmac_f32_e32 v18, 0xbb000000, v42
	v_fmamk_f32 v9, v42, 0xbb000000, v9
	v_fmac_f32_e32 v8, 0xbb000000, v42
	v_fmamk_f32 v11, v42, 0xbb000000, v11
	s_waitcnt lgkmcnt(0)
	v_add_f32_e32 v46, v40, v41
	ds_bpermute_b32 v47, v78, v46
	v_fmac_f32_e32 v10, 0xbb000000, v42
	v_pk_mul_f32 v[40:41], v[18:19], v[18:19]
	v_pk_mul_f32 v[42:43], v[16:17], v[16:17]
	s_waitcnt lgkmcnt(0)
	v_add_f32_e32 v46, v46, v47
	ds_bpermute_b32 v47, v76, v46
	v_pk_mov_b32 v[44:45], v[42:43], v[40:41] op_sel:[1,0]
	v_mov_b32_e32 v43, v41
	v_pk_add_f32 v[40:41], v[44:45], v[42:43]
	v_pk_mul_f32 v[42:43], v[10:11], v[10:11]
	s_waitcnt lgkmcnt(0)
	v_add_f32_e32 v60, v46, v47
	ds_bpermute_b32 v61, v77, v60
	v_pk_mul_f32 v[44:45], v[8:9], v[8:9]
	v_mov_b32_e32 v46, v42
	v_mov_b32_e32 v47, v44
	v_mov_b32_e32 v44, v43
	v_pk_add_f32 v[42:43], v[46:47], v[44:45]
	s_waitcnt lgkmcnt(0)
	v_add_f32_e32 v44, v60, v61
	v_fmamk_f32 v3, v44, 0xbb000000, v3
	v_fmac_f32_e32 v2, 0xbb000000, v44
	v_fmamk_f32 v33, v44, 0xbb000000, v33
	v_fmac_f32_e32 v32, 0xbb000000, v44
	v_fmamk_f32 v5, v44, 0xbb000000, v5
	v_fmac_f32_e32 v4, 0xbb000000, v44
	v_fmamk_f32 v7, v44, 0xbb000000, v7
	v_fmac_f32_e32 v6, 0xbb000000, v44
	v_pk_mul_f32 v[44:45], v[32:33], v[32:33]
	v_pk_mul_f32 v[46:47], v[2:3], v[2:3]
	s_nop 0
	v_pk_mov_b32 v[60:61], v[46:47], v[44:45] op_sel:[1,0]
	v_mov_b32_e32 v47, v45
	v_pk_add_f32 v[44:45], v[60:61], v[46:47]
	v_pk_mul_f32 v[46:47], v[6:7], v[6:7]
	v_pk_mul_f32 v[60:61], v[4:5], v[4:5]
	v_mov_b32_e32 v62, v46
	v_mov_b32_e32 v63, v60
	v_mov_b32_e32 v60, v47
	v_pk_add_f32 v[46:47], v[62:63], v[60:61]
	v_mov_b32_e32 v60, v44
	v_mov_b32_e32 v61, v40
	v_mov_b32_e32 v40, v45
	v_pk_add_f32 v[40:41], v[60:61], v[40:41]
	v_mov_b32_e32 v44, v47
	v_mov_b32_e32 v45, v43
	v_pk_add_f32 v[40:41], v[44:45], v[40:41]
	v_mov_b32_e32 v47, v42
	v_pk_add_f32 v[40:41], v[46:47], v[40:41]
	ds_bpermute_b32 v43, v1, v41
	ds_bpermute_b32 v42, v1, v40
	v_add_co_u32_e32 v46, vcc, s6, v48
	v_add_f32_e32 v1, 1.0, v55
	s_nop 0
	v_addc_co_u32_e32 v47, vcc, 0, v49, vcc
	s_waitcnt lgkmcnt(0)
	v_pk_add_f32 v[40:41], v[40:41], v[42:43]
	ds_bpermute_b32 v43, v80, v41
	ds_bpermute_b32 v42, v80, v40
	global_store_dwordx2 v[46:47], v[34:35], off offset:1024
	v_rcp_f32_e32 v44, v1
	v_add_f32_e32 v1, 1.0, v64
	v_rcp_f32_e32 v45, v1
	s_waitcnt lgkmcnt(0)
	v_pk_add_f32 v[34:35], v[40:41], v[42:43]
	ds_bpermute_b32 v41, v79, v35
	ds_bpermute_b32 v40, v79, v34
	v_mul_f32_e32 v1, 0xbfb8aa3b, v12
	v_exp_f32_e32 v1, v1
	v_mul_f32_e32 v42, 0xbfb8aa3b, v13
	v_exp_f32_e32 v43, v42
	s_waitcnt lgkmcnt(0)
; __device__ __forceinline__ unsigned pk2(float lo, float hi) { f32x2_t v = {lo, hi}; bf16x2_t b = __builtin_convertvector(v, bf16x2_t); return __builtin_bit_cast(unsigned, b); }
; __device__ __forceinline__ float fsilu(float x) { return x * fsigmoid(x); }
; __device__ __forceinline__ void conv_phase(const Args& a, unsigned char* ws, int l, LAS unsigned char* lds, const int tid, const int bid) {
;     ...
; #pragma unroll
;         for (int tt = 0; tt < 8; ++tt) {
;             const f32x4 ya = accA[tt] + biasA, yb = accB[tt] + biasB;
;             const float mu = wave_sum((ya[0] + ya[1]) + (ya[2] + ya[3]) + (yb[0] + yb[1]) + (yb[2] + yb[3]), lane) * (1.f / 512);
;             const f32x4 da = ya - mu, db = yb - mu;
;             const float var = wave_sum((da[0] * da[0] + da[1] * da[1]) + (da[2] * da[2] + da[3] * da[3]) + (db[0] * db[0] + db[1] * db[1]) + (db[2] * db[2] + db[3] * db[3]), lane) * (1.f / 512);
;             const float rs = rsqrtf(var + EPS);
;             const f32x4 za = da * rs * lgA + lbA, zb = db * rs * lgB + lbB;
;             bf16_t* op = ATT + (size_t)(row0 + tt) * 1024 + 512;
;             u32x2 w; w.x = pk2(fsilu(za[0]), fsilu(za[1])); w.y = pk2(fsilu(za[2]), fsilu(za[3])); *(u32x2*)(op + cA) = w;
;             w.x = pk2(fsilu(zb[0]), fsilu(zb[1])); w.y = pk2(fsilu(zb[2]), fsilu(zb[3])); *(u32x2*)(op + cB) = w;
;         }
	v_pk_add_f32 v[34:35], v[34:35], v[40:41]
	ds_bpermute_b32 v41, v78, v35
	ds_bpermute_b32 v40, v78, v34
	v_add_f32_e32 v1, 1.0, v1
	v_rcp_f32_e32 v42, v1
	v_add_f32_e32 v1, 1.0, v43
	v_rcp_f32_e32 v43, v1
	s_waitcnt lgkmcnt(0)
	v_pk_add_f32 v[34:35], v[34:35], v[40:41]
	ds_bpermute_b32 v41, v76, v35
	ds_bpermute_b32 v40, v76, v34
	v_pk_mul_f32 v[14:15], v[14:15], v[44:45]
	v_pk_mul_f32 v[12:13], v[12:13], v[42:43]
	v_cvt_pk_bf16_f32 v14, v14, v15
	v_cvt_pk_bf16_f32 v15, v12, v13
	s_waitcnt lgkmcnt(0)
	v_pk_add_f32 v[12:13], v[34:35], v[40:41]
	global_store_dwordx2 v[50:51], v[14:15], off offset:512
	ds_bpermute_b32 v15, v77, v13
	ds_bpermute_b32 v14, v77, v12
	v_or_b32_e32 v34, 6, v54
	v_ashrrev_i32_e32 v35, 31, v34
	v_lshlrev_b64 v[34:35], 11, v[34:35]
	v_lshl_add_u64 v[34:35], s[86:87], 0, v[34:35]
	s_waitcnt lgkmcnt(0)
	v_pk_add_f32 v[12:13], v[12:13], v[14:15]
	v_lshl_add_u64 v[14:15], v[34:35], 0, s[8:9]
	v_pk_fma_f32 v[12:13], v[12:13], s[10:11], v[56:57] op_sel_hi:[1,0,0]
	v_lshl_add_u64 v[34:35], v[14:15], 0, v[52:53]
	v_mul_f32_e32 v1, 0x4b800000, v13
	v_cmp_gt_f32_e32 vcc, s67, v13
	v_lshl_add_u64 v[14:15], v[14:15], 0, v[58:59]
	s_nop 0
	v_cndmask_b32_e32 v1, v13, v1, vcc
	v_rsq_f32_e32 v1, v1
	s_nop 0
	v_mul_f32_e32 v13, 0x45800000, v1
	v_cndmask_b32_e32 v40, v1, v13, vcc
	v_pk_mul_f32 v[16:17], v[16:17], v[40:41] op_sel_hi:[1,0]
	v_pk_mul_f32 v[18:19], v[18:19], v[40:41] op_sel_hi:[1,0]
	v_pk_fma_f32 v[16:17], v[20:21], v[16:17], v[36:37]
	v_pk_fma_f32 v[18:19], v[22:23], v[18:19], v[38:39]
	v_mul_f32_e32 v1, 0xbfb8aa3b, v16
	v_exp_f32_e32 v1, v1
	v_mul_f32_e32 v13, 0xbfb8aa3b, v17
	v_exp_f32_e32 v13, v13
	v_pk_mul_f32 v[8:9], v[8:9], v[40:41] op_sel_hi:[1,0]
	v_add_f32_e32 v1, 1.0, v1
	v_rcp_f32_e32 v42, v1
	v_add_f32_e32 v1, 1.0, v13
	v_rcp_f32_e32 v43, v1
	v_mul_f32_e32 v1, 0xbfb8aa3b, v18
	v_exp_f32_e32 v1, v1
	v_mul_f32_e32 v13, 0xbfb8aa3b, v19
	v_exp_f32_e32 v13, v13
	v_pk_fma_f32 v[8:9], v[24:25], v[8:9], v[28:29]
	v_add_f32_e32 v1, 1.0, v1
	v_pk_mul_f32 v[10:11], v[10:11], v[40:41] op_sel_hi:[1,0]
	v_pk_mul_f32 v[16:17], v[16:17], v[42:43]
	v_rcp_f32_e32 v40, v1
	v_add_f32_e32 v1, 1.0, v13
	v_mul_f32_e32 v13, 0xbfb8aa3b, v8
	v_cvt_pk_bf16_f32 v16, v16, v17
	v_exp_f32_e32 v13, v13
	v_mul_f32_e32 v17, 0xbfb8aa3b, v9
	v_exp_f32_e32 v17, v17
	v_rcp_f32_e32 v41, v1
	v_add_f32_e32 v1, 1.0, v13
	v_pk_fma_f32 v[10:11], v[26:27], v[10:11], v[30:31]
	v_rcp_f32_e32 v42, v1
	v_add_f32_e32 v1, 1.0, v17
	v_rcp_f32_e32 v43, v1
	v_mul_f32_e32 v1, 0xbfb8aa3b, v10
	v_exp_f32_e32 v1, v1
	v_mul_f32_e32 v13, 0xbfb8aa3b, v11
	v_exp_f32_e32 v13, v13
	v_pk_mul_f32 v[18:19], v[18:19], v[40:41]
	v_add_f32_e32 v1, 1.0, v1
	v_cvt_pk_bf16_f32 v17, v18, v19
	global_store_dwordx2 v[34:35], v[16:17], off
	v_rcp_f32_e32 v16, v1
	v_add_f32_e32 v1, 1.0, v13
	v_rcp_f32_e32 v17, v1
	v_mul_f32_e32 v1, 0x4b800000, v12
	v_cmp_gt_f32_e32 vcc, s67, v12
	v_pk_mul_f32 v[8:9], v[8:9], v[42:43]
	v_pk_mul_f32 v[10:11], v[10:11], v[16:17]
	v_cndmask_b32_e32 v1, v12, v1, vcc
	v_rsq_f32_e32 v1, v1
	v_cvt_pk_bf16_f32 v8, v8, v9
	v_cvt_pk_bf16_f32 v9, v10, v11
	global_store_dwordx2 v[14:15], v[8:9], off
	v_mul_f32_e32 v8, 0x45800000, v1
	v_cndmask_b32_e32 v8, v1, v8, vcc
	v_pk_mul_f32 v[2:3], v[2:3], v[8:9] op_sel_hi:[1,0]
	v_pk_mul_f32 v[10:11], v[32:33], v[8:9] op_sel_hi:[1,0]
	v_pk_fma_f32 v[2:3], v[20:21], v[2:3], v[36:37]
	v_pk_fma_f32 v[10:11], v[22:23], v[10:11], v[38:39]
	v_mul_f32_e32 v1, 0xbfb8aa3b, v2
	v_exp_f32_e32 v1, v1
	v_mul_f32_e32 v12, 0xbfb8aa3b, v3
	v_exp_f32_e32 v13, v12
	v_pk_mul_f32 v[4:5], v[4:5], v[8:9] op_sel_hi:[1,0]
	v_add_f32_e32 v1, 1.0, v1
	v_rcp_f32_e32 v12, v1
	v_add_f32_e32 v1, 1.0, v13
	v_mul_f32_e32 v13, 0xbfb8aa3b, v10
	v_exp_f32_e32 v14, v13
	v_mul_f32_e32 v13, 0xbfb8aa3b, v11
	v_exp_f32_e32 v15, v13
	v_rcp_f32_e32 v13, v1
	v_add_f32_e32 v1, 1.0, v14
	v_pk_fma_f32 v[4:5], v[24:25], v[4:5], v[28:29]
	v_rcp_f32_e32 v14, v1
	v_add_f32_e32 v1, 1.0, v15
	v_rcp_f32_e32 v15, v1
	v_mul_f32_e32 v1, 0xbfb8aa3b, v4
	v_pk_mul_f32 v[2:3], v[2:3], v[12:13]
	v_exp_f32_e32 v1, v1
	v_mul_f32_e32 v12, 0xbfb8aa3b, v5
	v_exp_f32_e32 v13, v12
	v_pk_mul_f32 v[6:7], v[6:7], v[8:9] op_sel_hi:[1,0]
	v_add_f32_e32 v1, 1.0, v1
	v_pk_fma_f32 v[6:7], v[26:27], v[6:7], v[30:31]
	v_rcp_f32_e32 v12, v1
	v_add_f32_e32 v1, 1.0, v13
	v_mul_f32_e32 v13, 0xbfb8aa3b, v6
	v_pk_mul_f32 v[10:11], v[10:11], v[14:15]
	v_exp_f32_e32 v14, v13
	v_mul_f32_e32 v13, 0xbfb8aa3b, v7
	v_exp_f32_e32 v15, v13
	v_or_b32_e32 v8, 7, v54
	v_ashrrev_i32_e32 v9, 31, v8
	v_rcp_f32_e32 v13, v1
	v_add_f32_e32 v1, 1.0, v14
	v_lshlrev_b64 v[8:9], 11, v[8:9]
	v_rcp_f32_e32 v14, v1
	v_add_f32_e32 v1, 1.0, v15
	v_lshl_add_u64 v[8:9], s[86:87], 0, v[8:9]
	v_rcp_f32_e32 v15, v1
	v_lshl_add_u64 v[8:9], v[8:9], 0, v[52:53]
	v_cvt_pk_bf16_f32 v2, v2, v3
	v_cvt_pk_bf16_f32 v3, v10, v11
	v_lshl_add_u64 v[10:11], v[8:9], 0, s[8:9]
	v_add_co_u32_e32 v8, vcc, s6, v8
	v_readlane_b32 s6, v255, 5
	s_nop 0
	v_addc_co_u32_e32 v9, vcc, 0, v9, vcc
	global_store_dwordx2 v[8:9], v[2:3], off offset:1024
	v_pk_mul_f32 v[2:3], v[4:5], v[12:13]
	v_pk_mul_f32 v[4:5], v[6:7], v[14:15]
	s_add_i32 s37, s6, s37
	v_cvt_pk_bf16_f32 v2, v2, v3
	v_cvt_pk_bf16_f32 v3, v4, v5
	s_cmpk_gt_i32 s37, 0x1ff
	global_store_dwordx2 v[10:11], v[2:3], off offset:512
	s_cbranch_scc1 .LBB0_447
; #define LAS __attribute__((address_space(3)))
; __device__ __forceinline__ void conv_phase(const Args& a, unsigned char* ws, int l, LAS unsigned char* lds, const int tid, const int bid) {
;     ...
;     for (int bt = bid - nskip; bt < T / 64; bt += nb) {
;         const int R0 = bt * 64, tb0 = R0 & (SEQ - 1);
;         __syncthreads();
;         {
;             int tq = tid; asm volatile("" : "+v"(tq));
;             const int i0 = tq >> 6, ch = tq & 63;
;             const bf16_t* gsrc = GLU + (size_t)(R0 - 30 + i0) * 512 + ch * 8;
;             LAS unsigned char* ldst = rows + tq * 16;
;             u32x4 v[12];
; #pragma unroll
;             for (int it = 0; it < 12; ++it) { const int i = i0 + 8 * it;
;                 v[it] = (i < 94 && tb0 - 30 + i >= 0) ? *(const u32x4*)(gsrc + (size_t)it * 8 * 512) : (u32x4){0u, 0u, 0u, 0u}; }
.LBB0_390:
	s_lshl_b32 s48, s37, 6
	v_mov_b32_e32 v1, v178
	s_barrier
	s_sub_i32 s7, s48, 30
	v_ashrrev_i32_e32 v43, 6, v1
	v_add_u32_e32 v2, s7, v43
	s_and_b32 s6, s48, 0xfc0
	v_ashrrev_i32_e32 v3, 31, v2
	v_lshlrev_b64 v[2:3], 10, v[2:3]
	v_lshlrev_b32_e32 v4, 4, v1
	s_sub_i32 s46, 29, s6
	s_movk_i32 s6, 0x5e
	v_lshl_add_u64 v[2:3], s[4:5], 0, v[2:3]
	v_and_b32_e32 v4, 0x3f0, v4
	v_mov_b32_e32 v5, v0
	v_cmp_gt_i32_e64 s[6:7], s6, v43
	v_cmp_lt_i32_e32 vcc, s46, v43
	v_lshl_add_u64 v[50:51], v[2:3], 0, v[4:5]
	s_and_b64 s[10:11], s[6:7], vcc
	v_mov_b32_e32 v2, 0
	v_mov_b32_e32 v6, 0
	v_mov_b32_e32 v7, 0
	v_mov_b32_e32 v8, 0
	v_mov_b32_e32 v9, 0
	s_and_saveexec_b64 s[8:9], s[10:11]
	s_cbranch_execz .LBB0_392
	global_load_dwordx4 v[6:9], v[50:51], off
.LBB0_392:
	s_or_b64 exec, exec, s[8:9]
	v_add_u32_e32 v3, 8, v43
	s_movk_i32 s8, 0x56
	v_cmp_gt_i32_e64 s[8:9], s8, v43
	v_cmp_lt_i32_e32 vcc, s46, v3
	s_and_b64 s[12:13], s[8:9], vcc
	v_mov_b32_e32 v3, 0
	v_mov_b32_e32 v4, 0
	v_mov_b32_e32 v5, 0
	s_and_saveexec_b64 s[10:11], s[12:13]
	s_cbranch_execz .LBB0_394
	v_add_co_u32_e32 v2, vcc, 0x2000, v50
	s_nop 1
	v_addc_co_u32_e32 v3, vcc, 0, v51, vcc
	global_load_dwordx4 v[2:5], v[2:3], off
.LBB0_394:
	s_or_b64 exec, exec, s[10:11]
	v_add_u32_e32 v10, 16, v43
	s_movk_i32 s10, 0x4e
	v_cmp_gt_i32_e64 s[10:11], s10, v43
	v_cmp_lt_i32_e32 vcc, s46, v10
	s_and_b64 s[14:15], s[10:11], vcc
	v_mov_b32_e32 v10, 0
	v_mov_b32_e32 v14, 0
	v_mov_b32_e32 v15, 0
	v_mov_b32_e32 v16, 0
	v_mov_b32_e32 v17, 0
	s_and_saveexec_b64 s[12:13], s[14:15]
	s_cbranch_execz .LBB0_396
	v_add_co_u32_e32 v12, vcc, 0x4000, v50
	s_nop 1
	v_addc_co_u32_e32 v13, vcc, 0, v51, vcc
	global_load_dwordx4 v[14:17], v[12:13], off
.LBB0_396:
	s_or_b64 exec, exec, s[12:13]
	v_add_u32_e32 v11, 24, v43
	s_movk_i32 s12, 0x46
	v_cmp_gt_i32_e64 s[12:13], s12, v43
	v_cmp_lt_i32_e32 vcc, s46, v11
	s_and_b64 s[16:17], s[12:13], vcc
	v_mov_b32_e32 v11, 0
	v_mov_b32_e32 v12, 0
	v_mov_b32_e32 v13, 0
	s_and_saveexec_b64 s[14:15], s[16:17]
	s_cbranch_execz .LBB0_398
	v_add_co_u32_e32 v10, vcc, 0x6000, v50
	s_nop 1
	v_addc_co_u32_e32 v11, vcc, 0, v51, vcc
	global_load_dwordx4 v[10:13], v[10:11], off
.LBB0_398:
	s_or_b64 exec, exec, s[14:15]
	v_add_u32_e32 v18, 32, v43
	v_cmp_gt_i32_e64 s[14:15], 62, v43
	v_cmp_lt_i32_e32 vcc, s46, v18
	s_and_b64 s[18:19], s[14:15], vcc
	v_mov_b32_e32 v18, 0
	v_mov_b32_e32 v22, 0
	v_mov_b32_e32 v23, 0
	v_mov_b32_e32 v24, 0
	v_mov_b32_e32 v25, 0
	s_and_saveexec_b64 s[16:17], s[18:19]
	s_cbranch_execz .LBB0_400
	v_add_co_u32_e32 v20, vcc, 0x8000, v50
	s_nop 1
	v_addc_co_u32_e32 v21, vcc, 0, v51, vcc
	global_load_dwordx4 v[22:25], v[20:21], off
.LBB0_400:
	s_or_b64 exec, exec, s[16:17]
	v_add_u32_e32 v19, 40, v43
	v_cmp_gt_i32_e64 s[16:17], 54, v43
	v_cmp_lt_i32_e32 vcc, s46, v19
	s_and_b64 s[20:21], s[16:17], vcc
	v_mov_b32_e32 v19, 0
	v_mov_b32_e32 v20, 0
	v_mov_b32_e32 v21, 0
	s_and_saveexec_b64 s[18:19], s[20:21]
	s_cbranch_execz .LBB0_402
	v_add_co_u32_e32 v18, vcc, 0xa000, v50
	s_nop 1
	v_addc_co_u32_e32 v19, vcc, 0, v51, vcc
	global_load_dwordx4 v[18:21], v[18:19], off
.LBB0_402:
	s_or_b64 exec, exec, s[18:19]
	v_add_u32_e32 v26, 48, v43
	v_cmp_gt_i32_e64 s[18:19], 46, v43
	v_cmp_lt_i32_e32 vcc, s46, v26
	s_and_b64 s[22:23], s[18:19], vcc
	v_mov_b32_e32 v26, 0
	v_mov_b32_e32 v30, 0
	v_mov_b32_e32 v31, 0
	v_mov_b32_e32 v32, 0
	v_mov_b32_e32 v33, 0
	s_and_saveexec_b64 s[20:21], s[22:23]
	s_cbranch_execz .LBB0_404
	v_add_co_u32_e32 v28, vcc, 0xc000, v50
	s_nop 1
	v_addc_co_u32_e32 v29, vcc, 0, v51, vcc
	global_load_dwordx4 v[30:33], v[28:29], off
.LBB0_404:
	s_or_b64 exec, exec, s[20:21]
	v_add_u32_e32 v27, 56, v43
	v_cmp_gt_i32_e64 s[20:21], 38, v43
	v_cmp_lt_i32_e32 vcc, s46, v27
	s_and_b64 s[24:25], s[20:21], vcc
	v_mov_b32_e32 v27, 0
	v_mov_b32_e32 v28, 0
	v_mov_b32_e32 v29, 0
	s_and_saveexec_b64 s[22:23], s[24:25]
	s_cbranch_execz .LBB0_406
	v_add_co_u32_e32 v26, vcc, 0xe000, v50
	s_nop 1
	v_addc_co_u32_e32 v27, vcc, 0, v51, vcc
	global_load_dwordx4 v[26:29], v[26:27], off
.LBB0_406:
	s_or_b64 exec, exec, s[22:23]
	v_add_u32_e32 v34, 64, v43
	v_cmp_gt_i32_e64 s[22:23], 30, v43
	v_cmp_lt_i32_e32 vcc, s46, v34
	s_and_b64 s[26:27], s[22:23], vcc
	v_mov_b32_e32 v34, 0
	v_mov_b32_e32 v38, 0
	v_mov_b32_e32 v39, 0
	v_mov_b32_e32 v40, 0
	v_mov_b32_e32 v41, 0
	s_and_saveexec_b64 s[24:25], s[26:27]
	s_cbranch_execz .LBB0_408
	v_add_co_u32_e32 v36, vcc, 0x10000, v50
	s_nop 1
	v_addc_co_u32_e32 v37, vcc, 0, v51, vcc
	global_load_dwordx4 v[38:41], v[36:37], off
.LBB0_408:
	s_or_b64 exec, exec, s[24:25]
	v_add_u32_e32 v35, 0x48, v43
	v_cmp_gt_i32_e64 s[24:25], 22, v43
	v_cmp_lt_i32_e32 vcc, s46, v35
	s_and_b64 s[28:29], s[24:25], vcc
	v_mov_b32_e32 v35, 0
	v_mov_b32_e32 v36, 0
	v_mov_b32_e32 v37, 0
	s_and_saveexec_b64 s[26:27], s[28:29]
	s_cbranch_execz .LBB0_410
	v_add_co_u32_e32 v34, vcc, 0x12000, v50
	s_nop 1
	v_addc_co_u32_e32 v35, vcc, 0, v51, vcc
	global_load_dwordx4 v[34:37], v[34:35], off
.LBB0_410:
	s_or_b64 exec, exec, s[26:27]
	v_add_u32_e32 v42, 0x50, v43
	v_cmp_gt_i32_e64 s[26:27], 14, v43
	v_cmp_lt_i32_e32 vcc, s46, v42
	s_and_b64 s[68:69], s[26:27], vcc
	v_mov_b32_e32 v42, 0
	v_mov_b32_e32 v46, 0
	v_mov_b32_e32 v47, 0
	v_mov_b32_e32 v48, 0
	v_mov_b32_e32 v49, 0
	s_and_saveexec_b64 s[28:29], s[68:69]
	s_cbranch_execz .LBB0_412
	v_add_co_u32_e32 v44, vcc, 0x14000, v50
	s_nop 1
	v_addc_co_u32_e32 v45, vcc, 0, v51, vcc
	global_load_dwordx4 v[46:49], v[44:45], off
.LBB0_412:
	s_or_b64 exec, exec, s[28:29]
	v_add_u32_e32 v44, 0x58, v43
	v_cmp_gt_i32_e64 s[28:29], 6, v43
	v_cmp_lt_i32_e32 vcc, s46, v44
	s_and_b64 s[68:69], s[28:29], vcc
	v_mov_b32_e32 v43, 0
	v_mov_b32_e32 v44, 0
	v_mov_b32_e32 v45, 0
	s_and_saveexec_b64 s[46:47], s[68:69]
	s_cbranch_execz .LBB0_414
	v_add_co_u32_e32 v42, vcc, 0x16000, v50
	s_nop 1
	v_addc_co_u32_e32 v43, vcc, 0, v51, vcc
	global_load_dwordx4 v[42:45], v[42:43], off

; #define LAS __attribute__((address_space(3)))
; __device__ __forceinline__ float row_rscale(const float* SSP, int row) {
;     const f32x4 p = *(const f32x4*)(SSP + (size_t)row * 4);
;     return rsqrtf(((p[0] + p[1]) + (p[2] + p[3])) * (1.f / 1024.f) + 1e-6f);
; }
; __device__ __forceinline__ void row_scales8(const float* SSP, int row0, int key, LAS float* rsc  , LAS int* rtag  , int wv, int fr, int fq, float (&rsv)[2][4]) {
;     const int tag = __builtin_amdgcn_readfirstlane(rtag[wv]);
;     LAS float* tab = rsc + (wv * 16 + fr) * 8;
;     if (tag == key) {
;         const f32x4 a = *(const LAS f32x4*)tab, b = *(const LAS f32x4*)(tab + 4);
; #pragma unroll
;         for (int m = 0; m < 4; ++m) { rsv[0][m] = a[m]; rsv[1][m] = b[m]; }
;     } else {
; #pragma unroll
;         for (int ai = 0; ai < 2; ++ai)
; #pragma unroll
;             for (int m = 0; m < 4; ++m) rsv[ai][m] = row_rscale(SSP, row0 + ai * HALF + m * 16);
;         if (fq == 0) { *(LAS f32x4*)tab = (f32x4){rsv[0][0], rsv[0][1], rsv[0][2], rsv[0][3]}; *(LAS f32x4*)(tab + 4) = (f32x4){rsv[1][0], rsv[1][1], rsv[1][2], rsv[1][3]}; if (fr == 0) rtag[wv] = key; }
;     }
.LBB0_474:
	v_mov_b32_e32 v156, v1
	v_mov_b32_e32 v154, v164
	v_mov_b32_e32 v50, s93
	ds_read_b32 v50, v50
	s_lshl_b32 s9, s8, 8
	s_add_i32 s9, s9, s24
	v_add_u32_e32 v150, s9, v156
	s_add_i32 s10, s69, s8
	s_waitcnt lgkmcnt(0)
	v_readfirstlane_b32 s11, v50
	v_lshlrev_b32_e32 v155, 5, v156
	s_mov_b64 s[8:9], -1
	s_cmp_eq_u32 s11, s10
	v_ashrrev_i32_e32 v151, 31, v150
	s_cbranch_scc1 .LBB0_479
	v_lshl_add_u64 v[152:153], v[150:151], 4, s[20:21]
	global_load_dwordx4 v[50:53], v[152:153], off
	global_load_dwordx4 v[102:105], v[152:153], off offset:256
	s_mov_b32 s8, 0x358637bd
	s_waitcnt vmcnt(0) lgkmcnt(0)
	v_mov_b32_e32 v158, v50
	v_mov_b32_e32 v159, v102
	v_mov_b32_e32 v102, v51
	v_pk_add_f32 v[50:51], v[158:159], v[102:103]
	global_load_dwordx4 v[158:161], v[152:153], off offset:512
	v_mov_b32_e32 v102, v52
	v_mov_b32_e32 v103, v104
	v_mov_b32_e32 v104, v53
	v_pk_add_f32 v[52:53], v[102:103], v[104:105]
	s_waitcnt vmcnt(0) lgkmcnt(0)
	v_add_f32_e32 v104, v160, v161
	v_pk_add_f32 v[50:51], v[50:51], v[52:53]
	v_mov_b64_e32 v[52:53], s[8:9]
	v_pk_fma_f32 v[50:51], v[50:51], s[72:73], v[52:53] op_sel_hi:[1,0,0]
	s_nop 0
	v_mul_f32_e32 v102, 0x4b800000, v50
	v_cmp_gt_f32_e64 s[8:9], s67, v50
	v_cmp_gt_f32_e32 vcc, s67, v51
	s_nop 0
	v_cndmask_b32_e64 v50, v50, v102, s[8:9]
	v_mul_f32_e32 v102, 0x4b800000, v51
	v_cndmask_b32_e32 v51, v51, v102, vcc
	v_rsq_f32_e32 v50, v50
	v_rsq_f32_e32 v51, v51
	s_nop 0
	v_pk_mul_f32 v[102:103], v[50:51], s[76:77] op_sel_hi:[1,0]
	s_nop 0
	v_cndmask_b32_e64 v102, v50, v102, s[8:9]
	v_add_f32_e32 v50, v158, v159
	global_load_dwordx4 v[158:161], v[152:153], off offset:768
	v_cndmask_b32_e32 v103, v51, v103, vcc
	s_waitcnt vmcnt(0) lgkmcnt(0)
	v_mov_b32_e32 v162, v159
	v_mov_b32_e32 v163, v160
	v_mov_b32_e32 v159, v161
	v_pk_add_f32 v[158:159], v[162:163], v[158:159]
	s_nop 0
	v_mov_b32_e32 v51, v158
	v_mov_b32_e32 v105, v159
	global_load_dwordx4 v[158:161], v[152:153], off offset:2048
	global_load_dwordx4 v[180:183], v[152:153], off offset:2304
	v_pk_add_f32 v[50:51], v[50:51], v[104:105]
	s_nop 0
	v_pk_fma_f32 v[50:51], v[50:51], s[72:73], v[52:53] op_sel_hi:[1,0,0]
	s_nop 0
	v_mul_f32_e32 v104, 0x4b800000, v50
	v_cmp_gt_f32_e64 s[8:9], s67, v50
	v_cmp_gt_f32_e32 vcc, s67, v51
	s_nop 0
	v_cndmask_b32_e64 v50, v50, v104, s[8:9]
	v_mul_f32_e32 v104, 0x4b800000, v51
	v_cndmask_b32_e32 v51, v51, v104, vcc
	v_rsq_f32_e32 v50, v50
	v_rsq_f32_e32 v51, v51
	s_nop 0
	v_pk_mul_f32 v[104:105], v[50:51], s[76:77] op_sel_hi:[1,0]
	s_nop 0
	v_cndmask_b32_e32 v105, v51, v105, vcc
	v_cndmask_b32_e64 v104, v50, v104, s[8:9]
	s_waitcnt vmcnt(0) lgkmcnt(0)
	v_mov_b32_e32 v50, v158
	v_mov_b32_e32 v51, v180
	v_mov_b32_e32 v180, v159
	v_mov_b32_e32 v158, v160
	v_mov_b32_e32 v159, v182
	v_mov_b32_e32 v182, v161
	v_pk_add_f32 v[50:51], v[50:51], v[180:181]
	v_pk_add_f32 v[158:159], v[158:159], v[182:183]
	s_nop 0
	v_pk_add_f32 v[50:51], v[50:51], v[158:159]
	s_nop 0
	v_pk_fma_f32 v[50:51], v[50:51], s[72:73], v[52:53] op_sel_hi:[1,0,0]
	s_nop 0
	v_mul_f32_e32 v157, 0x4b800000, v50
	v_cmp_gt_f32_e64 s[8:9], s67, v50
	v_cmp_gt_f32_e32 vcc, s67, v51
	s_nop 0
	v_cndmask_b32_e64 v50, v50, v157, s[8:9]
	v_mul_f32_e32 v157, 0x4b800000, v51
	v_cndmask_b32_e32 v51, v51, v157, vcc
	v_rsq_f32_e32 v50, v50
	v_rsq_f32_e32 v51, v51
	s_nop 0
	v_pk_mul_f32 v[158:159], v[50:51], s[76:77] op_sel_hi:[1,0]
	s_nop 0
	v_cndmask_b32_e32 v51, v51, v159, vcc
	v_cndmask_b32_e64 v50, v50, v158, s[8:9]
	global_load_dwordx4 v[158:161], v[152:153], off offset:2560
	s_waitcnt vmcnt(0) lgkmcnt(0)
	v_add_f32_e32 v162, v158, v159
	v_add_f32_e32 v180, v160, v161
	global_load_dwordx4 v[158:161], v[152:153], off offset:2816
	s_waitcnt vmcnt(0) lgkmcnt(0)
	v_mov_b32_e32 v152, v159
	v_mov_b32_e32 v153, v160
	v_mov_b32_e32 v159, v161
	v_pk_add_f32 v[152:153], v[152:153], v[158:159]
	s_nop 0
	v_mov_b32_e32 v163, v152
	v_mov_b32_e32 v181, v153
	v_pk_add_f32 v[152:153], v[162:163], v[180:181]
	s_nop 0
	v_pk_fma_f32 v[52:53], v[152:153], s[72:73], v[52:53] op_sel_hi:[1,0,0]
	s_nop 0
	v_mul_f32_e32 v152, 0x4b800000, v52
	v_cmp_gt_f32_e64 s[8:9], s67, v52
	v_cmp_gt_f32_e32 vcc, s67, v53
	s_nop 0
	v_cndmask_b32_e64 v52, v52, v152, s[8:9]
	v_mul_f32_e32 v152, 0x4b800000, v53
	v_cndmask_b32_e32 v53, v53, v152, vcc
	v_rsq_f32_e32 v52, v52
	v_rsq_f32_e32 v53, v53
	s_nop 0
	v_pk_mul_f32 v[152:153], v[52:53], s[76:77] op_sel_hi:[1,0]
	s_nop 0
	v_cndmask_b32_e32 v53, v53, v153, vcc
	v_cndmask_b32_e64 v52, v52, v152, s[8:9]
	v_cmp_eq_u32_e32 vcc, 0, v154
	s_and_saveexec_b64 s[8:9], vcc
	s_cbranch_execz .LBB0_478
	v_add_u32_e32 v152, s94, v155
	v_cmp_eq_u32_e32 vcc, 0, v156
	ds_write_b128 v152, v[102:105]
	ds_write_b128 v152, v[50:53] offset:16
	s_and_b64 exec, exec, vcc
	v_mov_b32_e32 v152, s93
	v_mov_b32_e32 v153, s10
	ds_write_b32 v152, v153

; __device__ __forceinline__ unsigned pk2(float lo, float hi) { f32x2_t v = {lo, hi}; bf16x2_t b = __builtin_convertvector(v, bf16x2_t); return __builtin_bit_cast(unsigned, b); }
;     __device__ __forceinline__ void operator()(const f32x4 (&acc)[2][2][4][2], const Unit& u, int wr, int wc, int fr, int fq) const {
;     ...
; #pragma unroll
;                     for (int bj = 0; bj < 2; ++bj) {
;                         const float rq = (pn < 2) ? rs * (0.125f * LOG2E) : rs;
;                         const f32x4 v0 = acc[ai][bj][m][0] * rq, v1 = acc[ai][bj][m][1] * rq;
;                         u32x4 w; w.x = pk2(v0[0], v0[1]); w.y = pk2(v0[2], v0[3]); w.z = pk2(v1[0], v1[1]); w.w = pk2(v1[2], v1[3]);
;                         bf16_t* dst;
;                         if (pn < 2) dst = (bf16_t*)(ws + WS_Q) + (size_t)row * 512 + pn * 256 + bj * 128 + cl;
;                         else if (pn == 2) { const int b = row >> 12, tok = row & 4095, gg = cl >> 6, d0 = cl & 63;
;                             dst = (bf16_t*)(ws + WS_KCMP) + ((size_t)((bj * 16 + b * 2 + gg) * 4096 + tok)) * 64 + d0; }
;                         else if (pn == 3) dst = (bf16_t*)(ws + (bj ? WS_VS : WS_KS)) + (size_t)row * 128 + cl;
;                         else dst = (bf16_t*)(ws + (bj ? WS_VW : WS_KW)) + (size_t)row * 128 + cl;
;                         *(u32x4*)dst = w;
.LBB0_495:
	s_waitcnt lgkmcnt(0)
	v_mul_f32_e32 v158, 0x3e38aa3b, v102
	v_cndmask_b32_e64 v158, v102, v158, s[8:9]
	v_pk_mul_f32 v[184:185], v[132:133], v[158:159] op_sel_hi:[1,0]
	v_pk_mul_f32 v[182:183], v[130:131], v[158:159] op_sel_hi:[1,0]
	v_pk_mul_f32 v[186:187], v[128:129], v[158:159] op_sel_hi:[1,0]
	v_pk_mul_f32 v[188:189], v[126:127], v[158:159] op_sel_hi:[1,0]
	v_cvt_pk_bf16_f32 v182, v182, v183
	v_cvt_pk_bf16_f32 v183, v184, v185
	v_cvt_pk_bf16_f32 v184, v188, v189
	v_cvt_pk_bf16_f32 v185, v186, v187
	s_andn2_b64 vcc, exec, s[84:85]
	s_mov_b64 s[12:13], -1
	global_store_dwordx4 v[162:163], v[182:185], off
	s_cbranch_vccnz .LBB0_505
	s_cmp_lt_i32 s40, 3
	s_cbranch_scc1 .LBB0_502
	s_cmp_lg_u32 s40, 3
	s_cbranch_scc0 .LBB0_499
	v_readlane_b32 s12, v255, 29
	v_readlane_b32 s13, v255, 30
	s_nop 1
	v_lshl_add_u64 v[162:163], s[12:13], 0, v[156:157]
	v_lshl_add_u64 v[162:163], v[152:153], 1, v[162:163]
	s_mov_b64 s[12:13], 0

; __device__ __forceinline__ unsigned pk2(float lo, float hi) { f32x2_t v = {lo, hi}; bf16x2_t b = __builtin_convertvector(v, bf16x2_t); return __builtin_bit_cast(unsigned, b); }
; __device__ __forceinline__ float fsigmoid(float x) { return __builtin_amdgcn_rcpf(1.0f + __expf(-x)); }
;     __device__ __forceinline__ void operator()(const f32x4 (&acc)[2][2][4][2], const Unit& u, int wr, int wc, int fr, int fq) const {
;     ...
;                     if (wc == 0) {
;                         const f32x4 a0 = acc[ai][0][m][0] * rs, a1 = acc[ai][0][m][1] * rs;
;                         float* gp = (float*)(ws + WS_G) + (size_t)row * 32 + 8 * fq;
;                         *(f32x4*)gp = (f32x4){fsigmoid(a0[0]), fsigmoid(a0[1]), fsigmoid(a0[2]), fsigmoid(a0[3])};
;                         *(f32x4*)(gp + 4) = (f32x4){fsigmoid(a1[0]), fsigmoid(a1[1]), fsigmoid(a1[2]), fsigmoid(a1[3])};
;                     }
;     ...
; #pragma unroll
;                     for (int bj = 0; bj < 2; ++bj) {
;                         const float rq = (pn < 2) ? rs * (0.125f * LOG2E) : rs;
;                         const f32x4 v0 = acc[ai][bj][m][0] * rq, v1 = acc[ai][bj][m][1] * rq;
;                         u32x4 w; w.x = pk2(v0[0], v0[1]); w.y = pk2(v0[2], v0[3]); w.z = pk2(v1[0], v1[1]); w.w = pk2(v1[2], v1[3]);
;                         bf16_t* dst;
;                         if (pn < 2) dst = (bf16_t*)(ws + WS_Q) + (size_t)row * 512 + pn * 256 + bj * 128 + cl;
;                         else if (pn == 2) { const int b = row >> 12, tok = row & 4095, gg = cl >> 6, d0 = cl & 63;
;                             dst = (bf16_t*)(ws + WS_KCMP) + ((size_t)((bj * 16 + b * 2 + gg) * 4096 + tok)) * 64 + d0; }
;                         else if (pn == 3) dst = (bf16_t*)(ws + (bj ? WS_VS : WS_KS)) + (size_t)row * 128 + cl;
;                         else dst = (bf16_t*)(ws + (bj ? WS_VW : WS_KW)) + (size_t)row * 128 + cl;
;                         *(u32x4*)dst = w;
.LBB0_507:
	v_mov_b32_e32 v159, v158
	v_mov_b32_e32 v156, v158
	v_mov_b32_e32 v157, v158
	v_pk_mul_f32 v[160:161], v[136:137], v[156:157]
	v_pk_mul_f32 v[180:181], v[134:135], v[158:159]
	v_pk_mul_f32 v[182:183], v[124:125], v[156:157]
	v_pk_mul_f32 v[158:159], v[122:123], v[158:159]
	v_cvt_pk_bf16_f32 v156, v180, v181
	v_cvt_pk_bf16_f32 v157, v160, v161
	v_cvt_pk_bf16_f32 v158, v158, v159
	v_cvt_pk_bf16_f32 v159, v182, v183
	s_mov_b64 s[12:13], 0
	global_store_dwordx4 v[162:163], v[156:159], off
.LBB0_508:
	s_and_b64 vcc, exec, s[12:13]
	s_cbranch_vccz .LBB0_511
	s_andn2_b64 vcc, exec, s[22:23]
	s_cbranch_vccnz .LBB0_511
	s_waitcnt lgkmcnt(0)
	v_pk_mul_f32 v[158:159], v[132:133], v[102:103] op_sel_hi:[1,0]
	v_pk_mul_f32 v[156:157], v[130:131], v[102:103] op_sel_hi:[1,0]
	v_pk_mul_f32 v[162:163], v[128:129], v[102:103] op_sel_hi:[1,0]
	v_pk_mul_f32 v[160:161], v[126:127], v[102:103] op_sel_hi:[1,0]
	v_mul_f32_e32 v156, 0xbfb8aa3b, v156
	v_mul_f32_e32 v157, 0xbfb8aa3b, v157
	v_mul_f32_e32 v158, 0xbfb8aa3b, v158
	v_mul_f32_e32 v159, 0xbfb8aa3b, v159
	v_exp_f32_e32 v156, v156
	v_exp_f32_e32 v157, v157
	v_exp_f32_e32 v158, v158
	v_exp_f32_e32 v159, v159
	v_mul_f32_e32 v160, 0xbfb8aa3b, v160
	v_mul_f32_e32 v161, 0xbfb8aa3b, v161
	v_mul_f32_e32 v162, 0xbfb8aa3b, v162
	v_mul_f32_e32 v163, 0xbfb8aa3b, v163
	v_exp_f32_e32 v160, v160
	v_exp_f32_e32 v161, v161
	v_exp_f32_e32 v162, v162
	v_exp_f32_e32 v163, v163
	v_add_f32_e32 v156, 1.0, v156
	v_add_f32_e32 v157, 1.0, v157
	v_add_f32_e32 v158, 1.0, v158
	v_add_f32_e32 v159, 1.0, v159
	v_rcp_f32_e32 v156, v156
	v_rcp_f32_e32 v157, v157
	v_rcp_f32_e32 v158, v158
	v_rcp_f32_e32 v159, v159
	v_add_f32_e32 v160, 1.0, v160
	v_add_f32_e32 v161, 1.0, v161
	v_add_f32_e32 v162, 1.0, v162
	v_add_f32_e32 v163, 1.0, v163
	v_lshlrev_b64 v[180:181], 7, v[150:151]
	v_rcp_f32_e32 v160, v160
	v_rcp_f32_e32 v161, v161
	v_rcp_f32_e32 v162, v162
	v_rcp_f32_e32 v163, v163
	v_lshl_add_u64 v[180:181], s[96:97], 0, v[180:181]
	v_lshl_add_u64 v[180:181], v[154:155], 2, v[180:181]
	global_store_dwordx4 v[180:181], v[156:159], off
	global_store_dwordx4 v[180:181], v[160:163], off offset:16

; __device__ __forceinline__ unsigned pk2(float lo, float hi) { f32x2_t v = {lo, hi}; bf16x2_t b = __builtin_convertvector(v, bf16x2_t); return __builtin_bit_cast(unsigned, b); }
; __device__ __forceinline__ f32x2 glu_pk(f32x2 a, f32x2 b, float c1, float rs) {
;     const f32x2 t = b * c1; f32x2 e; e.x = __builtin_amdgcn_exp2f(t.x); e.y = __builtin_amdgcn_exp2f(t.y);
;     const f32x2 d = e + 1.0f; f32x2 sg; sg.x = __builtin_amdgcn_rcpf(d.x); sg.y = __builtin_amdgcn_rcpf(d.y);
;     return a * (sg * rs);
; }
;     __device__ __forceinline__ void operator()(const f32x4 (&acc)[2][2][4][2], const Unit& u, int wr, int wc, int fr, int fq) const {
;     ...
;                 if (pn >= 4 && pn <= 7) {
;                     const float c1 = -rs * LOG2E;
;                     const f32x4 a0 = acc[ai][0][m][0], a1 = acc[ai][0][m][1], b0 = acc[ai][1][m][0], b1 = acc[ai][1][m][1];
;                     const f32x2 o0 = glu_pk((f32x2){a0[0], a0[1]}, (f32x2){b0[0], b0[1]}, c1, rs), o1 = glu_pk((f32x2){a0[2], a0[3]}, (f32x2){b0[2], b0[3]}, c1, rs);
;                     const f32x2 o2 = glu_pk((f32x2){a1[0], a1[1]}, (f32x2){b1[0], b1[1]}, c1, rs), o3 = glu_pk((f32x2){a1[2], a1[3]}, (f32x2){b1[2], b1[3]}, c1, rs);
;                     u32x4 w; w.x = pk2(o0.x, o0.y); w.y = pk2(o1.x, o1.y); w.z = pk2(o2.x, o2.y); w.w = pk2(o3.x, o3.y);
;                     *(u32x4*)((bf16_t*)(ws + WS_GLU) + (size_t)row * 512 + (pn - 4) * 128 + cl) = w;
.LBB0_512:
	s_andn2_b64 vcc, exec, s[12:13]
	s_lshl_b32 s43, s40, 7
	s_cbranch_vccnz .LBB0_514
	s_waitcnt lgkmcnt(0)
	v_mul_f32_e32 v156, 0xbfb8aa3b, v102
	v_pk_mul_f32 v[122:123], v[122:123], v[156:157] op_sel_hi:[1,0]
	v_pk_mul_f32 v[124:125], v[124:125], v[156:157] op_sel_hi:[1,0]
	v_exp_f32_e32 v122, v122
	v_exp_f32_e32 v123, v123
	v_exp_f32_e32 v124, v124
	v_exp_f32_e32 v125, v125
	v_pk_mul_f32 v[134:135], v[134:135], v[156:157] op_sel_hi:[1,0]
	v_pk_mul_f32 v[136:137], v[136:137], v[156:157] op_sel_hi:[1,0]
	v_exp_f32_e32 v134, v134
	v_exp_f32_e32 v135, v135
	v_pk_add_f32 v[122:123], v[122:123], 1.0 op_sel_hi:[1,0]
	v_exp_f32_e32 v136, v136
	v_exp_f32_e32 v137, v137
	v_rcp_f32_e32 v122, v122
	v_rcp_f32_e32 v123, v123
	v_pk_add_f32 v[124:125], v[124:125], 1.0 op_sel_hi:[1,0]
	v_pk_add_f32 v[134:135], v[134:135], 1.0 op_sel_hi:[1,0]
	v_rcp_f32_e32 v124, v124
	v_rcp_f32_e32 v125, v125
	v_rcp_f32_e32 v134, v134
	v_rcp_f32_e32 v135, v135
	v_pk_add_f32 v[136:137], v[136:137], 1.0 op_sel_hi:[1,0]
	v_pk_mul_f32 v[122:123], v[102:103], v[122:123] op_sel_hi:[0,1]
	v_rcp_f32_e32 v136, v136
	v_rcp_f32_e32 v137, v137
	v_pk_mul_f32 v[126:127], v[126:127], v[122:123]
	v_pk_mul_f32 v[122:123], v[102:103], v[124:125] op_sel_hi:[0,1]
	v_cvt_pk_bf16_f32 v124, v126, v127
	v_lshlrev_b64 v[126:127], 10, v[150:151]
	v_lshl_add_u64 v[126:127], s[86:87], 0, v[126:127]
	s_lshl_b32 s62, s43, 1
	v_pk_mul_f32 v[134:135], v[102:103], v[134:135] op_sel_hi:[0,1]
	v_lshl_add_u64 v[126:127], v[126:127], 0, s[62:63]
	v_pk_mul_f32 v[130:131], v[130:131], v[134:135]
	v_pk_mul_f32 v[134:135], v[102:103], v[136:137] op_sel_hi:[0,1]
	v_lshl_add_u64 v[126:127], v[152:153], 1, v[126:127]
	v_pk_mul_f32 v[132:133], v[132:133], v[134:135]
	v_pk_mul_f32 v[128:129], v[128:129], v[122:123]
	v_add_co_u32_e32 v126, vcc, 0x139ff000, v126
	v_cvt_pk_bf16_f32 v122, v130, v131
	v_cvt_pk_bf16_f32 v123, v132, v133
	v_cvt_pk_bf16_f32 v125, v128, v129
	v_addc_co_u32_e32 v127, vcc, 0, v127, vcc
	global_store_dwordx4 v[126:127], v[122:125], off offset:3072

; __device__ __forceinline__ unsigned pk2(float lo, float hi) { f32x2_t v = {lo, hi}; bf16x2_t b = __builtin_convertvector(v, bf16x2_t); return __builtin_bit_cast(unsigned, b); }
;     __device__ __forceinline__ void operator()(const f32x4 (&acc)[2][2][4][2], const Unit& u, int wr, int wc, int fr, int fq) const {
;     ...
; #pragma unroll
;                     for (int bj = 0; bj < 2; ++bj) {
;                         const float rq = (pn < 2) ? rs * (0.125f * LOG2E) : rs;
;                         const f32x4 v0 = acc[ai][bj][m][0] * rq, v1 = acc[ai][bj][m][1] * rq;
;                         u32x4 w; w.x = pk2(v0[0], v0[1]); w.y = pk2(v0[2], v0[3]); w.z = pk2(v1[0], v1[1]); w.w = pk2(v1[2], v1[3]);
;                         bf16_t* dst;
;                         if (pn < 2) dst = (bf16_t*)(ws + WS_Q) + (size_t)row * 512 + pn * 256 + bj * 128 + cl;
;                         else if (pn == 2) { const int b = row >> 12, tok = row & 4095, gg = cl >> 6, d0 = cl & 63;
;                             dst = (bf16_t*)(ws + WS_KCMP) + ((size_t)((bj * 16 + b * 2 + gg) * 4096 + tok)) * 64 + d0; }
;                         else if (pn == 3) dst = (bf16_t*)(ws + (bj ? WS_VS : WS_KS)) + (size_t)row * 128 + cl;
;                         else dst = (bf16_t*)(ws + (bj ? WS_VW : WS_KW)) + (size_t)row * 128 + cl;
;                         *(u32x4*)dst = w;
.LBB0_528:
	s_waitcnt lgkmcnt(0)
	v_mul_f32_e32 v123, 0x3e38aa3b, v103
	v_cndmask_b32_e64 v126, v103, v123, s[8:9]
	v_pk_mul_f32 v[136:137], v[116:117], v[126:127] op_sel_hi:[1,0]
	v_pk_mul_f32 v[134:135], v[114:115], v[126:127] op_sel_hi:[1,0]
	v_pk_mul_f32 v[156:157], v[112:113], v[126:127] op_sel_hi:[1,0]
	v_pk_mul_f32 v[158:159], v[110:111], v[126:127] op_sel_hi:[1,0]
	v_cvt_pk_bf16_f32 v134, v134, v135
	v_cvt_pk_bf16_f32 v135, v136, v137
	v_cvt_pk_bf16_f32 v136, v158, v159
	v_cvt_pk_bf16_f32 v137, v156, v157
	s_and_b64 vcc, exec, s[14:15]
	s_mov_b64 s[14:15], -1
	global_store_dwordx4 v[130:131], v[134:137], off
	s_cbranch_vccnz .LBB0_538
	s_cmp_lt_i32 s40, 3
	s_cbranch_scc1 .LBB0_535
	s_cmp_lg_u32 s40, 3
	s_cbranch_scc0 .LBB0_532
	v_readlane_b32 s14, v255, 29
	v_readlane_b32 s15, v255, 30
	s_nop 1
	v_lshl_add_u64 v[130:131], s[14:15], 0, v[124:125]
	v_lshl_add_u64 v[130:131], v[152:153], 1, v[130:131]
	s_mov_b64 s[14:15], 0

; __device__ __forceinline__ unsigned pk2(float lo, float hi) { f32x2_t v = {lo, hi}; bf16x2_t b = __builtin_convertvector(v, bf16x2_t); return __builtin_bit_cast(unsigned, b); }
;     __device__ __forceinline__ void operator()(const f32x4 (&acc)[2][2][4][2], const Unit& u, int wr, int wc, int fr, int fq) const {
;     ...
; #pragma unroll
;                     for (int bj = 0; bj < 2; ++bj) {
;                         const float rq = (pn < 2) ? rs * (0.125f * LOG2E) : rs;
;                         const f32x4 v0 = acc[ai][bj][m][0] * rq, v1 = acc[ai][bj][m][1] * rq;
;                         u32x4 w; w.x = pk2(v0[0], v0[1]); w.y = pk2(v0[2], v0[3]); w.z = pk2(v1[0], v1[1]); w.w = pk2(v1[2], v1[3]);
;                         bf16_t* dst;
;                         if (pn < 2) dst = (bf16_t*)(ws + WS_Q) + (size_t)row * 512 + pn * 256 + bj * 128 + cl;
;                         else if (pn == 2) { const int b = row >> 12, tok = row & 4095, gg = cl >> 6, d0 = cl & 63;
;                             dst = (bf16_t*)(ws + WS_KCMP) + ((size_t)((bj * 16 + b * 2 + gg) * 4096 + tok)) * 64 + d0; }
;                         else if (pn == 3) dst = (bf16_t*)(ws + (bj ? WS_VS : WS_KS)) + (size_t)row * 128 + cl;
;                         else dst = (bf16_t*)(ws + (bj ? WS_VW : WS_KW)) + (size_t)row * 128 + cl;
;                         *(u32x4*)dst = w;
.LBB0_540:
	v_mov_b32_e32 v127, v126
	v_mov_b32_e32 v124, v126
	v_mov_b32_e32 v125, v126
	v_pk_mul_f32 v[128:129], v[120:121], v[124:125]
	v_pk_mul_f32 v[132:133], v[118:119], v[126:127]
	v_pk_mul_f32 v[134:135], v[108:109], v[124:125]
	v_pk_mul_f32 v[126:127], v[106:107], v[126:127]
	v_cvt_pk_bf16_f32 v124, v132, v133
	v_cvt_pk_bf16_f32 v125, v128, v129
	v_cvt_pk_bf16_f32 v126, v126, v127
	v_cvt_pk_bf16_f32 v127, v134, v135
	s_mov_b64 s[14:15], 0
	global_store_dwordx4 v[130:131], v[124:127], off

; __device__ __forceinline__ unsigned pk2(float lo, float hi) { f32x2_t v = {lo, hi}; bf16x2_t b = __builtin_convertvector(v, bf16x2_t); return __builtin_bit_cast(unsigned, b); }
;     __device__ __forceinline__ void operator()(const f32x4 (&acc)[2][2][4][2], const Unit& u, int wr, int wc, int fr, int fq) const {
;     ...
; #pragma unroll
;                     for (int bj = 0; bj < 2; ++bj) {
;                         const float rq = (pn < 2) ? rs * (0.125f * LOG2E) : rs;
;                         const f32x4 v0 = acc[ai][bj][m][0] * rq, v1 = acc[ai][bj][m][1] * rq;
;                         u32x4 w; w.x = pk2(v0[0], v0[1]); w.y = pk2(v0[2], v0[3]); w.z = pk2(v1[0], v1[1]); w.w = pk2(v1[2], v1[3]);
;                         bf16_t* dst;
;                         if (pn < 2) dst = (bf16_t*)(ws + WS_Q) + (size_t)row * 512 + pn * 256 + bj * 128 + cl;
;                         else if (pn == 2) { const int b = row >> 12, tok = row & 4095, gg = cl >> 6, d0 = cl & 63;
;                             dst = (bf16_t*)(ws + WS_KCMP) + ((size_t)((bj * 16 + b * 2 + gg) * 4096 + tok)) * 64 + d0; }
;                         else if (pn == 3) dst = (bf16_t*)(ws + (bj ? WS_VS : WS_KS)) + (size_t)row * 128 + cl;
;                         else dst = (bf16_t*)(ws + (bj ? WS_VW : WS_KW)) + (size_t)row * 128 + cl;
;                         *(u32x4*)dst = w;
.LBB0_558:
	v_mul_f32_e32 v103, 0x3e38aa3b, v104
	v_cndmask_b32_e64 v108, v104, v103, s[8:9]
	v_pk_mul_f32 v[118:119], v[96:97], v[108:109] op_sel_hi:[1,0]
	v_pk_mul_f32 v[116:117], v[94:95], v[108:109] op_sel_hi:[1,0]
	v_pk_mul_f32 v[120:121], v[92:93], v[108:109] op_sel_hi:[1,0]
	v_pk_mul_f32 v[122:123], v[90:91], v[108:109] op_sel_hi:[1,0]
	v_cvt_pk_bf16_f32 v116, v116, v117
	v_cvt_pk_bf16_f32 v117, v118, v119
	v_cvt_pk_bf16_f32 v118, v122, v123
	v_cvt_pk_bf16_f32 v119, v120, v121
	s_and_b64 vcc, exec, s[14:15]
	s_mov_b64 s[14:15], -1
	global_store_dwordx4 v[112:113], v[116:119], off
	s_cbranch_vccnz .LBB0_568
	s_cmp_lt_i32 s40, 3
	s_cbranch_scc1 .LBB0_565
	s_cmp_lg_u32 s40, 3
	s_cbranch_scc0 .LBB0_562
	v_readlane_b32 s14, v255, 29
	v_readlane_b32 s15, v255, 30
	s_nop 1
	v_lshl_add_u64 v[112:113], s[14:15], 0, v[106:107]
	v_lshl_add_u64 v[112:113], v[152:153], 1, v[112:113]
	s_mov_b64 s[14:15], 0

; __device__ __forceinline__ unsigned pk2(float lo, float hi) { f32x2_t v = {lo, hi}; bf16x2_t b = __builtin_convertvector(v, bf16x2_t); return __builtin_bit_cast(unsigned, b); }
;     __device__ __forceinline__ void operator()(const f32x4 (&acc)[2][2][4][2], const Unit& u, int wr, int wc, int fr, int fq) const {
;     ...
; #pragma unroll
;                     for (int bj = 0; bj < 2; ++bj) {
;                         const float rq = (pn < 2) ? rs * (0.125f * LOG2E) : rs;
;                         const f32x4 v0 = acc[ai][bj][m][0] * rq, v1 = acc[ai][bj][m][1] * rq;
;                         u32x4 w; w.x = pk2(v0[0], v0[1]); w.y = pk2(v0[2], v0[3]); w.z = pk2(v1[0], v1[1]); w.w = pk2(v1[2], v1[3]);
;                         bf16_t* dst;
;                         if (pn < 2) dst = (bf16_t*)(ws + WS_Q) + (size_t)row * 512 + pn * 256 + bj * 128 + cl;
;                         else if (pn == 2) { const int b = row >> 12, tok = row & 4095, gg = cl >> 6, d0 = cl & 63;
;                             dst = (bf16_t*)(ws + WS_KCMP) + ((size_t)((bj * 16 + b * 2 + gg) * 4096 + tok)) * 64 + d0; }
;                         else if (pn == 3) dst = (bf16_t*)(ws + (bj ? WS_VS : WS_KS)) + (size_t)row * 128 + cl;
;                         else dst = (bf16_t*)(ws + (bj ? WS_VW : WS_KW)) + (size_t)row * 128 + cl;
;                         *(u32x4*)dst = w;
.LBB0_570:
	v_mov_b32_e32 v109, v108
	v_mov_b32_e32 v106, v108
	v_mov_b32_e32 v107, v108
	v_pk_mul_f32 v[110:111], v[100:101], v[106:107]
	v_pk_mul_f32 v[114:115], v[98:99], v[108:109]
	v_pk_mul_f32 v[116:117], v[88:89], v[106:107]
	v_pk_mul_f32 v[108:109], v[86:87], v[108:109]
	v_cvt_pk_bf16_f32 v106, v114, v115
	v_cvt_pk_bf16_f32 v107, v110, v111
	v_cvt_pk_bf16_f32 v108, v108, v109
	v_cvt_pk_bf16_f32 v109, v116, v117
	s_mov_b64 s[14:15], 0
	global_store_dwordx4 v[112:113], v[106:109], off

; __device__ __forceinline__ unsigned pk2(float lo, float hi) { f32x2_t v = {lo, hi}; bf16x2_t b = __builtin_convertvector(v, bf16x2_t); return __builtin_bit_cast(unsigned, b); }
;     __device__ __forceinline__ void operator()(const f32x4 (&acc)[2][2][4][2], const Unit& u, int wr, int wc, int fr, int fq) const {
;     ...
; #pragma unroll
;                     for (int bj = 0; bj < 2; ++bj) {
;                         const float rq = (pn < 2) ? rs * (0.125f * LOG2E) : rs;
;                         const f32x4 v0 = acc[ai][bj][m][0] * rq, v1 = acc[ai][bj][m][1] * rq;
;                         u32x4 w; w.x = pk2(v0[0], v0[1]); w.y = pk2(v0[2], v0[3]); w.z = pk2(v1[0], v1[1]); w.w = pk2(v1[2], v1[3]);
;                         bf16_t* dst;
;                         if (pn < 2) dst = (bf16_t*)(ws + WS_Q) + (size_t)row * 512 + pn * 256 + bj * 128 + cl;
;                         else if (pn == 2) { const int b = row >> 12, tok = row & 4095, gg = cl >> 6, d0 = cl & 63;
;                             dst = (bf16_t*)(ws + WS_KCMP) + ((size_t)((bj * 16 + b * 2 + gg) * 4096 + tok)) * 64 + d0; }
;                         else if (pn == 3) dst = (bf16_t*)(ws + (bj ? WS_VS : WS_KS)) + (size_t)row * 128 + cl;
;                         else dst = (bf16_t*)(ws + (bj ? WS_VW : WS_KW)) + (size_t)row * 128 + cl;
;                         *(u32x4*)dst = w;
.LBB0_588:
	v_mul_f32_e32 v87, 0x3e38aa3b, v105
	v_cndmask_b32_e64 v90, v105, v87, s[8:9]
	v_pk_mul_f32 v[100:101], v[80:81], v[90:91] op_sel_hi:[1,0]
	v_pk_mul_f32 v[98:99], v[78:79], v[90:91] op_sel_hi:[1,0]
	v_pk_mul_f32 v[102:103], v[76:77], v[90:91] op_sel_hi:[1,0]
	v_pk_mul_f32 v[106:107], v[74:75], v[90:91] op_sel_hi:[1,0]
	v_cvt_pk_bf16_f32 v98, v98, v99
	v_cvt_pk_bf16_f32 v99, v100, v101
	v_cvt_pk_bf16_f32 v100, v106, v107
	v_cvt_pk_bf16_f32 v101, v102, v103
	s_and_b64 vcc, exec, s[14:15]
	s_mov_b64 s[14:15], -1
	global_store_dwordx4 v[94:95], v[98:101], off
	s_cbranch_vccnz .LBB0_598
	s_cmp_lt_i32 s40, 3
	s_cbranch_scc1 .LBB0_595
	s_cmp_lg_u32 s40, 3
	s_cbranch_scc0 .LBB0_592
	v_readlane_b32 s14, v255, 29
	v_readlane_b32 s15, v255, 30
	s_nop 1
	v_lshl_add_u64 v[94:95], s[14:15], 0, v[88:89]
	v_lshl_add_u64 v[94:95], v[152:153], 1, v[94:95]
	s_mov_b64 s[14:15], 0

; __device__ __forceinline__ unsigned pk2(float lo, float hi) { f32x2_t v = {lo, hi}; bf16x2_t b = __builtin_convertvector(v, bf16x2_t); return __builtin_bit_cast(unsigned, b); }
;     __device__ __forceinline__ void operator()(const f32x4 (&acc)[2][2][4][2], const Unit& u, int wr, int wc, int fr, int fq) const {
;     ...
; #pragma unroll
;                     for (int bj = 0; bj < 2; ++bj) {
;                         const float rq = (pn < 2) ? rs * (0.125f * LOG2E) : rs;
;                         const f32x4 v0 = acc[ai][bj][m][0] * rq, v1 = acc[ai][bj][m][1] * rq;
;                         u32x4 w; w.x = pk2(v0[0], v0[1]); w.y = pk2(v0[2], v0[3]); w.z = pk2(v1[0], v1[1]); w.w = pk2(v1[2], v1[3]);
;                         bf16_t* dst;
;                         if (pn < 2) dst = (bf16_t*)(ws + WS_Q) + (size_t)row * 512 + pn * 256 + bj * 128 + cl;
;                         else if (pn == 2) { const int b = row >> 12, tok = row & 4095, gg = cl >> 6, d0 = cl & 63;
;                             dst = (bf16_t*)(ws + WS_KCMP) + ((size_t)((bj * 16 + b * 2 + gg) * 4096 + tok)) * 64 + d0; }
;                         else if (pn == 3) dst = (bf16_t*)(ws + (bj ? WS_VS : WS_KS)) + (size_t)row * 128 + cl;
;                         else dst = (bf16_t*)(ws + (bj ? WS_VW : WS_KW)) + (size_t)row * 128 + cl;
;                         *(u32x4*)dst = w;
.LBB0_600:
	v_mov_b32_e32 v91, v90
	v_mov_b32_e32 v88, v90
	v_mov_b32_e32 v89, v90
	v_pk_mul_f32 v[92:93], v[84:85], v[88:89]
	v_pk_mul_f32 v[96:97], v[82:83], v[90:91]
	v_pk_mul_f32 v[98:99], v[72:73], v[88:89]
	v_pk_mul_f32 v[90:91], v[70:71], v[90:91]
	v_cvt_pk_bf16_f32 v88, v96, v97
	v_cvt_pk_bf16_f32 v89, v92, v93
	v_cvt_pk_bf16_f32 v90, v90, v91
	v_cvt_pk_bf16_f32 v91, v98, v99
	s_mov_b64 s[14:15], 0
	global_store_dwordx4 v[94:95], v[88:91], off

; __device__ __forceinline__ unsigned pk2(float lo, float hi) { f32x2_t v = {lo, hi}; bf16x2_t b = __builtin_convertvector(v, bf16x2_t); return __builtin_bit_cast(unsigned, b); }
;     __device__ __forceinline__ void operator()(const f32x4 (&acc)[2][2][4][2], const Unit& u, int wr, int wc, int fr, int fq) const {
;     ...
; #pragma unroll
;                     for (int bj = 0; bj < 2; ++bj) {
;                         const float rq = (pn < 2) ? rs * (0.125f * LOG2E) : rs;
;                         const f32x4 v0 = acc[ai][bj][m][0] * rq, v1 = acc[ai][bj][m][1] * rq;
;                         u32x4 w; w.x = pk2(v0[0], v0[1]); w.y = pk2(v0[2], v0[3]); w.z = pk2(v1[0], v1[1]); w.w = pk2(v1[2], v1[3]);
;                         bf16_t* dst;
;                         if (pn < 2) dst = (bf16_t*)(ws + WS_Q) + (size_t)row * 512 + pn * 256 + bj * 128 + cl;
;                         else if (pn == 2) { const int b = row >> 12, tok = row & 4095, gg = cl >> 6, d0 = cl & 63;
;                             dst = (bf16_t*)(ws + WS_KCMP) + ((size_t)((bj * 16 + b * 2 + gg) * 4096 + tok)) * 64 + d0; }
;                         else if (pn == 3) dst = (bf16_t*)(ws + (bj ? WS_VS : WS_KS)) + (size_t)row * 128 + cl;
;                         else dst = (bf16_t*)(ws + (bj ? WS_VW : WS_KW)) + (size_t)row * 128 + cl;
;                         *(u32x4*)dst = w;
.LBB0_618:
	v_mul_f32_e32 v71, 0x3e38aa3b, v50
	v_cndmask_b32_e64 v74, v50, v71, s[8:9]
	v_pk_mul_f32 v[84:85], v[64:65], v[74:75] op_sel_hi:[1,0]
	v_pk_mul_f32 v[82:83], v[62:63], v[74:75] op_sel_hi:[1,0]
	v_pk_mul_f32 v[86:87], v[60:61], v[74:75] op_sel_hi:[1,0]
	v_pk_mul_f32 v[88:89], v[58:59], v[74:75] op_sel_hi:[1,0]
	v_cvt_pk_bf16_f32 v82, v82, v83
	v_cvt_pk_bf16_f32 v83, v84, v85
	v_cvt_pk_bf16_f32 v84, v88, v89
	v_cvt_pk_bf16_f32 v85, v86, v87
	s_and_b64 vcc, exec, s[14:15]
	s_mov_b64 s[14:15], -1
	global_store_dwordx4 v[78:79], v[82:85], off
	s_cbranch_vccnz .LBB0_628
	s_cmp_lt_i32 s40, 3
	s_cbranch_scc1 .LBB0_625
	s_cmp_lg_u32 s40, 3
	s_cbranch_scc0 .LBB0_622
	v_readlane_b32 s14, v255, 29
	v_readlane_b32 s15, v255, 30
	s_nop 1
	v_lshl_add_u64 v[78:79], s[14:15], 0, v[72:73]
	v_lshl_add_u64 v[78:79], v[152:153], 1, v[78:79]
	s_mov_b64 s[14:15], 0

; __device__ __forceinline__ unsigned pk2(float lo, float hi) { f32x2_t v = {lo, hi}; bf16x2_t b = __builtin_convertvector(v, bf16x2_t); return __builtin_bit_cast(unsigned, b); }
;     __device__ __forceinline__ void operator()(const f32x4 (&acc)[2][2][4][2], const Unit& u, int wr, int wc, int fr, int fq) const {
;     ...
; #pragma unroll
;                     for (int bj = 0; bj < 2; ++bj) {
;                         const float rq = (pn < 2) ? rs * (0.125f * LOG2E) : rs;
;                         const f32x4 v0 = acc[ai][bj][m][0] * rq, v1 = acc[ai][bj][m][1] * rq;
;                         u32x4 w; w.x = pk2(v0[0], v0[1]); w.y = pk2(v0[2], v0[3]); w.z = pk2(v1[0], v1[1]); w.w = pk2(v1[2], v1[3]);
;                         bf16_t* dst;
;                         if (pn < 2) dst = (bf16_t*)(ws + WS_Q) + (size_t)row * 512 + pn * 256 + bj * 128 + cl;
;                         else if (pn == 2) { const int b = row >> 12, tok = row & 4095, gg = cl >> 6, d0 = cl & 63;
;                             dst = (bf16_t*)(ws + WS_KCMP) + ((size_t)((bj * 16 + b * 2 + gg) * 4096 + tok)) * 64 + d0; }
;                         else if (pn == 3) dst = (bf16_t*)(ws + (bj ? WS_VS : WS_KS)) + (size_t)row * 128 + cl;
;                         else dst = (bf16_t*)(ws + (bj ? WS_VW : WS_KW)) + (size_t)row * 128 + cl;
;                         *(u32x4*)dst = w;
.LBB0_630:
	v_mov_b32_e32 v75, v74
	v_mov_b32_e32 v72, v74
	v_mov_b32_e32 v73, v74
	v_pk_mul_f32 v[76:77], v[68:69], v[72:73]
	v_pk_mul_f32 v[80:81], v[66:67], v[74:75]
	v_pk_mul_f32 v[82:83], v[56:57], v[72:73]
	v_pk_mul_f32 v[74:75], v[54:55], v[74:75]
	v_cvt_pk_bf16_f32 v72, v80, v81
	v_cvt_pk_bf16_f32 v73, v76, v77
	v_cvt_pk_bf16_f32 v74, v74, v75
	v_cvt_pk_bf16_f32 v75, v82, v83
	s_mov_b64 s[14:15], 0
	global_store_dwordx4 v[78:79], v[72:75], off

; __device__ __forceinline__ unsigned pk2(float lo, float hi) { f32x2_t v = {lo, hi}; bf16x2_t b = __builtin_convertvector(v, bf16x2_t); return __builtin_bit_cast(unsigned, b); }
;     __device__ __forceinline__ void operator()(const f32x4 (&acc)[2][2][4][2], const Unit& u, int wr, int wc, int fr, int fq) const {
;     ...
; #pragma unroll
;                     for (int bj = 0; bj < 2; ++bj) {
;                         const float rq = (pn < 2) ? rs * (0.125f * LOG2E) : rs;
;                         const f32x4 v0 = acc[ai][bj][m][0] * rq, v1 = acc[ai][bj][m][1] * rq;
;                         u32x4 w; w.x = pk2(v0[0], v0[1]); w.y = pk2(v0[2], v0[3]); w.z = pk2(v1[0], v1[1]); w.w = pk2(v1[2], v1[3]);
;                         bf16_t* dst;
;                         if (pn < 2) dst = (bf16_t*)(ws + WS_Q) + (size_t)row * 512 + pn * 256 + bj * 128 + cl;
;                         else if (pn == 2) { const int b = row >> 12, tok = row & 4095, gg = cl >> 6, d0 = cl & 63;
;                             dst = (bf16_t*)(ws + WS_KCMP) + ((size_t)((bj * 16 + b * 2 + gg) * 4096 + tok)) * 64 + d0; }
;                         else if (pn == 3) dst = (bf16_t*)(ws + (bj ? WS_VS : WS_KS)) + (size_t)row * 128 + cl;
;                         else dst = (bf16_t*)(ws + (bj ? WS_VW : WS_KW)) + (size_t)row * 128 + cl;
;                         *(u32x4*)dst = w;
.LBB0_648:
	v_mul_f32_e32 v55, 0x3e38aa3b, v51
	v_cndmask_b32_e64 v58, v51, v55, s[8:9]
	v_pk_mul_f32 v[68:69], v[44:45], v[58:59] op_sel_hi:[1,0]
	v_pk_mul_f32 v[66:67], v[42:43], v[58:59] op_sel_hi:[1,0]
	v_pk_mul_f32 v[70:71], v[40:41], v[58:59] op_sel_hi:[1,0]
	v_pk_mul_f32 v[72:73], v[38:39], v[58:59] op_sel_hi:[1,0]
	v_cvt_pk_bf16_f32 v66, v66, v67
	v_cvt_pk_bf16_f32 v67, v68, v69
	v_cvt_pk_bf16_f32 v68, v72, v73
	v_cvt_pk_bf16_f32 v69, v70, v71
	s_and_b64 vcc, exec, s[14:15]
	s_mov_b64 s[14:15], -1
	global_store_dwordx4 v[62:63], v[66:69], off
	s_cbranch_vccnz .LBB0_658
	s_cmp_lt_i32 s40, 3
	s_cbranch_scc1 .LBB0_655
	s_cmp_lg_u32 s40, 3
	s_cbranch_scc0 .LBB0_652
	v_readlane_b32 s14, v255, 29
	v_readlane_b32 s15, v255, 30
	s_nop 1
	v_lshl_add_u64 v[62:63], s[14:15], 0, v[56:57]
	v_lshl_add_u64 v[62:63], v[152:153], 1, v[62:63]
	s_mov_b64 s[14:15], 0

; __device__ __forceinline__ unsigned pk2(float lo, float hi) { f32x2_t v = {lo, hi}; bf16x2_t b = __builtin_convertvector(v, bf16x2_t); return __builtin_bit_cast(unsigned, b); }
;     __device__ __forceinline__ void operator()(const f32x4 (&acc)[2][2][4][2], const Unit& u, int wr, int wc, int fr, int fq) const {
;     ...
; #pragma unroll
;                     for (int bj = 0; bj < 2; ++bj) {
;                         const float rq = (pn < 2) ? rs * (0.125f * LOG2E) : rs;
;                         const f32x4 v0 = acc[ai][bj][m][0] * rq, v1 = acc[ai][bj][m][1] * rq;
;                         u32x4 w; w.x = pk2(v0[0], v0[1]); w.y = pk2(v0[2], v0[3]); w.z = pk2(v1[0], v1[1]); w.w = pk2(v1[2], v1[3]);
;                         bf16_t* dst;
;                         if (pn < 2) dst = (bf16_t*)(ws + WS_Q) + (size_t)row * 512 + pn * 256 + bj * 128 + cl;
;                         else if (pn == 2) { const int b = row >> 12, tok = row & 4095, gg = cl >> 6, d0 = cl & 63;
;                             dst = (bf16_t*)(ws + WS_KCMP) + ((size_t)((bj * 16 + b * 2 + gg) * 4096 + tok)) * 64 + d0; }
;                         else if (pn == 3) dst = (bf16_t*)(ws + (bj ? WS_VS : WS_KS)) + (size_t)row * 128 + cl;
;                         else dst = (bf16_t*)(ws + (bj ? WS_VW : WS_KW)) + (size_t)row * 128 + cl;
;                         *(u32x4*)dst = w;
.LBB0_660:
	v_mov_b32_e32 v59, v58
	v_mov_b32_e32 v56, v58
	v_mov_b32_e32 v57, v58
	v_pk_mul_f32 v[60:61], v[48:49], v[56:57]
	v_pk_mul_f32 v[64:65], v[46:47], v[58:59]
	v_pk_mul_f32 v[66:67], v[36:37], v[56:57]
	v_pk_mul_f32 v[58:59], v[34:35], v[58:59]
	v_cvt_pk_bf16_f32 v56, v64, v65
	v_cvt_pk_bf16_f32 v57, v60, v61
	v_cvt_pk_bf16_f32 v58, v58, v59
	v_cvt_pk_bf16_f32 v59, v66, v67
	s_mov_b64 s[14:15], 0
	global_store_dwordx4 v[62:63], v[56:59], off

; __device__ __forceinline__ unsigned pk2(float lo, float hi) { f32x2_t v = {lo, hi}; bf16x2_t b = __builtin_convertvector(v, bf16x2_t); return __builtin_bit_cast(unsigned, b); }
;     __device__ __forceinline__ void operator()(const f32x4 (&acc)[2][2][4][2], const Unit& u, int wr, int wc, int fr, int fq) const {
;     ...
; #pragma unroll
;                     for (int bj = 0; bj < 2; ++bj) {
;                         const float rq = (pn < 2) ? rs * (0.125f * LOG2E) : rs;
;                         const f32x4 v0 = acc[ai][bj][m][0] * rq, v1 = acc[ai][bj][m][1] * rq;
;                         u32x4 w; w.x = pk2(v0[0], v0[1]); w.y = pk2(v0[2], v0[3]); w.z = pk2(v1[0], v1[1]); w.w = pk2(v1[2], v1[3]);
;                         bf16_t* dst;
;                         if (pn < 2) dst = (bf16_t*)(ws + WS_Q) + (size_t)row * 512 + pn * 256 + bj * 128 + cl;
;                         else if (pn == 2) { const int b = row >> 12, tok = row & 4095, gg = cl >> 6, d0 = cl & 63;
;                             dst = (bf16_t*)(ws + WS_KCMP) + ((size_t)((bj * 16 + b * 2 + gg) * 4096 + tok)) * 64 + d0; }
;                         else if (pn == 3) dst = (bf16_t*)(ws + (bj ? WS_VS : WS_KS)) + (size_t)row * 128 + cl;
;                         else dst = (bf16_t*)(ws + (bj ? WS_VW : WS_KW)) + (size_t)row * 128 + cl;
;                         *(u32x4*)dst = w;
.LBB0_678:
	v_mul_f32_e32 v35, 0x3e38aa3b, v52
	v_cndmask_b32_e64 v38, v52, v35, s[8:9]
	v_pk_mul_f32 v[48:49], v[28:29], v[38:39] op_sel_hi:[1,0]
	v_pk_mul_f32 v[46:47], v[26:27], v[38:39] op_sel_hi:[1,0]
	v_pk_mul_f32 v[50:51], v[24:25], v[38:39] op_sel_hi:[1,0]
	v_pk_mul_f32 v[54:55], v[22:23], v[38:39] op_sel_hi:[1,0]
	v_cvt_pk_bf16_f32 v46, v46, v47
	v_cvt_pk_bf16_f32 v47, v48, v49
	v_cvt_pk_bf16_f32 v48, v54, v55
	v_cvt_pk_bf16_f32 v49, v50, v51
	s_and_b64 vcc, exec, s[14:15]
	s_mov_b64 s[14:15], -1
	global_store_dwordx4 v[42:43], v[46:49], off
	s_cbranch_vccnz .LBB0_688
	s_cmp_lt_i32 s40, 3
	s_cbranch_scc1 .LBB0_685
	s_cmp_lg_u32 s40, 3
	s_cbranch_scc0 .LBB0_682
	v_readlane_b32 s14, v255, 29
	v_readlane_b32 s15, v255, 30
	s_nop 1
	v_lshl_add_u64 v[42:43], s[14:15], 0, v[36:37]
	v_lshl_add_u64 v[42:43], v[152:153], 1, v[42:43]
	s_mov_b64 s[14:15], 0

; __device__ __forceinline__ unsigned pk2(float lo, float hi) { f32x2_t v = {lo, hi}; bf16x2_t b = __builtin_convertvector(v, bf16x2_t); return __builtin_bit_cast(unsigned, b); }
;     __device__ __forceinline__ void operator()(const f32x4 (&acc)[2][2][4][2], const Unit& u, int wr, int wc, int fr, int fq) const {
;     ...
; #pragma unroll
;                     for (int bj = 0; bj < 2; ++bj) {
;                         const float rq = (pn < 2) ? rs * (0.125f * LOG2E) : rs;
;                         const f32x4 v0 = acc[ai][bj][m][0] * rq, v1 = acc[ai][bj][m][1] * rq;
;                         u32x4 w; w.x = pk2(v0[0], v0[1]); w.y = pk2(v0[2], v0[3]); w.z = pk2(v1[0], v1[1]); w.w = pk2(v1[2], v1[3]);
;                         bf16_t* dst;
;                         if (pn < 2) dst = (bf16_t*)(ws + WS_Q) + (size_t)row * 512 + pn * 256 + bj * 128 + cl;
;                         else if (pn == 2) { const int b = row >> 12, tok = row & 4095, gg = cl >> 6, d0 = cl & 63;
;                             dst = (bf16_t*)(ws + WS_KCMP) + ((size_t)((bj * 16 + b * 2 + gg) * 4096 + tok)) * 64 + d0; }
;                         else if (pn == 3) dst = (bf16_t*)(ws + (bj ? WS_VS : WS_KS)) + (size_t)row * 128 + cl;
;                         else dst = (bf16_t*)(ws + (bj ? WS_VW : WS_KW)) + (size_t)row * 128 + cl;
;                         *(u32x4*)dst = w;
.LBB0_690:
	v_mov_b32_e32 v39, v38
	v_mov_b32_e32 v36, v38
	v_mov_b32_e32 v37, v38
	v_pk_mul_f32 v[40:41], v[32:33], v[36:37]
	v_pk_mul_f32 v[44:45], v[30:31], v[38:39]
	v_pk_mul_f32 v[46:47], v[20:21], v[36:37]
	v_pk_mul_f32 v[38:39], v[18:19], v[38:39]
	v_cvt_pk_bf16_f32 v36, v44, v45
	v_cvt_pk_bf16_f32 v37, v40, v41
	v_cvt_pk_bf16_f32 v38, v38, v39
	v_cvt_pk_bf16_f32 v39, v46, v47
	s_mov_b64 s[14:15], 0
	global_store_dwordx4 v[42:43], v[36:39], off

; __device__ __forceinline__ unsigned pk2(float lo, float hi) { f32x2_t v = {lo, hi}; bf16x2_t b = __builtin_convertvector(v, bf16x2_t); return __builtin_bit_cast(unsigned, b); }
;     __device__ __forceinline__ void operator()(const f32x4 (&acc)[2][2][4][2], const Unit& u, int wr, int wc, int fr, int fq) const {
;     ...
; #pragma unroll
;                     for (int bj = 0; bj < 2; ++bj) {
;                         const float rq = (pn < 2) ? rs * (0.125f * LOG2E) : rs;
;                         const f32x4 v0 = acc[ai][bj][m][0] * rq, v1 = acc[ai][bj][m][1] * rq;
;                         u32x4 w; w.x = pk2(v0[0], v0[1]); w.y = pk2(v0[2], v0[3]); w.z = pk2(v1[0], v1[1]); w.w = pk2(v1[2], v1[3]);
;                         bf16_t* dst;
;                         if (pn < 2) dst = (bf16_t*)(ws + WS_Q) + (size_t)row * 512 + pn * 256 + bj * 128 + cl;
;                         else if (pn == 2) { const int b = row >> 12, tok = row & 4095, gg = cl >> 6, d0 = cl & 63;
;                             dst = (bf16_t*)(ws + WS_KCMP) + ((size_t)((bj * 16 + b * 2 + gg) * 4096 + tok)) * 64 + d0; }
;                         else if (pn == 3) dst = (bf16_t*)(ws + (bj ? WS_VS : WS_KS)) + (size_t)row * 128 + cl;
;                         else dst = (bf16_t*)(ws + (bj ? WS_VW : WS_KW)) + (size_t)row * 128 + cl;
;                         *(u32x4*)dst = w;
.LBB0_708:
	v_mul_f32_e32 v19, 0x3e38aa3b, v53
	v_cndmask_b32_e64 v22, v53, v19, s[8:9]
	v_pk_mul_f32 v[32:33], v[12:13], v[22:23] op_sel_hi:[1,0]
	v_pk_mul_f32 v[30:31], v[10:11], v[22:23] op_sel_hi:[1,0]
	v_pk_mul_f32 v[34:35], v[8:9], v[22:23] op_sel_hi:[1,0]
	v_pk_mul_f32 v[36:37], v[6:7], v[22:23] op_sel_hi:[1,0]
	v_cvt_pk_bf16_f32 v30, v30, v31
	v_cvt_pk_bf16_f32 v31, v32, v33
	v_cvt_pk_bf16_f32 v32, v36, v37
	v_cvt_pk_bf16_f32 v33, v34, v35
	s_and_b64 vcc, exec, s[10:11]
	s_mov_b64 s[8:9], -1
	global_store_dwordx4 v[26:27], v[30:33], off
	s_cbranch_vccnz .LBB0_718
	s_cmp_lt_i32 s40, 3
	s_cbranch_scc1 .LBB0_715
	s_cmp_lg_u32 s40, 3
	s_cbranch_scc0 .LBB0_712
	v_readlane_b32 s8, v255, 29
	v_readlane_b32 s9, v255, 30
	s_nop 1
	v_lshl_add_u64 v[26:27], s[8:9], 0, v[20:21]
	v_lshl_add_u64 v[26:27], v[152:153], 1, v[26:27]
	s_mov_b64 s[8:9], 0

; __device__ __forceinline__ unsigned pk2(float lo, float hi) { f32x2_t v = {lo, hi}; bf16x2_t b = __builtin_convertvector(v, bf16x2_t); return __builtin_bit_cast(unsigned, b); }
;     __device__ __forceinline__ void operator()(const f32x4 (&acc)[2][2][4][2], const Unit& u, int wr, int wc, int fr, int fq) const {
;     ...
; #pragma unroll
;                     for (int bj = 0; bj < 2; ++bj) {
;                         const float rq = (pn < 2) ? rs * (0.125f * LOG2E) : rs;
;                         const f32x4 v0 = acc[ai][bj][m][0] * rq, v1 = acc[ai][bj][m][1] * rq;
;                         u32x4 w; w.x = pk2(v0[0], v0[1]); w.y = pk2(v0[2], v0[3]); w.z = pk2(v1[0], v1[1]); w.w = pk2(v1[2], v1[3]);
;                         bf16_t* dst;
;                         if (pn < 2) dst = (bf16_t*)(ws + WS_Q) + (size_t)row * 512 + pn * 256 + bj * 128 + cl;
;                         else if (pn == 2) { const int b = row >> 12, tok = row & 4095, gg = cl >> 6, d0 = cl & 63;
;                             dst = (bf16_t*)(ws + WS_KCMP) + ((size_t)((bj * 16 + b * 2 + gg) * 4096 + tok)) * 64 + d0; }
;                         else if (pn == 3) dst = (bf16_t*)(ws + (bj ? WS_VS : WS_KS)) + (size_t)row * 128 + cl;
;                         else dst = (bf16_t*)(ws + (bj ? WS_VW : WS_KW)) + (size_t)row * 128 + cl;
;                         *(u32x4*)dst = w;
.LBB0_720:
	v_mov_b32_e32 v23, v22
	v_mov_b32_e32 v20, v22
	v_mov_b32_e32 v21, v22
	v_pk_mul_f32 v[24:25], v[16:17], v[20:21]
	v_pk_mul_f32 v[28:29], v[14:15], v[22:23]
	v_pk_mul_f32 v[30:31], v[4:5], v[20:21]
	v_pk_mul_f32 v[22:23], v[2:3], v[22:23]
	v_cvt_pk_bf16_f32 v20, v28, v29
	v_cvt_pk_bf16_f32 v21, v24, v25
	v_cvt_pk_bf16_f32 v22, v22, v23
	v_cvt_pk_bf16_f32 v23, v30, v31
	s_mov_b64 s[10:11], 0
	global_store_dwordx4 v[26:27], v[20:23], off

; __device__ __forceinline__ unsigned pk2(float lo, float hi) { f32x2_t v = {lo, hi}; bf16x2_t b = __builtin_convertvector(v, bf16x2_t); return __builtin_bit_cast(unsigned, b); }
; __device__ __forceinline__ f32x2 glu_pk(f32x2 a, f32x2 b, float c1, float rs) {
;     const f32x2 t = b * c1; f32x2 e; e.x = __builtin_amdgcn_exp2f(t.x); e.y = __builtin_amdgcn_exp2f(t.y);
;     const f32x2 d = e + 1.0f; f32x2 sg; sg.x = __builtin_amdgcn_rcpf(d.x); sg.y = __builtin_amdgcn_rcpf(d.y);
;     return a * (sg * rs);
; }
;     __device__ __forceinline__ void operator()(const f32x4 (&acc)[2][2][4][2], const Unit& u, int wr, int wc, int fr, int fq) const {
;     ...
;                 if (pn >= 4 && pn <= 7) {
;                     const float c1 = -rs * LOG2E;
;                     const f32x4 a0 = acc[ai][0][m][0], a1 = acc[ai][0][m][1], b0 = acc[ai][1][m][0], b1 = acc[ai][1][m][1];
;                     const f32x2 o0 = glu_pk((f32x2){a0[0], a0[1]}, (f32x2){b0[0], b0[1]}, c1, rs), o1 = glu_pk((f32x2){a0[2], a0[3]}, (f32x2){b0[2], b0[3]}, c1, rs);
;                     const f32x2 o2 = glu_pk((f32x2){a1[0], a1[1]}, (f32x2){b1[0], b1[1]}, c1, rs), o3 = glu_pk((f32x2){a1[2], a1[3]}, (f32x2){b1[2], b1[3]}, c1, rs);
;                     u32x4 w; w.x = pk2(o0.x, o0.y); w.y = pk2(o1.x, o1.y); w.z = pk2(o2.x, o2.y); w.w = pk2(o3.x, o3.y);
;                     *(u32x4*)((bf16_t*)(ws + WS_GLU) + (size_t)row * 512 + (pn - 4) * 128 + cl) = w;
.LBB0_726:
	s_waitcnt lgkmcnt(0)
	v_mul_f32_e32 v124, 0xbfb8aa3b, v103
	v_pk_mul_f32 v[118:119], v[118:119], v[124:125] op_sel_hi:[1,0]
	v_pk_mul_f32 v[120:121], v[120:121], v[124:125] op_sel_hi:[1,0]
	v_exp_f32_e32 v118, v118
	v_exp_f32_e32 v119, v119
	v_pk_mul_f32 v[106:107], v[106:107], v[124:125] op_sel_hi:[1,0]
	v_pk_mul_f32 v[108:109], v[108:109], v[124:125] op_sel_hi:[1,0]
	v_exp_f32_e32 v120, v120
	v_exp_f32_e32 v121, v121
	v_exp_f32_e32 v106, v106
	v_exp_f32_e32 v107, v107
	v_exp_f32_e32 v108, v108
	v_exp_f32_e32 v109, v109
	v_pk_add_f32 v[118:119], v[118:119], 1.0 op_sel_hi:[1,0]
	v_pk_add_f32 v[120:121], v[120:121], 1.0 op_sel_hi:[1,0]
	v_rcp_f32_e32 v118, v118
	v_rcp_f32_e32 v119, v119
	v_pk_add_f32 v[106:107], v[106:107], 1.0 op_sel_hi:[1,0]
	v_pk_add_f32 v[108:109], v[108:109], 1.0 op_sel_hi:[1,0]
	v_rcp_f32_e32 v120, v120
	v_rcp_f32_e32 v121, v121
	v_rcp_f32_e32 v106, v106
	v_rcp_f32_e32 v107, v107
	v_rcp_f32_e32 v108, v108
	v_rcp_f32_e32 v109, v109
	v_pk_mul_f32 v[118:119], v[102:103], v[118:119] op_sel:[1,0]
	v_pk_mul_f32 v[106:107], v[102:103], v[106:107] op_sel:[1,0]
	v_pk_mul_f32 v[114:115], v[114:115], v[118:119]
	v_pk_mul_f32 v[118:119], v[102:103], v[120:121] op_sel:[1,0]
	v_pk_mul_f32 v[102:103], v[102:103], v[108:109] op_sel:[1,0]
	v_ashrrev_i32_e32 v123, 31, v122
	v_pk_mul_f32 v[102:103], v[112:113], v[102:103]
	s_lshl_b32 s62, s43, 1
	v_cvt_pk_bf16_f32 v109, v102, v103
	v_lshlrev_b64 v[102:103], 10, v[122:123]
	v_lshl_add_u64 v[102:103], s[86:87], 0, v[102:103]
	v_lshl_add_u64 v[102:103], v[102:103], 0, s[62:63]
	v_lshl_add_u64 v[102:103], v[152:153], 1, v[102:103]
	v_pk_mul_f32 v[116:117], v[116:117], v[118:119]
	v_pk_mul_f32 v[110:111], v[110:111], v[106:107]
	v_add_co_u32_e32 v102, vcc, 0x139ff000, v102
	v_cvt_pk_bf16_f32 v106, v114, v115
	v_cvt_pk_bf16_f32 v107, v116, v117
	v_cvt_pk_bf16_f32 v108, v110, v111
	v_addc_co_u32_e32 v103, vcc, 0, v103, vcc
	global_store_dwordx4 v[102:103], v[106:109], off offset:3072
	v_add_u32_e32 v102, 32, v150
	s_and_b64 vcc, exec, s[12:13]
	s_mov_b64 s[14:15], -1
	s_cbranch_vccz .LBB0_545

; __device__ __forceinline__ unsigned pk2(float lo, float hi) { f32x2_t v = {lo, hi}; bf16x2_t b = __builtin_convertvector(v, bf16x2_t); return __builtin_bit_cast(unsigned, b); }
; __device__ __forceinline__ f32x2 glu_pk(f32x2 a, f32x2 b, float c1, float rs) {
;     const f32x2 t = b * c1; f32x2 e; e.x = __builtin_amdgcn_exp2f(t.x); e.y = __builtin_amdgcn_exp2f(t.y);
;     const f32x2 d = e + 1.0f; f32x2 sg; sg.x = __builtin_amdgcn_rcpf(d.x); sg.y = __builtin_amdgcn_rcpf(d.y);
;     return a * (sg * rs);
; }
;     __device__ __forceinline__ void operator()(const f32x4 (&acc)[2][2][4][2], const Unit& u, int wr, int wc, int fr, int fq) const {
;     ...
;                 if (pn >= 4 && pn <= 7) {
;                     const float c1 = -rs * LOG2E;
;                     const f32x4 a0 = acc[ai][0][m][0], a1 = acc[ai][0][m][1], b0 = acc[ai][1][m][0], b1 = acc[ai][1][m][1];
;                     const f32x2 o0 = glu_pk((f32x2){a0[0], a0[1]}, (f32x2){b0[0], b0[1]}, c1, rs), o1 = glu_pk((f32x2){a0[2], a0[3]}, (f32x2){b0[2], b0[3]}, c1, rs);
;                     const f32x2 o2 = glu_pk((f32x2){a1[0], a1[1]}, (f32x2){b1[0], b1[1]}, c1, rs), o3 = glu_pk((f32x2){a1[2], a1[3]}, (f32x2){b1[2], b1[3]}, c1, rs);
;                     u32x4 w; w.x = pk2(o0.x, o0.y); w.y = pk2(o1.x, o1.y); w.z = pk2(o2.x, o2.y); w.w = pk2(o3.x, o3.y);
;                     *(u32x4*)((bf16_t*)(ws + WS_GLU) + (size_t)row * 512 + (pn - 4) * 128 + cl) = w;
.LBB0_728:
	v_mul_f32_e32 v106, 0xbfb8aa3b, v104
	v_pk_mul_f32 v[86:87], v[86:87], v[106:107] op_sel_hi:[1,0]
	v_pk_mul_f32 v[88:89], v[88:89], v[106:107] op_sel_hi:[1,0]
	v_exp_f32_e32 v86, v86
	v_exp_f32_e32 v87, v87
	v_exp_f32_e32 v88, v88
	v_exp_f32_e32 v89, v89
	v_pk_mul_f32 v[98:99], v[98:99], v[106:107] op_sel_hi:[1,0]
	v_pk_mul_f32 v[100:101], v[100:101], v[106:107] op_sel_hi:[1,0]
	v_exp_f32_e32 v98, v98
	v_exp_f32_e32 v99, v99
	v_pk_add_f32 v[86:87], v[86:87], 1.0 op_sel_hi:[1,0]
	v_exp_f32_e32 v100, v100
	v_exp_f32_e32 v101, v101
	v_rcp_f32_e32 v86, v86
	v_rcp_f32_e32 v87, v87
	v_pk_add_f32 v[88:89], v[88:89], 1.0 op_sel_hi:[1,0]
	v_pk_add_f32 v[98:99], v[98:99], 1.0 op_sel_hi:[1,0]
	v_rcp_f32_e32 v88, v88
	v_rcp_f32_e32 v89, v89
	v_rcp_f32_e32 v98, v98
	v_rcp_f32_e32 v99, v99
	v_pk_add_f32 v[100:101], v[100:101], 1.0 op_sel_hi:[1,0]
	v_pk_mul_f32 v[86:87], v[104:105], v[86:87] op_sel_hi:[0,1]
	v_rcp_f32_e32 v100, v100
	v_rcp_f32_e32 v101, v101
	v_pk_mul_f32 v[90:91], v[90:91], v[86:87]
	v_ashrrev_i32_e32 v103, 31, v102
	v_pk_mul_f32 v[86:87], v[104:105], v[88:89] op_sel_hi:[0,1]
	v_cvt_pk_bf16_f32 v88, v90, v91
	v_lshlrev_b64 v[90:91], 10, v[102:103]
	v_lshl_add_u64 v[90:91], s[86:87], 0, v[90:91]
	s_lshl_b32 s62, s43, 1
	v_pk_mul_f32 v[98:99], v[104:105], v[98:99] op_sel_hi:[0,1]
	v_lshl_add_u64 v[90:91], v[90:91], 0, s[62:63]
	v_pk_mul_f32 v[94:95], v[94:95], v[98:99]
	v_pk_mul_f32 v[98:99], v[104:105], v[100:101] op_sel_hi:[0,1]
	v_lshl_add_u64 v[90:91], v[152:153], 1, v[90:91]
	v_pk_mul_f32 v[96:97], v[96:97], v[98:99]
	v_pk_mul_f32 v[92:93], v[92:93], v[86:87]
	v_add_co_u32_e32 v90, vcc, 0x139ff000, v90
	v_cvt_pk_bf16_f32 v86, v94, v95
	v_cvt_pk_bf16_f32 v87, v96, v97
	v_cvt_pk_bf16_f32 v89, v92, v93
	v_addc_co_u32_e32 v91, vcc, 0, v91, vcc
	global_store_dwordx4 v[90:91], v[86:89], off offset:3072
	s_nop 1
	v_add_u32_e32 v86, 48, v150
	s_and_b64 vcc, exec, s[12:13]
	s_mov_b64 s[14:15], -1
	s_cbranch_vccz .LBB0_575

; __device__ __forceinline__ unsigned pk2(float lo, float hi) { f32x2_t v = {lo, hi}; bf16x2_t b = __builtin_convertvector(v, bf16x2_t); return __builtin_bit_cast(unsigned, b); }
; __device__ __forceinline__ f32x2 glu_pk(f32x2 a, f32x2 b, float c1, float rs) {
;     const f32x2 t = b * c1; f32x2 e; e.x = __builtin_amdgcn_exp2f(t.x); e.y = __builtin_amdgcn_exp2f(t.y);
;     const f32x2 d = e + 1.0f; f32x2 sg; sg.x = __builtin_amdgcn_rcpf(d.x); sg.y = __builtin_amdgcn_rcpf(d.y);
;     return a * (sg * rs);
; }
;     __device__ __forceinline__ void operator()(const f32x4 (&acc)[2][2][4][2], const Unit& u, int wr, int wc, int fr, int fq) const {
;     ...
;                 if (pn >= 4 && pn <= 7) {
;                     const float c1 = -rs * LOG2E;
;                     const f32x4 a0 = acc[ai][0][m][0], a1 = acc[ai][0][m][1], b0 = acc[ai][1][m][0], b1 = acc[ai][1][m][1];
;                     const f32x2 o0 = glu_pk((f32x2){a0[0], a0[1]}, (f32x2){b0[0], b0[1]}, c1, rs), o1 = glu_pk((f32x2){a0[2], a0[3]}, (f32x2){b0[2], b0[3]}, c1, rs);
;                     const f32x2 o2 = glu_pk((f32x2){a1[0], a1[1]}, (f32x2){b1[0], b1[1]}, c1, rs), o3 = glu_pk((f32x2){a1[2], a1[3]}, (f32x2){b1[2], b1[3]}, c1, rs);
;                     u32x4 w; w.x = pk2(o0.x, o0.y); w.y = pk2(o1.x, o1.y); w.z = pk2(o2.x, o2.y); w.w = pk2(o3.x, o3.y);
;                     *(u32x4*)((bf16_t*)(ws + WS_GLU) + (size_t)row * 512 + (pn - 4) * 128 + cl) = w;
.LBB0_730:
	v_mul_f32_e32 v88, 0xbfb8aa3b, v105
	v_pk_mul_f32 v[70:71], v[70:71], v[88:89] op_sel_hi:[1,0]
	v_pk_mul_f32 v[72:73], v[72:73], v[88:89] op_sel_hi:[1,0]
	v_exp_f32_e32 v70, v70
	v_exp_f32_e32 v71, v71
	v_exp_f32_e32 v72, v72
	v_exp_f32_e32 v73, v73
	v_pk_mul_f32 v[82:83], v[82:83], v[88:89] op_sel_hi:[1,0]
	v_pk_mul_f32 v[84:85], v[84:85], v[88:89] op_sel_hi:[1,0]
	v_exp_f32_e32 v82, v82
	v_exp_f32_e32 v83, v83
	v_pk_add_f32 v[70:71], v[70:71], 1.0 op_sel_hi:[1,0]
	v_exp_f32_e32 v84, v84
	v_exp_f32_e32 v85, v85
	v_rcp_f32_e32 v70, v70
	v_rcp_f32_e32 v71, v71
	v_pk_add_f32 v[72:73], v[72:73], 1.0 op_sel_hi:[1,0]
	v_pk_add_f32 v[82:83], v[82:83], 1.0 op_sel_hi:[1,0]
	v_rcp_f32_e32 v72, v72
	v_rcp_f32_e32 v73, v73
	v_mov_b32_e32 v90, v105
	v_rcp_f32_e32 v82, v82
	v_rcp_f32_e32 v83, v83
	v_pk_add_f32 v[84:85], v[84:85], 1.0 op_sel_hi:[1,0]
	v_pk_mul_f32 v[70:71], v[90:91], v[70:71] op_sel_hi:[0,1]
	v_rcp_f32_e32 v84, v84
	v_rcp_f32_e32 v85, v85
	v_pk_mul_f32 v[74:75], v[74:75], v[70:71]
	v_ashrrev_i32_e32 v87, 31, v86
	v_pk_mul_f32 v[70:71], v[90:91], v[72:73] op_sel_hi:[0,1]
	v_cvt_pk_bf16_f32 v72, v74, v75
	v_lshlrev_b64 v[74:75], 10, v[86:87]
	v_lshl_add_u64 v[74:75], s[86:87], 0, v[74:75]
	s_lshl_b32 s62, s43, 1
	v_pk_mul_f32 v[82:83], v[90:91], v[82:83] op_sel_hi:[0,1]
	v_lshl_add_u64 v[74:75], v[74:75], 0, s[62:63]
	v_pk_mul_f32 v[78:79], v[78:79], v[82:83]
	v_pk_mul_f32 v[82:83], v[90:91], v[84:85] op_sel_hi:[0,1]
	v_lshl_add_u64 v[74:75], v[152:153], 1, v[74:75]
	v_pk_mul_f32 v[80:81], v[80:81], v[82:83]
	v_pk_mul_f32 v[76:77], v[76:77], v[70:71]
	v_add_co_u32_e32 v74, vcc, 0x139ff000, v74
	v_cvt_pk_bf16_f32 v70, v78, v79
	v_cvt_pk_bf16_f32 v71, v80, v81
	v_cvt_pk_bf16_f32 v73, v76, v77
	v_addc_co_u32_e32 v75, vcc, 0, v75, vcc
	global_store_dwordx4 v[74:75], v[70:73], off offset:3072
	s_nop 1
	v_add_u32_e32 v70, 0x80, v150
	s_and_b64 vcc, exec, s[12:13]
	s_mov_b64 s[14:15], -1
	s_cbranch_vccz .LBB0_605

; __device__ __forceinline__ unsigned pk2(float lo, float hi) { f32x2_t v = {lo, hi}; bf16x2_t b = __builtin_convertvector(v, bf16x2_t); return __builtin_bit_cast(unsigned, b); }
; __device__ __forceinline__ f32x2 glu_pk(f32x2 a, f32x2 b, float c1, float rs) {
;     const f32x2 t = b * c1; f32x2 e; e.x = __builtin_amdgcn_exp2f(t.x); e.y = __builtin_amdgcn_exp2f(t.y);
;     const f32x2 d = e + 1.0f; f32x2 sg; sg.x = __builtin_amdgcn_rcpf(d.x); sg.y = __builtin_amdgcn_rcpf(d.y);
;     return a * (sg * rs);
; }
;     __device__ __forceinline__ void operator()(const f32x4 (&acc)[2][2][4][2], const Unit& u, int wr, int wc, int fr, int fq) const {
;     ...
;                 if (pn >= 4 && pn <= 7) {
;                     const float c1 = -rs * LOG2E;
;                     const f32x4 a0 = acc[ai][0][m][0], a1 = acc[ai][0][m][1], b0 = acc[ai][1][m][0], b1 = acc[ai][1][m][1];
;                     const f32x2 o0 = glu_pk((f32x2){a0[0], a0[1]}, (f32x2){b0[0], b0[1]}, c1, rs), o1 = glu_pk((f32x2){a0[2], a0[3]}, (f32x2){b0[2], b0[3]}, c1, rs);
;                     const f32x2 o2 = glu_pk((f32x2){a1[0], a1[1]}, (f32x2){b1[0], b1[1]}, c1, rs), o3 = glu_pk((f32x2){a1[2], a1[3]}, (f32x2){b1[2], b1[3]}, c1, rs);
;                     u32x4 w; w.x = pk2(o0.x, o0.y); w.y = pk2(o1.x, o1.y); w.z = pk2(o2.x, o2.y); w.w = pk2(o3.x, o3.y);
;                     *(u32x4*)((bf16_t*)(ws + WS_GLU) + (size_t)row * 512 + (pn - 4) * 128 + cl) = w;
.LBB0_732:
	v_mul_f32_e32 v72, 0xbfb8aa3b, v50
	v_pk_mul_f32 v[54:55], v[54:55], v[72:73] op_sel_hi:[1,0]
	v_pk_mul_f32 v[56:57], v[56:57], v[72:73] op_sel_hi:[1,0]
	v_exp_f32_e32 v54, v54
	v_exp_f32_e32 v55, v55
	v_exp_f32_e32 v56, v56
	v_exp_f32_e32 v57, v57
	v_pk_mul_f32 v[66:67], v[66:67], v[72:73] op_sel_hi:[1,0]
	v_pk_mul_f32 v[68:69], v[68:69], v[72:73] op_sel_hi:[1,0]
	v_exp_f32_e32 v66, v66
	v_exp_f32_e32 v67, v67
	v_pk_add_f32 v[54:55], v[54:55], 1.0 op_sel_hi:[1,0]
	v_exp_f32_e32 v68, v68
	v_exp_f32_e32 v69, v69
	v_rcp_f32_e32 v54, v54
	v_rcp_f32_e32 v55, v55
	v_pk_add_f32 v[56:57], v[56:57], 1.0 op_sel_hi:[1,0]
	v_pk_add_f32 v[66:67], v[66:67], 1.0 op_sel_hi:[1,0]
	v_rcp_f32_e32 v56, v56
	v_rcp_f32_e32 v57, v57
	v_rcp_f32_e32 v66, v66
	v_rcp_f32_e32 v67, v67
	v_pk_add_f32 v[68:69], v[68:69], 1.0 op_sel_hi:[1,0]
	v_pk_mul_f32 v[54:55], v[50:51], v[54:55] op_sel_hi:[0,1]
	v_rcp_f32_e32 v68, v68
	v_rcp_f32_e32 v69, v69
	v_pk_mul_f32 v[58:59], v[58:59], v[54:55]
	v_ashrrev_i32_e32 v71, 31, v70
	v_pk_mul_f32 v[54:55], v[50:51], v[56:57] op_sel_hi:[0,1]
	v_cvt_pk_bf16_f32 v56, v58, v59
	v_lshlrev_b64 v[58:59], 10, v[70:71]
	v_lshl_add_u64 v[58:59], s[86:87], 0, v[58:59]
	s_lshl_b32 s62, s43, 1
	v_pk_mul_f32 v[66:67], v[50:51], v[66:67] op_sel_hi:[0,1]
	v_lshl_add_u64 v[58:59], v[58:59], 0, s[62:63]
	v_pk_mul_f32 v[62:63], v[62:63], v[66:67]
	v_pk_mul_f32 v[66:67], v[50:51], v[68:69] op_sel_hi:[0,1]
	v_lshl_add_u64 v[58:59], v[152:153], 1, v[58:59]
	v_pk_mul_f32 v[64:65], v[64:65], v[66:67]
	v_pk_mul_f32 v[60:61], v[60:61], v[54:55]
	v_add_co_u32_e32 v58, vcc, 0x139ff000, v58
	v_cvt_pk_bf16_f32 v54, v62, v63
	v_cvt_pk_bf16_f32 v55, v64, v65
	v_cvt_pk_bf16_f32 v57, v60, v61
	v_addc_co_u32_e32 v59, vcc, 0, v59, vcc
	global_store_dwordx4 v[58:59], v[54:57], off offset:3072
	s_nop 1
	v_add_u32_e32 v54, 0x90, v150
	s_and_b64 vcc, exec, s[12:13]
	s_mov_b64 s[14:15], -1
	s_cbranch_vccz .LBB0_635

; __device__ __forceinline__ unsigned pk2(float lo, float hi) { f32x2_t v = {lo, hi}; bf16x2_t b = __builtin_convertvector(v, bf16x2_t); return __builtin_bit_cast(unsigned, b); }
; __device__ __forceinline__ f32x2 glu_pk(f32x2 a, f32x2 b, float c1, float rs) {
;     const f32x2 t = b * c1; f32x2 e; e.x = __builtin_amdgcn_exp2f(t.x); e.y = __builtin_amdgcn_exp2f(t.y);
;     const f32x2 d = e + 1.0f; f32x2 sg; sg.x = __builtin_amdgcn_rcpf(d.x); sg.y = __builtin_amdgcn_rcpf(d.y);
;     return a * (sg * rs);
; }
;     __device__ __forceinline__ void operator()(const f32x4 (&acc)[2][2][4][2], const Unit& u, int wr, int wc, int fr, int fq) const {
;     ...
;                 if (pn >= 4 && pn <= 7) {
;                     const float c1 = -rs * LOG2E;
;                     const f32x4 a0 = acc[ai][0][m][0], a1 = acc[ai][0][m][1], b0 = acc[ai][1][m][0], b1 = acc[ai][1][m][1];
;                     const f32x2 o0 = glu_pk((f32x2){a0[0], a0[1]}, (f32x2){b0[0], b0[1]}, c1, rs), o1 = glu_pk((f32x2){a0[2], a0[3]}, (f32x2){b0[2], b0[3]}, c1, rs);
;                     const f32x2 o2 = glu_pk((f32x2){a1[0], a1[1]}, (f32x2){b1[0], b1[1]}, c1, rs), o3 = glu_pk((f32x2){a1[2], a1[3]}, (f32x2){b1[2], b1[3]}, c1, rs);
;                     u32x4 w; w.x = pk2(o0.x, o0.y); w.y = pk2(o1.x, o1.y); w.z = pk2(o2.x, o2.y); w.w = pk2(o3.x, o3.y);
;                     *(u32x4*)((bf16_t*)(ws + WS_GLU) + (size_t)row * 512 + (pn - 4) * 128 + cl) = w;
.LBB0_734:
	v_mul_f32_e32 v56, 0xbfb8aa3b, v51
	v_pk_mul_f32 v[34:35], v[34:35], v[56:57] op_sel_hi:[1,0]
	v_pk_mul_f32 v[36:37], v[36:37], v[56:57] op_sel_hi:[1,0]
	v_exp_f32_e32 v34, v34
	v_exp_f32_e32 v35, v35
	v_exp_f32_e32 v36, v36
	v_exp_f32_e32 v37, v37
	v_pk_mul_f32 v[46:47], v[46:47], v[56:57] op_sel_hi:[1,0]
	v_pk_mul_f32 v[48:49], v[48:49], v[56:57] op_sel_hi:[1,0]
	v_exp_f32_e32 v46, v46
	v_exp_f32_e32 v47, v47
	v_pk_add_f32 v[34:35], v[34:35], 1.0 op_sel_hi:[1,0]
	v_exp_f32_e32 v48, v48
	v_exp_f32_e32 v49, v49
	v_rcp_f32_e32 v34, v34
	v_rcp_f32_e32 v35, v35
	v_pk_add_f32 v[36:37], v[36:37], 1.0 op_sel_hi:[1,0]
	v_pk_add_f32 v[46:47], v[46:47], 1.0 op_sel_hi:[1,0]
	v_rcp_f32_e32 v36, v36
	v_rcp_f32_e32 v37, v37
	v_rcp_f32_e32 v46, v46
	v_rcp_f32_e32 v47, v47
	v_pk_add_f32 v[48:49], v[48:49], 1.0 op_sel_hi:[1,0]
	v_pk_mul_f32 v[34:35], v[50:51], v[34:35] op_sel:[1,0]
	v_rcp_f32_e32 v48, v48
	v_rcp_f32_e32 v49, v49
	v_pk_mul_f32 v[38:39], v[38:39], v[34:35]
	v_ashrrev_i32_e32 v55, 31, v54
	v_pk_mul_f32 v[34:35], v[50:51], v[36:37] op_sel:[1,0]
	v_cvt_pk_bf16_f32 v36, v38, v39
	v_lshlrev_b64 v[38:39], 10, v[54:55]
	v_lshl_add_u64 v[38:39], s[86:87], 0, v[38:39]
	s_lshl_b32 s62, s43, 1
	v_pk_mul_f32 v[46:47], v[50:51], v[46:47] op_sel:[1,0]
	v_lshl_add_u64 v[38:39], v[38:39], 0, s[62:63]
	v_pk_mul_f32 v[42:43], v[42:43], v[46:47]
	v_pk_mul_f32 v[46:47], v[50:51], v[48:49] op_sel:[1,0]
	v_lshl_add_u64 v[38:39], v[152:153], 1, v[38:39]
	v_pk_mul_f32 v[44:45], v[44:45], v[46:47]
	v_pk_mul_f32 v[40:41], v[40:41], v[34:35]
	v_add_co_u32_e32 v38, vcc, 0x139ff000, v38
	v_cvt_pk_bf16_f32 v34, v42, v43
	v_cvt_pk_bf16_f32 v35, v44, v45
	v_cvt_pk_bf16_f32 v37, v40, v41
	v_addc_co_u32_e32 v39, vcc, 0, v39, vcc
	global_store_dwordx4 v[38:39], v[34:37], off offset:3072
	s_nop 1
	v_add_u32_e32 v34, 0xa0, v150
	s_and_b64 vcc, exec, s[12:13]
	s_mov_b64 s[14:15], -1
	s_cbranch_vccz .LBB0_665

; __device__ __forceinline__ unsigned pk2(float lo, float hi) { f32x2_t v = {lo, hi}; bf16x2_t b = __builtin_convertvector(v, bf16x2_t); return __builtin_bit_cast(unsigned, b); }
; __device__ __forceinline__ f32x2 glu_pk(f32x2 a, f32x2 b, float c1, float rs) {
;     const f32x2 t = b * c1; f32x2 e; e.x = __builtin_amdgcn_exp2f(t.x); e.y = __builtin_amdgcn_exp2f(t.y);
;     const f32x2 d = e + 1.0f; f32x2 sg; sg.x = __builtin_amdgcn_rcpf(d.x); sg.y = __builtin_amdgcn_rcpf(d.y);
;     return a * (sg * rs);
; }
;     __device__ __forceinline__ void operator()(const f32x4 (&acc)[2][2][4][2], const Unit& u, int wr, int wc, int fr, int fq) const {
;     ...
;                 if (pn >= 4 && pn <= 7) {
;                     const float c1 = -rs * LOG2E;
;                     const f32x4 a0 = acc[ai][0][m][0], a1 = acc[ai][0][m][1], b0 = acc[ai][1][m][0], b1 = acc[ai][1][m][1];
;                     const f32x2 o0 = glu_pk((f32x2){a0[0], a0[1]}, (f32x2){b0[0], b0[1]}, c1, rs), o1 = glu_pk((f32x2){a0[2], a0[3]}, (f32x2){b0[2], b0[3]}, c1, rs);
;                     const f32x2 o2 = glu_pk((f32x2){a1[0], a1[1]}, (f32x2){b1[0], b1[1]}, c1, rs), o3 = glu_pk((f32x2){a1[2], a1[3]}, (f32x2){b1[2], b1[3]}, c1, rs);
;                     u32x4 w; w.x = pk2(o0.x, o0.y); w.y = pk2(o1.x, o1.y); w.z = pk2(o2.x, o2.y); w.w = pk2(o3.x, o3.y);
;                     *(u32x4*)((bf16_t*)(ws + WS_GLU) + (size_t)row * 512 + (pn - 4) * 128 + cl) = w;
.LBB0_736:
	v_mul_f32_e32 v36, 0xbfb8aa3b, v52
	v_pk_mul_f32 v[18:19], v[18:19], v[36:37] op_sel_hi:[1,0]
	v_pk_mul_f32 v[20:21], v[20:21], v[36:37] op_sel_hi:[1,0]
	v_exp_f32_e32 v18, v18
	v_exp_f32_e32 v19, v19
	v_exp_f32_e32 v20, v20
	v_exp_f32_e32 v21, v21
	v_pk_mul_f32 v[30:31], v[30:31], v[36:37] op_sel_hi:[1,0]
	v_pk_mul_f32 v[32:33], v[32:33], v[36:37] op_sel_hi:[1,0]
	v_exp_f32_e32 v30, v30
	v_exp_f32_e32 v31, v31
	v_pk_add_f32 v[18:19], v[18:19], 1.0 op_sel_hi:[1,0]
	v_exp_f32_e32 v32, v32
	v_exp_f32_e32 v33, v33
	v_rcp_f32_e32 v18, v18
	v_rcp_f32_e32 v19, v19
	v_pk_add_f32 v[20:21], v[20:21], 1.0 op_sel_hi:[1,0]
	v_pk_add_f32 v[30:31], v[30:31], 1.0 op_sel_hi:[1,0]
	v_rcp_f32_e32 v20, v20
	v_rcp_f32_e32 v21, v21
	v_rcp_f32_e32 v30, v30
	v_rcp_f32_e32 v31, v31
	v_pk_add_f32 v[32:33], v[32:33], 1.0 op_sel_hi:[1,0]
	v_pk_mul_f32 v[18:19], v[52:53], v[18:19] op_sel_hi:[0,1]
	v_rcp_f32_e32 v32, v32
	v_rcp_f32_e32 v33, v33
	v_pk_mul_f32 v[22:23], v[22:23], v[18:19]
	v_ashrrev_i32_e32 v35, 31, v34
	v_pk_mul_f32 v[18:19], v[52:53], v[20:21] op_sel_hi:[0,1]
	v_cvt_pk_bf16_f32 v20, v22, v23
	v_lshlrev_b64 v[22:23], 10, v[34:35]
	v_lshl_add_u64 v[22:23], s[86:87], 0, v[22:23]
	s_lshl_b32 s62, s43, 1
	v_pk_mul_f32 v[30:31], v[52:53], v[30:31] op_sel_hi:[0,1]
	v_lshl_add_u64 v[22:23], v[22:23], 0, s[62:63]
	v_pk_mul_f32 v[26:27], v[26:27], v[30:31]
	v_pk_mul_f32 v[30:31], v[52:53], v[32:33] op_sel_hi:[0,1]
	v_lshl_add_u64 v[22:23], v[152:153], 1, v[22:23]
	v_pk_mul_f32 v[28:29], v[28:29], v[30:31]
	v_pk_mul_f32 v[24:25], v[24:25], v[18:19]
	v_add_co_u32_e32 v22, vcc, 0x139ff000, v22
	v_cvt_pk_bf16_f32 v18, v26, v27
	v_cvt_pk_bf16_f32 v19, v28, v29
	v_cvt_pk_bf16_f32 v21, v24, v25
	v_addc_co_u32_e32 v23, vcc, 0, v23, vcc
	global_store_dwordx4 v[22:23], v[18:21], off offset:3072
	s_nop 1
	v_add_u32_e32 v18, 0xb0, v150
	s_and_b64 vcc, exec, s[12:13]
	s_mov_b64 s[12:13], -1
	s_cbranch_vccz .LBB0_695

; __device__ __forceinline__ unsigned pk2(float lo, float hi) { f32x2_t v = {lo, hi}; bf16x2_t b = __builtin_convertvector(v, bf16x2_t); return __builtin_bit_cast(unsigned, b); }
; __device__ __forceinline__ f32x2 glu_pk(f32x2 a, f32x2 b, float c1, float rs) {
;     const f32x2 t = b * c1; f32x2 e; e.x = __builtin_amdgcn_exp2f(t.x); e.y = __builtin_amdgcn_exp2f(t.y);
;     const f32x2 d = e + 1.0f; f32x2 sg; sg.x = __builtin_amdgcn_rcpf(d.x); sg.y = __builtin_amdgcn_rcpf(d.y);
;     return a * (sg * rs);
; }
;     __device__ __forceinline__ void operator()(const f32x4 (&acc)[2][2][4][2], const Unit& u, int wr, int wc, int fr, int fq) const {
;     ...
;                 if (pn >= 4 && pn <= 7) {
;                     const float c1 = -rs * LOG2E;
;                     const f32x4 a0 = acc[ai][0][m][0], a1 = acc[ai][0][m][1], b0 = acc[ai][1][m][0], b1 = acc[ai][1][m][1];
;                     const f32x2 o0 = glu_pk((f32x2){a0[0], a0[1]}, (f32x2){b0[0], b0[1]}, c1, rs), o1 = glu_pk((f32x2){a0[2], a0[3]}, (f32x2){b0[2], b0[3]}, c1, rs);
;                     const f32x2 o2 = glu_pk((f32x2){a1[0], a1[1]}, (f32x2){b1[0], b1[1]}, c1, rs), o3 = glu_pk((f32x2){a1[2], a1[3]}, (f32x2){b1[2], b1[3]}, c1, rs);
;                     u32x4 w; w.x = pk2(o0.x, o0.y); w.y = pk2(o1.x, o1.y); w.z = pk2(o2.x, o2.y); w.w = pk2(o3.x, o3.y);
;                     *(u32x4*)((bf16_t*)(ws + WS_GLU) + (size_t)row * 512 + (pn - 4) * 128 + cl) = w;
.LBB0_738:
	v_mul_f32_e32 v20, 0xbfb8aa3b, v53
	v_pk_mul_f32 v[2:3], v[2:3], v[20:21] op_sel_hi:[1,0]
	v_pk_mul_f32 v[4:5], v[4:5], v[20:21] op_sel_hi:[1,0]
	v_exp_f32_e32 v2, v2
	v_exp_f32_e32 v3, v3
	v_exp_f32_e32 v4, v4
	v_exp_f32_e32 v5, v5
	v_pk_mul_f32 v[14:15], v[14:15], v[20:21] op_sel_hi:[1,0]
	v_pk_mul_f32 v[16:17], v[16:17], v[20:21] op_sel_hi:[1,0]
	v_exp_f32_e32 v14, v14
	v_exp_f32_e32 v15, v15
	v_pk_add_f32 v[2:3], v[2:3], 1.0 op_sel_hi:[1,0]
	v_exp_f32_e32 v16, v16
	v_exp_f32_e32 v17, v17
	v_rcp_f32_e32 v2, v2
	v_rcp_f32_e32 v3, v3
	v_pk_add_f32 v[4:5], v[4:5], 1.0 op_sel_hi:[1,0]
	v_pk_add_f32 v[14:15], v[14:15], 1.0 op_sel_hi:[1,0]
	v_rcp_f32_e32 v4, v4
	v_rcp_f32_e32 v5, v5
	v_mov_b32_e32 v22, v53
	v_rcp_f32_e32 v14, v14
	v_rcp_f32_e32 v15, v15
	v_pk_add_f32 v[16:17], v[16:17], 1.0 op_sel_hi:[1,0]
	v_pk_mul_f32 v[2:3], v[22:23], v[2:3] op_sel_hi:[0,1]
	v_rcp_f32_e32 v16, v16
	v_rcp_f32_e32 v17, v17
	v_pk_mul_f32 v[6:7], v[6:7], v[2:3]
	v_ashrrev_i32_e32 v19, 31, v18
	v_pk_mul_f32 v[2:3], v[22:23], v[4:5] op_sel_hi:[0,1]
	v_cvt_pk_bf16_f32 v4, v6, v7
	v_lshlrev_b64 v[6:7], 10, v[18:19]
	v_lshl_add_u64 v[6:7], s[86:87], 0, v[6:7]
	s_lshl_b32 s62, s43, 1
	v_pk_mul_f32 v[14:15], v[22:23], v[14:15] op_sel_hi:[0,1]
	v_lshl_add_u64 v[6:7], v[6:7], 0, s[62:63]
	v_pk_mul_f32 v[10:11], v[10:11], v[14:15]
	v_pk_mul_f32 v[14:15], v[22:23], v[16:17] op_sel_hi:[0,1]
	v_lshl_add_u64 v[6:7], v[152:153], 1, v[6:7]
	v_pk_mul_f32 v[12:13], v[12:13], v[14:15]
	v_pk_mul_f32 v[8:9], v[8:9], v[2:3]
	v_add_co_u32_e32 v6, vcc, 0x139ff000, v6
	v_cvt_pk_bf16_f32 v2, v10, v11
	v_cvt_pk_bf16_f32 v3, v12, v13
	v_cvt_pk_bf16_f32 v5, v8, v9
	v_addc_co_u32_e32 v7, vcc, 0, v7, vcc
	global_store_dwordx4 v[6:7], v[2:5], off offset:3072
	s_andn2_b64 vcc, exec, s[6:7]
	s_mov_b64 s[6:7], -1
	s_cbranch_vccnz .LBB0_463

; __device__ __forceinline__ float fsigmoid(float x) { return __builtin_amdgcn_rcpf(1.0f + __expf(-x)); }
;     __device__ __forceinline__ void operator()(const f32x4 (&acc)[2][2][4][2], const Unit& u, int wr, int wc, int fr, int fq) const {
;     ...
;                     if (wc == 0) {
;                         const f32x4 a0 = acc[ai][0][m][0] * rs, a1 = acc[ai][0][m][1] * rs;
;                         float* gp = (float*)(ws + WS_G) + (size_t)row * 32 + 8 * fq;
;                         *(f32x4*)gp = (f32x4){fsigmoid(a0[0]), fsigmoid(a0[1]), fsigmoid(a0[2]), fsigmoid(a0[3])};
;                         *(f32x4*)(gp + 4) = (f32x4){fsigmoid(a1[0]), fsigmoid(a1[1]), fsigmoid(a1[2]), fsigmoid(a1[3])};
;                     }
.LBB0_741:
	s_waitcnt lgkmcnt(0)
	v_pk_mul_f32 v[124:125], v[114:115], v[102:103] op_sel:[0,1]
	v_ashrrev_i32_e32 v123, 31, v122
	v_mul_f32_e32 v124, 0xbfb8aa3b, v124
	v_exp_f32_e32 v124, v124
	v_mul_f32_e32 v125, 0xbfb8aa3b, v125
	v_exp_f32_e32 v125, v125
	v_pk_mul_f32 v[126:127], v[116:117], v[102:103] op_sel:[0,1]
	v_lshlrev_b64 v[132:133], 7, v[122:123]
	v_add_f32_e32 v123, 1.0, v124
	v_rcp_f32_e32 v124, v123
	v_add_f32_e32 v123, 1.0, v125
	v_mul_f32_e32 v125, 0xbfb8aa3b, v126
	v_exp_f32_e32 v126, v125
	v_mul_f32_e32 v125, 0xbfb8aa3b, v127
	v_exp_f32_e32 v127, v125
	v_pk_mul_f32 v[128:129], v[110:111], v[102:103] op_sel:[0,1]
	v_rcp_f32_e32 v125, v123
	v_add_f32_e32 v123, 1.0, v126
	v_rcp_f32_e32 v126, v123
	v_add_f32_e32 v123, 1.0, v127
	v_mul_f32_e32 v127, 0xbfb8aa3b, v128
	v_exp_f32_e32 v128, v127
	v_mul_f32_e32 v127, 0xbfb8aa3b, v129
	v_exp_f32_e32 v129, v127
	v_pk_mul_f32 v[130:131], v[112:113], v[102:103] op_sel:[0,1]
	v_rcp_f32_e32 v127, v123
	v_add_f32_e32 v123, 1.0, v128
	v_rcp_f32_e32 v128, v123
	v_add_f32_e32 v123, 1.0, v129
	v_mul_f32_e32 v129, 0xbfb8aa3b, v130
	v_exp_f32_e32 v130, v129
	v_mul_f32_e32 v129, 0xbfb8aa3b, v131
	v_exp_f32_e32 v131, v129
	v_rcp_f32_e32 v129, v123
	v_add_f32_e32 v123, 1.0, v130
	v_rcp_f32_e32 v130, v123
	v_add_f32_e32 v123, 1.0, v131
	v_rcp_f32_e32 v131, v123
	v_lshl_add_u64 v[132:133], s[96:97], 0, v[132:133]
	v_lshl_add_u64 v[132:133], v[154:155], 2, v[132:133]
	global_store_dwordx4 v[132:133], v[124:127], off
	global_store_dwordx4 v[132:133], v[128:131], off offset:16
	s_cbranch_execnz .LBB0_544
	s_branch .LBB0_726
.LBB0_742:
	v_pk_mul_f32 v[106:107], v[94:95], v[104:105] op_sel_hi:[1,0]
	v_ashrrev_i32_e32 v103, 31, v102
	v_mul_f32_e32 v106, 0xbfb8aa3b, v106
	v_exp_f32_e32 v106, v106
	v_mul_f32_e32 v107, 0xbfb8aa3b, v107
	v_exp_f32_e32 v107, v107
	v_pk_mul_f32 v[108:109], v[96:97], v[104:105] op_sel_hi:[1,0]
	v_lshlrev_b64 v[114:115], 7, v[102:103]
	v_add_f32_e32 v103, 1.0, v106
	v_rcp_f32_e32 v106, v103
	v_add_f32_e32 v103, 1.0, v107
	v_mul_f32_e32 v107, 0xbfb8aa3b, v108
	v_exp_f32_e32 v108, v107
	v_mul_f32_e32 v107, 0xbfb8aa3b, v109
	v_exp_f32_e32 v109, v107
	v_pk_mul_f32 v[110:111], v[90:91], v[104:105] op_sel_hi:[1,0]
	v_rcp_f32_e32 v107, v103
	v_add_f32_e32 v103, 1.0, v108
	v_rcp_f32_e32 v108, v103
	v_add_f32_e32 v103, 1.0, v109
	v_mul_f32_e32 v109, 0xbfb8aa3b, v110
	v_exp_f32_e32 v110, v109
	v_mul_f32_e32 v109, 0xbfb8aa3b, v111
	v_exp_f32_e32 v111, v109
	v_pk_mul_f32 v[112:113], v[92:93], v[104:105] op_sel_hi:[1,0]
	v_rcp_f32_e32 v109, v103
	v_add_f32_e32 v103, 1.0, v110
	v_rcp_f32_e32 v110, v103
	v_add_f32_e32 v103, 1.0, v111
	v_mul_f32_e32 v111, 0xbfb8aa3b, v112
	v_exp_f32_e32 v112, v111
	v_mul_f32_e32 v111, 0xbfb8aa3b, v113
	v_exp_f32_e32 v113, v111
	v_rcp_f32_e32 v111, v103
	v_add_f32_e32 v103, 1.0, v112
	v_rcp_f32_e32 v112, v103
	v_add_f32_e32 v103, 1.0, v113
	v_rcp_f32_e32 v113, v103
	v_lshl_add_u64 v[114:115], s[96:97], 0, v[114:115]
	v_lshl_add_u64 v[114:115], v[154:155], 2, v[114:115]
	global_store_dwordx4 v[114:115], v[106:109], off
	global_store_dwordx4 v[114:115], v[110:113], off offset:16
	s_cbranch_execnz .LBB0_574
	s_branch .LBB0_728
.LBB0_743:
	v_mov_b32_e32 v88, v105
	v_pk_mul_f32 v[92:93], v[78:79], v[88:89] op_sel_hi:[1,0]
	v_pk_mul_f32 v[90:91], v[80:81], v[88:89] op_sel_hi:[1,0]
	v_pk_mul_f32 v[94:95], v[76:77], v[88:89] op_sel_hi:[1,0]
	v_pk_mul_f32 v[96:97], v[74:75], v[88:89] op_sel_hi:[1,0]
	v_mul_f32_e32 v88, 0xbfb8aa3b, v92
	v_exp_f32_e32 v88, v88
	v_mul_f32_e32 v89, 0xbfb8aa3b, v93
	v_exp_f32_e32 v89, v89
	v_ashrrev_i32_e32 v87, 31, v86
	v_lshlrev_b64 v[98:99], 7, v[86:87]
	v_add_f32_e32 v87, 1.0, v88
	v_rcp_f32_e32 v88, v87
	v_add_f32_e32 v87, 1.0, v89
	v_mul_f32_e32 v89, 0xbfb8aa3b, v90
	v_exp_f32_e32 v90, v89
	v_mul_f32_e32 v89, 0xbfb8aa3b, v91
	v_exp_f32_e32 v91, v89
	v_rcp_f32_e32 v89, v87
	v_add_f32_e32 v87, 1.0, v90
	v_rcp_f32_e32 v90, v87
	v_add_f32_e32 v87, 1.0, v91
	v_mul_f32_e32 v91, 0xbfb8aa3b, v96
	v_exp_f32_e32 v92, v91
	v_mul_f32_e32 v91, 0xbfb8aa3b, v97
	v_exp_f32_e32 v93, v91
	v_rcp_f32_e32 v91, v87
	v_add_f32_e32 v87, 1.0, v92
	v_rcp_f32_e32 v92, v87
	v_add_f32_e32 v87, 1.0, v93
	v_mul_f32_e32 v93, 0xbfb8aa3b, v94
	v_exp_f32_e32 v94, v93
	v_mul_f32_e32 v93, 0xbfb8aa3b, v95
	v_exp_f32_e32 v95, v93
	v_rcp_f32_e32 v93, v87
	v_add_f32_e32 v87, 1.0, v94
	v_rcp_f32_e32 v94, v87
	v_add_f32_e32 v87, 1.0, v95
	v_rcp_f32_e32 v95, v87
	v_lshl_add_u64 v[96:97], s[96:97], 0, v[98:99]
	v_lshl_add_u64 v[96:97], v[154:155], 2, v[96:97]
	global_store_dwordx4 v[96:97], v[88:91], off
	global_store_dwordx4 v[96:97], v[92:95], off offset:16
	s_cbranch_execnz .LBB0_604
	s_branch .LBB0_730
; __device__ __forceinline__ float fsigmoid(float x) { return __builtin_amdgcn_rcpf(1.0f + __expf(-x)); }
;     __device__ __forceinline__ void operator()(const f32x4 (&acc)[2][2][4][2], const Unit& u, int wr, int wc, int fr, int fq) const {
;     ...
;                     if (wc == 0) {
;                         const f32x4 a0 = acc[ai][0][m][0] * rs, a1 = acc[ai][0][m][1] * rs;
;                         float* gp = (float*)(ws + WS_G) + (size_t)row * 32 + 8 * fq;
;                         *(f32x4*)gp = (f32x4){fsigmoid(a0[0]), fsigmoid(a0[1]), fsigmoid(a0[2]), fsigmoid(a0[3])};
;                         *(f32x4*)(gp + 4) = (f32x4){fsigmoid(a1[0]), fsigmoid(a1[1]), fsigmoid(a1[2]), fsigmoid(a1[3])};
;                     }
.LBB0_744:
	v_pk_mul_f32 v[72:73], v[62:63], v[50:51] op_sel_hi:[1,0]
	v_ashrrev_i32_e32 v71, 31, v70
	v_mul_f32_e32 v72, 0xbfb8aa3b, v72
	v_exp_f32_e32 v72, v72
	v_mul_f32_e32 v73, 0xbfb8aa3b, v73
	v_exp_f32_e32 v73, v73
	v_pk_mul_f32 v[74:75], v[64:65], v[50:51] op_sel_hi:[1,0]
	v_lshlrev_b64 v[80:81], 7, v[70:71]
	v_add_f32_e32 v71, 1.0, v72
	v_rcp_f32_e32 v72, v71
	v_add_f32_e32 v71, 1.0, v73
	v_mul_f32_e32 v73, 0xbfb8aa3b, v74
	v_exp_f32_e32 v74, v73
	v_mul_f32_e32 v73, 0xbfb8aa3b, v75
	v_exp_f32_e32 v75, v73
	v_pk_mul_f32 v[76:77], v[58:59], v[50:51] op_sel_hi:[1,0]
	v_rcp_f32_e32 v73, v71
	v_add_f32_e32 v71, 1.0, v74
	v_rcp_f32_e32 v74, v71
	v_add_f32_e32 v71, 1.0, v75
	v_mul_f32_e32 v75, 0xbfb8aa3b, v76
	v_exp_f32_e32 v76, v75
	v_mul_f32_e32 v75, 0xbfb8aa3b, v77
	v_exp_f32_e32 v77, v75
	v_pk_mul_f32 v[78:79], v[60:61], v[50:51] op_sel_hi:[1,0]
	v_rcp_f32_e32 v75, v71
	v_add_f32_e32 v71, 1.0, v76
	v_rcp_f32_e32 v76, v71
	v_add_f32_e32 v71, 1.0, v77
	v_mul_f32_e32 v77, 0xbfb8aa3b, v78
	v_exp_f32_e32 v78, v77
	v_mul_f32_e32 v77, 0xbfb8aa3b, v79
	v_exp_f32_e32 v79, v77
	v_rcp_f32_e32 v77, v71
	v_add_f32_e32 v71, 1.0, v78
	v_rcp_f32_e32 v78, v71
	v_add_f32_e32 v71, 1.0, v79
	v_rcp_f32_e32 v79, v71
	v_lshl_add_u64 v[80:81], s[96:97], 0, v[80:81]
	v_lshl_add_u64 v[80:81], v[154:155], 2, v[80:81]
	global_store_dwordx4 v[80:81], v[72:75], off
	global_store_dwordx4 v[80:81], v[76:79], off offset:16
	s_cbranch_execnz .LBB0_634
	s_branch .LBB0_732
.LBB0_745:
	v_pk_mul_f32 v[56:57], v[42:43], v[50:51] op_sel:[0,1]
	v_ashrrev_i32_e32 v55, 31, v54
	v_mul_f32_e32 v56, 0xbfb8aa3b, v56
	v_exp_f32_e32 v56, v56
	v_mul_f32_e32 v57, 0xbfb8aa3b, v57
	v_exp_f32_e32 v57, v57
	v_pk_mul_f32 v[58:59], v[44:45], v[50:51] op_sel:[0,1]
	v_lshlrev_b64 v[64:65], 7, v[54:55]
	v_add_f32_e32 v55, 1.0, v56
	v_rcp_f32_e32 v56, v55
	v_add_f32_e32 v55, 1.0, v57
	v_mul_f32_e32 v57, 0xbfb8aa3b, v58
	v_exp_f32_e32 v58, v57
	v_mul_f32_e32 v57, 0xbfb8aa3b, v59
	v_exp_f32_e32 v59, v57
	v_pk_mul_f32 v[60:61], v[38:39], v[50:51] op_sel:[0,1]
	v_rcp_f32_e32 v57, v55
	v_add_f32_e32 v55, 1.0, v58
	v_rcp_f32_e32 v58, v55
	v_add_f32_e32 v55, 1.0, v59
	v_mul_f32_e32 v59, 0xbfb8aa3b, v60
	v_exp_f32_e32 v60, v59
	v_mul_f32_e32 v59, 0xbfb8aa3b, v61
	v_exp_f32_e32 v61, v59
	v_pk_mul_f32 v[62:63], v[40:41], v[50:51] op_sel:[0,1]
	v_rcp_f32_e32 v59, v55
	v_add_f32_e32 v55, 1.0, v60
	v_rcp_f32_e32 v60, v55
	v_add_f32_e32 v55, 1.0, v61
	v_mul_f32_e32 v61, 0xbfb8aa3b, v62
	v_exp_f32_e32 v62, v61
	v_mul_f32_e32 v61, 0xbfb8aa3b, v63
	v_exp_f32_e32 v63, v61
	v_rcp_f32_e32 v61, v55
	v_add_f32_e32 v55, 1.0, v62
	v_rcp_f32_e32 v62, v55
	v_add_f32_e32 v55, 1.0, v63
	v_rcp_f32_e32 v63, v55
	v_lshl_add_u64 v[64:65], s[96:97], 0, v[64:65]
	v_lshl_add_u64 v[64:65], v[154:155], 2, v[64:65]
	global_store_dwordx4 v[64:65], v[56:59], off
	global_store_dwordx4 v[64:65], v[60:63], off offset:16
	s_cbranch_execnz .LBB0_664
	s_branch .LBB0_734
.LBB0_746:
	v_pk_mul_f32 v[36:37], v[26:27], v[52:53] op_sel_hi:[1,0]
	v_ashrrev_i32_e32 v35, 31, v34
	v_mul_f32_e32 v36, 0xbfb8aa3b, v36
	v_exp_f32_e32 v36, v36
	v_mul_f32_e32 v37, 0xbfb8aa3b, v37
	v_exp_f32_e32 v37, v37
	v_pk_mul_f32 v[38:39], v[28:29], v[52:53] op_sel_hi:[1,0]
	v_lshlrev_b64 v[44:45], 7, v[34:35]
	v_add_f32_e32 v35, 1.0, v36
	v_rcp_f32_e32 v36, v35
	v_add_f32_e32 v35, 1.0, v37
	v_mul_f32_e32 v37, 0xbfb8aa3b, v38
	v_exp_f32_e32 v38, v37
	v_mul_f32_e32 v37, 0xbfb8aa3b, v39
	v_exp_f32_e32 v39, v37
	v_pk_mul_f32 v[40:41], v[22:23], v[52:53] op_sel_hi:[1,0]
	v_rcp_f32_e32 v37, v35
	v_add_f32_e32 v35, 1.0, v38
	v_rcp_f32_e32 v38, v35
	v_add_f32_e32 v35, 1.0, v39
	v_mul_f32_e32 v39, 0xbfb8aa3b, v40
	v_exp_f32_e32 v40, v39
	v_mul_f32_e32 v39, 0xbfb8aa3b, v41
	v_exp_f32_e32 v41, v39
	v_pk_mul_f32 v[42:43], v[24:25], v[52:53] op_sel_hi:[1,0]
	v_rcp_f32_e32 v39, v35
	v_add_f32_e32 v35, 1.0, v40
	v_rcp_f32_e32 v40, v35
	v_add_f32_e32 v35, 1.0, v41
	v_mul_f32_e32 v41, 0xbfb8aa3b, v42
	v_exp_f32_e32 v42, v41
	v_mul_f32_e32 v41, 0xbfb8aa3b, v43
	v_exp_f32_e32 v43, v41
	v_rcp_f32_e32 v41, v35
	v_add_f32_e32 v35, 1.0, v42
	v_rcp_f32_e32 v42, v35
	v_add_f32_e32 v35, 1.0, v43
	v_rcp_f32_e32 v43, v35
	v_lshl_add_u64 v[44:45], s[96:97], 0, v[44:45]
	v_lshl_add_u64 v[44:45], v[154:155], 2, v[44:45]
	global_store_dwordx4 v[44:45], v[36:39], off
	global_store_dwordx4 v[44:45], v[40:43], off offset:16
	s_cbranch_execnz .LBB0_694
	s_branch .LBB0_736
.LBB0_747:
	v_mov_b32_e32 v20, v53
	v_pk_mul_f32 v[24:25], v[10:11], v[20:21] op_sel_hi:[1,0]
	v_pk_mul_f32 v[22:23], v[12:13], v[20:21] op_sel_hi:[1,0]
	v_pk_mul_f32 v[26:27], v[8:9], v[20:21] op_sel_hi:[1,0]
	v_pk_mul_f32 v[28:29], v[6:7], v[20:21] op_sel_hi:[1,0]
	v_mul_f32_e32 v20, 0xbfb8aa3b, v24
	v_exp_f32_e32 v20, v20
	v_mul_f32_e32 v21, 0xbfb8aa3b, v25
	v_exp_f32_e32 v21, v21
	v_ashrrev_i32_e32 v19, 31, v18
	v_lshlrev_b64 v[30:31], 7, v[18:19]
	v_add_f32_e32 v19, 1.0, v20
	v_rcp_f32_e32 v20, v19
	v_add_f32_e32 v19, 1.0, v21
	v_mul_f32_e32 v21, 0xbfb8aa3b, v22
	v_exp_f32_e32 v22, v21
	v_mul_f32_e32 v21, 0xbfb8aa3b, v23
	v_exp_f32_e32 v23, v21
	v_rcp_f32_e32 v21, v19
	v_add_f32_e32 v19, 1.0, v22
	v_rcp_f32_e32 v22, v19
	v_add_f32_e32 v19, 1.0, v23
	v_mul_f32_e32 v23, 0xbfb8aa3b, v28
	v_exp_f32_e32 v24, v23
	v_mul_f32_e32 v23, 0xbfb8aa3b, v29
	v_exp_f32_e32 v25, v23
	v_rcp_f32_e32 v23, v19
	v_add_f32_e32 v19, 1.0, v24
	v_rcp_f32_e32 v24, v19
	v_add_f32_e32 v19, 1.0, v25
	v_mul_f32_e32 v25, 0xbfb8aa3b, v26
	v_exp_f32_e32 v26, v25
	v_mul_f32_e32 v25, 0xbfb8aa3b, v27
	v_exp_f32_e32 v27, v25
	v_rcp_f32_e32 v25, v19
	v_add_f32_e32 v19, 1.0, v26
	v_rcp_f32_e32 v26, v19
	v_add_f32_e32 v19, 1.0, v27
	v_rcp_f32_e32 v27, v19
	v_lshl_add_u64 v[28:29], s[96:97], 0, v[30:31]
	v_lshl_add_u64 v[28:29], v[154:155], 2, v[28:29]
	global_store_dwordx4 v[28:29], v[20:23], off
	global_store_dwordx4 v[28:29], v[24:27], off offset:16
	s_cbranch_execnz .LBB0_724
	s_branch .LBB0_738

; __device__ __forceinline__ unsigned pk2(float lo, float hi) { f32x2_t v = {lo, hi}; bf16x2_t b = __builtin_convertvector(v, bf16x2_t); return __builtin_bit_cast(unsigned, b); }
; __device__ __forceinline__ float shflx(float v, int mask, int lane) { return __builtin_bit_cast(float, __builtin_amdgcn_ds_bpermute(((lane ^ mask) & 63) << 2, __builtin_bit_cast(int, v))); }
;     __device__ __forceinline__ void operator()(const f32x4 (&acc)[2][2][4][2], const Unit& u, int wr, int wc, int fr, int fq) const {
;     ...
;             u32x4 xin[4][2];
; #pragma unroll
;             for (int m = 0; m < 4; ++m) { const size_t ro = (size_t)(row0 + ai * HALF + m * 16) * D + col0; xin[m][0] = *(const u32x4*)(XB + ro); xin[m][1] = *(const u32x4*)(XB + ro + HALF); }
; #pragma unroll
;             for (int m = 0; m < 4; ++m) {
;                 const int row = row0 + ai * HALF + m * 16;
;                 const size_t ro = (size_t)row * D + col0;
;                 float ss = 0.f;
; #pragma unroll
;                 for (int bj = 0; bj < 2; ++bj) {
;                     const u32x4 xi = xin[m][bj];
;                     const f32x4 a0 = acc[ai][bj][m][0] * scale, a1 = acc[ai][bj][m][1] * scale;
;                     u32x4 w;
;                     w.x = pk2(bflo(xi.x) + a0[0], bfhi(xi.x) + a0[1]); w.y = pk2(bflo(xi.y) + a0[2], bfhi(xi.y) + a0[3]);
;                     w.z = pk2(bflo(xi.z) + a1[0], bfhi(xi.z) + a1[1]); w.w = pk2(bflo(xi.w) + a1[2], bfhi(xi.w) + a1[3]);
;                     *(u32x4*)(XB + ro + bj * HALF) = w;
;                     const float r0 = bflo(w.x), r1 = bfhi(w.x), r2 = bflo(w.y), r3 = bfhi(w.y), r4 = bflo(w.z), r5 = bfhi(w.z), r6 = bflo(w.w), r7 = bfhi(w.w);
;                     ss += ((r0 * r0 + r1 * r1) + (r2 * r2 + r3 * r3)) + ((r4 * r4 + r5 * r5) + (r6 * r6 + r7 * r7));
;                 }
;                 { const int ln_ = fq * 16 + fr; ss += shflx(ss, 16, ln_); ss += shflx(ss, 32, ln_); }
;                 if (fq == 0) red[((wr * 4 + wc) * 8 + ai * 4 + m) * 16 + fr] = ss;
.LBB0_781:
	s_lshl_b32 s18, s4, 8
	v_mov_b32_e32 v201, v179
	v_mov_b32_e32 v126, v1
	s_lshl_b32 s5, s5, 8
	s_or_b32 s18, s18, s49
	s_add_i32 s5, s5, s48
	v_lshl_add_u32 v186, v126, 3, s18
	v_add_u32_e32 v188, s5, v201
	v_ashrrev_i32_e32 v187, 31, v186
	v_lshl_add_u32 v200, v126, 4, v201
	v_lshlrev_b64 v[208:209], 1, v[186:187]
	v_ashrrev_i32_e32 v189, 31, v188
	v_lshlrev_b32_e32 v127, 2, v200
	v_lshl_add_u64 v[190:191], s[34:35], 0, v[208:209]
	v_lshlrev_b64 v[210:211], 11, v[188:189]
	v_bitop3_b32 v203, v127, 64, v240 bitop3:0x6c
	v_bitop3_b32 v202, v127, s66, v240 bitop3:0x6c
	v_cmp_eq_u32_e32 vcc, 0, v126
	v_lshl_add_u64 v[126:127], v[190:191], 0, v[210:211]
	global_load_dwordx4 v[204:207], v[126:127], off
	global_load_dwordx4 v[154:157], v[126:127], off offset:256
	s_mov_b64 s[18:19], 0x8000
	v_lshl_add_u64 v[196:197], v[210:211], 0, s[18:19]
	s_mov_b64 s[18:19], 0x10000
	v_lshl_add_u64 v[126:127], v[190:191], 0, v[196:197]
	v_lshl_add_u64 v[194:195], v[210:211], 0, s[18:19]
	s_mov_b64 s[18:19], 0x18000
	global_load_dwordx4 v[150:153], v[126:127], off
	global_load_dwordx4 v[146:149], v[126:127], off offset:256
	v_lshl_add_u64 v[126:127], v[190:191], 0, v[194:195]
	v_lshl_add_u64 v[192:193], v[210:211], 0, s[18:19]
	global_load_dwordx4 v[142:145], v[126:127], off
	global_load_dwordx4 v[138:141], v[126:127], off offset:256
	v_lshl_add_u64 v[126:127], v[190:191], 0, v[192:193]
	global_load_dwordx4 v[134:137], v[126:127], off
	s_nop 0
	global_load_dwordx4 v[126:129], v[126:127], off offset:256
	v_mov_b32_e32 v167, v166
	s_waitcnt vmcnt(0) lgkmcnt(0)
	v_lshlrev_b32_e32 v212, 16, v204
	v_and_b32_e32 v213, 0xffff0000, v204
	v_lshlrev_b32_e32 v204, 16, v205
	v_and_b32_e32 v205, 0xffff0000, v205
	v_pk_fma_f32 v[130:131], v[180:181], v[130:131], v[212:213]
	v_pk_fma_f32 v[132:133], v[166:167], v[132:133], v[204:205]
	v_cvt_pk_bf16_f32 v130, v130, v131
	v_cvt_pk_bf16_f32 v131, v132, v133
	v_lshlrev_b32_e32 v132, 16, v206
	v_and_b32_e32 v133, 0xffff0000, v206
	v_pk_fma_f32 v[122:123], v[180:181], v[122:123], v[132:133]
	s_nop 0
	v_cvt_pk_bf16_f32 v132, v122, v123
	v_lshlrev_b32_e32 v122, 16, v207
	v_and_b32_e32 v123, 0xffff0000, v207
	v_pk_fma_f32 v[122:123], v[166:167], v[124:125], v[122:123]
	v_and_b32_e32 v125, 0xffff0000, v130
	v_cvt_pk_bf16_f32 v133, v122, v123
	v_lshl_add_u64 v[122:123], s[34:35], 0, v[210:211]
	v_lshl_add_u64 v[122:123], v[122:123], 0, v[208:209]
	global_store_dwordx4 v[122:123], v[130:133], off
	v_lshlrev_b32_e32 v124, 16, v130
	v_mul_f32_e32 v125, v125, v125
	v_lshlrev_b32_e32 v130, 16, v131
	v_and_b32_e32 v131, 0xffff0000, v131
	v_fmac_f32_e32 v125, v124, v124
	v_mul_f32_e32 v124, v131, v131
	v_lshlrev_b32_e32 v204, 16, v132
	v_and_b32_e32 v132, 0xffff0000, v132
	v_lshlrev_b32_e32 v205, 16, v133
	v_and_b32_e32 v133, 0xffff0000, v133
	v_fmac_f32_e32 v124, v130, v130
	v_add_f32_e32 v124, v125, v124
	v_mul_f32_e32 v125, v132, v132
	v_mul_f32_e32 v130, v133, v133
	v_fmac_f32_e32 v125, v204, v204
	v_fmac_f32_e32 v130, v205, v205
	v_add_f32_e32 v125, v125, v130
	v_add_f32_e32 v130, v124, v125
	v_lshlrev_b32_e32 v124, 16, v154
	v_and_b32_e32 v125, 0xffff0000, v154
	v_pk_fma_f32 v[118:119], v[180:181], v[118:119], v[124:125]
	v_lshlrev_b32_e32 v124, 16, v155
	v_and_b32_e32 v125, 0xffff0000, v155
	v_pk_fma_f32 v[120:121], v[166:167], v[120:121], v[124:125]
	v_cvt_pk_bf16_f32 v118, v118, v119
	v_cvt_pk_bf16_f32 v119, v120, v121
	v_lshlrev_b32_e32 v120, 16, v156
	v_and_b32_e32 v121, 0xffff0000, v156
	v_pk_fma_f32 v[114:115], v[180:181], v[114:115], v[120:121]
	s_nop 0
	v_cvt_pk_bf16_f32 v120, v114, v115
	v_lshlrev_b32_e32 v114, 16, v157
	v_and_b32_e32 v115, 0xffff0000, v157
	v_pk_fma_f32 v[114:115], v[166:167], v[116:117], v[114:115]
	v_and_b32_e32 v117, 0xffff0000, v119
	v_cvt_pk_bf16_f32 v121, v114, v115
	v_and_b32_e32 v115, 0xffff0000, v118
	v_lshlrev_b32_e32 v114, 16, v118
	v_mul_f32_e32 v115, v115, v115
	v_lshlrev_b32_e32 v116, 16, v119
	v_fmac_f32_e32 v115, v114, v114
	v_mul_f32_e32 v114, v117, v117
	global_store_dwordx4 v[122:123], v[118:121], off offset:256
	v_fmac_f32_e32 v114, v116, v116
	v_add_f32_e32 v114, v115, v114
	v_lshlrev_b32_e32 v118, 16, v120
	v_and_b32_e32 v119, 0xffff0000, v120
	v_lshlrev_b32_e32 v120, 16, v121
	v_and_b32_e32 v121, 0xffff0000, v121
	v_mul_f32_e32 v115, v119, v119
	v_mul_f32_e32 v116, v121, v121
	v_fmac_f32_e32 v115, v118, v118
	v_fmac_f32_e32 v116, v120, v120
	v_add_f32_e32 v115, v115, v116
	v_add_f32_e32 v114, v114, v115
	v_add_f32_e32 v114, v130, v114
	ds_bpermute_b32 v115, v203, v114
	s_waitcnt lgkmcnt(0)
	v_add_f32_e32 v115, v114, v115
	ds_bpermute_b32 v116, v202, v115
	v_lshl_add_u32 v114, v201, 2, s83
	s_and_saveexec_b64 s[18:19], vcc
	s_cbranch_execz .LBB0_783
	s_waitcnt lgkmcnt(0)
	v_add_f32_e32 v115, v115, v116
	ds_write_b32 v114, v115
; __device__ __forceinline__ unsigned pk2(float lo, float hi) { f32x2_t v = {lo, hi}; bf16x2_t b = __builtin_convertvector(v, bf16x2_t); return __builtin_bit_cast(unsigned, b); }
; __device__ __forceinline__ float shflx(float v, int mask, int lane) { return __builtin_bit_cast(float, __builtin_amdgcn_ds_bpermute(((lane ^ mask) & 63) << 2, __builtin_bit_cast(int, v))); }
;     __device__ __forceinline__ void operator()(const f32x4 (&acc)[2][2][4][2], const Unit& u, int wr, int wc, int fr, int fq) const {
;     ...
;             for (int m = 0; m < 4; ++m) { const size_t ro = (size_t)(row0 + ai * HALF + m * 16) * D + col0; xin[m][0] = *(const u32x4*)(XB + ro); xin[m][1] = *(const u32x4*)(XB + ro + HALF); }
; #pragma unroll
;             for (int m = 0; m < 4; ++m) {
;                 const int row = row0 + ai * HALF + m * 16;
;                 const size_t ro = (size_t)row * D + col0;
;                 float ss = 0.f;
; #pragma unroll
;                 for (int bj = 0; bj < 2; ++bj) {
;                     const u32x4 xi = xin[m][bj];
;                     const f32x4 a0 = acc[ai][bj][m][0] * scale, a1 = acc[ai][bj][m][1] * scale;
;                     u32x4 w;
;                     w.x = pk2(bflo(xi.x) + a0[0], bfhi(xi.x) + a0[1]); w.y = pk2(bflo(xi.y) + a0[2], bfhi(xi.y) + a0[3]);
;                     w.z = pk2(bflo(xi.z) + a1[0], bfhi(xi.z) + a1[1]); w.w = pk2(bflo(xi.w) + a1[2], bfhi(xi.w) + a1[3]);
;                     *(u32x4*)(XB + ro + bj * HALF) = w;
;                     const float r0 = bflo(w.x), r1 = bfhi(w.x), r2 = bflo(w.y), r3 = bfhi(w.y), r4 = bflo(w.z), r5 = bfhi(w.z), r6 = bflo(w.w), r7 = bfhi(w.w);
;                     ss += ((r0 * r0 + r1 * r1) + (r2 * r2 + r3 * r3)) + ((r4 * r4 + r5 * r5) + (r6 * r6 + r7 * r7));
;                 }
;                 { const int ln_ = fq * 16 + fr; ss += shflx(ss, 16, ln_); ss += shflx(ss, 32, ln_); }
;                 if (fq == 0) red[((wr * 4 + wc) * 8 + ai * 4 + m) * 16 + fr] = ss;
.LBB0_783:
	s_or_b64 exec, exec, s[18:19]
	s_waitcnt lgkmcnt(0)
	v_lshlrev_b32_e32 v116, 16, v150
	v_and_b32_e32 v117, 0xffff0000, v150
	v_pk_fma_f32 v[110:111], v[180:181], v[110:111], v[116:117]
	v_lshlrev_b32_e32 v116, 16, v151
	v_and_b32_e32 v117, 0xffff0000, v151
	v_pk_fma_f32 v[112:113], v[166:167], v[112:113], v[116:117]
	v_cvt_pk_bf16_f32 v110, v110, v111
	v_cvt_pk_bf16_f32 v111, v112, v113
	v_lshlrev_b32_e32 v112, 16, v152
	v_and_b32_e32 v113, 0xffff0000, v152
	v_pk_fma_f32 v[106:107], v[180:181], v[106:107], v[112:113]
	s_nop 0
	v_cvt_pk_bf16_f32 v112, v106, v107
	v_lshlrev_b32_e32 v106, 16, v153
	v_and_b32_e32 v107, 0xffff0000, v153
	v_pk_fma_f32 v[106:107], v[166:167], v[108:109], v[106:107]
	v_and_b32_e32 v109, 0xffff0000, v111
	v_cvt_pk_bf16_f32 v113, v106, v107
	v_and_b32_e32 v107, 0xffff0000, v110
	v_lshlrev_b32_e32 v106, 16, v110
	v_mul_f32_e32 v107, v107, v107
	v_lshlrev_b32_e32 v108, 16, v111
	v_fmac_f32_e32 v107, v106, v106
	v_mul_f32_e32 v106, v109, v109
	v_and_b32_e32 v116, 0xffff0000, v112
	v_and_b32_e32 v118, 0xffff0000, v113
	v_fmac_f32_e32 v106, v108, v108
	v_lshlrev_b32_e32 v115, 16, v112
	v_lshlrev_b32_e32 v117, 16, v113
	v_add_f32_e32 v106, v107, v106
	v_mul_f32_e32 v107, v116, v116
	v_mul_f32_e32 v108, v118, v118
	v_fmac_f32_e32 v107, v115, v115
	v_fmac_f32_e32 v108, v117, v117
	v_add_f32_e32 v107, v107, v108
	v_add_f32_e32 v108, v106, v107
	v_lshlrev_b32_e32 v106, 16, v146
	v_and_b32_e32 v107, 0xffff0000, v146
	v_pk_fma_f32 v[102:103], v[180:181], v[102:103], v[106:107]
	v_lshlrev_b32_e32 v106, 16, v147
	v_and_b32_e32 v107, 0xffff0000, v147
	v_pk_fma_f32 v[104:105], v[166:167], v[104:105], v[106:107]
	v_cvt_pk_bf16_f32 v102, v102, v103
	v_cvt_pk_bf16_f32 v103, v104, v105
	v_lshlrev_b32_e32 v104, 16, v148
	v_and_b32_e32 v105, 0xffff0000, v148
	v_pk_fma_f32 v[98:99], v[180:181], v[98:99], v[104:105]
	s_nop 0
	v_cvt_pk_bf16_f32 v104, v98, v99
	v_lshlrev_b32_e32 v98, 16, v149
	v_and_b32_e32 v99, 0xffff0000, v149
	v_pk_fma_f32 v[98:99], v[166:167], v[100:101], v[98:99]
	v_and_b32_e32 v101, 0xffff0000, v103
	v_cvt_pk_bf16_f32 v105, v98, v99
	v_and_b32_e32 v99, 0xffff0000, v102
	v_lshlrev_b32_e32 v98, 16, v102
	v_mul_f32_e32 v99, v99, v99
	v_lshlrev_b32_e32 v100, 16, v103
	v_fmac_f32_e32 v99, v98, v98
	v_mul_f32_e32 v98, v101, v101
	v_and_b32_e32 v107, 0xffff0000, v104
	v_and_b32_e32 v115, 0xffff0000, v105
	v_fmac_f32_e32 v98, v100, v100
	v_lshlrev_b32_e32 v106, 16, v104
	v_lshlrev_b32_e32 v109, 16, v105
	v_add_f32_e32 v98, v99, v98
	v_mul_f32_e32 v99, v107, v107
	v_mul_f32_e32 v100, v115, v115
	v_fmac_f32_e32 v99, v106, v106
	v_fmac_f32_e32 v100, v109, v109
	v_add_f32_e32 v99, v99, v100
	v_add_f32_e32 v98, v98, v99
	v_add_f32_e32 v98, v108, v98
	ds_bpermute_b32 v99, v203, v98
	v_lshl_add_u64 v[100:101], s[34:35], 0, v[196:197]
	v_lshl_add_u64 v[100:101], v[186:187], 1, v[100:101]
	global_store_dwordx4 v[100:101], v[110:113], off
	global_store_dwordx4 v[100:101], v[102:105], off offset:256
	s_waitcnt lgkmcnt(0)
	v_add_f32_e32 v98, v98, v99
	ds_bpermute_b32 v99, v202, v98
	s_and_saveexec_b64 s[18:19], vcc
	s_cbranch_execz .LBB0_785
	s_waitcnt lgkmcnt(0)
	v_add_f32_e32 v98, v98, v99
	ds_write_b32 v114, v98 offset:64
.LBB0_785:
	s_or_b64 exec, exec, s[18:19]
	v_lshlrev_b32_e32 v98, 16, v142
	s_waitcnt lgkmcnt(0)
	v_and_b32_e32 v99, 0xffff0000, v142
	v_mov_b32_e32 v167, v166
	v_pk_fma_f32 v[94:95], v[180:181], v[94:95], v[98:99]
	v_lshlrev_b32_e32 v98, 16, v143
	v_and_b32_e32 v99, 0xffff0000, v143
	v_pk_fma_f32 v[96:97], v[166:167], v[96:97], v[98:99]
	v_cvt_pk_bf16_f32 v94, v94, v95
	v_cvt_pk_bf16_f32 v95, v96, v97
	v_lshlrev_b32_e32 v96, 16, v144
	v_and_b32_e32 v97, 0xffff0000, v144
	v_pk_fma_f32 v[90:91], v[180:181], v[90:91], v[96:97]
	s_nop 0
	v_cvt_pk_bf16_f32 v96, v90, v91
	v_lshlrev_b32_e32 v90, 16, v145
	v_and_b32_e32 v91, 0xffff0000, v145
	v_pk_fma_f32 v[90:91], v[166:167], v[92:93], v[90:91]
	v_and_b32_e32 v93, 0xffff0000, v95
	v_cvt_pk_bf16_f32 v97, v90, v91
	v_and_b32_e32 v91, 0xffff0000, v94
	v_lshlrev_b32_e32 v90, 16, v94
	v_mul_f32_e32 v91, v91, v91
	v_lshlrev_b32_e32 v92, 16, v95
	v_fmac_f32_e32 v91, v90, v90
	v_mul_f32_e32 v90, v93, v93
	v_and_b32_e32 v99, 0xffff0000, v96
	v_and_b32_e32 v101, 0xffff0000, v97
	v_fmac_f32_e32 v90, v92, v92
	v_lshlrev_b32_e32 v98, 16, v96
	v_lshlrev_b32_e32 v100, 16, v97
	v_add_f32_e32 v90, v91, v90
	v_mul_f32_e32 v91, v99, v99
	v_mul_f32_e32 v92, v101, v101
	v_fmac_f32_e32 v91, v98, v98
	v_fmac_f32_e32 v92, v100, v100
	v_add_f32_e32 v91, v91, v92
	v_add_f32_e32 v92, v90, v91
	v_lshlrev_b32_e32 v90, 16, v138
	v_and_b32_e32 v91, 0xffff0000, v138
	v_pk_fma_f32 v[86:87], v[180:181], v[86:87], v[90:91]
	v_lshlrev_b32_e32 v90, 16, v139
	v_and_b32_e32 v91, 0xffff0000, v139
	v_pk_fma_f32 v[88:89], v[166:167], v[88:89], v[90:91]
	v_cvt_pk_bf16_f32 v86, v86, v87
	v_cvt_pk_bf16_f32 v87, v88, v89
	v_lshlrev_b32_e32 v88, 16, v140
	v_and_b32_e32 v89, 0xffff0000, v140
	v_pk_fma_f32 v[82:83], v[180:181], v[82:83], v[88:89]
	s_nop 0
	v_cvt_pk_bf16_f32 v88, v82, v83
	v_lshlrev_b32_e32 v82, 16, v141
	v_and_b32_e32 v83, 0xffff0000, v141
	v_pk_fma_f32 v[82:83], v[166:167], v[84:85], v[82:83]
	v_and_b32_e32 v85, 0xffff0000, v87
	v_cvt_pk_bf16_f32 v89, v82, v83
	v_and_b32_e32 v83, 0xffff0000, v86
	v_lshlrev_b32_e32 v82, 16, v86
	v_mul_f32_e32 v83, v83, v83
	v_lshlrev_b32_e32 v84, 16, v87
	v_fmac_f32_e32 v83, v82, v82
	v_mul_f32_e32 v82, v85, v85
	v_and_b32_e32 v91, 0xffff0000, v88
	v_and_b32_e32 v98, 0xffff0000, v89
	v_fmac_f32_e32 v82, v84, v84
	v_lshlrev_b32_e32 v90, 16, v88
	v_lshlrev_b32_e32 v93, 16, v89
	v_add_f32_e32 v82, v83, v82
	v_mul_f32_e32 v83, v91, v91
	v_mul_f32_e32 v84, v98, v98
	v_fmac_f32_e32 v83, v90, v90
	v_fmac_f32_e32 v84, v93, v93
	v_add_f32_e32 v83, v83, v84
	v_add_f32_e32 v82, v82, v83
	v_add_f32_e32 v82, v92, v82
	ds_bpermute_b32 v83, v203, v82
	v_lshl_add_u64 v[84:85], s[34:35], 0, v[194:195]
	v_lshl_add_u64 v[84:85], v[186:187], 1, v[84:85]
	global_store_dwordx4 v[84:85], v[94:97], off
	global_store_dwordx4 v[84:85], v[86:89], off offset:256
	s_waitcnt lgkmcnt(0)
	v_add_f32_e32 v82, v82, v83
	ds_bpermute_b32 v83, v202, v82
	s_and_saveexec_b64 s[18:19], vcc
	s_cbranch_execz .LBB0_787
	s_waitcnt lgkmcnt(0)
	v_add_f32_e32 v82, v82, v83
	ds_write_b32 v114, v82 offset:128
; __device__ __forceinline__ unsigned pk2(float lo, float hi) { f32x2_t v = {lo, hi}; bf16x2_t b = __builtin_convertvector(v, bf16x2_t); return __builtin_bit_cast(unsigned, b); }
; __device__ __forceinline__ float shflx(float v, int mask, int lane) { return __builtin_bit_cast(float, __builtin_amdgcn_ds_bpermute(((lane ^ mask) & 63) << 2, __builtin_bit_cast(int, v))); }
;     __device__ __forceinline__ void operator()(const f32x4 (&acc)[2][2][4][2], const Unit& u, int wr, int wc, int fr, int fq) const {
;     ...
;             for (int m = 0; m < 4; ++m) { const size_t ro = (size_t)(row0 + ai * HALF + m * 16) * D + col0; xin[m][0] = *(const u32x4*)(XB + ro); xin[m][1] = *(const u32x4*)(XB + ro + HALF); }
; #pragma unroll
;             for (int m = 0; m < 4; ++m) {
;                 const int row = row0 + ai * HALF + m * 16;
;                 const size_t ro = (size_t)row * D + col0;
;                 float ss = 0.f;
; #pragma unroll
;                 for (int bj = 0; bj < 2; ++bj) {
;                     const u32x4 xi = xin[m][bj];
;                     const f32x4 a0 = acc[ai][bj][m][0] * scale, a1 = acc[ai][bj][m][1] * scale;
;                     u32x4 w;
;                     w.x = pk2(bflo(xi.x) + a0[0], bfhi(xi.x) + a0[1]); w.y = pk2(bflo(xi.y) + a0[2], bfhi(xi.y) + a0[3]);
;                     w.z = pk2(bflo(xi.z) + a1[0], bfhi(xi.z) + a1[1]); w.w = pk2(bflo(xi.w) + a1[2], bfhi(xi.w) + a1[3]);
;                     *(u32x4*)(XB + ro + bj * HALF) = w;
;                     const float r0 = bflo(w.x), r1 = bfhi(w.x), r2 = bflo(w.y), r3 = bfhi(w.y), r4 = bflo(w.z), r5 = bfhi(w.z), r6 = bflo(w.w), r7 = bfhi(w.w);
;                     ss += ((r0 * r0 + r1 * r1) + (r2 * r2 + r3 * r3)) + ((r4 * r4 + r5 * r5) + (r6 * r6 + r7 * r7));
;                 }
;                 { const int ln_ = fq * 16 + fr; ss += shflx(ss, 16, ln_); ss += shflx(ss, 32, ln_); }
;                 if (fq == 0) red[((wr * 4 + wc) * 8 + ai * 4 + m) * 16 + fr] = ss;
.LBB0_787:
	s_or_b64 exec, exec, s[18:19]
	v_lshlrev_b32_e32 v82, 16, v134
	s_waitcnt lgkmcnt(0)
	v_and_b32_e32 v83, 0xffff0000, v134
	v_pk_fma_f32 v[78:79], v[180:181], v[78:79], v[82:83]
	v_lshlrev_b32_e32 v82, 16, v135
	v_and_b32_e32 v83, 0xffff0000, v135
	v_pk_fma_f32 v[80:81], v[166:167], v[80:81], v[82:83]
	v_cvt_pk_bf16_f32 v78, v78, v79
	v_cvt_pk_bf16_f32 v79, v80, v81
	v_lshlrev_b32_e32 v80, 16, v136
	v_and_b32_e32 v81, 0xffff0000, v136
	v_pk_fma_f32 v[74:75], v[180:181], v[74:75], v[80:81]
	s_nop 0
	v_cvt_pk_bf16_f32 v80, v74, v75
	v_lshlrev_b32_e32 v74, 16, v137
	v_and_b32_e32 v75, 0xffff0000, v137
	v_pk_fma_f32 v[74:75], v[166:167], v[76:77], v[74:75]
	v_and_b32_e32 v77, 0xffff0000, v79
	v_cvt_pk_bf16_f32 v81, v74, v75
	v_and_b32_e32 v75, 0xffff0000, v78
	v_lshlrev_b32_e32 v74, 16, v78
	v_mul_f32_e32 v75, v75, v75
	v_lshlrev_b32_e32 v76, 16, v79
	v_fmac_f32_e32 v75, v74, v74
	v_mul_f32_e32 v74, v77, v77
	v_and_b32_e32 v83, 0xffff0000, v80
	v_and_b32_e32 v85, 0xffff0000, v81
	v_fmac_f32_e32 v74, v76, v76
	v_lshlrev_b32_e32 v82, 16, v80
	v_lshlrev_b32_e32 v84, 16, v81
	v_add_f32_e32 v74, v75, v74
	v_mul_f32_e32 v75, v83, v83
	v_mul_f32_e32 v76, v85, v85
	v_fmac_f32_e32 v75, v82, v82
	v_fmac_f32_e32 v76, v84, v84
	v_add_f32_e32 v75, v75, v76
	v_add_f32_e32 v76, v74, v75
	v_lshlrev_b32_e32 v74, 16, v126
	v_and_b32_e32 v75, 0xffff0000, v126
	v_pk_fma_f32 v[70:71], v[180:181], v[70:71], v[74:75]
	v_lshlrev_b32_e32 v74, 16, v127
	v_and_b32_e32 v75, 0xffff0000, v127
	v_pk_fma_f32 v[72:73], v[166:167], v[72:73], v[74:75]
	v_cvt_pk_bf16_f32 v70, v70, v71
	v_cvt_pk_bf16_f32 v71, v72, v73
	v_lshlrev_b32_e32 v72, 16, v128
	v_and_b32_e32 v73, 0xffff0000, v128
	v_pk_fma_f32 v[66:67], v[180:181], v[66:67], v[72:73]
	s_nop 0
	v_cvt_pk_bf16_f32 v72, v66, v67
	v_lshlrev_b32_e32 v66, 16, v129
	v_and_b32_e32 v67, 0xffff0000, v129
	v_pk_fma_f32 v[66:67], v[166:167], v[68:69], v[66:67]
	v_and_b32_e32 v69, 0xffff0000, v71
	v_cvt_pk_bf16_f32 v73, v66, v67
	v_and_b32_e32 v67, 0xffff0000, v70
	v_lshlrev_b32_e32 v66, 16, v70
	v_mul_f32_e32 v67, v67, v67
	v_lshlrev_b32_e32 v68, 16, v71
	v_fmac_f32_e32 v67, v66, v66
	v_mul_f32_e32 v66, v69, v69
	v_and_b32_e32 v75, 0xffff0000, v72
	v_and_b32_e32 v82, 0xffff0000, v73
	v_fmac_f32_e32 v66, v68, v68
	v_lshlrev_b32_e32 v74, 16, v72
	v_lshlrev_b32_e32 v77, 16, v73
	v_add_f32_e32 v66, v67, v66
	v_mul_f32_e32 v67, v75, v75
	v_mul_f32_e32 v68, v82, v82
	v_fmac_f32_e32 v67, v74, v74
	v_fmac_f32_e32 v68, v77, v77
	v_add_f32_e32 v67, v67, v68
	v_add_f32_e32 v66, v66, v67
	v_add_f32_e32 v66, v76, v66
	ds_bpermute_b32 v67, v203, v66
	v_lshl_add_u64 v[68:69], s[34:35], 0, v[192:193]
	v_lshl_add_u64 v[68:69], v[186:187], 1, v[68:69]
	global_store_dwordx4 v[68:69], v[78:81], off
	global_store_dwordx4 v[68:69], v[70:73], off offset:256
	s_waitcnt lgkmcnt(0)
	v_add_f32_e32 v66, v66, v67
	ds_bpermute_b32 v67, v202, v66
	s_and_saveexec_b64 s[18:19], vcc
	s_cbranch_execz .LBB0_789
	s_waitcnt lgkmcnt(0)
	v_add_f32_e32 v66, v66, v67
	ds_write_b32 v114, v66 offset:192
.LBB0_789:
	s_or_b64 exec, exec, s[18:19]
	s_waitcnt lgkmcnt(0)
	v_lshlrev_b64 v[66:67], 11, v[188:189]
	s_mov_b64 s[18:19], 0x40000
	v_lshl_add_u64 v[104:105], v[66:67], 0, s[18:19]
	v_lshl_add_u64 v[68:69], v[190:191], 0, v[104:105]
	global_load_dwordx4 v[100:103], v[68:69], off
	global_load_dwordx4 v[90:93], v[68:69], off offset:256
	s_mov_b64 s[18:19], 0x48000
	v_lshl_add_u64 v[98:99], v[66:67], 0, s[18:19]
	s_mov_b64 s[18:19], 0x50000
	v_lshl_add_u64 v[96:97], v[66:67], 0, s[18:19]
	s_mov_b64 s[18:19], 0x58000
	v_lshl_add_u64 v[68:69], v[190:191], 0, v[98:99]
	v_lshl_add_u64 v[94:95], v[66:67], 0, s[18:19]
	global_load_dwordx4 v[86:89], v[68:69], off
	global_load_dwordx4 v[82:85], v[68:69], off offset:256
	v_lshl_add_u64 v[68:69], v[190:191], 0, v[96:97]
	v_lshl_add_u64 v[66:67], v[190:191], 0, v[94:95]
	global_load_dwordx4 v[78:81], v[68:69], off
	global_load_dwordx4 v[74:77], v[68:69], off offset:256
	global_load_dwordx4 v[70:73], v[66:67], off
	s_nop 0
	global_load_dwordx4 v[66:69], v[66:67], off offset:256
	v_mov_b32_e32 v167, v166
	s_waitcnt vmcnt(0) lgkmcnt(0)
	v_lshlrev_b32_e32 v106, 16, v100
	v_and_b32_e32 v107, 0xffff0000, v100
	v_lshlrev_b32_e32 v100, 16, v101
	v_and_b32_e32 v101, 0xffff0000, v101
	v_pk_fma_f32 v[62:63], v[180:181], v[62:63], v[106:107]
	v_pk_fma_f32 v[64:65], v[166:167], v[64:65], v[100:101]
	v_cvt_pk_bf16_f32 v62, v62, v63
	v_cvt_pk_bf16_f32 v63, v64, v65
	v_lshlrev_b32_e32 v64, 16, v102
	v_and_b32_e32 v65, 0xffff0000, v102
	v_pk_fma_f32 v[58:59], v[180:181], v[58:59], v[64:65]
	s_nop 0
	v_cvt_pk_bf16_f32 v64, v58, v59
	v_lshlrev_b32_e32 v58, 16, v103
	v_and_b32_e32 v59, 0xffff0000, v103
	v_pk_fma_f32 v[58:59], v[166:167], v[60:61], v[58:59]
	v_and_b32_e32 v61, 0xffff0000, v62
	v_cvt_pk_bf16_f32 v65, v58, v59
	v_lshl_add_u64 v[58:59], s[34:35], 0, v[104:105]
	v_lshl_add_u64 v[58:59], v[186:187], 1, v[58:59]
	global_store_dwordx4 v[58:59], v[62:65], off
	v_lshlrev_b32_e32 v60, 16, v62
	v_mul_f32_e32 v61, v61, v61
	v_lshlrev_b32_e32 v62, 16, v63
	v_and_b32_e32 v63, 0xffff0000, v63
	v_fmac_f32_e32 v61, v60, v60
	v_mul_f32_e32 v60, v63, v63
	v_lshlrev_b32_e32 v100, 16, v64
	v_and_b32_e32 v64, 0xffff0000, v64
	v_lshlrev_b32_e32 v101, 16, v65
	v_and_b32_e32 v65, 0xffff0000, v65
	v_fmac_f32_e32 v60, v62, v62
	v_add_f32_e32 v60, v61, v60
	v_mul_f32_e32 v61, v64, v64
	v_mul_f32_e32 v62, v65, v65
	v_fmac_f32_e32 v61, v100, v100
	v_fmac_f32_e32 v62, v101, v101
	v_add_f32_e32 v61, v61, v62
	v_add_f32_e32 v62, v60, v61
	v_lshlrev_b32_e32 v60, 16, v90
	v_and_b32_e32 v61, 0xffff0000, v90
	v_pk_fma_f32 v[54:55], v[180:181], v[54:55], v[60:61]
	v_lshlrev_b32_e32 v60, 16, v91
	v_and_b32_e32 v61, 0xffff0000, v91
	v_pk_fma_f32 v[56:57], v[166:167], v[56:57], v[60:61]
	v_cvt_pk_bf16_f32 v54, v54, v55
	v_cvt_pk_bf16_f32 v55, v56, v57
	v_lshlrev_b32_e32 v56, 16, v92
	v_and_b32_e32 v57, 0xffff0000, v92
	v_pk_fma_f32 v[50:51], v[180:181], v[50:51], v[56:57]
	s_nop 0
	v_cvt_pk_bf16_f32 v56, v50, v51
	v_lshlrev_b32_e32 v50, 16, v93
	v_and_b32_e32 v51, 0xffff0000, v93
	v_pk_fma_f32 v[50:51], v[166:167], v[52:53], v[50:51]
	v_and_b32_e32 v53, 0xffff0000, v55
	v_cvt_pk_bf16_f32 v57, v50, v51
	v_and_b32_e32 v51, 0xffff0000, v54
	v_lshlrev_b32_e32 v50, 16, v54
	v_mul_f32_e32 v51, v51, v51
	v_lshlrev_b32_e32 v52, 16, v55
	v_fmac_f32_e32 v51, v50, v50
	v_mul_f32_e32 v50, v53, v53
	global_store_dwordx4 v[58:59], v[54:57], off offset:256
	v_fmac_f32_e32 v50, v52, v52
	v_add_f32_e32 v50, v51, v50
	v_lshlrev_b32_e32 v54, 16, v56
	v_and_b32_e32 v55, 0xffff0000, v56
	v_lshlrev_b32_e32 v56, 16, v57
	v_and_b32_e32 v57, 0xffff0000, v57
	v_mul_f32_e32 v51, v55, v55
	v_mul_f32_e32 v52, v57, v57
	v_fmac_f32_e32 v51, v54, v54
	v_fmac_f32_e32 v52, v56, v56
	v_add_f32_e32 v51, v51, v52
	v_add_f32_e32 v50, v50, v51
	v_add_f32_e32 v50, v62, v50
	ds_bpermute_b32 v51, v203, v50
	s_waitcnt lgkmcnt(0)
	v_add_f32_e32 v50, v50, v51
	ds_bpermute_b32 v51, v202, v50
	s_and_saveexec_b64 s[18:19], vcc
	s_cbranch_execz .LBB0_791
; __device__ __forceinline__ unsigned pk2(float lo, float hi) { f32x2_t v = {lo, hi}; bf16x2_t b = __builtin_convertvector(v, bf16x2_t); return __builtin_bit_cast(unsigned, b); }
; __device__ __forceinline__ float shflx(float v, int mask, int lane) { return __builtin_bit_cast(float, __builtin_amdgcn_ds_bpermute(((lane ^ mask) & 63) << 2, __builtin_bit_cast(int, v))); }
;     __device__ __forceinline__ void operator()(const f32x4 (&acc)[2][2][4][2], const Unit& u, int wr, int wc, int fr, int fq) const {
;     ...
;                 for (int bj = 0; bj < 2; ++bj) {
;                     const u32x4 xi = xin[m][bj];
;                     const f32x4 a0 = acc[ai][bj][m][0] * scale, a1 = acc[ai][bj][m][1] * scale;
;                     u32x4 w;
;                     w.x = pk2(bflo(xi.x) + a0[0], bfhi(xi.x) + a0[1]); w.y = pk2(bflo(xi.y) + a0[2], bfhi(xi.y) + a0[3]);
;                     w.z = pk2(bflo(xi.z) + a1[0], bfhi(xi.z) + a1[1]); w.w = pk2(bflo(xi.w) + a1[2], bfhi(xi.w) + a1[3]);
;                     *(u32x4*)(XB + ro + bj * HALF) = w;
;                     const float r0 = bflo(w.x), r1 = bfhi(w.x), r2 = bflo(w.y), r3 = bfhi(w.y), r4 = bflo(w.z), r5 = bfhi(w.z), r6 = bflo(w.w), r7 = bfhi(w.w);
;                     ss += ((r0 * r0 + r1 * r1) + (r2 * r2 + r3 * r3)) + ((r4 * r4 + r5 * r5) + (r6 * r6 + r7 * r7));
;                 }
;                 { const int ln_ = fq * 16 + fr; ss += shflx(ss, 16, ln_); ss += shflx(ss, 32, ln_); }
;                 if (fq == 0) red[((wr * 4 + wc) * 8 + ai * 4 + m) * 16 + fr] = ss;
	s_waitcnt lgkmcnt(0)
	v_add_f32_e32 v50, v50, v51
	ds_write_b32 v114, v50 offset:256
.LBB0_791:
	s_or_b64 exec, exec, s[18:19]
	v_lshlrev_b32_e32 v50, 16, v86
	s_waitcnt lgkmcnt(0)
	v_and_b32_e32 v51, 0xffff0000, v86
	v_pk_fma_f32 v[46:47], v[180:181], v[46:47], v[50:51]
	v_lshlrev_b32_e32 v50, 16, v87
	v_and_b32_e32 v51, 0xffff0000, v87
	v_pk_fma_f32 v[48:49], v[166:167], v[48:49], v[50:51]
	v_cvt_pk_bf16_f32 v46, v46, v47
	v_cvt_pk_bf16_f32 v47, v48, v49
	v_lshlrev_b32_e32 v48, 16, v88
	v_and_b32_e32 v49, 0xffff0000, v88
	v_pk_fma_f32 v[42:43], v[180:181], v[42:43], v[48:49]
	s_nop 0
	v_cvt_pk_bf16_f32 v48, v42, v43
	v_lshlrev_b32_e32 v42, 16, v89
	v_and_b32_e32 v43, 0xffff0000, v89
	v_pk_fma_f32 v[42:43], v[166:167], v[44:45], v[42:43]
	v_and_b32_e32 v45, 0xffff0000, v47
	v_cvt_pk_bf16_f32 v49, v42, v43
	v_and_b32_e32 v43, 0xffff0000, v46
	v_lshlrev_b32_e32 v42, 16, v46
	v_mul_f32_e32 v43, v43, v43
	v_lshlrev_b32_e32 v44, 16, v47
	v_fmac_f32_e32 v43, v42, v42
	v_mul_f32_e32 v42, v45, v45
	v_and_b32_e32 v51, 0xffff0000, v48
	v_and_b32_e32 v53, 0xffff0000, v49
	v_fmac_f32_e32 v42, v44, v44
	v_lshlrev_b32_e32 v50, 16, v48
	v_lshlrev_b32_e32 v52, 16, v49
	v_add_f32_e32 v42, v43, v42
	v_mul_f32_e32 v43, v51, v51
	v_mul_f32_e32 v44, v53, v53
	v_fmac_f32_e32 v43, v50, v50
	v_fmac_f32_e32 v44, v52, v52
	v_add_f32_e32 v43, v43, v44
	v_add_f32_e32 v44, v42, v43
	v_lshlrev_b32_e32 v42, 16, v82
	v_and_b32_e32 v43, 0xffff0000, v82
	v_pk_fma_f32 v[38:39], v[180:181], v[38:39], v[42:43]
	v_lshlrev_b32_e32 v42, 16, v83
	v_and_b32_e32 v43, 0xffff0000, v83
	v_pk_fma_f32 v[40:41], v[166:167], v[40:41], v[42:43]
	v_cvt_pk_bf16_f32 v38, v38, v39
	v_cvt_pk_bf16_f32 v39, v40, v41
	v_lshlrev_b32_e32 v40, 16, v84
	v_and_b32_e32 v41, 0xffff0000, v84
	v_pk_fma_f32 v[34:35], v[180:181], v[34:35], v[40:41]
	s_nop 0
	v_cvt_pk_bf16_f32 v40, v34, v35
	v_lshlrev_b32_e32 v34, 16, v85
	v_and_b32_e32 v35, 0xffff0000, v85
	v_pk_fma_f32 v[34:35], v[166:167], v[36:37], v[34:35]
	v_and_b32_e32 v37, 0xffff0000, v39
	v_cvt_pk_bf16_f32 v41, v34, v35
	v_and_b32_e32 v35, 0xffff0000, v38
	v_lshlrev_b32_e32 v34, 16, v38
	v_mul_f32_e32 v35, v35, v35
	v_lshlrev_b32_e32 v36, 16, v39
	v_fmac_f32_e32 v35, v34, v34
	v_mul_f32_e32 v34, v37, v37
	v_and_b32_e32 v43, 0xffff0000, v40
	v_and_b32_e32 v50, 0xffff0000, v41
	v_fmac_f32_e32 v34, v36, v36
	v_lshlrev_b32_e32 v42, 16, v40
	v_lshlrev_b32_e32 v45, 16, v41
	v_add_f32_e32 v34, v35, v34
	v_mul_f32_e32 v35, v43, v43
	v_mul_f32_e32 v36, v50, v50
	v_fmac_f32_e32 v35, v42, v42
	v_fmac_f32_e32 v36, v45, v45
	v_add_f32_e32 v35, v35, v36
	v_add_f32_e32 v34, v34, v35
	v_add_f32_e32 v34, v44, v34
	ds_bpermute_b32 v35, v203, v34
	v_lshl_add_u64 v[36:37], s[34:35], 0, v[98:99]
	v_lshl_add_u64 v[36:37], v[186:187], 1, v[36:37]
	global_store_dwordx4 v[36:37], v[46:49], off
	global_store_dwordx4 v[36:37], v[38:41], off offset:256
	s_waitcnt lgkmcnt(0)
	v_add_f32_e32 v34, v34, v35
	ds_bpermute_b32 v35, v202, v34
	s_and_saveexec_b64 s[18:19], vcc
	s_cbranch_execz .LBB0_793
	s_waitcnt lgkmcnt(0)
	v_add_f32_e32 v34, v34, v35
	ds_write_b32 v114, v34 offset:320
; __device__ __forceinline__ unsigned pk2(float lo, float hi) { f32x2_t v = {lo, hi}; bf16x2_t b = __builtin_convertvector(v, bf16x2_t); return __builtin_bit_cast(unsigned, b); }
; __device__ __forceinline__ float shflx(float v, int mask, int lane) { return __builtin_bit_cast(float, __builtin_amdgcn_ds_bpermute(((lane ^ mask) & 63) << 2, __builtin_bit_cast(int, v))); }
;     __device__ __forceinline__ void operator()(const f32x4 (&acc)[2][2][4][2], const Unit& u, int wr, int wc, int fr, int fq) const {
;     ...
;             for (int m = 0; m < 4; ++m) { const size_t ro = (size_t)(row0 + ai * HALF + m * 16) * D + col0; xin[m][0] = *(const u32x4*)(XB + ro); xin[m][1] = *(const u32x4*)(XB + ro + HALF); }
; #pragma unroll
;             for (int m = 0; m < 4; ++m) {
;                 const int row = row0 + ai * HALF + m * 16;
;                 const size_t ro = (size_t)row * D + col0;
;                 float ss = 0.f;
; #pragma unroll
;                 for (int bj = 0; bj < 2; ++bj) {
;                     const u32x4 xi = xin[m][bj];
;                     const f32x4 a0 = acc[ai][bj][m][0] * scale, a1 = acc[ai][bj][m][1] * scale;
;                     u32x4 w;
;                     w.x = pk2(bflo(xi.x) + a0[0], bfhi(xi.x) + a0[1]); w.y = pk2(bflo(xi.y) + a0[2], bfhi(xi.y) + a0[3]);
;                     w.z = pk2(bflo(xi.z) + a1[0], bfhi(xi.z) + a1[1]); w.w = pk2(bflo(xi.w) + a1[2], bfhi(xi.w) + a1[3]);
;                     *(u32x4*)(XB + ro + bj * HALF) = w;
;                     const float r0 = bflo(w.x), r1 = bfhi(w.x), r2 = bflo(w.y), r3 = bfhi(w.y), r4 = bflo(w.z), r5 = bfhi(w.z), r6 = bflo(w.w), r7 = bfhi(w.w);
;                     ss += ((r0 * r0 + r1 * r1) + (r2 * r2 + r3 * r3)) + ((r4 * r4 + r5 * r5) + (r6 * r6 + r7 * r7));
;                 }
;                 { const int ln_ = fq * 16 + fr; ss += shflx(ss, 16, ln_); ss += shflx(ss, 32, ln_); }
;                 if (fq == 0) red[((wr * 4 + wc) * 8 + ai * 4 + m) * 16 + fr] = ss;
.LBB0_793:
	s_or_b64 exec, exec, s[18:19]
	v_lshlrev_b32_e32 v34, 16, v78
	s_waitcnt lgkmcnt(0)
	v_and_b32_e32 v35, 0xffff0000, v78
	v_mov_b32_e32 v167, v166
	v_pk_fma_f32 v[30:31], v[180:181], v[30:31], v[34:35]
	v_lshlrev_b32_e32 v34, 16, v79
	v_and_b32_e32 v35, 0xffff0000, v79
	v_pk_fma_f32 v[32:33], v[166:167], v[32:33], v[34:35]
	v_cvt_pk_bf16_f32 v30, v30, v31
	v_cvt_pk_bf16_f32 v31, v32, v33
	v_lshlrev_b32_e32 v32, 16, v80
	v_and_b32_e32 v33, 0xffff0000, v80
	v_pk_fma_f32 v[26:27], v[180:181], v[26:27], v[32:33]
	s_nop 0
	v_cvt_pk_bf16_f32 v32, v26, v27
	v_lshlrev_b32_e32 v26, 16, v81
	v_and_b32_e32 v27, 0xffff0000, v81
	v_pk_fma_f32 v[26:27], v[166:167], v[28:29], v[26:27]
	v_and_b32_e32 v29, 0xffff0000, v31
	v_cvt_pk_bf16_f32 v33, v26, v27
	v_and_b32_e32 v27, 0xffff0000, v30
	v_lshlrev_b32_e32 v26, 16, v30
	v_mul_f32_e32 v27, v27, v27
	v_lshlrev_b32_e32 v28, 16, v31
	v_fmac_f32_e32 v27, v26, v26
	v_mul_f32_e32 v26, v29, v29
	v_and_b32_e32 v35, 0xffff0000, v32
	v_and_b32_e32 v37, 0xffff0000, v33
	v_fmac_f32_e32 v26, v28, v28
	v_lshlrev_b32_e32 v34, 16, v32
	v_lshlrev_b32_e32 v36, 16, v33
	v_add_f32_e32 v26, v27, v26
	v_mul_f32_e32 v27, v35, v35
	v_mul_f32_e32 v28, v37, v37
	v_fmac_f32_e32 v27, v34, v34
	v_fmac_f32_e32 v28, v36, v36
	v_add_f32_e32 v27, v27, v28
	v_add_f32_e32 v28, v26, v27
	v_lshlrev_b32_e32 v26, 16, v74
	v_and_b32_e32 v27, 0xffff0000, v74
	v_pk_fma_f32 v[22:23], v[180:181], v[22:23], v[26:27]
	v_lshlrev_b32_e32 v26, 16, v75
	v_and_b32_e32 v27, 0xffff0000, v75
	v_pk_fma_f32 v[24:25], v[166:167], v[24:25], v[26:27]
	v_cvt_pk_bf16_f32 v22, v22, v23
	v_cvt_pk_bf16_f32 v23, v24, v25
	v_lshlrev_b32_e32 v24, 16, v76
	v_and_b32_e32 v25, 0xffff0000, v76
	v_pk_fma_f32 v[18:19], v[180:181], v[18:19], v[24:25]
	s_nop 0
	v_cvt_pk_bf16_f32 v24, v18, v19
	v_lshlrev_b32_e32 v18, 16, v77
	v_and_b32_e32 v19, 0xffff0000, v77
	v_pk_fma_f32 v[18:19], v[166:167], v[20:21], v[18:19]
	v_and_b32_e32 v21, 0xffff0000, v23
	v_cvt_pk_bf16_f32 v25, v18, v19
	v_and_b32_e32 v19, 0xffff0000, v22
	v_lshlrev_b32_e32 v18, 16, v22
	v_mul_f32_e32 v19, v19, v19
	v_lshlrev_b32_e32 v20, 16, v23
	v_fmac_f32_e32 v19, v18, v18
	v_mul_f32_e32 v18, v21, v21
	v_and_b32_e32 v27, 0xffff0000, v24
	v_and_b32_e32 v34, 0xffff0000, v25
	v_fmac_f32_e32 v18, v20, v20
	v_lshlrev_b32_e32 v26, 16, v24
	v_lshlrev_b32_e32 v29, 16, v25
	v_add_f32_e32 v18, v19, v18
	v_mul_f32_e32 v19, v27, v27
	v_mul_f32_e32 v20, v34, v34
	v_fmac_f32_e32 v19, v26, v26
	v_fmac_f32_e32 v20, v29, v29
	v_add_f32_e32 v19, v19, v20
	v_add_f32_e32 v18, v18, v19
	v_add_f32_e32 v18, v28, v18
	ds_bpermute_b32 v19, v203, v18
	v_lshl_add_u64 v[20:21], s[34:35], 0, v[96:97]
	v_lshl_add_u64 v[20:21], v[186:187], 1, v[20:21]
	global_store_dwordx4 v[20:21], v[30:33], off
	global_store_dwordx4 v[20:21], v[22:25], off offset:256
	s_waitcnt lgkmcnt(0)
	v_add_f32_e32 v18, v18, v19
	ds_bpermute_b32 v19, v202, v18
	s_and_saveexec_b64 s[18:19], vcc
	s_cbranch_execz .LBB0_795
	s_waitcnt lgkmcnt(0)
	v_add_f32_e32 v18, v18, v19
	ds_write_b32 v114, v18 offset:384
.LBB0_795:
	s_or_b64 exec, exec, s[18:19]
	v_lshlrev_b32_e32 v18, 16, v70
	s_waitcnt lgkmcnt(0)
	v_and_b32_e32 v19, 0xffff0000, v70
	v_pk_fma_f32 v[14:15], v[180:181], v[14:15], v[18:19]
	v_lshlrev_b32_e32 v18, 16, v71
	v_and_b32_e32 v19, 0xffff0000, v71
	v_pk_fma_f32 v[16:17], v[166:167], v[16:17], v[18:19]
	v_cvt_pk_bf16_f32 v14, v14, v15
	v_cvt_pk_bf16_f32 v15, v16, v17
	v_lshlrev_b32_e32 v16, 16, v72
	v_and_b32_e32 v17, 0xffff0000, v72
	v_pk_fma_f32 v[10:11], v[180:181], v[10:11], v[16:17]
	s_nop 0
	v_cvt_pk_bf16_f32 v16, v10, v11
	v_lshlrev_b32_e32 v10, 16, v73
	v_and_b32_e32 v11, 0xffff0000, v73
	v_pk_fma_f32 v[10:11], v[166:167], v[12:13], v[10:11]
	v_and_b32_e32 v13, 0xffff0000, v15
	v_cvt_pk_bf16_f32 v17, v10, v11
	v_and_b32_e32 v11, 0xffff0000, v14
	v_lshlrev_b32_e32 v10, 16, v14
	v_mul_f32_e32 v11, v11, v11
	v_lshlrev_b32_e32 v12, 16, v15
	v_fmac_f32_e32 v11, v10, v10
	v_mul_f32_e32 v10, v13, v13
	v_and_b32_e32 v19, 0xffff0000, v16
	v_and_b32_e32 v21, 0xffff0000, v17
	v_fmac_f32_e32 v10, v12, v12
	v_lshlrev_b32_e32 v18, 16, v16
	v_lshlrev_b32_e32 v20, 16, v17
	v_add_f32_e32 v10, v11, v10
	v_mul_f32_e32 v11, v19, v19
	v_mul_f32_e32 v12, v21, v21
	v_fmac_f32_e32 v11, v18, v18
	v_fmac_f32_e32 v12, v20, v20
	v_add_f32_e32 v11, v11, v12
	v_add_f32_e32 v12, v10, v11
	v_lshlrev_b32_e32 v10, 16, v66
	v_and_b32_e32 v11, 0xffff0000, v66
	v_pk_fma_f32 v[6:7], v[180:181], v[6:7], v[10:11]
	v_lshlrev_b32_e32 v10, 16, v67
	v_and_b32_e32 v11, 0xffff0000, v67
	v_pk_fma_f32 v[8:9], v[166:167], v[8:9], v[10:11]
	v_cvt_pk_bf16_f32 v6, v6, v7
	v_cvt_pk_bf16_f32 v7, v8, v9
	v_lshlrev_b32_e32 v8, 16, v68
	v_and_b32_e32 v9, 0xffff0000, v68
	v_pk_fma_f32 v[2:3], v[180:181], v[2:3], v[8:9]
	s_nop 0
	v_cvt_pk_bf16_f32 v8, v2, v3
	v_lshlrev_b32_e32 v2, 16, v69
	v_and_b32_e32 v3, 0xffff0000, v69
	v_pk_fma_f32 v[2:3], v[166:167], v[4:5], v[2:3]
	v_and_b32_e32 v5, 0xffff0000, v7
	v_cvt_pk_bf16_f32 v9, v2, v3
	v_and_b32_e32 v3, 0xffff0000, v6
	v_lshlrev_b32_e32 v2, 16, v6
	v_mul_f32_e32 v3, v3, v3
	v_lshlrev_b32_e32 v4, 16, v7
	v_fmac_f32_e32 v3, v2, v2
	v_mul_f32_e32 v2, v5, v5
	v_and_b32_e32 v11, 0xffff0000, v8
	v_and_b32_e32 v18, 0xffff0000, v9
	v_fmac_f32_e32 v2, v4, v4
	v_lshlrev_b32_e32 v10, 16, v8
	v_lshlrev_b32_e32 v13, 16, v9
	v_add_f32_e32 v2, v3, v2
	v_mul_f32_e32 v3, v11, v11
	v_mul_f32_e32 v4, v18, v18
	v_fmac_f32_e32 v3, v10, v10
	v_fmac_f32_e32 v4, v13, v13
	v_add_f32_e32 v3, v3, v4
	v_add_f32_e32 v2, v2, v3
	v_add_f32_e32 v2, v12, v2
	ds_bpermute_b32 v3, v203, v2
	v_lshl_add_u64 v[4:5], s[34:35], 0, v[94:95]
	v_lshl_add_u64 v[4:5], v[186:187], 1, v[4:5]
	global_store_dwordx4 v[4:5], v[14:17], off
	global_store_dwordx4 v[4:5], v[6:9], off offset:256
	s_waitcnt lgkmcnt(0)
	v_add_f32_e32 v2, v2, v3
	ds_bpermute_b32 v3, v202, v2
	s_and_saveexec_b64 s[18:19], vcc
	s_cbranch_execz .LBB0_797
	s_waitcnt lgkmcnt(0)
	v_add_f32_e32 v2, v2, v3
	ds_write_b32 v114, v2 offset:448

;     __device__ __forceinline__ void operator()(const f32x4 (&acc)[2][2][4][2], const Unit& u, int wr, int wc, int fr, int fq) const {
;     ...
;         asm volatile("s_waitcnt lgkmcnt(0)" ::: "memory"); __builtin_amdgcn_s_barrier(); asm volatile("" ::: "memory");
;         if (wc == 0) {
;             const int ln_ = fq * 16 + fr;
; #pragma unroll
;             for (int e = 0; e < 2; ++e) {
;                 const int idx = ln_ + 64 * e, k = idx >> 4, f = idx & 15;
;                 const float sum = (red[((wr * 4 + 0) * 8 + k) * 16 + f] + red[((wr * 4 + 1) * 8 + k) * 16 + f]) + (red[((wr * 4 + 2) * 8 + k) * 16 + f] + red[((wr * 4 + 3) * 8 + k) * 16 + f]);
;                 SSP[(size_t)(u.pm * BM + (k >> 2) * HALF + wr * 64 + (k & 3) * 16 + f) * 4 + u.pn] = sum;
;             }
.LBB0_799:
	v_and_b32_e32 v2, 15, v201
	s_waitcnt lgkmcnt(0)
	v_lshlrev_b32_e32 v3, 2, v2
	s_add_i32 s18, 0, 0x20000
	v_add_u32_e32 v4, s82, v3
	v_add_u32_e32 v5, s18, v3
	v_and_b32_e32 v3, 48, v200
	v_or3_b32 v6, s5, v3, v2
	v_ashrrev_i32_e32 v2, 4, v200
	v_and_b32_e32 v3, 0x3ffffff0, v200
	v_add_u32_e32 v7, s85, v2
	v_add_u32_e32 v8, s88, v2
	v_add_u32_e32 v2, s89, v2
	v_lshl_add_u32 v3, v3, 2, v4
	v_lshl_add_u32 v7, v7, 6, v5
	v_lshl_add_u32 v8, v8, 6, v5
	v_lshl_add_u32 v2, v2, 6, v5
	ds_read_b32 v3, v3
	ds_read_b32 v7, v7
	ds_read_b32 v8, v8
	ds_read_b32 v2, v2
	s_ashr_i32 s5, s4, 31
	s_lshl_b64 s[4:5], s[4:5], 2
	s_waitcnt lgkmcnt(0)
	v_add_f32_e32 v3, v3, v7
	s_add_u32 s4, s43, s4
	v_add_f32_e32 v2, v8, v2
	v_add_f32_e32 v7, v3, v2
	v_lshlrev_b32_e32 v2, 1, v200
	v_and_b32_e32 v2, 0xffffff80, v2
	v_add_u32_e32 v2, v6, v2
	s_addc_u32 s5, s44, s5
	v_ashrrev_i32_e32 v3, 31, v2
	v_lshl_add_u64 v[2:3], v[2:3], 4, s[4:5]
	global_store_dword v[2:3], v7, off
	v_add_u32_e32 v2, 64, v200
	v_ashrrev_i32_e32 v3, 4, v2
	v_and_b32_e32 v7, 0x3ffffff0, v2
	v_lshl_add_u32 v4, v7, 2, v4
	v_add_u32_e32 v7, s85, v3
	v_add_u32_e32 v8, s88, v3
	v_add_u32_e32 v3, s89, v3
	v_lshl_add_u32 v7, v7, 6, v5
	v_lshl_add_u32 v3, v3, 6, v5
	v_lshl_add_u32 v8, v8, 6, v5
	ds_read_b32 v4, v4
	ds_read_b32 v5, v7
	ds_read_b32 v7, v8
	ds_read_b32 v3, v3
	v_lshlrev_b32_e32 v2, 1, v2
	v_and_b32_e32 v2, 0xffffff80, v2
	s_waitcnt lgkmcnt(0)
	v_add_f32_e32 v4, v4, v5
	v_add_u32_e32 v2, v6, v2
	v_add_f32_e32 v3, v7, v3
	v_add_f32_e32 v4, v4, v3
	v_ashrrev_i32_e32 v3, 31, v2
	v_lshl_add_u64 v[2:3], v[2:3], 4, s[4:5]
	global_store_dword v[2:3], v4, off
	s_and_b64 vcc, exec, s[6:7]
	s_mov_b64 s[4:5], -1
	s_cbranch_vccnz .LBB0_766

; __global__ void __launch_bounds__(512, 2) fwd_megakernel(Args a_) {
;     ...
;                 if (ph == 2) { const int gt = bid * 512 + tid; if (gt < 2048) { const float* PART = (const float*)(ws + WS_BPART); float sacc = 0.f;
; #pragma unroll
;                     for (int c = 0; c < 64; ++c) sacc += PART[c * 2048 + gt];
;                     ((float*)(ws + WS_BIAS1))[gt] = sacc; } }
.LBB0_805:
	s_andn2_b64 vcc, exec, s[4:5]
	s_cbranch_vccnz .LBB0_833
	s_cmp_eq_u32 s30, 2
	v_lshl_add_u32 v2, s36, 9, v178
	s_movk_i32 s6, 0x800
	s_cselect_b64 s[4:5], -1, 0
	v_cmp_gt_i32_e32 vcc, s6, v2
	s_and_b64 s[6:7], s[4:5], vcc
	s_and_saveexec_b64 s[4:5], s[6:7]
	s_cbranch_execz .LBB0_808
	s_waitcnt lgkmcnt(0)
	v_ashrrev_i32_e32 v3, 31, v2
	v_lshl_add_u64 v[2:3], v[2:3], 2, s[86:87]
	v_add_co_u32_e32 v4, vcc, 0x1a700000, v2
	s_nop 1
	v_addc_co_u32_e32 v5, vcc, 0, v3, vcc
	v_add_co_u32_e32 v6, vcc, 0x1a702000, v2
	s_nop 1
	v_addc_co_u32_e32 v7, vcc, 0, v3, vcc
	v_add_co_u32_e32 v8, vcc, 0x1a704000, v2
	s_nop 1
	v_addc_co_u32_e32 v9, vcc, 0, v3, vcc
	v_add_co_u32_e32 v10, vcc, 0x1a706000, v2
	s_nop 1
	v_addc_co_u32_e32 v11, vcc, 0, v3, vcc
	v_add_co_u32_e32 v12, vcc, 0x1a708000, v2
	s_nop 1
	v_addc_co_u32_e32 v13, vcc, 0, v3, vcc
	v_add_co_u32_e32 v14, vcc, 0x1a70a000, v2
	s_nop 1
	v_addc_co_u32_e32 v15, vcc, 0, v3, vcc
	v_add_co_u32_e32 v16, vcc, 0x1a70c000, v2
	s_nop 1
	v_addc_co_u32_e32 v17, vcc, 0, v3, vcc
	v_add_co_u32_e32 v18, vcc, 0x1a70e000, v2
	s_nop 1
	v_addc_co_u32_e32 v19, vcc, 0, v3, vcc
	global_load_dword v1, v[4:5], off
	global_load_dword v20, v[6:7], off
	global_load_dword v21, v[8:9], off
	global_load_dword v22, v[10:11], off
	global_load_dword v23, v[12:13], off
	global_load_dword v24, v[14:15], off
	global_load_dword v25, v[16:17], off
	global_load_dword v26, v[18:19], off
	v_add_co_u32_e32 v4, vcc, 0x1a710000, v2
	s_waitcnt vmcnt(0) lgkmcnt(0)
	v_add_f32_e32 v1, 0, v1
	v_addc_co_u32_e32 v5, vcc, 0, v3, vcc
	v_add_co_u32_e32 v6, vcc, 0x1a712000, v2
	v_add_f32_e32 v1, v1, v20
	s_nop 0
	v_addc_co_u32_e32 v7, vcc, 0, v3, vcc
	v_add_co_u32_e32 v8, vcc, 0x1a714000, v2
	v_add_f32_e32 v1, v1, v21
	s_nop 0
	v_addc_co_u32_e32 v9, vcc, 0, v3, vcc
	v_add_co_u32_e32 v10, vcc, 0x1a716000, v2
	v_add_f32_e32 v1, v1, v22
	s_nop 0
	v_addc_co_u32_e32 v11, vcc, 0, v3, vcc
	v_add_co_u32_e32 v12, vcc, 0x1a718000, v2
	v_add_f32_e32 v1, v1, v23
	s_nop 0
	v_addc_co_u32_e32 v13, vcc, 0, v3, vcc
	v_add_co_u32_e32 v14, vcc, 0x1a71a000, v2
	v_add_f32_e32 v1, v1, v24
	s_nop 0
	v_addc_co_u32_e32 v15, vcc, 0, v3, vcc
	v_add_co_u32_e32 v16, vcc, 0x1a71c000, v2
	v_add_f32_e32 v1, v1, v25
	s_nop 0
	v_addc_co_u32_e32 v17, vcc, 0, v3, vcc
	v_add_co_u32_e32 v18, vcc, 0x1a71e000, v2
	v_add_f32_e32 v1, v1, v26
	s_nop 0
	v_addc_co_u32_e32 v19, vcc, 0, v3, vcc
	global_load_dword v27, v[4:5], off
	global_load_dword v28, v[6:7], off
	global_load_dword v29, v[8:9], off
	global_load_dword v30, v[10:11], off
	global_load_dword v31, v[12:13], off
	global_load_dword v32, v[14:15], off
	global_load_dword v33, v[16:17], off
	global_load_dword v34, v[18:19], off
	v_add_co_u32_e32 v4, vcc, 0x1a720000, v2
	s_waitcnt vmcnt(0) lgkmcnt(0)
	v_add_f32_e32 v1, v1, v27
	v_addc_co_u32_e32 v5, vcc, 0, v3, vcc
	v_add_co_u32_e32 v6, vcc, 0x1a722000, v2
	v_add_f32_e32 v1, v1, v28
	s_nop 0
	v_addc_co_u32_e32 v7, vcc, 0, v3, vcc
	v_add_co_u32_e32 v8, vcc, 0x1a724000, v2
	v_add_f32_e32 v1, v1, v29
	s_nop 0
	v_addc_co_u32_e32 v9, vcc, 0, v3, vcc
	v_add_co_u32_e32 v10, vcc, 0x1a726000, v2
	v_add_f32_e32 v1, v1, v30
	s_nop 0
	v_addc_co_u32_e32 v11, vcc, 0, v3, vcc
	v_add_co_u32_e32 v12, vcc, 0x1a728000, v2
	v_add_f32_e32 v1, v1, v31
	s_nop 0
	v_addc_co_u32_e32 v13, vcc, 0, v3, vcc
	v_add_co_u32_e32 v14, vcc, 0x1a72a000, v2
	v_add_f32_e32 v1, v1, v32
	s_nop 0
	v_addc_co_u32_e32 v15, vcc, 0, v3, vcc
	v_add_co_u32_e32 v16, vcc, 0x1a72c000, v2
	v_add_f32_e32 v1, v1, v33
	s_nop 0
	v_addc_co_u32_e32 v17, vcc, 0, v3, vcc
	v_add_co_u32_e32 v18, vcc, 0x1a72e000, v2
	v_add_f32_e32 v1, v1, v34
	s_nop 0
	v_addc_co_u32_e32 v19, vcc, 0, v3, vcc
	global_load_dword v35, v[4:5], off
	global_load_dword v36, v[6:7], off
	global_load_dword v37, v[8:9], off
	global_load_dword v38, v[10:11], off
	global_load_dword v39, v[12:13], off
	global_load_dword v40, v[14:15], off
	global_load_dword v41, v[16:17], off
	global_load_dword v42, v[18:19], off
	v_add_co_u32_e32 v4, vcc, 0x1a730000, v2
	s_waitcnt vmcnt(0) lgkmcnt(0)
	v_add_f32_e32 v1, v1, v35
	v_addc_co_u32_e32 v5, vcc, 0, v3, vcc
	v_add_co_u32_e32 v6, vcc, 0x1a732000, v2
	v_add_f32_e32 v1, v1, v36
	s_nop 0
	v_addc_co_u32_e32 v7, vcc, 0, v3, vcc
	v_add_co_u32_e32 v8, vcc, 0x1a734000, v2
	v_add_f32_e32 v1, v1, v37
	s_nop 0
	v_addc_co_u32_e32 v9, vcc, 0, v3, vcc
	v_add_co_u32_e32 v10, vcc, 0x1a736000, v2
	v_add_f32_e32 v1, v1, v38
	s_nop 0
	v_addc_co_u32_e32 v11, vcc, 0, v3, vcc
	v_add_co_u32_e32 v12, vcc, 0x1a738000, v2
	v_add_f32_e32 v1, v1, v39
	s_nop 0
	v_addc_co_u32_e32 v13, vcc, 0, v3, vcc
	v_add_co_u32_e32 v14, vcc, 0x1a73a000, v2
	v_add_f32_e32 v1, v1, v40
	s_nop 0
	v_addc_co_u32_e32 v15, vcc, 0, v3, vcc
	v_add_co_u32_e32 v16, vcc, 0x1a73c000, v2
	v_add_f32_e32 v1, v1, v41
	s_nop 0
	v_addc_co_u32_e32 v17, vcc, 0, v3, vcc
	v_add_co_u32_e32 v18, vcc, 0x1a73e000, v2
	v_add_f32_e32 v1, v1, v42
	s_nop 0
	v_addc_co_u32_e32 v19, vcc, 0, v3, vcc
	global_load_dword v43, v[4:5], off
	global_load_dword v44, v[6:7], off
	global_load_dword v45, v[8:9], off
	global_load_dword v46, v[10:11], off
	global_load_dword v47, v[12:13], off
	global_load_dword v48, v[14:15], off
	global_load_dword v49, v[16:17], off
	global_load_dword v50, v[18:19], off
	v_add_co_u32_e32 v4, vcc, 0x1a740000, v2
	s_waitcnt vmcnt(0) lgkmcnt(0)
; __global__ void __launch_bounds__(512, 2) fwd_megakernel(Args a_) {
;     ...
;                 if (ph == 2) { const int gt = bid * 512 + tid; if (gt < 2048) { const float* PART = (const float*)(ws + WS_BPART); float sacc = 0.f;
; #pragma unroll
;                     for (int c = 0; c < 64; ++c) sacc += PART[c * 2048 + gt];
;                     ((float*)(ws + WS_BIAS1))[gt] = sacc; } }
	v_add_f32_e32 v1, v1, v43
	v_addc_co_u32_e32 v5, vcc, 0, v3, vcc
	v_add_co_u32_e32 v6, vcc, 0x1a742000, v2
	v_add_f32_e32 v1, v1, v44
	s_nop 0
	v_addc_co_u32_e32 v7, vcc, 0, v3, vcc
	v_add_co_u32_e32 v8, vcc, 0x1a744000, v2
	v_add_f32_e32 v1, v1, v45
	s_nop 0
	v_addc_co_u32_e32 v9, vcc, 0, v3, vcc
	v_add_co_u32_e32 v10, vcc, 0x1a746000, v2
	v_add_f32_e32 v1, v1, v46
	s_nop 0
	v_addc_co_u32_e32 v11, vcc, 0, v3, vcc
	v_add_co_u32_e32 v12, vcc, 0x1a748000, v2
	v_add_f32_e32 v1, v1, v47
	s_nop 0
	v_addc_co_u32_e32 v13, vcc, 0, v3, vcc
	v_add_co_u32_e32 v14, vcc, 0x1a74a000, v2
	v_add_f32_e32 v1, v1, v48
	s_nop 0
	v_addc_co_u32_e32 v15, vcc, 0, v3, vcc
	v_add_co_u32_e32 v16, vcc, 0x1a74c000, v2
	v_add_f32_e32 v1, v1, v49
	s_nop 0
	v_addc_co_u32_e32 v17, vcc, 0, v3, vcc
	v_add_co_u32_e32 v18, vcc, 0x1a74e000, v2
	v_add_f32_e32 v1, v1, v50
	s_nop 0
	v_addc_co_u32_e32 v19, vcc, 0, v3, vcc
	global_load_dword v51, v[4:5], off
	global_load_dword v52, v[6:7], off
	global_load_dword v53, v[8:9], off
	global_load_dword v54, v[10:11], off
	global_load_dword v55, v[12:13], off
	global_load_dword v56, v[14:15], off
	global_load_dword v57, v[16:17], off
	global_load_dword v58, v[18:19], off
	v_add_co_u32_e32 v4, vcc, 0x1a750000, v2
	s_waitcnt vmcnt(0) lgkmcnt(0)
	v_add_f32_e32 v1, v1, v51
	v_addc_co_u32_e32 v5, vcc, 0, v3, vcc
	v_add_co_u32_e32 v6, vcc, 0x1a752000, v2
	v_add_f32_e32 v1, v1, v52
	s_nop 0
	v_addc_co_u32_e32 v7, vcc, 0, v3, vcc
	v_add_co_u32_e32 v8, vcc, 0x1a754000, v2
	v_add_f32_e32 v1, v1, v53
	s_nop 0
	v_addc_co_u32_e32 v9, vcc, 0, v3, vcc
	v_add_co_u32_e32 v10, vcc, 0x1a756000, v2
	v_add_f32_e32 v1, v1, v54
	s_nop 0
	v_addc_co_u32_e32 v11, vcc, 0, v3, vcc
	v_add_co_u32_e32 v12, vcc, 0x1a758000, v2
	v_add_f32_e32 v1, v1, v55
	s_nop 0
	v_addc_co_u32_e32 v13, vcc, 0, v3, vcc
	v_add_co_u32_e32 v14, vcc, 0x1a75a000, v2
	v_add_f32_e32 v1, v1, v56
	s_nop 0
	v_addc_co_u32_e32 v15, vcc, 0, v3, vcc
	v_add_co_u32_e32 v16, vcc, 0x1a75c000, v2
	v_add_f32_e32 v1, v1, v57
	s_nop 0
	v_addc_co_u32_e32 v17, vcc, 0, v3, vcc
	v_add_co_u32_e32 v18, vcc, 0x1a75e000, v2
	v_add_f32_e32 v1, v1, v58
	s_nop 0
	v_addc_co_u32_e32 v19, vcc, 0, v3, vcc
	global_load_dword v59, v[4:5], off
	global_load_dword v60, v[6:7], off
	global_load_dword v61, v[8:9], off
	global_load_dword v62, v[10:11], off
	global_load_dword v63, v[12:13], off
	global_load_dword v64, v[14:15], off
	global_load_dword v65, v[16:17], off
	global_load_dword v66, v[18:19], off
	v_add_co_u32_e32 v4, vcc, 0x1a760000, v2
	s_waitcnt vmcnt(0) lgkmcnt(0)
	v_add_f32_e32 v1, v1, v59
	v_addc_co_u32_e32 v5, vcc, 0, v3, vcc
	v_add_co_u32_e32 v6, vcc, 0x1a762000, v2
	v_add_f32_e32 v1, v1, v60
	s_nop 0
	v_addc_co_u32_e32 v7, vcc, 0, v3, vcc
	v_add_co_u32_e32 v8, vcc, 0x1a764000, v2
	v_add_f32_e32 v1, v1, v61
	s_nop 0
	v_addc_co_u32_e32 v9, vcc, 0, v3, vcc
	v_add_co_u32_e32 v10, vcc, 0x1a766000, v2
	v_add_f32_e32 v1, v1, v62
	s_nop 0
	v_addc_co_u32_e32 v11, vcc, 0, v3, vcc
	v_add_co_u32_e32 v12, vcc, 0x1a768000, v2
	v_add_f32_e32 v1, v1, v63
	s_nop 0
	v_addc_co_u32_e32 v13, vcc, 0, v3, vcc
	v_add_co_u32_e32 v14, vcc, 0x1a76a000, v2
	v_add_f32_e32 v1, v1, v64
	s_nop 0
	v_addc_co_u32_e32 v15, vcc, 0, v3, vcc
	v_add_co_u32_e32 v16, vcc, 0x1a76c000, v2
	v_add_f32_e32 v1, v1, v65
	s_nop 0
	v_addc_co_u32_e32 v17, vcc, 0, v3, vcc
	v_add_co_u32_e32 v18, vcc, 0x1a76e000, v2
	v_add_f32_e32 v1, v1, v66
	s_nop 0
	v_addc_co_u32_e32 v19, vcc, 0, v3, vcc
	global_load_dword v67, v[4:5], off
	global_load_dword v68, v[6:7], off
	global_load_dword v69, v[8:9], off
	global_load_dword v70, v[10:11], off
	global_load_dword v71, v[12:13], off
	global_load_dword v72, v[14:15], off
	global_load_dword v73, v[16:17], off
	global_load_dword v74, v[18:19], off
	v_add_co_u32_e32 v4, vcc, 0x1a770000, v2
	s_waitcnt vmcnt(0) lgkmcnt(0)
	v_add_f32_e32 v1, v1, v67
	v_addc_co_u32_e32 v5, vcc, 0, v3, vcc
	v_add_co_u32_e32 v6, vcc, 0x1a772000, v2
	v_add_f32_e32 v1, v1, v68
	s_nop 0
	v_addc_co_u32_e32 v7, vcc, 0, v3, vcc
	v_add_co_u32_e32 v8, vcc, 0x1a774000, v2
	v_add_f32_e32 v1, v1, v69
	s_nop 0
	v_addc_co_u32_e32 v9, vcc, 0, v3, vcc
	v_add_co_u32_e32 v10, vcc, 0x1a776000, v2
	v_add_f32_e32 v1, v1, v70
	s_nop 0
	v_addc_co_u32_e32 v11, vcc, 0, v3, vcc
	v_add_co_u32_e32 v12, vcc, 0x1a778000, v2
	v_add_f32_e32 v1, v1, v71
	s_nop 0
	v_addc_co_u32_e32 v13, vcc, 0, v3, vcc
	v_add_co_u32_e32 v14, vcc, 0x1a77a000, v2
	v_add_f32_e32 v1, v1, v72
	s_nop 0
	v_addc_co_u32_e32 v15, vcc, 0, v3, vcc
	v_add_co_u32_e32 v16, vcc, 0x1a77c000, v2
	v_add_f32_e32 v1, v1, v73
	s_nop 0
	v_addc_co_u32_e32 v17, vcc, 0, v3, vcc
	v_add_co_u32_e32 v18, vcc, 0x1a77e000, v2
	v_add_f32_e32 v1, v1, v74
	s_nop 0
	v_addc_co_u32_e32 v19, vcc, 0, v3, vcc
	global_load_dword v4, v[4:5], off
	s_nop 0
	global_load_dword v5, v[6:7], off
	s_nop 0
	global_load_dword v6, v[8:9], off
	global_load_dword v7, v[10:11], off
	s_nop 0
	global_load_dword v8, v[12:13], off
	global_load_dword v9, v[14:15], off
	global_load_dword v10, v[16:17], off
	global_load_dword v11, v[18:19], off
	v_add_co_u32_e32 v2, vcc, 0xa900000, v2
	s_waitcnt vmcnt(0) lgkmcnt(0)
	v_add_f32_e32 v1, v1, v4
	v_add_f32_e32 v1, v1, v5
	v_add_f32_e32 v1, v1, v6
	v_add_f32_e32 v1, v1, v7
	v_add_f32_e32 v1, v1, v8
	v_add_f32_e32 v1, v1, v9
	v_add_f32_e32 v1, v1, v10
	v_add_f32_e32 v1, v1, v11
	v_addc_co_u32_e32 v3, vcc, 0, v3, vcc
	global_store_dword v[2:3], v1, off

; #define LAS __attribute__((address_space(3)))
; __device__ __forceinline__ float row_rscale(const float* SSP, int row) {
;     const f32x4 p = *(const f32x4*)(SSP + (size_t)row * 4);
;     return rsqrtf(((p[0] + p[1]) + (p[2] + p[3])) * (1.f / 1024.f) + 1e-6f);
; }
; __device__ __forceinline__ void row_scales8(const float* SSP, int row0, int key, LAS float* rsc  , LAS int* rtag  , int wv, int fr, int fq, float (&rsv)[2][4]) {
;     const int tag = __builtin_amdgcn_readfirstlane(rtag[wv]);
;     LAS float* tab = rsc + (wv * 16 + fr) * 8;
;     if (tag == key) {
;         const f32x4 a = *(const LAS f32x4*)tab, b = *(const LAS f32x4*)(tab + 4);
; #pragma unroll
;         for (int m = 0; m < 4; ++m) { rsv[0][m] = a[m]; rsv[1][m] = b[m]; }
;     } else {
; #pragma unroll
;         for (int ai = 0; ai < 2; ++ai)
; #pragma unroll
;             for (int m = 0; m < 4; ++m) rsv[ai][m] = row_rscale(SSP, row0 + ai * HALF + m * 16);
;         if (fq == 0) { *(LAS f32x4*)tab = (f32x4){rsv[0][0], rsv[0][1], rsv[0][2], rsv[0][3]}; *(LAS f32x4*)(tab + 4) = (f32x4){rsv[1][0], rsv[1][1], rsv[1][2], rsv[1][3]}; if (fr == 0) rtag[wv] = key; }
;     }
.LBB0_822:
	v_mov_b32_e32 v167, v164
	v_mov_b32_e32 v179, v1
	v_mov_b32_e32 v98, s48
	ds_read_b32 v98, v98
	s_lshl_b32 s9, s8, 8
	s_add_i32 s9, s9, s44
	v_add_u32_e32 v156, s9, v179
	s_add_i32 s15, s30, s8
	s_waitcnt lgkmcnt(0)
	v_readfirstlane_b32 s17, v98
	v_add_u32_e32 v160, 16, v156
	v_add_u32_e32 v158, 32, v156
	v_add_u32_e32 v152, 48, v156
	v_lshlrev_b32_e32 v155, 5, v179
	s_mov_b64 s[8:9], -1
	s_cmp_eq_u32 s17, s15
	v_ashrrev_i32_e32 v157, 31, v156
	v_ashrrev_i32_e32 v161, 31, v160
	v_ashrrev_i32_e32 v159, 31, v158
	v_ashrrev_i32_e32 v153, 31, v152
	v_add_u32_e32 v154, 0x80, v156
	s_cbranch_scc1 .LBB0_827
	v_lshl_add_u64 v[162:163], v[156:157], 4, s[10:11]
	v_lshl_add_u64 v[134:135], v[160:161], 4, s[10:11]
	global_load_dwordx4 v[98:101], v[162:163], off
	s_mov_b32 s8, 0x358637bd
	global_load_dwordx4 v[134:137], v[134:135], off
	s_waitcnt vmcnt(0) lgkmcnt(0)
	v_mov_b32_e32 v150, v98
	v_mov_b32_e32 v151, v134
	v_mov_b32_e32 v134, v99
	v_pk_add_f32 v[98:99], v[150:151], v[134:135]
	v_mov_b32_e32 v134, v100
	v_mov_b32_e32 v135, v136
	v_mov_b32_e32 v136, v101
	v_pk_add_f32 v[100:101], v[134:135], v[136:137]
	v_lshl_add_u64 v[150:151], v[152:153], 4, s[10:11]
	v_pk_add_f32 v[98:99], v[98:99], v[100:101]
	v_mov_b64_e32 v[100:101], s[8:9]
	v_pk_fma_f32 v[98:99], v[98:99], s[72:73], v[100:101] op_sel_hi:[1,0,0]
	s_nop 0
	v_mul_f32_e32 v134, 0x4b800000, v98
	v_cmp_gt_f32_e64 s[8:9], s67, v98
	v_cmp_gt_f32_e32 vcc, s67, v99
	s_nop 0
	v_cndmask_b32_e64 v98, v98, v134, s[8:9]
	v_mul_f32_e32 v134, 0x4b800000, v99
	v_cndmask_b32_e32 v99, v99, v134, vcc
	v_rsq_f32_e32 v98, v98
	v_rsq_f32_e32 v99, v99
	s_nop 0
	v_pk_mul_f32 v[134:135], v[98:99], s[76:77] op_sel_hi:[1,0]
	s_nop 0
	v_cndmask_b32_e32 v135, v99, v135, vcc
	v_cndmask_b32_e64 v134, v98, v134, s[8:9]
	v_lshl_add_u64 v[98:99], v[158:159], 4, s[10:11]
	global_load_dwordx4 v[180:183], v[98:99], off
	s_waitcnt vmcnt(0) lgkmcnt(0)
	v_add_f32_e32 v98, v180, v181
	v_add_f32_e32 v136, v182, v183
	global_load_dwordx4 v[180:183], v[150:151], off
	s_waitcnt vmcnt(0) lgkmcnt(0)
	v_mov_b32_e32 v150, v181
	v_mov_b32_e32 v151, v182
	v_mov_b32_e32 v181, v183
	v_pk_add_f32 v[150:151], v[150:151], v[180:181]
	s_nop 0
	v_mov_b32_e32 v99, v150
	v_mov_b32_e32 v137, v151
	v_pk_add_f32 v[98:99], v[98:99], v[136:137]
	v_add_u32_e32 v150, 0x80, v156
	v_pk_fma_f32 v[98:99], v[98:99], s[72:73], v[100:101] op_sel_hi:[1,0,0]
	v_ashrrev_i32_e32 v151, 31, v150
	v_mul_f32_e32 v136, 0x4b800000, v98
	v_cmp_gt_f32_e64 s[8:9], s67, v98
	v_cmp_gt_f32_e32 vcc, s67, v99
	s_nop 0
	v_cndmask_b32_e64 v98, v98, v136, s[8:9]
	v_mul_f32_e32 v136, 0x4b800000, v99
	v_cndmask_b32_e32 v99, v99, v136, vcc
	v_rsq_f32_e32 v98, v98
	v_rsq_f32_e32 v99, v99
	s_nop 0
	v_pk_mul_f32 v[136:137], v[98:99], s[76:77] op_sel_hi:[1,0]
	s_nop 0
	v_cndmask_b32_e32 v137, v99, v137, vcc
	v_cndmask_b32_e64 v136, v98, v136, s[8:9]
	v_lshl_add_u64 v[98:99], v[150:151], 4, s[10:11]
	global_load_dwordx4 v[180:183], v[98:99], off
	global_load_dwordx4 v[184:187], v[162:163], off offset:2304
	s_waitcnt vmcnt(0) lgkmcnt(0)
	v_mov_b32_e32 v98, v180
	v_mov_b32_e32 v99, v184
	v_mov_b32_e32 v184, v181
	v_mov_b32_e32 v180, v182
	v_mov_b32_e32 v181, v186
	v_mov_b32_e32 v186, v183
	v_pk_add_f32 v[98:99], v[98:99], v[184:185]
	v_pk_add_f32 v[180:181], v[180:181], v[186:187]
	s_nop 0
	v_pk_add_f32 v[98:99], v[98:99], v[180:181]
	s_nop 0
	v_pk_fma_f32 v[98:99], v[98:99], s[72:73], v[100:101] op_sel_hi:[1,0,0]
	s_nop 0
	v_mul_f32_e32 v180, 0x4b800000, v98
	v_cmp_gt_f32_e64 s[8:9], s67, v98
	v_cmp_gt_f32_e32 vcc, s67, v99
	s_nop 0
	v_cndmask_b32_e64 v98, v98, v180, s[8:9]
	v_mul_f32_e32 v180, 0x4b800000, v99
	v_cndmask_b32_e32 v99, v99, v180, vcc
	v_rsq_f32_e32 v98, v98
	v_rsq_f32_e32 v99, v99
	s_nop 0
	v_pk_mul_f32 v[180:181], v[98:99], s[76:77] op_sel_hi:[1,0]
	s_nop 0
	v_cndmask_b32_e32 v99, v99, v181, vcc
	v_cndmask_b32_e64 v98, v98, v180, s[8:9]
	global_load_dwordx4 v[180:183], v[162:163], off offset:2560
	s_waitcnt vmcnt(0) lgkmcnt(0)
	v_add_f32_e32 v184, v180, v181
	v_add_f32_e32 v186, v182, v183
	global_load_dwordx4 v[180:183], v[162:163], off offset:2816
	s_waitcnt vmcnt(0) lgkmcnt(0)
	v_mov_b32_e32 v162, v181
	v_mov_b32_e32 v163, v182
	v_mov_b32_e32 v181, v183
	v_pk_add_f32 v[162:163], v[162:163], v[180:181]
	s_nop 0
	v_mov_b32_e32 v185, v162
	v_mov_b32_e32 v187, v163
	v_pk_add_f32 v[162:163], v[184:185], v[186:187]
	s_nop 0
	v_pk_fma_f32 v[100:101], v[162:163], s[72:73], v[100:101] op_sel_hi:[1,0,0]
	s_nop 0
	v_mul_f32_e32 v162, 0x4b800000, v100
	v_cmp_gt_f32_e64 s[8:9], s67, v100
	v_cmp_gt_f32_e32 vcc, s67, v101
	s_nop 0
	v_cndmask_b32_e64 v100, v100, v162, s[8:9]
	v_mul_f32_e32 v162, 0x4b800000, v101
	v_cndmask_b32_e32 v101, v101, v162, vcc
	v_rsq_f32_e32 v100, v100
	v_rsq_f32_e32 v101, v101
	s_nop 0
	v_pk_mul_f32 v[162:163], v[100:101], s[76:77] op_sel_hi:[1,0]
	s_nop 0
	v_cndmask_b32_e32 v101, v101, v163, vcc
	v_cndmask_b32_e64 v100, v100, v162, s[8:9]
	v_cmp_eq_u32_e32 vcc, 0, v167
	s_and_saveexec_b64 s[8:9], vcc
	s_cbranch_execz .LBB0_826
	v_add_u32_e32 v162, s49, v155
	v_cmp_eq_u32_e32 vcc, 0, v179
	ds_write_b128 v162, v[134:137]
	ds_write_b128 v162, v[98:101] offset:16
	s_and_b64 exec, exec, vcc
	v_mov_b32_e32 v162, s48
	v_mov_b32_e32 v163, s15
	ds_write_b32 v162, v163

; __device__ __forceinline__ unsigned pk2(float lo, float hi) { f32x2_t v = {lo, hi}; bf16x2_t b = __builtin_convertvector(v, bf16x2_t); return __builtin_bit_cast(unsigned, b); }
; __device__ __forceinline__ f32x2 swiglu_pk(f32x2 g, f32x2 u, float c1, float rs2) {
;     const f32x2 t = g * c1; f32x2 e; e.x = __builtin_amdgcn_exp2f(t.x); e.y = __builtin_amdgcn_exp2f(t.y);
;     const f32x2 d = e + 1.0f; f32x2 sg; sg.x = __builtin_amdgcn_rcpf(d.x); sg.y = __builtin_amdgcn_rcpf(d.y);
;     return (g * u) * (sg * rs2);
; }
;     __device__ __forceinline__ void operator()(const f32x4 (&acc)[2][2][4][2], const Unit& u, int wr, int wc, int fr, int fq) const {
;         const int row0 = u.pm * BM + wr * 64 + fr, col0 = u.pn * 128 + wc * 32 + 8 * fq;
;         float rsv[2][4];
;         row_scales8(SSP, row0, key0 + u.pm, rsc, rtag, wr * 4 + wc, fr, fq, rsv);
; #pragma unroll
;         for (int ai = 0; ai < 2; ++ai) {
; #pragma unroll
;             for (int m = 0; m < 4; ++m) {
;                 const int row = row0 + ai * HALF + m * 16;
;                 const float rs = rsv[ai][m];
;                 bf16_t* rowp = U + (size_t)row * FF + col0;
;                 const float c1 = -rs * LOG2E, rs2 = rs * rs;
;                 const f32x4 g0 = acc[ai][0][m][0], g1 = acc[ai][0][m][1], u0 = acc[ai][1][m][0], u1 = acc[ai][1][m][1];
;                 const f32x2 o0 = swiglu_pk((f32x2){g0[0], g0[1]}, (f32x2){u0[0], u0[1]}, c1, rs2), o1 = swiglu_pk((f32x2){g0[2], g0[3]}, (f32x2){u0[2], u0[3]}, c1, rs2);
;                 const f32x2 o2 = swiglu_pk((f32x2){g1[0], g1[1]}, (f32x2){u1[0], u1[1]}, c1, rs2), o3 = swiglu_pk((f32x2){g1[2], g1[3]}, (f32x2){u1[2], u1[3]}, c1, rs2);
;                 u32x4 w; w.x = pk2(o0.x, o0.y); w.y = pk2(o1.x, o1.y); w.z = pk2(o2.x, o2.y); w.w = pk2(o3.x, o3.y);
;                 *(u32x4*)rowp = w;
;             }
.LBB0_829:
	s_lshl_b32 s8, s68, 7
	s_or_b32 s8, s8, s45
	v_mov_b64_e32 v[154:155], s[38:39]
	v_lshl_add_u32 v180, v167, 3, s8
	v_mad_u64_u32 v[182:183], s[8:9], v156, s57, v[154:155]
	v_mov_b32_e32 v156, v183
	v_ashrrev_i32_e32 v181, 31, v180
	v_mad_u64_u32 v[156:157], s[8:9], v157, s57, v[156:157]
	v_mov_b32_e32 v183, v156
	v_lshlrev_b64 v[156:157], 1, v[180:181]
	v_lshl_add_u64 v[180:181], v[182:183], 0, v[156:157]
	s_waitcnt lgkmcnt(0)
	v_mul_f32_e32 v182, 0xbfb8aa3b, v134
	v_pk_mul_f32 v[184:185], v[130:131], v[182:183] op_sel_hi:[1,0]
	v_mul_f32_e32 v134, v134, v134
	v_exp_f32_e32 v184, v184
	v_exp_f32_e32 v185, v185
	v_pk_mul_f32 v[126:127], v[130:131], v[126:127]
	v_pk_mul_f32 v[128:129], v[132:133], v[128:129]
	v_pk_mul_f32 v[124:125], v[120:121], v[124:125]
	v_pk_add_f32 v[184:185], v[184:185], 1.0 op_sel_hi:[1,0]
	v_pk_mul_f32 v[110:111], v[114:115], v[110:111]
	v_rcp_f32_e32 v184, v184
	v_rcp_f32_e32 v185, v185
	v_pk_mul_f32 v[112:113], v[116:117], v[112:113]
	v_pk_mul_f32 v[108:109], v[104:105], v[108:109]
	v_pk_mul_f32 v[90:91], v[94:95], v[90:91]
	v_pk_mul_f32 v[130:131], v[134:135], v[184:185] op_sel_hi:[0,1]
	v_pk_mul_f32 v[126:127], v[126:127], v[130:131]
	v_pk_mul_f32 v[130:131], v[132:133], v[182:183] op_sel_hi:[1,0]
	v_pk_mul_f32 v[92:93], v[96:97], v[92:93]
	v_exp_f32_e32 v130, v130
	v_exp_f32_e32 v131, v131
	v_pk_mul_f32 v[88:89], v[84:85], v[88:89]
	v_pk_mul_f32 v[74:75], v[78:79], v[74:75]
	v_pk_mul_f32 v[76:77], v[80:81], v[76:77]
	v_pk_add_f32 v[130:131], v[130:131], 1.0 op_sel_hi:[1,0]
	v_pk_mul_f32 v[72:73], v[68:69], v[72:73]
	v_rcp_f32_e32 v130, v130
	v_rcp_f32_e32 v131, v131
	v_pk_mul_f32 v[58:59], v[62:63], v[58:59]
	v_pk_mul_f32 v[60:61], v[64:65], v[60:61]
	v_pk_mul_f32 v[56:57], v[52:53], v[56:57]
	v_pk_mul_f32 v[130:131], v[134:135], v[130:131] op_sel_hi:[0,1]
	v_pk_mul_f32 v[128:129], v[128:129], v[130:131]
	v_pk_mul_f32 v[130:131], v[118:119], v[182:183] op_sel_hi:[1,0]
	v_pk_mul_f32 v[118:119], v[118:119], v[122:123]
	v_exp_f32_e32 v130, v130
	v_exp_f32_e32 v131, v131
	v_pk_mul_f32 v[42:43], v[46:47], v[42:43]
	v_pk_mul_f32 v[44:45], v[48:49], v[44:45]
	v_pk_mul_f32 v[40:41], v[36:37], v[40:41]
	v_pk_add_f32 v[130:131], v[130:131], 1.0 op_sel_hi:[1,0]
	v_pk_mul_f32 v[26:27], v[30:31], v[26:27]
	v_rcp_f32_e32 v130, v130
	v_rcp_f32_e32 v131, v131
	v_pk_mul_f32 v[28:29], v[32:33], v[28:29]
	v_pk_mul_f32 v[24:25], v[20:21], v[24:25]
	v_pk_mul_f32 v[10:11], v[14:15], v[10:11]
	v_pk_mul_f32 v[122:123], v[134:135], v[130:131] op_sel_hi:[0,1]
	v_pk_mul_f32 v[122:123], v[118:119], v[122:123]
	v_pk_mul_f32 v[118:119], v[120:121], v[182:183] op_sel_hi:[1,0]
	v_cvt_pk_bf16_f32 v120, v122, v123
	v_exp_f32_e32 v118, v118
	v_exp_f32_e32 v119, v119
	v_mul_f32_e32 v122, v135, v135
	v_pk_mul_f32 v[12:13], v[16:17], v[12:13]
	v_pk_mul_f32 v[2:3], v[6:7], v[2:3]
	v_pk_add_f32 v[118:119], v[118:119], 1.0 op_sel_hi:[1,0]
	v_pk_mul_f32 v[4:5], v[8:9], v[4:5]
	v_rcp_f32_e32 v118, v118
	v_rcp_f32_e32 v119, v119
	s_andn2_b64 vcc, exec, s[6:7]
	v_pk_mul_f32 v[118:119], v[134:135], v[118:119] op_sel_hi:[0,1]
	v_pk_mul_f32 v[124:125], v[124:125], v[118:119]
	v_cvt_pk_bf16_f32 v118, v126, v127
	v_cvt_pk_bf16_f32 v119, v128, v129
	v_cvt_pk_bf16_f32 v121, v124, v125
	global_store_dwordx4 v[180:181], v[118:121], off
	s_nop 1
	v_mad_u64_u32 v[118:119], s[8:9], v160, s57, v[154:155]
	v_mov_b32_e32 v120, v119
	v_mad_u64_u32 v[120:121], s[8:9], v161, s57, v[120:121]
	v_mov_b32_e32 v119, v120
	v_mul_f32_e32 v120, 0xbfb8aa3b, v135
	v_pk_mul_f32 v[124:125], v[114:115], v[120:121] op_sel_hi:[1,0]
	v_lshl_add_u64 v[118:119], v[118:119], 0, v[156:157]
	v_exp_f32_e32 v124, v124
	v_exp_f32_e32 v125, v125
	s_nop 0
	v_pk_add_f32 v[124:125], v[124:125], 1.0 op_sel_hi:[1,0]
	s_nop 0
	v_rcp_f32_e32 v124, v124
	v_rcp_f32_e32 v125, v125
	s_nop 0
	v_pk_mul_f32 v[114:115], v[122:123], v[124:125] op_sel_hi:[0,1]
	v_pk_mul_f32 v[110:111], v[110:111], v[114:115]
	v_pk_mul_f32 v[114:115], v[116:117], v[120:121] op_sel_hi:[1,0]
	s_nop 0
	v_exp_f32_e32 v114, v114
	v_exp_f32_e32 v115, v115
	s_nop 0
	v_pk_add_f32 v[114:115], v[114:115], 1.0 op_sel_hi:[1,0]
	s_nop 0
	v_rcp_f32_e32 v114, v114
	v_rcp_f32_e32 v115, v115
	s_nop 0
	v_pk_mul_f32 v[114:115], v[122:123], v[114:115] op_sel_hi:[0,1]
	v_pk_mul_f32 v[112:113], v[112:113], v[114:115]
	v_pk_mul_f32 v[114:115], v[102:103], v[120:121] op_sel_hi:[1,0]
	v_pk_mul_f32 v[102:103], v[102:103], v[106:107]
	v_exp_f32_e32 v114, v114
	v_exp_f32_e32 v115, v115
	s_nop 0
	v_pk_add_f32 v[114:115], v[114:115], 1.0 op_sel_hi:[1,0]
	s_nop 0
	v_rcp_f32_e32 v114, v114
	v_rcp_f32_e32 v115, v115
	s_nop 0
	v_pk_mul_f32 v[106:107], v[122:123], v[114:115] op_sel_hi:[0,1]
	v_pk_mul_f32 v[106:107], v[102:103], v[106:107]
	v_pk_mul_f32 v[102:103], v[104:105], v[120:121] op_sel_hi:[1,0]
	v_cvt_pk_bf16_f32 v104, v106, v107
	v_exp_f32_e32 v102, v102
	v_exp_f32_e32 v103, v103
	v_mul_f32_e32 v106, v136, v136
	v_pk_add_f32 v[102:103], v[102:103], 1.0 op_sel_hi:[1,0]
	s_nop 0
	v_rcp_f32_e32 v102, v102
	v_rcp_f32_e32 v103, v103
	s_nop 0
	v_pk_mul_f32 v[102:103], v[122:123], v[102:103] op_sel_hi:[0,1]
	v_pk_mul_f32 v[108:109], v[108:109], v[102:103]
	v_cvt_pk_bf16_f32 v102, v110, v111
	v_cvt_pk_bf16_f32 v103, v112, v113
	v_cvt_pk_bf16_f32 v105, v108, v109
	global_store_dwordx4 v[118:119], v[102:105], off
	s_nop 1
	v_mad_u64_u32 v[102:103], s[8:9], v158, s57, v[154:155]
	v_mov_b32_e32 v104, v103
	v_mad_u64_u32 v[104:105], s[8:9], v159, s57, v[104:105]
	v_mov_b32_e32 v103, v104
	v_mul_f32_e32 v104, 0xbfb8aa3b, v136
	v_pk_mul_f32 v[108:109], v[94:95], v[104:105] op_sel_hi:[1,0]
	v_lshl_add_u64 v[102:103], v[102:103], 0, v[156:157]
	v_exp_f32_e32 v108, v108
; __device__ __forceinline__ unsigned pk2(float lo, float hi) { f32x2_t v = {lo, hi}; bf16x2_t b = __builtin_convertvector(v, bf16x2_t); return __builtin_bit_cast(unsigned, b); }
; __device__ __forceinline__ f32x2 swiglu_pk(f32x2 g, f32x2 u, float c1, float rs2) {
;     const f32x2 t = g * c1; f32x2 e; e.x = __builtin_amdgcn_exp2f(t.x); e.y = __builtin_amdgcn_exp2f(t.y);
;     const f32x2 d = e + 1.0f; f32x2 sg; sg.x = __builtin_amdgcn_rcpf(d.x); sg.y = __builtin_amdgcn_rcpf(d.y);
;     return (g * u) * (sg * rs2);
; }
;     __device__ __forceinline__ void operator()(const f32x4 (&acc)[2][2][4][2], const Unit& u, int wr, int wc, int fr, int fq) const {
;         const int row0 = u.pm * BM + wr * 64 + fr, col0 = u.pn * 128 + wc * 32 + 8 * fq;
;         float rsv[2][4];
;         row_scales8(SSP, row0, key0 + u.pm, rsc, rtag, wr * 4 + wc, fr, fq, rsv);
; #pragma unroll
;         for (int ai = 0; ai < 2; ++ai) {
; #pragma unroll
;             for (int m = 0; m < 4; ++m) {
;                 const int row = row0 + ai * HALF + m * 16;
;                 const float rs = rsv[ai][m];
;                 bf16_t* rowp = U + (size_t)row * FF + col0;
;                 const float c1 = -rs * LOG2E, rs2 = rs * rs;
;                 const f32x4 g0 = acc[ai][0][m][0], g1 = acc[ai][0][m][1], u0 = acc[ai][1][m][0], u1 = acc[ai][1][m][1];
;                 const f32x2 o0 = swiglu_pk((f32x2){g0[0], g0[1]}, (f32x2){u0[0], u0[1]}, c1, rs2), o1 = swiglu_pk((f32x2){g0[2], g0[3]}, (f32x2){u0[2], u0[3]}, c1, rs2);
;                 const f32x2 o2 = swiglu_pk((f32x2){g1[0], g1[1]}, (f32x2){u1[0], u1[1]}, c1, rs2), o3 = swiglu_pk((f32x2){g1[2], g1[3]}, (f32x2){u1[2], u1[3]}, c1, rs2);
;                 u32x4 w; w.x = pk2(o0.x, o0.y); w.y = pk2(o1.x, o1.y); w.z = pk2(o2.x, o2.y); w.w = pk2(o3.x, o3.y);
;                 *(u32x4*)rowp = w;
;             }
	v_exp_f32_e32 v109, v109
	s_nop 0
	v_pk_add_f32 v[108:109], v[108:109], 1.0 op_sel_hi:[1,0]
	s_nop 0
	v_rcp_f32_e32 v108, v108
	v_rcp_f32_e32 v109, v109
	s_nop 0
	v_pk_mul_f32 v[94:95], v[106:107], v[108:109] op_sel_hi:[0,1]
	v_pk_mul_f32 v[90:91], v[90:91], v[94:95]
	v_pk_mul_f32 v[94:95], v[96:97], v[104:105] op_sel_hi:[1,0]
	s_nop 0
	v_exp_f32_e32 v94, v94
	v_exp_f32_e32 v95, v95
	s_nop 0
	v_pk_add_f32 v[94:95], v[94:95], 1.0 op_sel_hi:[1,0]
	s_nop 0
	v_rcp_f32_e32 v94, v94
	v_rcp_f32_e32 v95, v95
	s_nop 0
	v_pk_mul_f32 v[94:95], v[106:107], v[94:95] op_sel_hi:[0,1]
	v_pk_mul_f32 v[92:93], v[92:93], v[94:95]
	v_pk_mul_f32 v[94:95], v[82:83], v[104:105] op_sel_hi:[1,0]
	v_pk_mul_f32 v[82:83], v[82:83], v[86:87]
	v_exp_f32_e32 v94, v94
	v_exp_f32_e32 v95, v95
	s_nop 0
	v_pk_add_f32 v[94:95], v[94:95], 1.0 op_sel_hi:[1,0]
	s_nop 0
	v_rcp_f32_e32 v94, v94
	v_rcp_f32_e32 v95, v95
	s_nop 0
	v_pk_mul_f32 v[86:87], v[106:107], v[94:95] op_sel_hi:[0,1]
	v_pk_mul_f32 v[86:87], v[82:83], v[86:87]
	v_pk_mul_f32 v[82:83], v[84:85], v[104:105] op_sel_hi:[1,0]
	v_cvt_pk_bf16_f32 v84, v86, v87
	v_exp_f32_e32 v82, v82
	v_exp_f32_e32 v83, v83
	v_mul_f32_e32 v86, v137, v137
	v_pk_add_f32 v[82:83], v[82:83], 1.0 op_sel_hi:[1,0]
	s_nop 0
	v_rcp_f32_e32 v82, v82
	v_rcp_f32_e32 v83, v83
	s_nop 0
	v_pk_mul_f32 v[82:83], v[106:107], v[82:83] op_sel_hi:[0,1]
	v_pk_mul_f32 v[88:89], v[88:89], v[82:83]
	v_cvt_pk_bf16_f32 v82, v90, v91
	v_cvt_pk_bf16_f32 v83, v92, v93
	v_cvt_pk_bf16_f32 v85, v88, v89
	global_store_dwordx4 v[102:103], v[82:85], off
	s_nop 1
	v_mad_u64_u32 v[82:83], s[8:9], v152, s57, v[154:155]
	v_mov_b32_e32 v84, v83
	v_mad_u64_u32 v[84:85], s[8:9], v153, s57, v[84:85]
	v_mov_b32_e32 v83, v84
	v_mul_f32_e32 v84, 0xbfb8aa3b, v137
	v_pk_mul_f32 v[88:89], v[78:79], v[84:85] op_sel_hi:[1,0]
	v_lshl_add_u64 v[82:83], v[82:83], 0, v[156:157]
	v_exp_f32_e32 v88, v88
	v_exp_f32_e32 v89, v89
	s_nop 0
	v_pk_add_f32 v[88:89], v[88:89], 1.0 op_sel_hi:[1,0]
	s_nop 0
	v_rcp_f32_e32 v88, v88
	v_rcp_f32_e32 v89, v89
	s_nop 0
	v_pk_mul_f32 v[78:79], v[86:87], v[88:89] op_sel_hi:[0,1]
	v_pk_mul_f32 v[74:75], v[74:75], v[78:79]
	v_pk_mul_f32 v[78:79], v[80:81], v[84:85] op_sel_hi:[1,0]
	s_nop 0
	v_exp_f32_e32 v78, v78
	v_exp_f32_e32 v79, v79
	s_nop 0
	v_pk_add_f32 v[78:79], v[78:79], 1.0 op_sel_hi:[1,0]
	s_nop 0
	v_rcp_f32_e32 v78, v78
	v_rcp_f32_e32 v79, v79
	s_nop 0
	v_pk_mul_f32 v[78:79], v[86:87], v[78:79] op_sel_hi:[0,1]
	v_pk_mul_f32 v[76:77], v[76:77], v[78:79]
	v_pk_mul_f32 v[78:79], v[66:67], v[84:85] op_sel_hi:[1,0]
	v_pk_mul_f32 v[66:67], v[66:67], v[70:71]
	v_exp_f32_e32 v78, v78
	v_exp_f32_e32 v79, v79
	s_nop 0
	v_pk_add_f32 v[78:79], v[78:79], 1.0 op_sel_hi:[1,0]
	s_nop 0
	v_rcp_f32_e32 v78, v78
	v_rcp_f32_e32 v79, v79
	s_nop 0
	v_pk_mul_f32 v[70:71], v[86:87], v[78:79] op_sel_hi:[0,1]
	v_pk_mul_f32 v[70:71], v[66:67], v[70:71]
	v_pk_mul_f32 v[66:67], v[68:69], v[84:85] op_sel_hi:[1,0]
	v_cvt_pk_bf16_f32 v68, v70, v71
	v_exp_f32_e32 v66, v66
	v_exp_f32_e32 v67, v67
	v_mul_f32_e32 v70, v98, v98
	v_pk_add_f32 v[66:67], v[66:67], 1.0 op_sel_hi:[1,0]
	s_nop 0
	v_rcp_f32_e32 v66, v66
	v_rcp_f32_e32 v67, v67
	s_nop 0
	v_pk_mul_f32 v[66:67], v[86:87], v[66:67] op_sel_hi:[0,1]
	v_pk_mul_f32 v[72:73], v[72:73], v[66:67]
	v_cvt_pk_bf16_f32 v66, v74, v75
	v_cvt_pk_bf16_f32 v67, v76, v77
	v_cvt_pk_bf16_f32 v69, v72, v73
	global_store_dwordx4 v[82:83], v[66:69], off
	s_nop 1
	v_mad_u64_u32 v[66:67], s[8:9], v162, s57, v[154:155]
	v_mov_b32_e32 v68, v67
	v_mad_u64_u32 v[68:69], s[8:9], v163, s57, v[68:69]
	v_mov_b32_e32 v67, v68
	v_mul_f32_e32 v68, 0xbfb8aa3b, v98
	v_pk_mul_f32 v[72:73], v[62:63], v[68:69] op_sel_hi:[1,0]
	v_lshl_add_u64 v[66:67], v[66:67], 0, v[156:157]
	v_exp_f32_e32 v72, v72
	v_exp_f32_e32 v73, v73
	s_nop 0
	v_pk_add_f32 v[72:73], v[72:73], 1.0 op_sel_hi:[1,0]
	s_nop 0
	v_rcp_f32_e32 v72, v72
	v_rcp_f32_e32 v73, v73
	s_nop 0
	v_pk_mul_f32 v[62:63], v[70:71], v[72:73] op_sel_hi:[0,1]
	v_pk_mul_f32 v[58:59], v[58:59], v[62:63]
	v_pk_mul_f32 v[62:63], v[64:65], v[68:69] op_sel_hi:[1,0]
	s_nop 0
	v_exp_f32_e32 v62, v62
	v_exp_f32_e32 v63, v63
	s_nop 0
	v_pk_add_f32 v[62:63], v[62:63], 1.0 op_sel_hi:[1,0]
	s_nop 0
	v_rcp_f32_e32 v62, v62
	v_rcp_f32_e32 v63, v63
	s_nop 0
	v_pk_mul_f32 v[62:63], v[70:71], v[62:63] op_sel_hi:[0,1]
	v_pk_mul_f32 v[60:61], v[60:61], v[62:63]
	v_pk_mul_f32 v[62:63], v[50:51], v[68:69] op_sel_hi:[1,0]
	v_pk_mul_f32 v[50:51], v[50:51], v[54:55]
	v_exp_f32_e32 v62, v62
	v_exp_f32_e32 v63, v63
	s_nop 0
	v_pk_add_f32 v[62:63], v[62:63], 1.0 op_sel_hi:[1,0]
	s_nop 0
	v_rcp_f32_e32 v62, v62
	v_rcp_f32_e32 v63, v63
	s_nop 0
	v_pk_mul_f32 v[54:55], v[70:71], v[62:63] op_sel_hi:[0,1]
	v_pk_mul_f32 v[54:55], v[50:51], v[54:55]
	v_pk_mul_f32 v[50:51], v[52:53], v[68:69] op_sel_hi:[1,0]
	v_cvt_pk_bf16_f32 v52, v54, v55
	v_exp_f32_e32 v50, v50
	v_exp_f32_e32 v51, v51
	v_mul_f32_e32 v54, v99, v99
	v_pk_add_f32 v[50:51], v[50:51], 1.0 op_sel_hi:[1,0]
	s_nop 0
	v_rcp_f32_e32 v50, v50
	v_rcp_f32_e32 v51, v51
	s_nop 0
	v_pk_mul_f32 v[50:51], v[70:71], v[50:51] op_sel_hi:[0,1]
	v_pk_mul_f32 v[56:57], v[56:57], v[50:51]
	v_cvt_pk_bf16_f32 v50, v58, v59
	v_cvt_pk_bf16_f32 v51, v60, v61
	v_cvt_pk_bf16_f32 v53, v56, v57
	global_store_dwordx4 v[66:67], v[50:53], off
	s_nop 1
	v_mul_f32_e32 v52, 0xbfb8aa3b, v99
; __device__ __forceinline__ unsigned pk2(float lo, float hi) { f32x2_t v = {lo, hi}; bf16x2_t b = __builtin_convertvector(v, bf16x2_t); return __builtin_bit_cast(unsigned, b); }
; __device__ __forceinline__ f32x2 swiglu_pk(f32x2 g, f32x2 u, float c1, float rs2) {
;     const f32x2 t = g * c1; f32x2 e; e.x = __builtin_amdgcn_exp2f(t.x); e.y = __builtin_amdgcn_exp2f(t.y);
;     const f32x2 d = e + 1.0f; f32x2 sg; sg.x = __builtin_amdgcn_rcpf(d.x); sg.y = __builtin_amdgcn_rcpf(d.y);
;     return (g * u) * (sg * rs2);
; }
;     __device__ __forceinline__ void operator()(const f32x4 (&acc)[2][2][4][2], const Unit& u, int wr, int wc, int fr, int fq) const {
;         const int row0 = u.pm * BM + wr * 64 + fr, col0 = u.pn * 128 + wc * 32 + 8 * fq;
;         float rsv[2][4];
;         row_scales8(SSP, row0, key0 + u.pm, rsc, rtag, wr * 4 + wc, fr, fq, rsv);
; #pragma unroll
;         for (int ai = 0; ai < 2; ++ai) {
; #pragma unroll
;             for (int m = 0; m < 4; ++m) {
;                 const int row = row0 + ai * HALF + m * 16;
;                 const float rs = rsv[ai][m];
;                 bf16_t* rowp = U + (size_t)row * FF + col0;
;                 const float c1 = -rs * LOG2E, rs2 = rs * rs;
;                 const f32x4 g0 = acc[ai][0][m][0], g1 = acc[ai][0][m][1], u0 = acc[ai][1][m][0], u1 = acc[ai][1][m][1];
;                 const f32x2 o0 = swiglu_pk((f32x2){g0[0], g0[1]}, (f32x2){u0[0], u0[1]}, c1, rs2), o1 = swiglu_pk((f32x2){g0[2], g0[3]}, (f32x2){u0[2], u0[3]}, c1, rs2);
;                 const f32x2 o2 = swiglu_pk((f32x2){g1[0], g1[1]}, (f32x2){u1[0], u1[1]}, c1, rs2), o3 = swiglu_pk((f32x2){g1[2], g1[3]}, (f32x2){u1[2], u1[3]}, c1, rs2);
;                 u32x4 w; w.x = pk2(o0.x, o0.y); w.y = pk2(o1.x, o1.y); w.z = pk2(o2.x, o2.y); w.w = pk2(o3.x, o3.y);
;                 *(u32x4*)rowp = w;
;             }
	v_pk_mul_f32 v[56:57], v[46:47], v[52:53] op_sel_hi:[1,0]
	v_add_u32_e32 v50, 16, v150
	v_exp_f32_e32 v56, v56
	v_exp_f32_e32 v57, v57
	v_mad_i64_i32 v[50:51], s[8:9], v50, s57, v[154:155]
	v_lshl_add_u64 v[50:51], v[50:51], 0, v[156:157]
	v_pk_add_f32 v[56:57], v[56:57], 1.0 op_sel_hi:[1,0]
	s_nop 0
	v_rcp_f32_e32 v56, v56
	v_rcp_f32_e32 v57, v57
	s_nop 0
	v_pk_mul_f32 v[46:47], v[54:55], v[56:57] op_sel_hi:[0,1]
	v_pk_mul_f32 v[42:43], v[42:43], v[46:47]
	v_pk_mul_f32 v[46:47], v[48:49], v[52:53] op_sel_hi:[1,0]
	s_nop 0
	v_exp_f32_e32 v46, v46
	v_exp_f32_e32 v47, v47
	s_nop 0
	v_pk_add_f32 v[46:47], v[46:47], 1.0 op_sel_hi:[1,0]
	s_nop 0
	v_rcp_f32_e32 v46, v46
	v_rcp_f32_e32 v47, v47
	s_nop 0
	v_pk_mul_f32 v[46:47], v[54:55], v[46:47] op_sel_hi:[0,1]
	v_pk_mul_f32 v[44:45], v[44:45], v[46:47]
	v_pk_mul_f32 v[46:47], v[34:35], v[52:53] op_sel_hi:[1,0]
	v_pk_mul_f32 v[34:35], v[34:35], v[38:39]
	v_exp_f32_e32 v46, v46
	v_exp_f32_e32 v47, v47
	s_nop 0
	v_pk_add_f32 v[46:47], v[46:47], 1.0 op_sel_hi:[1,0]
	s_nop 0
	v_rcp_f32_e32 v46, v46
	v_rcp_f32_e32 v47, v47
	s_nop 0
	v_pk_mul_f32 v[38:39], v[54:55], v[46:47] op_sel_hi:[0,1]
	v_pk_mul_f32 v[38:39], v[34:35], v[38:39]
	v_pk_mul_f32 v[34:35], v[36:37], v[52:53] op_sel_hi:[1,0]
	v_cvt_pk_bf16_f32 v36, v38, v39
	v_exp_f32_e32 v34, v34
	v_exp_f32_e32 v35, v35
	v_mul_f32_e32 v38, v100, v100
	v_pk_add_f32 v[34:35], v[34:35], 1.0 op_sel_hi:[1,0]
	s_nop 0
	v_rcp_f32_e32 v34, v34
	v_rcp_f32_e32 v35, v35
	s_nop 0
	v_pk_mul_f32 v[34:35], v[54:55], v[34:35] op_sel_hi:[0,1]
	v_pk_mul_f32 v[40:41], v[40:41], v[34:35]
	v_cvt_pk_bf16_f32 v34, v42, v43
	v_cvt_pk_bf16_f32 v35, v44, v45
	v_cvt_pk_bf16_f32 v37, v40, v41
	global_store_dwordx4 v[50:51], v[34:37], off
	s_nop 1
	v_mul_f32_e32 v36, 0xbfb8aa3b, v100
	v_pk_mul_f32 v[40:41], v[30:31], v[36:37] op_sel_hi:[1,0]
	v_add_u32_e32 v34, 32, v150
	v_exp_f32_e32 v40, v40
	v_exp_f32_e32 v41, v41
	v_mad_i64_i32 v[34:35], s[8:9], v34, s57, v[154:155]
	v_lshl_add_u64 v[34:35], v[34:35], 0, v[156:157]
	v_pk_add_f32 v[40:41], v[40:41], 1.0 op_sel_hi:[1,0]
	s_nop 0
	v_rcp_f32_e32 v40, v40
	v_rcp_f32_e32 v41, v41
	s_nop 0
	v_pk_mul_f32 v[30:31], v[38:39], v[40:41] op_sel_hi:[0,1]
	v_pk_mul_f32 v[26:27], v[26:27], v[30:31]
	v_pk_mul_f32 v[30:31], v[32:33], v[36:37] op_sel_hi:[1,0]
	s_nop 0
	v_exp_f32_e32 v30, v30
	v_exp_f32_e32 v31, v31
	s_nop 0
	v_pk_add_f32 v[30:31], v[30:31], 1.0 op_sel_hi:[1,0]
	s_nop 0
	v_rcp_f32_e32 v30, v30
	v_rcp_f32_e32 v31, v31
	s_nop 0
	v_pk_mul_f32 v[30:31], v[38:39], v[30:31] op_sel_hi:[0,1]
	v_pk_mul_f32 v[28:29], v[28:29], v[30:31]
	v_pk_mul_f32 v[30:31], v[18:19], v[36:37] op_sel_hi:[1,0]
	v_pk_mul_f32 v[18:19], v[18:19], v[22:23]
	v_exp_f32_e32 v30, v30
	v_exp_f32_e32 v31, v31
	s_nop 0
	v_pk_add_f32 v[30:31], v[30:31], 1.0 op_sel_hi:[1,0]
	s_nop 0
	v_rcp_f32_e32 v30, v30
	v_rcp_f32_e32 v31, v31
	s_nop 0
	v_pk_mul_f32 v[22:23], v[38:39], v[30:31] op_sel_hi:[0,1]
	v_pk_mul_f32 v[22:23], v[18:19], v[22:23]
	v_pk_mul_f32 v[18:19], v[20:21], v[36:37] op_sel_hi:[1,0]
	v_cvt_pk_bf16_f32 v20, v22, v23
	v_exp_f32_e32 v18, v18
	v_exp_f32_e32 v19, v19
	v_mul_f32_e32 v22, v101, v101
	v_pk_add_f32 v[18:19], v[18:19], 1.0 op_sel_hi:[1,0]
	s_nop 0
	v_rcp_f32_e32 v18, v18
	v_rcp_f32_e32 v19, v19
	s_nop 0
	v_pk_mul_f32 v[18:19], v[38:39], v[18:19] op_sel_hi:[0,1]
	v_pk_mul_f32 v[24:25], v[24:25], v[18:19]
	v_cvt_pk_bf16_f32 v18, v26, v27
	v_cvt_pk_bf16_f32 v19, v28, v29
	v_cvt_pk_bf16_f32 v21, v24, v25
	global_store_dwordx4 v[34:35], v[18:21], off
	s_nop 1
	v_mul_f32_e32 v20, 0xbfb8aa3b, v101
	v_pk_mul_f32 v[24:25], v[14:15], v[20:21] op_sel_hi:[1,0]
	v_add_u32_e32 v18, 48, v150
	v_exp_f32_e32 v24, v24
	v_exp_f32_e32 v25, v25
	v_mad_i64_i32 v[18:19], s[8:9], v18, s57, v[154:155]
	v_lshl_add_u64 v[18:19], v[18:19], 0, v[156:157]
	v_pk_add_f32 v[24:25], v[24:25], 1.0 op_sel_hi:[1,0]
	s_mov_b64 s[8:9], -1
	v_rcp_f32_e32 v24, v24
	v_rcp_f32_e32 v25, v25
	s_nop 0
	v_pk_mul_f32 v[14:15], v[22:23], v[24:25] op_sel_hi:[0,1]
	v_pk_mul_f32 v[10:11], v[10:11], v[14:15]
	v_pk_mul_f32 v[14:15], v[16:17], v[20:21] op_sel_hi:[1,0]
	s_nop 0
	v_exp_f32_e32 v14, v14
	v_exp_f32_e32 v15, v15
	s_nop 0
	v_pk_add_f32 v[14:15], v[14:15], 1.0 op_sel_hi:[1,0]
	s_nop 0
	v_rcp_f32_e32 v14, v14
	v_rcp_f32_e32 v15, v15
	s_nop 0
	v_pk_mul_f32 v[14:15], v[22:23], v[14:15] op_sel_hi:[0,1]
	v_pk_mul_f32 v[12:13], v[12:13], v[14:15]
	v_pk_mul_f32 v[14:15], v[6:7], v[20:21] op_sel_hi:[1,0]
	s_nop 0
	v_exp_f32_e32 v14, v14
	v_exp_f32_e32 v15, v15
	s_nop 0
	v_pk_add_f32 v[14:15], v[14:15], 1.0 op_sel_hi:[1,0]
	s_nop 0
	v_rcp_f32_e32 v14, v14
	v_rcp_f32_e32 v15, v15
	s_nop 0
	v_pk_mul_f32 v[6:7], v[22:23], v[14:15] op_sel_hi:[0,1]
	v_pk_mul_f32 v[6:7], v[2:3], v[6:7]
	v_pk_mul_f32 v[2:3], v[8:9], v[20:21] op_sel_hi:[1,0]
	s_nop 0
	v_exp_f32_e32 v2, v2
	v_exp_f32_e32 v3, v3
	s_nop 0
	v_pk_add_f32 v[2:3], v[2:3], 1.0 op_sel_hi:[1,0]
	s_nop 0
	v_rcp_f32_e32 v2, v2
	v_rcp_f32_e32 v3, v3
	s_nop 0
	v_pk_mul_f32 v[2:3], v[22:23], v[2:3] op_sel_hi:[0,1]
	v_pk_mul_f32 v[8:9], v[4:5], v[2:3]
	v_cvt_pk_bf16_f32 v2, v10, v11
	v_cvt_pk_bf16_f32 v3, v12, v13
	v_cvt_pk_bf16_f32 v4, v6, v7
	v_cvt_pk_bf16_f32 v5, v8, v9
	global_store_dwordx4 v[18:19], v[2:5], off
	s_cbranch_vccnz .LBB0_815
	s_andn2_b64 vcc, exec, s[4:5]
	s_cbranch_vccnz .LBB0_814
	s_barrier
	s_branch .LBB0_814

; __device__ __forceinline__ float row_rscale(const float* SSP, int row) {
;     const f32x4 p = *(const f32x4*)(SSP + (size_t)row * 4);
;     return rsqrtf(((p[0] + p[1]) + (p[2] + p[3])) * (1.f / 1024.f) + 1e-6f);
; }
; __device__ __forceinline__ void final_norm_phase(const bf16_t* XB, float* OUT, const float* gvec, const float* SSP, const int tid, const int bid) {
;     ...
;     for (int m0 = gw; m0 < T; m0 += 4 * NGW) {
;         u32x2 w[4][4]; float r[4];
; #pragma unroll
;         for (int e = 0; e < 4; ++e) { const int m = m0 + e * NGW;
;             if (m < T) { const bf16_t* xr = XB + (size_t)m * D + 4 * lane;
; #pragma unroll
;                 for (int j = 0; j < 4; ++j) w[e][j] = __builtin_nontemporal_load((const u32x2*)(xr + 256 * j));
;                 r[e] = pg8::row_rscale(SSP, m); } }
.LBB0_838:
	v_ashrrev_i32_e32 v55, 31, v54
	v_lshl_add_u64 v[50:51], v[54:55], 4, s[12:13]
	global_load_dwordx4 v[50:53], v[50:51], off
	v_lshlrev_b64 v[56:57], 11, v[54:55]
	v_lshl_add_u64 v[56:57], v[18:19], 0, v[56:57]
	global_load_dwordx2 v[64:65], v[56:57], off nt
	global_load_dwordx2 v[62:63], v[56:57], off offset:512 nt
	global_load_dwordx2 v[60:61], v[56:57], off offset:1024 nt
	global_load_dwordx2 v[58:59], v[56:57], off offset:1536 nt
	s_waitcnt vmcnt(0) lgkmcnt(0)
	v_mov_b32_e32 v56, v51
	v_mov_b32_e32 v57, v52
	v_mov_b32_e32 v51, v53
	v_pk_add_f32 v[50:51], v[56:57], v[50:51]
	s_nop 0
	v_add_f32_e32 v1, v50, v51
	v_fmamk_f32 v1, v1, 0x3a800000, v239
	v_mul_f32_e32 v22, 0x4b800000, v1
	v_cmp_gt_f32_e32 vcc, s67, v1
	v_add_u32_e32 v50, s73, v54
	v_cmp_gt_i32_e64 s[8:9], s61, v50
	v_cndmask_b32_e32 v1, v1, v22, vcc
	v_rsq_f32_e32 v1, v1
	v_ashrrev_i32_e32 v51, 31, v50
	v_mul_f32_e32 v22, 0x45800000, v1
	v_cndmask_b32_e32 v22, v1, v22, vcc
	s_and_saveexec_b64 s[6:7], s[8:9]
	s_cbranch_execz .LBB0_840
	v_lshl_add_u64 v[42:43], v[50:51], 4, s[12:13]
	global_load_dwordx4 v[66:69], v[42:43], off
	v_lshlrev_b64 v[42:43], 11, v[50:51]
	v_lshl_add_u64 v[42:43], v[18:19], 0, v[42:43]
	global_load_dwordx2 v[48:49], v[42:43], off nt
	global_load_dwordx2 v[46:47], v[42:43], off offset:512 nt
	global_load_dwordx2 v[44:45], v[42:43], off offset:1024 nt
	s_nop 0
	global_load_dwordx2 v[42:43], v[42:43], off offset:1536 nt
	s_waitcnt vmcnt(0) lgkmcnt(0)
	v_mov_b32_e32 v52, v67
	v_mov_b32_e32 v53, v68
	v_mov_b32_e32 v67, v69
	v_pk_add_f32 v[52:53], v[52:53], v[66:67]
	s_nop 0
	v_add_f32_e32 v1, v52, v53
	v_fmamk_f32 v1, v1, 0x3a800000, v239
	v_mul_f32_e32 v23, 0x4b800000, v1
	v_cmp_gt_f32_e32 vcc, s67, v1
	s_nop 1
	v_cndmask_b32_e32 v1, v1, v23, vcc
	v_rsq_f32_e32 v1, v1
	s_nop 0
	v_mul_f32_e32 v23, 0x45800000, v1
	v_cndmask_b32_e32 v23, v1, v23, vcc
.LBB0_840:
	s_or_b64 exec, exec, s[6:7]
	v_add_u32_e32 v56, s75, v54
	v_cmp_gt_i32_e64 s[6:7], s61, v56
	v_ashrrev_i32_e32 v57, 31, v56
	s_and_saveexec_b64 s[10:11], s[6:7]
	s_cbranch_execz .LBB0_842
	v_lshl_add_u64 v[34:35], v[56:57], 4, s[12:13]
	global_load_dwordx4 v[66:69], v[34:35], off
	v_lshlrev_b64 v[34:35], 11, v[56:57]
	v_lshl_add_u64 v[34:35], v[18:19], 0, v[34:35]
	global_load_dwordx2 v[40:41], v[34:35], off nt
	global_load_dwordx2 v[38:39], v[34:35], off offset:512 nt
	global_load_dwordx2 v[36:37], v[34:35], off offset:1024 nt
	s_nop 0
	global_load_dwordx2 v[34:35], v[34:35], off offset:1536 nt
	s_waitcnt vmcnt(0) lgkmcnt(0)
	v_mov_b32_e32 v52, v67
	v_mov_b32_e32 v53, v68
	v_mov_b32_e32 v67, v69
	v_pk_add_f32 v[52:53], v[52:53], v[66:67]
	s_nop 0
	v_add_f32_e32 v1, v52, v53
	v_fmamk_f32 v1, v1, 0x3a800000, v239
	v_mul_f32_e32 v24, 0x4b800000, v1
	v_cmp_gt_f32_e32 vcc, s67, v1
	s_nop 1
	v_cndmask_b32_e32 v1, v1, v24, vcc
	v_rsq_f32_e32 v1, v1
	s_nop 0
	v_mul_f32_e32 v24, 0x45800000, v1
	v_cndmask_b32_e32 v24, v1, v24, vcc
.LBB0_842:
	s_or_b64 exec, exec, s[10:11]
	v_add_u32_e32 v52, s50, v54
	v_cmp_gt_i32_e32 vcc, s61, v52
	v_ashrrev_i32_e32 v53, 31, v52
	s_and_saveexec_b64 s[16:17], vcc
	s_cbranch_execz .LBB0_844
	v_lshl_add_u64 v[26:27], v[52:53], 4, s[12:13]
	global_load_dwordx4 v[66:69], v[26:27], off
	v_lshlrev_b64 v[26:27], 11, v[52:53]
	v_lshl_add_u64 v[26:27], v[18:19], 0, v[26:27]
	global_load_dwordx2 v[32:33], v[26:27], off nt
	global_load_dwordx2 v[30:31], v[26:27], off offset:512 nt
	global_load_dwordx2 v[28:29], v[26:27], off offset:1024 nt
	s_nop 0
	global_load_dwordx2 v[26:27], v[26:27], off offset:1536 nt
	s_waitcnt vmcnt(0) lgkmcnt(0)
	v_mov_b32_e32 v70, v67
	v_mov_b32_e32 v71, v68
	v_mov_b32_e32 v67, v69
	v_pk_add_f32 v[66:67], v[70:71], v[66:67]
	s_nop 0
	v_add_f32_e32 v1, v66, v67
	v_fmamk_f32 v1, v1, 0x3a800000, v239
	v_mul_f32_e32 v25, 0x4b800000, v1
	v_cmp_gt_f32_e64 s[10:11], s67, v1
	s_nop 1
	v_cndmask_b32_e64 v1, v1, v25, s[10:11]
	v_rsq_f32_e32 v1, v1
	s_nop 0
	v_mul_f32_e32 v25, 0x45800000, v1
	v_cndmask_b32_e64 v25, v1, v25, s[10:11]

; __device__ __forceinline__ unsigned xb_ld(unsigned* p)              { return __hip_atomic_load(p, __ATOMIC_RELAXED, __HIP_MEMORY_SCOPE_AGENT); }
; __device__ __forceinline__ void xcd_barrier_complete(unsigned* bar, unsigned x, unsigned& nloc, unsigned& nx) {
;     const unsigned G = gridDim.x * gridDim.y * gridDim.z;
;     unsigned sum, cnt, mine, sp = 0u;
;     for (;;) {
;         sum = 0u; cnt = 0u; mine = 0u;
; #pragma unroll
;         for (unsigned j = 0; j < 16; ++j) { const unsigned c = xb_ld(&bar[XB_XCNT(j)]); sum += c; cnt += (c > 0u) ? 1u : 0u; mine = (j == x) ? c : mine; }
;         if (sum == G) break;
;         __builtin_amdgcn_s_sleep(1);
;         if ((++sp & 255u) == 0u) { if (xb_ld(&bar[XB_TMO])) break; if (sp > XB_SPIN_CAP) { atomicAdd(&bar[XB_TMO], 1u); break; } }
;     }
;     nloc = mine > 0u ? mine : 1u; nx = cnt > 0u ? cnt : 1u;
; }
.LBB0_869:
	s_waitcnt lgkmcnt(0)
	v_mov_b64_e32 v[2:3], s[8:9]
	global_load_dword v1, v[2:3], off sc1
	v_mov_b64_e32 v[2:3], s[10:11]
	global_load_dword v2, v[2:3], off sc1
	v_mov_b64_e32 v[4:5], s[12:13]
	global_load_dword v3, v[4:5], off sc1
	v_mov_b64_e32 v[4:5], s[14:15]
	global_load_dword v4, v[4:5], off sc1
	s_or_b64 s[84:85], s[84:85], exec
	s_or_b64 s[82:83], s[82:83], exec
	s_waitcnt vmcnt(0) lgkmcnt(0)
	v_add_u32_e32 v6, v2, v1
	v_add_u32_e32 v6, v6, v3
	v_add_u32_e32 v8, v6, v4
	v_mov_b64_e32 v[6:7], s[16:17]
	global_load_dword v5, v[6:7], off sc1
	v_mov_b64_e32 v[6:7], s[18:19]
	global_load_dword v6, v[6:7], off sc1
	s_waitcnt vmcnt(0) lgkmcnt(0)
	v_add_u32_e32 v8, v8, v5
	v_add_u32_e32 v10, v8, v6
	v_mov_b64_e32 v[8:9], s[20:21]
	global_load_dword v7, v[8:9], off sc1
	v_mov_b64_e32 v[8:9], s[22:23]
	global_load_dword v8, v[8:9], off sc1
	s_waitcnt vmcnt(0) lgkmcnt(0)
	v_add_u32_e32 v10, v10, v7
	v_add_u32_e32 v12, v10, v8
	v_mov_b64_e32 v[10:11], s[24:25]
	global_load_dword v9, v[10:11], off sc1
	v_mov_b64_e32 v[10:11], s[26:27]
	global_load_dword v10, v[10:11], off sc1
	s_waitcnt vmcnt(0) lgkmcnt(0)
	v_add_u32_e32 v12, v12, v9
	v_add_u32_e32 v14, v12, v10
	v_mov_b64_e32 v[12:13], s[28:29]
	global_load_dword v11, v[12:13], off sc1
	v_mov_b64_e32 v[12:13], s[34:35]
	global_load_dword v12, v[12:13], off sc1
	s_waitcnt vmcnt(0) lgkmcnt(0)
	v_add_u32_e32 v14, v14, v11
	v_add_u32_e32 v16, v14, v12
	v_mov_b64_e32 v[14:15], s[36:37]
	global_load_dword v13, v[14:15], off sc1
	v_mov_b64_e32 v[14:15], s[38:39]
	global_load_dword v14, v[14:15], off sc1
	s_waitcnt vmcnt(0) lgkmcnt(0)
	v_add_u32_e32 v16, v16, v13
	v_add_u32_e32 v18, v16, v14
	v_mov_b64_e32 v[16:17], s[40:41]
	global_load_dword v15, v[16:17], off sc1
	v_mov_b64_e32 v[16:17], s[42:43]
	global_load_dword v16, v[16:17], off sc1
	s_waitcnt vmcnt(0) lgkmcnt(0)
	v_add_u32_e32 v18, v18, v15
	v_add_u32_e32 v17, v18, v16
	v_cmp_ne_u32_e32 vcc, s77, v17
	s_and_saveexec_b64 s[88:89], vcc
	s_cbranch_execz .LBB0_868
	s_and_b32 s48, s31, 0xff
	s_mov_b64 s[90:91], -1
	s_cmp_eq_u32 s48, 0
	s_mov_b64 s[94:95], -1
	s_mov_b64 s[92:93], -1
	s_sleep 1
	s_cbranch_scc1 .LBB0_872
	s_and_saveexec_b64 s[48:49], s[94:95]
	s_cbranch_execz .LBB0_867
	s_branch .LBB0_875
.LBB0_872:
	v_mov_b64_e32 v[18:19], s[6:7]
	global_load_dword v17, v[18:19], off sc1
	s_mov_b64 s[94:95], 0
	s_waitcnt vmcnt(0) lgkmcnt(0)
	v_cmp_eq_u32_e32 vcc, 0, v17
	s_and_saveexec_b64 s[96:97], vcc
	s_cmp_lt_u32 s31, 0x40001
	s_cselect_b64 s[48:49], -1, 0
	s_xor_b64 s[92:93], exec, -1
	s_and_b64 s[94:95], s[48:49], exec
	s_or_b64 exec, exec, s[96:97]
	s_and_saveexec_b64 s[48:49], s[94:95]
	s_cbranch_execz .LBB0_867

; __device__ __forceinline__ unsigned xb_ld(unsigned* p)              { return __hip_atomic_load(p, __ATOMIC_RELAXED, __HIP_MEMORY_SCOPE_AGENT); }
; __device__ __forceinline__ unsigned xb_add(unsigned* p, unsigned v) { return __hip_atomic_fetch_add(p, v, __ATOMIC_RELAXED, __HIP_MEMORY_SCOPE_AGENT); }
; #define XB_SPIN(cond, bar) do { unsigned _sp = 0; while (cond) { __builtin_amdgcn_s_sleep(1); \
;     if ((++_sp & 255u) == 0u) { if (xb_ld(&(bar)[XB_TMO])) break; if (_sp > XB_SPIN_CAP) { atomicAdd(&(bar)[XB_TMO], 1u); break; } } } } while (0)
; __device__ __forceinline__ void xcd_barrier(unsigned* bar_, volatile LAS unsigned* st_) {
;     ...
;         unsigned nloc = b.st[0], nx = b.st[1];
;         if (nloc == 0u) { xcd_barrier_complete(bar, b.x, nloc, nx); b.st[0] = nloc; b.st[1] = nx; }
;         const unsigned old = xb_add(&bar[XB_XSUB(b.x)], 1u);
;         const unsigned gen = old / nloc;
;         if (old + 1u == (gen + 1u) * nloc) {
;             __builtin_amdgcn_fence(__ATOMIC_RELEASE, "agent");
;             asm volatile("s_waitcnt vmcnt(0)" ::: "memory");
;             const unsigned og = xb_add(&bar[XB_TOP], 1u);
;             const unsigned tg = og / nx;
;             if (og + 1u == (tg + 1u) * nx) xb_add(&bar[XB_TOPGEN], 1u);
;             else XB_SPIN(xb_ld(&bar[XB_TOPGEN]) == tg, bar);
;             __builtin_amdgcn_fence(__ATOMIC_ACQUIRE, "agent");
;             xb_add(&bar[XB_XGEN(b.x)], 1u);
;             asm volatile("s_waitcnt vmcnt(0)" ::: "memory");
;         } else {
;             XB_SPIN(xb_ld(&bar[XB_XGEN(b.x)]) == gen, bar);
.LBB0_880:
	s_lshl_b32 s6, s30, 8
	s_add_u32 s6, s86, s6
	s_addc_u32 s7, s87, 0
	v_mov_b32_e32 v1, s6
	v_add_co_u32_e32 v6, vcc, 0x1a401000, v1
	v_mov_b32_e32 v1, s7
	s_nop 0
	v_addc_co_u32_e32 v7, vcc, 0, v1, vcc
	flat_atomic_add v1, v[6:7], v237 offset:1024 sc0
	v_cvt_f32_u32_e32 v3, v4
	v_sub_u32_e32 v5, 0, v4
	s_add_u32 s29, s6, 0x1a400000
	s_addc_u32 s28, s7, 0
	v_rcp_iflag_f32_e32 v3, v3
	s_waitcnt vmcnt(0) lgkmcnt(0)
	v_add_u32_e32 v6, 1, v1
	v_mul_f32_e32 v3, 0x4f7ffffe, v3
	v_cvt_u32_f32_e32 v3, v3
	v_mul_lo_u32 v5, v5, v3
	v_mul_hi_u32 v5, v3, v5
	v_add_u32_e32 v3, v3, v5
	v_mul_hi_u32 v3, v1, v3
	v_mul_lo_u32 v5, v3, v4
	v_sub_u32_e32 v1, v1, v5
	v_add_u32_e32 v7, 1, v3
	v_cmp_ge_u32_e32 vcc, v1, v4
	v_sub_u32_e32 v5, v1, v4
	s_nop 0
	v_cndmask_b32_e32 v3, v3, v7, vcc
	v_cndmask_b32_e32 v1, v1, v5, vcc
	v_add_u32_e32 v5, 1, v3
	v_cmp_ge_u32_e32 vcc, v1, v4
	s_nop 1
	v_cndmask_b32_e32 v1, v3, v5, vcc
	v_mad_u64_u32 v[4:5], s[6:7], v4, v1, v[4:5]
	v_cmp_ne_u32_e32 vcc, v6, v4
	s_and_saveexec_b64 s[6:7], vcc
	s_xor_b64 s[6:7], exec, s[6:7]
	s_cbranch_execz .LBB0_893
	v_mov_b32_e32 v2, s29
	v_add_co_u32_e32 v2, vcc, 0x2000, v2
	v_mov_b32_e32 v3, s28
	s_nop 0
	v_addc_co_u32_e32 v3, vcc, 0, v3, vcc
	global_load_dword v2, v[2:3], off offset:1024 sc1
	s_add_u32 s10, s29, 0x2400
	s_addc_u32 s11, s28, 0
	s_waitcnt vmcnt(0) lgkmcnt(0)
	v_cmp_eq_u32_e32 vcc, v2, v1
	s_and_saveexec_b64 s[8:9], vcc
	s_cbranch_execz .LBB0_892
	s_add_u32 s12, s86, 0x1a400200
	s_addc_u32 s13, s87, 0
	s_mov_b32 s30, 1
	s_mov_b64 s[14:15], 0
	s_branch .LBB0_884

; __device__ __forceinline__ unsigned xb_ld(unsigned* p)              { return __hip_atomic_load(p, __ATOMIC_RELAXED, __HIP_MEMORY_SCOPE_AGENT); }
; #define XB_SPIN(cond, bar) do { unsigned _sp = 0; while (cond) { __builtin_amdgcn_s_sleep(1); \
;     if ((++_sp & 255u) == 0u) { if (xb_ld(&(bar)[XB_TMO])) break; if (_sp > XB_SPIN_CAP) { atomicAdd(&(bar)[XB_TMO], 1u); break; } } } } while (0)
; __device__ __forceinline__ void xcd_barrier(unsigned* bar_, volatile LAS unsigned* st_) {
;     ...
;             XB_SPIN(xb_ld(&bar[XB_XGEN(b.x)]) == gen, bar);
.LBB0_884:
	s_and_b32 s22, s30, 0xff
	s_mov_b64 s[20:21], -1
	s_cmp_lg_u32 s22, 0
	s_mov_b64 s[22:23], -1
	s_sleep 1
	s_cbranch_scc1 .LBB0_888
	v_mov_b64_e32 v[2:3], s[12:13]
	global_load_dword v2, v[2:3], off sc1
	s_mov_b64 s[22:23], 0
	s_mov_b64 s[24:25], -1
	s_waitcnt vmcnt(0) lgkmcnt(0)
	v_cmp_eq_u32_e32 vcc, 0, v2
	s_and_saveexec_b64 s[26:27], vcc
	s_cmp_lt_u32 s30, 0x40001
	s_cselect_b64 s[22:23], -1, 0
	s_xor_b64 s[24:25], exec, -1
	s_and_b64 s[22:23], s[22:23], exec
	s_or_b64 exec, exec, s[26:27]
.LBB0_888:
	s_andn2_b64 s[18:19], s[18:19], exec
	s_and_b64 s[24:25], s[24:25], exec
	s_or_b64 s[18:19], s[18:19], s[24:25]
	s_and_saveexec_b64 s[24:25], s[22:23]
	s_cbranch_execz .LBB0_883
	v_mov_b64_e32 v[2:3], s[10:11]
	global_load_dword v2, v[2:3], off sc1
	s_add_i32 s30, s30, 1
	s_or_b64 s[18:19], s[18:19], exec
	s_waitcnt vmcnt(0) lgkmcnt(0)
	v_cmp_ne_u32_e32 vcc, v2, v1
	s_orn2_b64 s[20:21], vcc, exec
	s_branch .LBB0_883

; __device__ __forceinline__ unsigned xb_ld(unsigned* p)              { return __hip_atomic_load(p, __ATOMIC_RELAXED, __HIP_MEMORY_SCOPE_AGENT); }
; __device__ __forceinline__ unsigned xb_add(unsigned* p, unsigned v) { return __hip_atomic_fetch_add(p, v, __ATOMIC_RELAXED, __HIP_MEMORY_SCOPE_AGENT); }
; #define XB_SPIN(cond, bar) do { unsigned _sp = 0; while (cond) { __builtin_amdgcn_s_sleep(1); \
;     if ((++_sp & 255u) == 0u) { if (xb_ld(&(bar)[XB_TMO])) break; if (_sp > XB_SPIN_CAP) { atomicAdd(&(bar)[XB_TMO], 1u); break; } } } } while (0)
; __device__ __forceinline__ void xcd_barrier(unsigned* bar_, volatile LAS unsigned* st_) {
;     ...
;         if (old + 1u == (gen + 1u) * nloc) {
;             __builtin_amdgcn_fence(__ATOMIC_RELEASE, "agent");
;             asm volatile("s_waitcnt vmcnt(0)" ::: "memory");
;             const unsigned og = xb_add(&bar[XB_TOP], 1u);
;             const unsigned tg = og / nx;
;             if (og + 1u == (tg + 1u) * nx) xb_add(&bar[XB_TOPGEN], 1u);
;             else XB_SPIN(xb_ld(&bar[XB_TOPGEN]) == tg, bar);
.LBB0_893:
	s_andn2_saveexec_b64 s[6:7], s[6:7]
	s_cbranch_execz .LBB0_8
	v_mov_b32_e32 v1, s86
	v_add_co_u32_e32 v4, vcc, 0x1a403000, v1
	v_mov_b32_e32 v1, s87
	buffer_wbl2 sc1
	s_waitcnt vmcnt(0)
	v_addc_co_u32_e32 v5, vcc, 0, v1, vcc
	flat_atomic_add v3, v[4:5], v237 offset:1024 sc0
	v_cvt_f32_u32_e32 v1, v2
	v_sub_u32_e32 v4, 0, v2
	s_mov_b64 s[10:11], -1
	v_rcp_iflag_f32_e32 v1, v1
	s_nop 0
	v_mul_f32_e32 v1, 0x4f7ffffe, v1
	v_cvt_u32_f32_e32 v1, v1
	v_mul_lo_u32 v4, v4, v1
	v_mul_hi_u32 v4, v1, v4
	v_add_u32_e32 v1, v1, v4
	s_waitcnt vmcnt(0) lgkmcnt(0)
	v_mul_hi_u32 v1, v3, v1
	v_mul_lo_u32 v4, v1, v2
	v_sub_u32_e32 v4, v3, v4
	v_cmp_ge_u32_e32 vcc, v4, v2
	v_add_u32_e32 v5, 1, v1
	s_nop 0
	v_cndmask_b32_e32 v1, v1, v5, vcc
	v_sub_u32_e32 v5, v4, v2
	v_cndmask_b32_e32 v4, v4, v5, vcc
	v_cmp_ge_u32_e32 vcc, v4, v2
	v_add_u32_e32 v4, 1, v1
	s_nop 0
	v_cndmask_b32_e32 v1, v1, v4, vcc
	v_add_u32_e32 v4, 1, v3
	v_mad_u64_u32 v[2:3], s[6:7], v2, v1, v[2:3]
	s_add_u32 s6, s86, 0x1a403500
	s_addc_u32 s7, s87, 0
	v_cmp_ne_u32_e32 vcc, v4, v2
	v_mov_b64_e32 v[2:3], s[6:7]
	s_and_saveexec_b64 s[8:9], vcc
	s_cbranch_execz .LBB0_906
	v_mov_b64_e32 v[2:3], s[6:7]
	global_load_dword v2, v[2:3], off sc1
	s_mov_b64 s[14:15], 0
	s_waitcnt vmcnt(0) lgkmcnt(0)
	v_cmp_eq_u32_e32 vcc, v2, v1
	s_and_saveexec_b64 s[12:13], vcc
	s_cbranch_execz .LBB0_905
	s_add_u32 s10, s86, 0x1a400200
	s_addc_u32 s11, s87, 0
	s_mov_b32 s26, 1
	s_branch .LBB0_898

; __device__ __forceinline__ unsigned xb_ld(unsigned* p)              { return __hip_atomic_load(p, __ATOMIC_RELAXED, __HIP_MEMORY_SCOPE_AGENT); }
; #define XB_SPIN(cond, bar) do { unsigned _sp = 0; while (cond) { __builtin_amdgcn_s_sleep(1); \
;     if ((++_sp & 255u) == 0u) { if (xb_ld(&(bar)[XB_TMO])) break; if (_sp > XB_SPIN_CAP) { atomicAdd(&(bar)[XB_TMO], 1u); break; } } } } while (0)
; __device__ __forceinline__ void xcd_barrier(unsigned* bar_, volatile LAS unsigned* st_) {
;     ...
;             else XB_SPIN(xb_ld(&bar[XB_TOPGEN]) == tg, bar);
.LBB0_900:
	v_mov_b64_e32 v[2:3], s[10:11]
	global_load_dword v2, v[2:3], off sc1
	s_mov_b64 s[22:23], 0
	s_mov_b64 s[20:21], -1
	s_waitcnt vmcnt(0) lgkmcnt(0)
	v_cmp_eq_u32_e32 vcc, 0, v2
	s_and_saveexec_b64 s[24:25], vcc
	s_cmp_lt_u32 s26, 0x40001
	s_cselect_b64 s[22:23], -1, 0
	s_xor_b64 s[20:21], exec, -1
	s_and_b64 s[22:23], s[22:23], exec
	s_or_b64 exec, exec, s[24:25]
	s_and_saveexec_b64 s[24:25], s[22:23]
	s_cbranch_execz .LBB0_897
.LBB0_903:
	v_mov_b64_e32 v[2:3], s[6:7]
	global_load_dword v2, v[2:3], off sc1
	s_add_i32 s26, s26, 1
	s_or_b64 s[20:21], s[20:21], exec
	s_waitcnt vmcnt(0) lgkmcnt(0)
	v_cmp_ne_u32_e32 vcc, v2, v1
	s_orn2_b64 s[18:19], vcc, exec
	s_branch .LBB0_897
